# first K-iteration of each tile: DMA waits no longer force the previous tile's epilogue stores (vmcnt 26 in 4 phases), prologue drains its stages before the first tile
# baseline (speedup 1.0000x reference)
; #define PG8_STAGE(bufoff, gbase, voff) do { _Pragma("unroll") for (int _i = 0; _i < 2; ++_i) \
;         __builtin_amdgcn_global_load_lds((const unsigned*)((const char*)(gbase) + (voff)[_i]), (LAS unsigned*)(lds + (bufoff) + ldsw + _i * 8192), 16, 0, 0); } while (0)
; #define PG8_WAIT_V(n) asm volatile("s_waitcnt vmcnt(" #n ")" ::: "memory")
; #define PG8_BAR __builtin_amdgcn_s_barrier()
; template <class Epi, class Sched>
; __device__ __forceinline__ void gemm_phase(LAS unsigned char* lds, const Gemm g, const Sched& S, const Epi& E) {
;     ...
;     const char* cA = (const char*)g.A + (size_t)cur.pm * tstep; const char* cB = (const char*)g.Bt + (size_t)cur.pn * tstep;
;     PG8_STAGE(PG8_SB(0, 0), cB, voffB); PG8_STAGE(PG8_SA(0, 0), cA, voffA); PG8_STAGE(PG8_SB(0, 1), cB + hstep, voffB); PG8_STAGE(PG8_SA(0, 1), cA + hstep, voffA);
;     if (wr == 1) PG8_BAR;
;     PG8_WAIT_V(4); PG8_BAR;
;     PG8_STAGE(PG8_SB(1, 0), cB + kstep, voffB); PG8_STAGE(PG8_SA(1, 0), cA + kstep, voffA); PG8_STAGE(PG8_SB(1, 1), cB + hstep + kstep, voffB);
;     PG8_WAIT_V(6); PG8_BAR;
.LBB0_231:
	s_lshl_b32 s0, s0, 5
	s_lshl_b32 s34, s1, 6
	s_lshl_b32 s3, s1, 13
	s_and_b32 s35, s0, 0x60
	s_mov_b64 s[0:1], 0x80
	s_add_i32 m0, s13, 0x18000
	v_lshl_add_u64 v[6:7], v[6:7], 0, s[0:1]
	s_lshl_b32 s6, s35, 7
	s_waitcnt vmcnt(4)
	s_barrier
	global_load_lds_dwordx4 v[6:7], off
	v_lshl_add_u64 v[4:5], v[4:5], 0, s[0:1]
	s_add_i32 m0, s13, 0x1a000
	s_add_i32 s36, s13, 0x8000
	s_add_i32 s37, s13, 0xa000
	global_load_lds_dwordx4 v[4:5], off
	v_lshl_add_u64 v[2:3], v[2:3], 0, s[0:1]
	s_mov_b32 m0, s36
	s_add_u32 s4, s18, 0x40080
	global_load_lds_dwordx4 v[2:3], off
	v_lshl_add_u64 v[0:1], v[0:1], 0, s[0:1]
	s_mov_b32 m0, s37
	s_addc_u32 s5, s19, 0
	global_load_lds_dwordx4 v[0:1], off
	s_add_i32 m0, s13, 0x1c000
	v_lshl_add_u64 v[0:1], s[4:5], 0, v[132:133]
	global_load_lds_dwordx4 v[0:1], off
	v_lshl_add_u64 v[0:1], s[4:5], 0, v[128:129]
	s_add_i32 m0, s13, 0x1e000
	v_bfe_u32 v145, v8, 4, 2
	global_load_lds_dwordx4 v[0:1], off
	v_and_b32_e32 v144, 15, v8
	v_lshlrev_b32_e32 v0, 4, v145
	v_lshlrev_b32_e32 v1, 2, v8
	v_lshl_or_b32 v0, v144, 6, v0
	v_and_b32_e32 v1, 32, v1
	v_bitop3_b32 v2, v0, s3, v1 bitop3:0xde
	v_bitop3_b32 v146, v0, s6, v1 bitop3:0xde
	v_lshlrev_b32_e32 v0, 14, v13
	v_and_b32_e32 v0, 0xffff8000, v0
	v_lshl_add_u32 v0, v12, 11, v0
	v_and_b32_e32 v1, 1, v13
	v_lshl_or_b32 v0, v1, 6, v0
	v_lshl_add_u32 v136, v14, 1, v0
	v_lshlrev_b32_e32 v0, 14, v9
	v_and_b32_e32 v0, 0xffff8000, v0
	s_waitcnt vmcnt(0)
	v_lshl_add_u32 v0, v10, 11, v0
	v_and_b32_e32 v1, 1, v9
	v_lshl_or_b32 v0, v1, 6, v0
	s_add_i32 s40, 0, 0x10000
	s_add_i32 s41, 0, 0x14000
	s_sext_i32_i16 s43, s2
	s_mov_b32 s38, 0
	s_ashr_i32 s39, s76, 31
	v_mov_b32_e32 v137, v133
	v_lshl_add_u32 v138, v11, 1, v0
	v_mov_b32_e32 v139, v133
	v_mov_b64_e32 v[140:141], 0x18c0
	v_mov_b64_e32 v[142:143], 0x18bf
	v_add_u32_e32 v147, s40, v146
	v_add_u32_e32 v148, 0, v2
	v_add_u32_e32 v149, s41, v146
	s_movk_i32 s42, 0x1600
	s_barrier

; #define PG8_STAGE(bufoff, gbase, voff) do { _Pragma("unroll") for (int _i = 0; _i < 2; ++_i) \
;         __builtin_amdgcn_global_load_lds((const unsigned*)((const char*)(gbase) + (voff)[_i]), (LAS unsigned*)(lds + (bufoff) + ldsw + _i * 8192), 16, 0, 0); } while (0)
; #define PG8_LDA(dst, b, h) do { _Pragma("unroll") for (int m = 0; m < 4; ++m) _Pragma("unroll") for (int k = 0; k < 2; ++k) dst[m][k] = *(const LAS bf16x8*)(lds + PG8_SA(b, h) + aoff + m * 2048 + k * 1024); } while (0)
; #define PG8_LDB(dst, b, h) do { _Pragma("unroll") for (int n = 0; n < 2; ++n) _Pragma("unroll") for (int k = 0; k < 2; ++k) dst[n][k] = *(const LAS bf16x8*)(lds + PG8_SB(b, h) + boff + n * 2048 + k * 1024); } while (0)
; #define PG8_MMA(ai, bj, At, Bt) do { __builtin_amdgcn_s_setprio(1); _Pragma("unroll") for (int m = 0; m < 4; ++m) _Pragma("unroll") for (int n = 0; n < 2; ++n) _Pragma("unroll") for (int k = 0; k < 2; ++k) \
;         acc[ai][bj][m][n] = __builtin_amdgcn_mfma_f32_16x16x32_bf16(Bt[n][k], At[m][k], acc[ai][bj][m][n], 0, 0, 0); __builtin_amdgcn_s_setprio(0); } while (0)
; #define PG8_WAIT_L(n) asm volatile("s_waitcnt lgkmcnt(" #n ")" ::: "memory")
; template <class Epi, class Sched>
; __device__ __forceinline__ void gemm_phase(LAS unsigned char* lds, const Gemm g, const Sched& S, const Epi& E) {
;     ...
;         const bool has_next = S.next(ui + 1, nxt);
;         const char* nA = has_next ? (const char*)g.A + (size_t)nxt.pm * tstep : cA; const char* nB = has_next ? (const char*)g.Bt + (size_t)nxt.pn * tstep : cB;
;         for (int t = 0; t < nt; t += 2) {
;             const bool last = (t == nt - 2);
;             const char* a1 = cA + (size_t)(t + 1) * kstep;
;             const char* a2 = last ? nA : cA + (size_t)(t + 2) * kstep; const char* b2 = last ? nB : cB + (size_t)(t + 2) * kstep;
;             const char* a3 = a2 + kstep; const char* b3 = b2 + kstep;
;             PG8_LDB(B0, 0, 0); PG8_SCHED; PG8_LDA(At, 0, 0); PG8_STAGE(PG8_SA(1, 1), a1 + hstep, voffA);
;             PG8_WAIT_L(8); PG8_BAR; PG8_WAIT_L(0); PG8_MMA(0, 0, At, B0); PG8_BAR; PG8_SCHED;
;             PG8_LDB(B1, 0, 1); PG8_STAGE(PG8_SB(0, 0), b2, voffB);
;             PG8_BAR; PG8_WAIT_L(0); PG8_MMA(0, 1, At, B1); PG8_BAR;
;             PG8_LDA(At, 0, 1); PG8_STAGE(PG8_SA(0, 0), a2, voffA);
;             PG8_BAR; PG8_WAIT_L(0); PG8_MMA(1, 0, At, B0); PG8_BAR; PG8_SCHED;
.LBB0_234:
	s_ashr_i32 s7, s6, 31
	v_cmp_lt_i64_e32 vcc, s[8:9], v[140:141]
	s_lshl_b64 s[8:9], s[6:7], 19
	s_add_u32 s8, s96, s8
	s_addc_u32 s9, s97, s9
	s_and_b64 s[10:11], vcc, exec
	s_cselect_b32 s7, s9, s15
	s_cselect_b32 s44, s8, s14
	s_ashr_i32 s5, s4, 31
	s_lshl_b64 s[10:11], s[4:5], 19
	s_add_u32 s10, s72, s10
	s_addc_u32 s11, s73, s11
	s_and_b64 s[16:17], vcc, exec
	s_cselect_b32 s5, s11, s19
	s_cselect_b32 s45, s10, s18
	s_add_u32 s14, s14, 0x40080
	s_addc_u32 s15, s15, 0
	s_add_u32 s46, s18, 0x100
	s_addc_u32 s47, s19, 0
	s_mov_b32 s48, -2
	ds_read_b128 v[150:153], v147
	ds_read_b128 v[154:157], v147 offset:1024
	ds_read_b128 v[158:161], v147 offset:2048
	ds_read_b128 v[162:165], v147 offset:3072
	s_add_u32 s16, s14, 0xfffc0080
	s_addc_u32 s17, s15, -1
	s_cmp_eq_u32 s48, 12
	s_cselect_b32 s23, s7, s17
	s_cselect_b32 s22, s44, s16
	s_cselect_b32 s19, s5, s47
	s_cselect_b32 s18, s45, s46
	s_add_i32 m0, s13, 0xc000
	ds_read_b128 v[166:169], v148
	ds_read_b128 v[170:173], v148 offset:1024
	ds_read_b128 v[174:177], v148 offset:2048
	ds_read_b128 v[178:181], v148 offset:3072
	ds_read_b128 v[182:185], v148 offset:4096
	ds_read_b128 v[186:189], v148 offset:5120
	ds_read_b128 v[190:193], v148 offset:6144
	ds_read_b128 v[194:197], v148 offset:7168
	global_load_lds_dwordx4 v136, s[14:15]
	s_add_i32 m0, s13, 0xe000
	s_nop 0
	global_load_lds_dwordx4 v138, s[14:15]
	s_waitcnt lgkmcnt(8)
	s_waitcnt vmcnt(26)
	s_barrier
	s_waitcnt lgkmcnt(0)
	s_setprio 1
	s_waitcnt lgkmcnt(0)
	v_mfma_f32_16x16x32_bf16 v[124:127], v[150:153], v[166:169], 0
	v_mfma_f32_16x16x32_bf16 v[116:119], v[158:161], v[166:169], 0
	v_mfma_f32_16x16x32_bf16 v[108:111], v[150:153], v[174:177], 0
	v_mfma_f32_16x16x32_bf16 v[100:103], v[158:161], v[174:177], 0
	v_mfma_f32_16x16x32_bf16 v[92:95], v[150:153], v[182:185], 0
	v_mfma_f32_16x16x32_bf16 v[84:87], v[158:161], v[182:185], 0
	v_mfma_f32_16x16x32_bf16 v[76:79], v[150:153], v[190:193], 0
	v_mfma_f32_16x16x32_bf16 v[68:71], v[158:161], v[190:193], 0
	v_mfma_f32_16x16x32_bf16 v[124:127], v[154:157], v[170:173], v[124:127]
	v_mfma_f32_16x16x32_bf16 v[116:119], v[162:165], v[170:173], v[116:119]
	v_mfma_f32_16x16x32_bf16 v[108:111], v[154:157], v[178:181], v[108:111]
	v_mfma_f32_16x16x32_bf16 v[100:103], v[162:165], v[178:181], v[100:103]
	v_mfma_f32_16x16x32_bf16 v[92:95], v[154:157], v[186:189], v[92:95]
	v_mfma_f32_16x16x32_bf16 v[84:87], v[162:165], v[186:189], v[84:87]
	v_mfma_f32_16x16x32_bf16 v[76:79], v[154:157], v[194:197], v[76:79]
	v_mfma_f32_16x16x32_bf16 v[68:71], v[162:165], v[194:197], v[68:71]
	s_setprio 0
	s_barrier
	s_add_i32 s16, s40, s25
	s_mov_b32 m0, s16
	ds_read_b128 v[202:205], v149
	ds_read_b128 v[206:209], v149 offset:1024
	ds_read_b128 v[210:213], v149 offset:2048
	ds_read_b128 v[214:217], v149 offset:3072
	global_load_lds_dwordx4 v132, s[18:19]
	s_add_i32 m0, s16, 0x2000
	s_nop 0
	global_load_lds_dwordx4 v128, s[18:19]
	s_waitcnt vmcnt(26)
	s_barrier
	s_waitcnt lgkmcnt(0)
	s_setprio 1
	s_waitcnt lgkmcnt(0)
	v_mfma_f32_16x16x32_bf16 v[120:123], v[202:205], v[166:169], 0
	v_mfma_f32_16x16x32_bf16 v[112:115], v[210:213], v[166:169], 0
	v_mfma_f32_16x16x32_bf16 v[104:107], v[202:205], v[174:177], 0
	v_mfma_f32_16x16x32_bf16 v[96:99], v[210:213], v[174:177], 0
	v_mfma_f32_16x16x32_bf16 v[88:91], v[202:205], v[182:185], 0
	v_mfma_f32_16x16x32_bf16 v[80:83], v[210:213], v[182:185], 0
	v_mfma_f32_16x16x32_bf16 v[72:75], v[202:205], v[190:193], 0
	v_mfma_f32_16x16x32_bf16 v[64:67], v[210:213], v[190:193], 0
	v_mfma_f32_16x16x32_bf16 v[120:123], v[206:209], v[170:173], v[120:123]
	v_mfma_f32_16x16x32_bf16 v[112:115], v[214:217], v[170:173], v[112:115]
	v_mfma_f32_16x16x32_bf16 v[104:107], v[206:209], v[178:181], v[104:107]
	v_mfma_f32_16x16x32_bf16 v[96:99], v[214:217], v[178:181], v[96:99]
	v_mfma_f32_16x16x32_bf16 v[88:91], v[206:209], v[186:189], v[88:91]
	v_mfma_f32_16x16x32_bf16 v[80:83], v[214:217], v[186:189], v[80:83]
	v_mfma_f32_16x16x32_bf16 v[72:75], v[206:209], v[194:197], v[72:75]
	v_mfma_f32_16x16x32_bf16 v[64:67], v[214:217], v[194:197], v[64:67]
	s_setprio 0
	s_mov_b32 m0, s13
	s_barrier
	ds_read_b128 v[166:169], v148 offset:16384
	ds_read_b128 v[170:173], v148 offset:17408
	ds_read_b128 v[174:177], v148 offset:18432
	ds_read_b128 v[178:181], v148 offset:19456
	ds_read_b128 v[182:185], v148 offset:20480
	ds_read_b128 v[186:189], v148 offset:21504
	ds_read_b128 v[190:193], v148 offset:22528
	ds_read_b128 v[194:197], v148 offset:23552
	global_load_lds_dwordx4 v134, s[22:23]
	s_mov_b32 m0, s28
	s_nop 0
	global_load_lds_dwordx4 v130, s[22:23]
	s_barrier
	s_waitcnt lgkmcnt(0)
	s_setprio 1
	s_waitcnt lgkmcnt(0)
	v_mfma_f32_16x16x32_bf16 v[60:63], v[150:153], v[166:169], 0
	v_mfma_f32_16x16x32_bf16 v[56:59], v[158:161], v[166:169], 0
	v_mfma_f32_16x16x32_bf16 v[44:47], v[150:153], v[174:177], 0
	v_mfma_f32_16x16x32_bf16 v[40:43], v[158:161], v[174:177], 0
	v_mfma_f32_16x16x32_bf16 v[28:31], v[150:153], v[182:185], 0
	v_mfma_f32_16x16x32_bf16 v[24:27], v[158:161], v[182:185], 0
	v_mfma_f32_16x16x32_bf16 v[12:15], v[150:153], v[190:193], 0
	v_mfma_f32_16x16x32_bf16 v[8:11], v[158:161], v[190:193], 0
	v_mfma_f32_16x16x32_bf16 v[60:63], v[154:157], v[170:173], v[60:63]
	v_mfma_f32_16x16x32_bf16 v[56:59], v[162:165], v[170:173], v[56:59]
	v_mfma_f32_16x16x32_bf16 v[44:47], v[154:157], v[178:181], v[44:47]
	v_mfma_f32_16x16x32_bf16 v[40:43], v[162:165], v[178:181], v[40:43]
	v_mfma_f32_16x16x32_bf16 v[28:31], v[154:157], v[186:189], v[28:31]
	v_mfma_f32_16x16x32_bf16 v[24:27], v[162:165], v[186:189], v[24:27]
	v_mfma_f32_16x16x32_bf16 v[12:15], v[154:157], v[194:197], v[12:15]
	v_mfma_f32_16x16x32_bf16 v[8:11], v[162:165], v[194:197], v[8:11]
	s_setprio 0
	s_barrier
; #define PG8_STAGE(bufoff, gbase, voff) do { _Pragma("unroll") for (int _i = 0; _i < 2; ++_i) \
;         __builtin_amdgcn_global_load_lds((const unsigned*)((const char*)(gbase) + (voff)[_i]), (LAS unsigned*)(lds + (bufoff) + ldsw + _i * 8192), 16, 0, 0); } while (0)
; #define PG8_LDA(dst, b, h) do { _Pragma("unroll") for (int m = 0; m < 4; ++m) _Pragma("unroll") for (int k = 0; k < 2; ++k) dst[m][k] = *(const LAS bf16x8*)(lds + PG8_SA(b, h) + aoff + m * 2048 + k * 1024); } while (0)
; #define PG8_LDB(dst, b, h) do { _Pragma("unroll") for (int n = 0; n < 2; ++n) _Pragma("unroll") for (int k = 0; k < 2; ++k) dst[n][k] = *(const LAS bf16x8*)(lds + PG8_SB(b, h) + boff + n * 2048 + k * 1024); } while (0)
; #define PG8_MMA(ai, bj, At, Bt) do { __builtin_amdgcn_s_setprio(1); _Pragma("unroll") for (int m = 0; m < 4; ++m) _Pragma("unroll") for (int n = 0; n < 2; ++n) _Pragma("unroll") for (int k = 0; k < 2; ++k) \
;         acc[ai][bj][m][n] = __builtin_amdgcn_mfma_f32_16x16x32_bf16(Bt[n][k], At[m][k], acc[ai][bj][m][n], 0, 0, 0); __builtin_amdgcn_s_setprio(0); } while (0)
; #define PG8_WAIT_V(n) asm volatile("s_waitcnt vmcnt(" #n ")" ::: "memory")
; #define PG8_WAIT_L(n) asm volatile("s_waitcnt lgkmcnt(" #n ")" ::: "memory")
; #define PG8_BAR __builtin_amdgcn_s_barrier()
; #define PG8_SCHED __builtin_amdgcn_sched_barrier(0)
; template <class Epi, class Sched>
; __device__ __forceinline__ void gemm_phase(LAS unsigned char* lds, const Gemm g, const Sched& S, const Epi& E) {
;     ...
;             PG8_BAR; PG8_WAIT_L(0); PG8_MMA(1, 0, At, B0); PG8_BAR; PG8_SCHED;
;             PG8_STAGE(PG8_SB(0, 1), b2 + hstep, voffB);
;             PG8_WAIT_V(6); PG8_BAR; PG8_MMA(1, 1, At, B1); PG8_BAR;
;             PG8_LDB(B0, 1, 0); PG8_SCHED; PG8_LDA(At, 1, 0); PG8_STAGE(PG8_SA(0, 1), a2 + hstep, voffA);
;             PG8_WAIT_L(8); PG8_BAR; PG8_WAIT_L(0); PG8_MMA(0, 0, At, B0); PG8_BAR; PG8_SCHED;
;             PG8_LDB(B1, 1, 1); PG8_STAGE(PG8_SB(1, 0), b3, voffB);
;             PG8_BAR; PG8_WAIT_L(0); PG8_MMA(0, 1, At, B1); PG8_BAR;
;             PG8_LDA(At, 1, 1); PG8_STAGE(PG8_SA(1, 0), a3, voffA);
;             PG8_BAR; PG8_WAIT_L(0); PG8_MMA(1, 0, At, B0); PG8_BAR; PG8_SCHED;
	s_add_u32 s16, s18, 0x40000
	s_addc_u32 s17, s19, 0
	s_add_i32 s20, s41, s25
	s_mov_b32 m0, s20
	s_nop 0
	global_load_lds_dwordx4 v132, s[16:17]
	s_add_i32 m0, s20, 0x2000
	s_nop 0
	global_load_lds_dwordx4 v128, s[16:17]
	s_waitcnt vmcnt(26)
	s_barrier
	s_setprio 1
	v_mfma_f32_16x16x32_bf16 v[52:55], v[202:205], v[166:169], 0
	v_mfma_f32_16x16x32_bf16 v[48:51], v[210:213], v[166:169], 0
	v_mfma_f32_16x16x32_bf16 v[36:39], v[202:205], v[174:177], 0
	v_mfma_f32_16x16x32_bf16 v[32:35], v[210:213], v[174:177], 0
	v_mfma_f32_16x16x32_bf16 v[20:23], v[202:205], v[182:185], 0
	v_mfma_f32_16x16x32_bf16 v[16:19], v[210:213], v[182:185], 0
	v_mfma_f32_16x16x32_bf16 v[4:7], v[202:205], v[190:193], 0
	v_mfma_f32_16x16x32_bf16 v[0:3], v[210:213], v[190:193], 0
	v_mfma_f32_16x16x32_bf16 v[52:55], v[206:209], v[170:173], v[52:55]
	v_mfma_f32_16x16x32_bf16 v[48:51], v[214:217], v[170:173], v[48:51]
	v_mfma_f32_16x16x32_bf16 v[36:39], v[206:209], v[178:181], v[36:39]
	v_mfma_f32_16x16x32_bf16 v[32:35], v[214:217], v[178:181], v[32:35]
	v_mfma_f32_16x16x32_bf16 v[20:23], v[206:209], v[186:189], v[20:23]
	v_mfma_f32_16x16x32_bf16 v[16:19], v[214:217], v[186:189], v[16:19]
	v_mfma_f32_16x16x32_bf16 v[4:7], v[206:209], v[194:197], v[4:7]
	v_mfma_f32_16x16x32_bf16 v[0:3], v[214:217], v[194:197], v[0:3]
	s_setprio 0
	s_add_i32 s20, 0, 0x18000
	v_add_u32_e32 v162, s20, v146
	s_barrier
	ds_read_b128 v[150:153], v162
	ds_read_b128 v[154:157], v162 offset:1024
	ds_read_b128 v[158:161], v162 offset:2048
	ds_read_b128 v[162:165], v162 offset:3072
	s_add_u32 s16, s22, 0x40000
	s_addc_u32 s17, s23, 0
	s_mov_b32 m0, s29
	ds_read_b128 v[166:169], v148 offset:32768
	ds_read_b128 v[170:173], v148 offset:33792
	ds_read_b128 v[174:177], v148 offset:34816
	ds_read_b128 v[178:181], v148 offset:35840
	ds_read_b128 v[182:185], v148 offset:36864
	ds_read_b128 v[186:189], v148 offset:37888
	ds_read_b128 v[190:193], v148 offset:38912
	ds_read_b128 v[194:197], v148 offset:39936
	global_load_lds_dwordx4 v134, s[16:17]
	s_mov_b32 m0, s33
	s_nop 0
	global_load_lds_dwordx4 v130, s[16:17]
	s_waitcnt lgkmcnt(8)
	s_waitcnt vmcnt(26)
	s_barrier
	s_waitcnt lgkmcnt(0)
	s_setprio 1
	s_waitcnt lgkmcnt(0)
	v_mfma_f32_16x16x32_bf16 v[124:127], v[150:153], v[166:169], v[124:127]
	v_mfma_f32_16x16x32_bf16 v[116:119], v[158:161], v[166:169], v[116:119]
	v_mfma_f32_16x16x32_bf16 v[108:111], v[150:153], v[174:177], v[108:111]
	v_mfma_f32_16x16x32_bf16 v[100:103], v[158:161], v[174:177], v[100:103]
	v_mfma_f32_16x16x32_bf16 v[92:95], v[150:153], v[182:185], v[92:95]
	v_mfma_f32_16x16x32_bf16 v[84:87], v[158:161], v[182:185], v[84:87]
	v_mfma_f32_16x16x32_bf16 v[76:79], v[150:153], v[190:193], v[76:79]
	v_mfma_f32_16x16x32_bf16 v[68:71], v[158:161], v[190:193], v[68:71]
	v_mfma_f32_16x16x32_bf16 v[124:127], v[154:157], v[170:173], v[124:127]
	v_mfma_f32_16x16x32_bf16 v[116:119], v[162:165], v[170:173], v[116:119]
	v_mfma_f32_16x16x32_bf16 v[108:111], v[154:157], v[178:181], v[108:111]
	v_mfma_f32_16x16x32_bf16 v[100:103], v[162:165], v[178:181], v[100:103]
	v_mfma_f32_16x16x32_bf16 v[92:95], v[154:157], v[186:189], v[92:95]
	v_mfma_f32_16x16x32_bf16 v[84:87], v[162:165], v[186:189], v[84:87]
	v_mfma_f32_16x16x32_bf16 v[76:79], v[154:157], v[194:197], v[76:79]
	v_mfma_f32_16x16x32_bf16 v[68:71], v[162:165], v[194:197], v[68:71]
	s_setprio 0
	s_barrier
	s_add_i32 s21, 0, 0x1c000
	s_add_i32 s16, s20, s25
	v_add_u32_e32 v214, s21, v146
	s_add_u32 s0, s18, 0x80
	s_addc_u32 s1, s19, 0
	s_mov_b32 m0, s16
	ds_read_b128 v[202:205], v214
	ds_read_b128 v[206:209], v214 offset:1024
	ds_read_b128 v[210:213], v214 offset:2048
	ds_read_b128 v[214:217], v214 offset:3072
	global_load_lds_dwordx4 v132, s[0:1]
	s_add_i32 m0, s16, 0x2000
	s_nop 0
	global_load_lds_dwordx4 v128, s[0:1]
	s_waitcnt vmcnt(10)
	s_barrier
; #define PG8_STAGE(bufoff, gbase, voff) do { _Pragma("unroll") for (int _i = 0; _i < 2; ++_i) \
;         __builtin_amdgcn_global_load_lds((const unsigned*)((const char*)(gbase) + (voff)[_i]), (LAS unsigned*)(lds + (bufoff) + ldsw + _i * 8192), 16, 0, 0); } while (0)
; #define PG8_MMA(ai, bj, At, Bt) do { __builtin_amdgcn_s_setprio(1); _Pragma("unroll") for (int m = 0; m < 4; ++m) _Pragma("unroll") for (int n = 0; n < 2; ++n) _Pragma("unroll") for (int k = 0; k < 2; ++k) \
;         acc[ai][bj][m][n] = __builtin_amdgcn_mfma_f32_16x16x32_bf16(Bt[n][k], At[m][k], acc[ai][bj][m][n], 0, 0, 0); __builtin_amdgcn_s_setprio(0); } while (0)
; #define PG8_WAIT_V(n) asm volatile("s_waitcnt vmcnt(" #n ")" ::: "memory")
; #define PG8_WAIT_L(n) asm volatile("s_waitcnt lgkmcnt(" #n ")" ::: "memory")
; #define PG8_BAR __builtin_amdgcn_s_barrier()
; #define PG8_SCHED __builtin_amdgcn_sched_barrier(0)
; template <class Epi, class Sched>
; __device__ __forceinline__ void gemm_phase(LAS unsigned char* lds, const Gemm g, const Sched& S, const Epi& E) {
;     ...
;             PG8_BAR; PG8_WAIT_L(0); PG8_MMA(1, 0, At, B0); PG8_BAR; PG8_SCHED;
;             PG8_STAGE(PG8_SB(1, 1), b3 + hstep, voffB);
;             PG8_WAIT_V(6); PG8_BAR; PG8_MMA(1, 1, At, B1); PG8_BAR;
;         }
	s_waitcnt lgkmcnt(0)
	s_setprio 1
	s_waitcnt lgkmcnt(0)
	v_mfma_f32_16x16x32_bf16 v[120:123], v[202:205], v[166:169], v[120:123]
	v_mfma_f32_16x16x32_bf16 v[112:115], v[210:213], v[166:169], v[112:115]
	v_mfma_f32_16x16x32_bf16 v[104:107], v[202:205], v[174:177], v[104:107]
	v_mfma_f32_16x16x32_bf16 v[96:99], v[210:213], v[174:177], v[96:99]
	v_mfma_f32_16x16x32_bf16 v[88:91], v[202:205], v[182:185], v[88:91]
	v_mfma_f32_16x16x32_bf16 v[80:83], v[210:213], v[182:185], v[80:83]
	v_mfma_f32_16x16x32_bf16 v[72:75], v[202:205], v[190:193], v[72:75]
	v_mfma_f32_16x16x32_bf16 v[64:67], v[210:213], v[190:193], v[64:67]
	v_mfma_f32_16x16x32_bf16 v[120:123], v[206:209], v[170:173], v[120:123]
	v_mfma_f32_16x16x32_bf16 v[112:115], v[214:217], v[170:173], v[112:115]
	v_mfma_f32_16x16x32_bf16 v[104:107], v[206:209], v[178:181], v[104:107]
	v_mfma_f32_16x16x32_bf16 v[96:99], v[214:217], v[178:181], v[96:99]
	v_mfma_f32_16x16x32_bf16 v[88:91], v[206:209], v[186:189], v[88:91]
	v_mfma_f32_16x16x32_bf16 v[80:83], v[214:217], v[186:189], v[80:83]
	v_mfma_f32_16x16x32_bf16 v[72:75], v[206:209], v[194:197], v[72:75]
	v_mfma_f32_16x16x32_bf16 v[64:67], v[214:217], v[194:197], v[64:67]
	s_setprio 0
	s_mov_b32 m0, s36
	s_add_u32 s0, s22, 0x80
	s_addc_u32 s1, s23, 0
	s_barrier
	ds_read_b128 v[166:169], v148 offset:49152
	ds_read_b128 v[170:173], v148 offset:50176
	ds_read_b128 v[174:177], v148 offset:51200
	ds_read_b128 v[178:181], v148 offset:52224
	ds_read_b128 v[182:185], v148 offset:53248
	ds_read_b128 v[186:189], v148 offset:54272
	ds_read_b128 v[190:193], v148 offset:55296
	ds_read_b128 v[194:197], v148 offset:56320
	global_load_lds_dwordx4 v134, s[0:1]
	s_mov_b32 m0, s37
	s_nop 0
	global_load_lds_dwordx4 v130, s[0:1]
	s_barrier
	s_waitcnt lgkmcnt(0)
	s_setprio 1
	s_waitcnt lgkmcnt(0)
	v_mfma_f32_16x16x32_bf16 v[60:63], v[150:153], v[166:169], v[60:63]
	v_mfma_f32_16x16x32_bf16 v[56:59], v[158:161], v[166:169], v[56:59]
	v_mfma_f32_16x16x32_bf16 v[44:47], v[150:153], v[174:177], v[44:47]
	v_mfma_f32_16x16x32_bf16 v[40:43], v[158:161], v[174:177], v[40:43]
	v_mfma_f32_16x16x32_bf16 v[28:31], v[150:153], v[182:185], v[28:31]
	v_mfma_f32_16x16x32_bf16 v[24:27], v[158:161], v[182:185], v[24:27]
	v_mfma_f32_16x16x32_bf16 v[12:15], v[150:153], v[190:193], v[12:15]
	v_mfma_f32_16x16x32_bf16 v[8:11], v[158:161], v[190:193], v[8:11]
	v_mfma_f32_16x16x32_bf16 v[60:63], v[154:157], v[170:173], v[60:63]
	v_mfma_f32_16x16x32_bf16 v[56:59], v[162:165], v[170:173], v[56:59]
	v_mfma_f32_16x16x32_bf16 v[44:47], v[154:157], v[178:181], v[44:47]
	v_mfma_f32_16x16x32_bf16 v[40:43], v[162:165], v[178:181], v[40:43]
	v_mfma_f32_16x16x32_bf16 v[28:31], v[154:157], v[186:189], v[28:31]
	v_mfma_f32_16x16x32_bf16 v[24:27], v[162:165], v[186:189], v[24:27]
	v_mfma_f32_16x16x32_bf16 v[12:15], v[154:157], v[194:197], v[12:15]
	v_mfma_f32_16x16x32_bf16 v[8:11], v[162:165], v[194:197], v[8:11]
	s_setprio 0
	s_barrier
	s_add_u32 s16, s18, 0x40080
	s_addc_u32 s17, s19, 0
	s_add_i32 s18, s21, s25
	s_mov_b32 m0, s18
	s_nop 0
	global_load_lds_dwordx4 v132, s[16:17]
	s_add_i32 m0, s18, 0x2000
	s_nop 0
	global_load_lds_dwordx4 v128, s[16:17]
	s_waitcnt vmcnt(10)
	s_barrier
	s_setprio 1
	v_mfma_f32_16x16x32_bf16 v[52:55], v[202:205], v[166:169], v[52:55]
	v_mfma_f32_16x16x32_bf16 v[48:51], v[210:213], v[166:169], v[48:51]
	v_mfma_f32_16x16x32_bf16 v[36:39], v[202:205], v[174:177], v[36:39]
	v_mfma_f32_16x16x32_bf16 v[32:35], v[210:213], v[174:177], v[32:35]
	v_mfma_f32_16x16x32_bf16 v[20:23], v[202:205], v[182:185], v[20:23]
	v_mfma_f32_16x16x32_bf16 v[16:19], v[210:213], v[182:185], v[16:19]
	v_mfma_f32_16x16x32_bf16 v[4:7], v[202:205], v[190:193], v[4:7]
	v_mfma_f32_16x16x32_bf16 v[0:3], v[210:213], v[190:193], v[0:3]
	v_mfma_f32_16x16x32_bf16 v[52:55], v[206:209], v[170:173], v[52:55]
	v_mfma_f32_16x16x32_bf16 v[48:51], v[214:217], v[170:173], v[48:51]
	v_mfma_f32_16x16x32_bf16 v[36:39], v[206:209], v[178:181], v[36:39]
	v_mfma_f32_16x16x32_bf16 v[32:35], v[214:217], v[178:181], v[32:35]
	v_mfma_f32_16x16x32_bf16 v[20:23], v[206:209], v[186:189], v[20:23]
	v_mfma_f32_16x16x32_bf16 v[16:19], v[214:217], v[186:189], v[16:19]
	v_mfma_f32_16x16x32_bf16 v[4:7], v[206:209], v[194:197], v[4:7]
	v_mfma_f32_16x16x32_bf16 v[0:3], v[214:217], v[194:197], v[0:3]
	s_setprio 0
	s_add_i32 s48, s48, 2
	s_add_u32 s14, s14, 0x100
	s_addc_u32 s15, s15, 0
	s_add_u32 s46, s46, 0x100
	s_addc_u32 s47, s47, 0
	s_cmp_gt_u32 s48, 13
	s_barrier

; #define PG8_STAGE(bufoff, gbase, voff) do { _Pragma("unroll") for (int _i = 0; _i < 2; ++_i) \
;         __builtin_amdgcn_global_load_lds((const unsigned*)((const char*)(gbase) + (voff)[_i]), (LAS unsigned*)(lds + (bufoff) + ldsw + _i * 8192), 16, 0, 0); } while (0)
; #define PG8_WAIT_V(n) asm volatile("s_waitcnt vmcnt(" #n ")" ::: "memory")
; #define PG8_BAR __builtin_amdgcn_s_barrier()
; template <class Epi, class Sched>
; __device__ __forceinline__ void gemm_phase(LAS unsigned char* lds, const Gemm g, const Sched& S, const Epi& E) {
;     ...
;     const char* cA = (const char*)g.A + (size_t)cur.pm * tstep; const char* cB = (const char*)g.Bt + (size_t)cur.pn * tstep;
;     PG8_STAGE(PG8_SB(0, 0), cB, voffB); PG8_STAGE(PG8_SA(0, 0), cA, voffA); PG8_STAGE(PG8_SB(0, 1), cB + hstep, voffB); PG8_STAGE(PG8_SA(0, 1), cA + hstep, voffA);
;     if (wr == 1) PG8_BAR;
;     PG8_WAIT_V(4); PG8_BAR;
;     PG8_STAGE(PG8_SB(1, 0), cB + kstep, voffB); PG8_STAGE(PG8_SA(1, 0), cA + kstep, voffA); PG8_STAGE(PG8_SB(1, 1), cB + hstep + kstep, voffB);
;     PG8_WAIT_V(6); PG8_BAR;
.LBB0_295:
	s_add_u32 s47, s72, 0x3282000
	s_addc_u32 s48, s73, 0
	s_lshl_b32 s2, s2, 5
	s_mov_b64 s[8:9], 0x80
	s_and_b32 s51, s2, 0x60
	s_add_i32 m0, s42, 0x18000
	v_lshl_add_u64 v[6:7], v[6:7], 0, s[8:9]
	s_lshl_b32 s49, s3, 6
	s_lshl_b32 s4, s3, 13
	s_lshl_b32 s5, s51, 7
	s_waitcnt vmcnt(4)
	s_barrier
	global_load_lds_dwordx4 v[6:7], off
	v_lshl_add_u64 v[4:5], v[4:5], 0, s[8:9]
	s_add_i32 m0, s42, 0x1a000
	s_add_i32 s52, s42, 0x8000
	s_add_i32 s53, s42, 0xa000
	global_load_lds_dwordx4 v[4:5], off
	v_lshl_add_u64 v[2:3], v[2:3], 0, s[8:9]
	s_mov_b32 m0, s52
	s_add_u32 s2, s28, 0xb0080
	global_load_lds_dwordx4 v[2:3], off
	v_lshl_add_u64 v[0:1], v[0:1], 0, s[8:9]
	s_mov_b32 m0, s53
	s_addc_u32 s3, s29, 0
	global_load_lds_dwordx4 v[0:1], off
	s_add_i32 m0, s42, 0x1c000
	v_lshl_add_u64 v[0:1], s[2:3], 0, v[132:133]
	global_load_lds_dwordx4 v[0:1], off
	v_lshl_add_u64 v[0:1], s[2:3], 0, v[128:129]
	s_add_i32 m0, s42, 0x1e000
	v_bfe_u32 v163, v10, 4, 2
	global_load_lds_dwordx4 v[0:1], off
	v_and_b32_e32 v162, 15, v10
	v_lshlrev_b32_e32 v0, 4, v163
	v_lshlrev_b32_e32 v1, 2, v10
	v_lshl_or_b32 v0, v162, 6, v0
	v_and_b32_e32 v1, 32, v1
	v_bitop3_b32 v2, v0, s4, v1 bitop3:0xde
	v_bitop3_b32 v164, v0, s5, v1 bitop3:0xde
	v_lshrrev_b32_e32 v1, 1, v14
	v_mul_lo_u32 v0, v13, s0
	s_mov_b32 s6, 0xb000
	v_mad_u64_u32 v[0:1], s[4:5], v1, s6, v[0:1]
	v_or_b32_e32 v0, v0, v15
	s_mov_b64 s[2:3], 0xb0080
	v_add_lshl_u32 v0, v0, v16, 1
	v_mov_b32_e32 v1, v133
	v_lshl_add_u64 v[136:137], v[0:1], 0, s[2:3]
	v_lshrrev_b32_e32 v1, 1, v8
	v_mul_lo_u32 v0, v9, s0
	v_mad_u64_u32 v[0:1], s[4:5], v1, s6, v[0:1]
	s_waitcnt vmcnt(0)
	v_or_b32_e32 v0, v0, v11
	v_add_lshl_u32 v0, v0, v12, 1
	v_mov_b32_e32 v1, v133
	s_add_i32 s58, 0, 0x10000
	s_add_i32 s59, 0, 0x14000
	s_mov_b32 s54, 0x18000
	s_mov_b32 s55, 0x8000
	s_ashr_i32 s56, s76, 31
	s_ashr_i32 s57, s74, 31
	v_lshl_add_u64 v[138:139], v[0:1], 0, s[2:3]
	v_mov_b64_e32 v[140:141], 0x480
	v_mov_b64_e32 v[142:143], 0x47f
	v_add_u32_e32 v165, s58, v164
	v_add_u32_e32 v166, 0, v2
	v_add_u32_e32 v167, s59, v164
	s_mov_b64 s[10:11], 0x10000
	s_mov_b64 s[12:13], 0x10200
	s_mov_b64 s[14:15], 0x20000
	s_mov_b32 s60, 0x20000
	s_mov_b64 s[18:19], 0x20200
	s_mov_b64 s[22:23], 0x30000
	s_mov_b32 s61, 0x30000
	s_mov_b64 s[24:25], 0x30200
	s_mov_b32 s62, 0
	s_mov_b64 s[70:71], s[82:83]
	s_barrier
	s_branch .LBB0_298

; #define PG8_STAGE(bufoff, gbase, voff) do { _Pragma("unroll") for (int _i = 0; _i < 2; ++_i) \
;         __builtin_amdgcn_global_load_lds((const unsigned*)((const char*)(gbase) + (voff)[_i]), (LAS unsigned*)(lds + (bufoff) + ldsw + _i * 8192), 16, 0, 0); } while (0)
; #define PG8_LDA(dst, b, h) do { _Pragma("unroll") for (int m = 0; m < 4; ++m) _Pragma("unroll") for (int k = 0; k < 2; ++k) dst[m][k] = *(const LAS bf16x8*)(lds + PG8_SA(b, h) + aoff + m * 2048 + k * 1024); } while (0)
; #define PG8_LDB(dst, b, h) do { _Pragma("unroll") for (int n = 0; n < 2; ++n) _Pragma("unroll") for (int k = 0; k < 2; ++k) dst[n][k] = *(const LAS bf16x8*)(lds + PG8_SB(b, h) + boff + n * 2048 + k * 1024); } while (0)
; #define PG8_WAIT_V(n) asm volatile("s_waitcnt vmcnt(" #n ")" ::: "memory")
; #define PG8_WAIT_L(n) asm volatile("s_waitcnt lgkmcnt(" #n ")" ::: "memory")
; #define PG8_BAR __builtin_amdgcn_s_barrier()
; #define PG8_SCHED __builtin_amdgcn_sched_barrier(0)
; template <class Epi, class Sched>
; __device__ __forceinline__ void gemm_phase(LAS unsigned char* lds, const Gemm g, const Sched& S, const Epi& E) {
;     ...
;         const bool has_next = S.next(ui + 1, nxt);
;         const char* nA = has_next ? (const char*)g.A + (size_t)nxt.pm * tstep : cA; const char* nB = has_next ? (const char*)g.Bt + (size_t)nxt.pn * tstep : cB;
;         for (int t = 0; t < nt; t += 2) {
;             const bool last = (t == nt - 2);
;             const char* a1 = cA + (size_t)(t + 1) * kstep;
;             const char* a2 = last ? nA : cA + (size_t)(t + 2) * kstep; const char* b2 = last ? nB : cB + (size_t)(t + 2) * kstep;
;             const char* a3 = a2 + kstep; const char* b3 = b2 + kstep;
;             PG8_LDB(B0, 0, 0); PG8_SCHED; PG8_LDA(At, 0, 0); PG8_STAGE(PG8_SA(1, 1), a1 + hstep, voffA);
;             PG8_WAIT_L(8); PG8_BAR; PG8_WAIT_L(0); PG8_MMA(0, 0, At, B0); PG8_BAR; PG8_SCHED;
;             PG8_LDB(B1, 0, 1); PG8_STAGE(PG8_SB(0, 0), b2, voffB);
;             PG8_BAR; PG8_WAIT_L(0); PG8_MMA(0, 1, At, B1); PG8_BAR;
;             PG8_LDA(At, 0, 1); PG8_STAGE(PG8_SA(0, 0), a2, voffA);
;             PG8_BAR; PG8_WAIT_L(0); PG8_MMA(1, 0, At, B0); PG8_BAR; PG8_SCHED;
;             PG8_STAGE(PG8_SB(0, 1), b2 + hstep, voffB);
;             PG8_WAIT_V(6); PG8_BAR; PG8_MMA(1, 1, At, B1); PG8_BAR;
.LBB0_304:
	s_add_u32 s0, s28, 0x100
	s_addc_u32 s67, s29, 0
	s_mov_b32 s68, -2
	ds_read_b128 v[144:147], v165
	ds_read_b128 v[148:151], v165 offset:1024
	ds_read_b128 v[152:155], v165 offset:2048
	ds_read_b128 v[156:159], v165 offset:3072
	s_add_u32 s28, s26, 0x100
	s_addc_u32 s29, s27, 0
	s_cmp_eq_u32 s68, 40
	s_cselect_b32 s37, s5, s29
	s_cselect_b32 s36, s4, s28
	s_cselect_b32 s35, s7, s67
	s_cselect_b32 s34, s6, s0
	v_lshl_add_u64 v[160:161], s[26:27], 0, v[136:137]
	s_add_i32 m0, s42, 0xc000
	ds_read_b128 v[168:171], v166
	ds_read_b128 v[172:175], v166 offset:1024
	ds_read_b128 v[176:179], v166 offset:2048
	ds_read_b128 v[180:183], v166 offset:3072
	ds_read_b128 v[184:187], v166 offset:4096
	ds_read_b128 v[188:191], v166 offset:5120
	ds_read_b128 v[192:195], v166 offset:6144
	ds_read_b128 v[196:199], v166 offset:7168
	global_load_lds_dwordx4 v[160:161], off
	v_lshl_add_u64 v[160:161], s[26:27], 0, v[138:139]
	s_add_i32 m0, s42, 0xe000
	s_nop 0
	global_load_lds_dwordx4 v[160:161], off
	s_waitcnt lgkmcnt(8)
	s_waitcnt vmcnt(26)
	s_barrier
	s_waitcnt lgkmcnt(0)
	s_setprio 1
	s_waitcnt lgkmcnt(0)
	v_mfma_f32_16x16x32_bf16 v[124:127], v[144:147], v[168:171], 0
	v_mfma_f32_16x16x32_bf16 v[120:123], v[152:155], v[168:171], 0
	v_mfma_f32_16x16x32_bf16 v[116:119], v[144:147], v[176:179], 0
	v_mfma_f32_16x16x32_bf16 v[104:107], v[152:155], v[176:179], 0
	v_mfma_f32_16x16x32_bf16 v[96:99], v[144:147], v[184:187], 0
	v_mfma_f32_16x16x32_bf16 v[88:91], v[152:155], v[184:187], 0
	v_mfma_f32_16x16x32_bf16 v[80:83], v[144:147], v[192:195], 0
	v_mfma_f32_16x16x32_bf16 v[72:75], v[152:155], v[192:195], 0
	v_mfma_f32_16x16x32_bf16 v[124:127], v[148:151], v[172:175], v[124:127]
	v_mfma_f32_16x16x32_bf16 v[120:123], v[156:159], v[172:175], v[120:123]
	v_mfma_f32_16x16x32_bf16 v[116:119], v[148:151], v[180:183], v[116:119]
	v_mfma_f32_16x16x32_bf16 v[104:107], v[156:159], v[180:183], v[104:107]
	v_mfma_f32_16x16x32_bf16 v[96:99], v[148:151], v[188:191], v[96:99]
	v_mfma_f32_16x16x32_bf16 v[88:91], v[156:159], v[188:191], v[88:91]
	v_mfma_f32_16x16x32_bf16 v[80:83], v[148:151], v[196:199], v[80:83]
	v_mfma_f32_16x16x32_bf16 v[72:75], v[156:159], v[196:199], v[72:75]
	s_setprio 0
	s_barrier
	s_add_i32 s16, s58, s40
	s_mov_b32 m0, s16
	ds_read_b128 v[202:205], v167
	ds_read_b128 v[206:209], v167 offset:1024
	ds_read_b128 v[210:213], v167 offset:2048
	ds_read_b128 v[214:217], v167 offset:3072
	global_load_lds_dwordx4 v132, s[34:35]
	s_add_i32 m0, s16, 0x2000
	s_nop 0
	global_load_lds_dwordx4 v128, s[34:35]
	s_waitcnt vmcnt(26)
	s_barrier
	s_waitcnt lgkmcnt(0)
	s_setprio 1
	s_waitcnt lgkmcnt(0)
	v_mfma_f32_16x16x32_bf16 v[112:115], v[202:205], v[168:171], 0
	v_mfma_f32_16x16x32_bf16 v[108:111], v[210:213], v[168:171], 0
	v_mfma_f32_16x16x32_bf16 v[100:103], v[202:205], v[176:179], 0
	v_mfma_f32_16x16x32_bf16 v[92:95], v[210:213], v[176:179], 0
	v_mfma_f32_16x16x32_bf16 v[84:87], v[202:205], v[184:187], 0
	v_mfma_f32_16x16x32_bf16 v[76:79], v[210:213], v[184:187], 0
	v_mfma_f32_16x16x32_bf16 v[68:71], v[202:205], v[192:195], 0
	v_mfma_f32_16x16x32_bf16 v[64:67], v[210:213], v[192:195], 0
	v_mfma_f32_16x16x32_bf16 v[112:115], v[206:209], v[172:175], v[112:115]
	v_mfma_f32_16x16x32_bf16 v[108:111], v[214:217], v[172:175], v[108:111]
	v_mfma_f32_16x16x32_bf16 v[100:103], v[206:209], v[180:183], v[100:103]
	v_mfma_f32_16x16x32_bf16 v[92:95], v[214:217], v[180:183], v[92:95]
	v_mfma_f32_16x16x32_bf16 v[84:87], v[206:209], v[188:191], v[84:87]
	v_mfma_f32_16x16x32_bf16 v[76:79], v[214:217], v[188:191], v[76:79]
	v_mfma_f32_16x16x32_bf16 v[68:71], v[206:209], v[196:199], v[68:71]
	v_mfma_f32_16x16x32_bf16 v[64:67], v[214:217], v[196:199], v[64:67]
	s_setprio 0
	s_mov_b32 m0, s42
	s_barrier
	ds_read_b128 v[168:171], v166 offset:16384
	ds_read_b128 v[172:175], v166 offset:17408
	ds_read_b128 v[176:179], v166 offset:18432
	ds_read_b128 v[180:183], v166 offset:19456
	ds_read_b128 v[184:187], v166 offset:20480
	ds_read_b128 v[188:191], v166 offset:21504
	ds_read_b128 v[192:195], v166 offset:22528
	ds_read_b128 v[196:199], v166 offset:23552
	global_load_lds_dwordx4 v134, s[36:37]
	s_mov_b32 m0, s43
	s_nop 0
	global_load_lds_dwordx4 v130, s[36:37]
	s_barrier
	s_waitcnt lgkmcnt(0)
	s_setprio 1
	s_waitcnt lgkmcnt(0)
	v_mfma_f32_16x16x32_bf16 v[60:63], v[144:147], v[168:171], 0
	v_mfma_f32_16x16x32_bf16 v[56:59], v[152:155], v[168:171], 0
	v_mfma_f32_16x16x32_bf16 v[48:51], v[144:147], v[176:179], 0
	v_mfma_f32_16x16x32_bf16 v[40:43], v[152:155], v[176:179], 0
	v_mfma_f32_16x16x32_bf16 v[32:35], v[144:147], v[184:187], 0
	v_mfma_f32_16x16x32_bf16 v[24:27], v[152:155], v[184:187], 0
	v_mfma_f32_16x16x32_bf16 v[16:19], v[144:147], v[192:195], 0
	v_mfma_f32_16x16x32_bf16 v[8:11], v[152:155], v[192:195], 0
	v_mfma_f32_16x16x32_bf16 v[60:63], v[148:151], v[172:175], v[60:63]
	v_mfma_f32_16x16x32_bf16 v[56:59], v[156:159], v[172:175], v[56:59]
	v_mfma_f32_16x16x32_bf16 v[48:51], v[148:151], v[180:183], v[48:51]
	v_mfma_f32_16x16x32_bf16 v[40:43], v[156:159], v[180:183], v[40:43]
	v_mfma_f32_16x16x32_bf16 v[32:35], v[148:151], v[188:191], v[32:35]
	v_mfma_f32_16x16x32_bf16 v[24:27], v[156:159], v[188:191], v[24:27]
	v_mfma_f32_16x16x32_bf16 v[16:19], v[148:151], v[196:199], v[16:19]
	v_mfma_f32_16x16x32_bf16 v[8:11], v[156:159], v[196:199], v[8:11]
	s_setprio 0
	s_barrier
	s_add_u32 s16, s34, 0xb0000
	s_addc_u32 s17, s35, 0
	s_add_i32 s20, s59, s40
	s_mov_b32 m0, s20
	s_nop 0
	global_load_lds_dwordx4 v132, s[16:17]
	s_add_i32 m0, s20, 0x2000
	s_nop 0
	global_load_lds_dwordx4 v128, s[16:17]
	s_waitcnt vmcnt(26)
	s_barrier
; #define PG8_STAGE(bufoff, gbase, voff) do { _Pragma("unroll") for (int _i = 0; _i < 2; ++_i) \
;         __builtin_amdgcn_global_load_lds((const unsigned*)((const char*)(gbase) + (voff)[_i]), (LAS unsigned*)(lds + (bufoff) + ldsw + _i * 8192), 16, 0, 0); } while (0)
; #define PG8_LDA(dst, b, h) do { _Pragma("unroll") for (int m = 0; m < 4; ++m) _Pragma("unroll") for (int k = 0; k < 2; ++k) dst[m][k] = *(const LAS bf16x8*)(lds + PG8_SA(b, h) + aoff + m * 2048 + k * 1024); } while (0)
; #define PG8_LDB(dst, b, h) do { _Pragma("unroll") for (int n = 0; n < 2; ++n) _Pragma("unroll") for (int k = 0; k < 2; ++k) dst[n][k] = *(const LAS bf16x8*)(lds + PG8_SB(b, h) + boff + n * 2048 + k * 1024); } while (0)
; #define PG8_MMA(ai, bj, At, Bt) do { __builtin_amdgcn_s_setprio(1); _Pragma("unroll") for (int m = 0; m < 4; ++m) _Pragma("unroll") for (int n = 0; n < 2; ++n) _Pragma("unroll") for (int k = 0; k < 2; ++k) \
;         acc[ai][bj][m][n] = __builtin_amdgcn_mfma_f32_16x16x32_bf16(Bt[n][k], At[m][k], acc[ai][bj][m][n], 0, 0, 0); __builtin_amdgcn_s_setprio(0); } while (0)
; #define PG8_WAIT_V(n) asm volatile("s_waitcnt vmcnt(" #n ")" ::: "memory")
; #define PG8_WAIT_L(n) asm volatile("s_waitcnt lgkmcnt(" #n ")" ::: "memory")
; #define PG8_BAR __builtin_amdgcn_s_barrier()
; #define PG8_SCHED __builtin_amdgcn_sched_barrier(0)
; template <class Epi, class Sched>
; __device__ __forceinline__ void gemm_phase(LAS unsigned char* lds, const Gemm g, const Sched& S, const Epi& E) {
;     ...
;             PG8_WAIT_V(6); PG8_BAR; PG8_MMA(1, 1, At, B1); PG8_BAR;
;             PG8_LDB(B0, 1, 0); PG8_SCHED; PG8_LDA(At, 1, 0); PG8_STAGE(PG8_SA(0, 1), a2 + hstep, voffA);
;             PG8_WAIT_L(8); PG8_BAR; PG8_WAIT_L(0); PG8_MMA(0, 0, At, B0); PG8_BAR; PG8_SCHED;
;             PG8_LDB(B1, 1, 1); PG8_STAGE(PG8_SB(1, 0), b3, voffB);
;             PG8_BAR; PG8_WAIT_L(0); PG8_MMA(0, 1, At, B1); PG8_BAR;
;             PG8_LDA(At, 1, 1); PG8_STAGE(PG8_SA(1, 0), a3, voffA);
;             PG8_BAR; PG8_WAIT_L(0); PG8_MMA(1, 0, At, B0); PG8_BAR; PG8_SCHED;
	s_setprio 1
	v_mfma_f32_16x16x32_bf16 v[52:55], v[202:205], v[168:171], 0
	v_mfma_f32_16x16x32_bf16 v[44:47], v[210:213], v[168:171], 0
	v_mfma_f32_16x16x32_bf16 v[36:39], v[202:205], v[176:179], 0
	v_mfma_f32_16x16x32_bf16 v[28:31], v[210:213], v[176:179], 0
	v_mfma_f32_16x16x32_bf16 v[20:23], v[202:205], v[184:187], 0
	v_mfma_f32_16x16x32_bf16 v[12:15], v[210:213], v[184:187], 0
	v_mfma_f32_16x16x32_bf16 v[4:7], v[202:205], v[192:195], 0
	v_mfma_f32_16x16x32_bf16 v[0:3], v[210:213], v[192:195], 0
	v_mfma_f32_16x16x32_bf16 v[52:55], v[206:209], v[172:175], v[52:55]
	v_mfma_f32_16x16x32_bf16 v[44:47], v[214:217], v[172:175], v[44:47]
	v_mfma_f32_16x16x32_bf16 v[36:39], v[206:209], v[180:183], v[36:39]
	v_mfma_f32_16x16x32_bf16 v[28:31], v[214:217], v[180:183], v[28:31]
	v_mfma_f32_16x16x32_bf16 v[20:23], v[206:209], v[188:191], v[20:23]
	v_mfma_f32_16x16x32_bf16 v[12:15], v[214:217], v[188:191], v[12:15]
	v_mfma_f32_16x16x32_bf16 v[4:7], v[206:209], v[196:199], v[4:7]
	v_mfma_f32_16x16x32_bf16 v[0:3], v[214:217], v[196:199], v[0:3]
	s_setprio 0
	s_add_i32 s20, 0, 0x18000
	v_add_u32_e32 v156, s20, v164
	s_barrier
	ds_read_b128 v[144:147], v156
	ds_read_b128 v[148:151], v156 offset:1024
	ds_read_b128 v[152:155], v156 offset:2048
	ds_read_b128 v[156:159], v156 offset:3072
	s_add_u32 s16, s36, 0xb0000
	s_addc_u32 s17, s37, 0
	s_mov_b32 m0, s44
	ds_read_b128 v[168:171], v166 offset:32768
	ds_read_b128 v[172:175], v166 offset:33792
	ds_read_b128 v[176:179], v166 offset:34816
	ds_read_b128 v[180:183], v166 offset:35840
	ds_read_b128 v[184:187], v166 offset:36864
	ds_read_b128 v[188:191], v166 offset:37888
	ds_read_b128 v[192:195], v166 offset:38912
	ds_read_b128 v[196:199], v166 offset:39936
	global_load_lds_dwordx4 v134, s[16:17]
	s_mov_b32 m0, s45
	s_nop 0
	global_load_lds_dwordx4 v130, s[16:17]
	s_waitcnt lgkmcnt(8)
	s_waitcnt vmcnt(26)
	s_barrier
	s_waitcnt lgkmcnt(0)
	s_setprio 1
	s_waitcnt lgkmcnt(0)
	v_mfma_f32_16x16x32_bf16 v[124:127], v[144:147], v[168:171], v[124:127]
	v_mfma_f32_16x16x32_bf16 v[120:123], v[152:155], v[168:171], v[120:123]
	v_mfma_f32_16x16x32_bf16 v[116:119], v[144:147], v[176:179], v[116:119]
	v_mfma_f32_16x16x32_bf16 v[104:107], v[152:155], v[176:179], v[104:107]
	v_mfma_f32_16x16x32_bf16 v[96:99], v[144:147], v[184:187], v[96:99]
	v_mfma_f32_16x16x32_bf16 v[88:91], v[152:155], v[184:187], v[88:91]
	v_mfma_f32_16x16x32_bf16 v[80:83], v[144:147], v[192:195], v[80:83]
	v_mfma_f32_16x16x32_bf16 v[72:75], v[152:155], v[192:195], v[72:75]
	v_mfma_f32_16x16x32_bf16 v[124:127], v[148:151], v[172:175], v[124:127]
	v_mfma_f32_16x16x32_bf16 v[120:123], v[156:159], v[172:175], v[120:123]
	v_mfma_f32_16x16x32_bf16 v[116:119], v[148:151], v[180:183], v[116:119]
	v_mfma_f32_16x16x32_bf16 v[104:107], v[156:159], v[180:183], v[104:107]
	v_mfma_f32_16x16x32_bf16 v[96:99], v[148:151], v[188:191], v[96:99]
	v_mfma_f32_16x16x32_bf16 v[88:91], v[156:159], v[188:191], v[88:91]
	v_mfma_f32_16x16x32_bf16 v[80:83], v[148:151], v[196:199], v[80:83]
	v_mfma_f32_16x16x32_bf16 v[72:75], v[156:159], v[196:199], v[72:75]
	s_setprio 0
	s_barrier
	s_add_i32 s21, 0, 0x1c000
	s_add_i32 s16, s20, s40
	v_add_u32_e32 v214, s21, v164
	s_add_u32 s8, s34, 0x80
	s_addc_u32 s9, s35, 0
	s_mov_b32 m0, s16
	ds_read_b128 v[202:205], v214
	ds_read_b128 v[206:209], v214 offset:1024
	ds_read_b128 v[210:213], v214 offset:2048
	ds_read_b128 v[214:217], v214 offset:3072
	global_load_lds_dwordx4 v132, s[8:9]
	s_add_i32 m0, s16, 0x2000
	s_nop 0
	global_load_lds_dwordx4 v128, s[8:9]
	s_waitcnt vmcnt(10)
	s_barrier
; #define PG8_STAGE(bufoff, gbase, voff) do { _Pragma("unroll") for (int _i = 0; _i < 2; ++_i) \
;         __builtin_amdgcn_global_load_lds((const unsigned*)((const char*)(gbase) + (voff)[_i]), (LAS unsigned*)(lds + (bufoff) + ldsw + _i * 8192), 16, 0, 0); } while (0)
; #define PG8_MMA(ai, bj, At, Bt) do { __builtin_amdgcn_s_setprio(1); _Pragma("unroll") for (int m = 0; m < 4; ++m) _Pragma("unroll") for (int n = 0; n < 2; ++n) _Pragma("unroll") for (int k = 0; k < 2; ++k) \
;         acc[ai][bj][m][n] = __builtin_amdgcn_mfma_f32_16x16x32_bf16(Bt[n][k], At[m][k], acc[ai][bj][m][n], 0, 0, 0); __builtin_amdgcn_s_setprio(0); } while (0)
; #define PG8_WAIT_V(n) asm volatile("s_waitcnt vmcnt(" #n ")" ::: "memory")
; #define PG8_WAIT_L(n) asm volatile("s_waitcnt lgkmcnt(" #n ")" ::: "memory")
; #define PG8_BAR __builtin_amdgcn_s_barrier()
; #define PG8_SCHED __builtin_amdgcn_sched_barrier(0)
; template <class Epi, class Sched>
; __device__ __forceinline__ void gemm_phase(LAS unsigned char* lds, const Gemm g, const Sched& S, const Epi& E) {
;     ...
;             PG8_BAR; PG8_WAIT_L(0); PG8_MMA(1, 0, At, B0); PG8_BAR; PG8_SCHED;
;             PG8_STAGE(PG8_SB(1, 1), b3 + hstep, voffB);
;             PG8_WAIT_V(6); PG8_BAR; PG8_MMA(1, 1, At, B1); PG8_BAR;
;         }
	s_waitcnt lgkmcnt(0)
	s_setprio 1
	s_waitcnt lgkmcnt(0)
	v_mfma_f32_16x16x32_bf16 v[112:115], v[202:205], v[168:171], v[112:115]
	v_mfma_f32_16x16x32_bf16 v[108:111], v[210:213], v[168:171], v[108:111]
	v_mfma_f32_16x16x32_bf16 v[100:103], v[202:205], v[176:179], v[100:103]
	v_mfma_f32_16x16x32_bf16 v[92:95], v[210:213], v[176:179], v[92:95]
	v_mfma_f32_16x16x32_bf16 v[84:87], v[202:205], v[184:187], v[84:87]
	v_mfma_f32_16x16x32_bf16 v[76:79], v[210:213], v[184:187], v[76:79]
	v_mfma_f32_16x16x32_bf16 v[68:71], v[202:205], v[192:195], v[68:71]
	v_mfma_f32_16x16x32_bf16 v[64:67], v[210:213], v[192:195], v[64:67]
	v_mfma_f32_16x16x32_bf16 v[112:115], v[206:209], v[172:175], v[112:115]
	v_mfma_f32_16x16x32_bf16 v[108:111], v[214:217], v[172:175], v[108:111]
	v_mfma_f32_16x16x32_bf16 v[100:103], v[206:209], v[180:183], v[100:103]
	v_mfma_f32_16x16x32_bf16 v[92:95], v[214:217], v[180:183], v[92:95]
	v_mfma_f32_16x16x32_bf16 v[84:87], v[206:209], v[188:191], v[84:87]
	v_mfma_f32_16x16x32_bf16 v[76:79], v[214:217], v[188:191], v[76:79]
	v_mfma_f32_16x16x32_bf16 v[68:71], v[206:209], v[196:199], v[68:71]
	v_mfma_f32_16x16x32_bf16 v[64:67], v[214:217], v[196:199], v[64:67]
	s_setprio 0
	s_mov_b32 m0, s52
	s_add_u32 s8, s36, 0x80
	s_addc_u32 s9, s37, 0
	s_barrier
	ds_read_b128 v[168:171], v166 offset:49152
	ds_read_b128 v[172:175], v166 offset:50176
	ds_read_b128 v[176:179], v166 offset:51200
	ds_read_b128 v[180:183], v166 offset:52224
	ds_read_b128 v[184:187], v166 offset:53248
	ds_read_b128 v[188:191], v166 offset:54272
	ds_read_b128 v[192:195], v166 offset:55296
	ds_read_b128 v[196:199], v166 offset:56320
	global_load_lds_dwordx4 v134, s[8:9]
	s_mov_b32 m0, s53
	s_nop 0
	global_load_lds_dwordx4 v130, s[8:9]
	s_barrier
	s_waitcnt lgkmcnt(0)
	s_setprio 1
	s_waitcnt lgkmcnt(0)
	v_mfma_f32_16x16x32_bf16 v[60:63], v[144:147], v[168:171], v[60:63]
	v_mfma_f32_16x16x32_bf16 v[56:59], v[152:155], v[168:171], v[56:59]
	v_mfma_f32_16x16x32_bf16 v[48:51], v[144:147], v[176:179], v[48:51]
	v_mfma_f32_16x16x32_bf16 v[40:43], v[152:155], v[176:179], v[40:43]
	v_mfma_f32_16x16x32_bf16 v[32:35], v[144:147], v[184:187], v[32:35]
	v_mfma_f32_16x16x32_bf16 v[24:27], v[152:155], v[184:187], v[24:27]
	v_mfma_f32_16x16x32_bf16 v[16:19], v[144:147], v[192:195], v[16:19]
	v_mfma_f32_16x16x32_bf16 v[8:11], v[152:155], v[192:195], v[8:11]
	v_mfma_f32_16x16x32_bf16 v[60:63], v[148:151], v[172:175], v[60:63]
	v_mfma_f32_16x16x32_bf16 v[56:59], v[156:159], v[172:175], v[56:59]
	v_mfma_f32_16x16x32_bf16 v[48:51], v[148:151], v[180:183], v[48:51]
	v_mfma_f32_16x16x32_bf16 v[40:43], v[156:159], v[180:183], v[40:43]
	v_mfma_f32_16x16x32_bf16 v[32:35], v[148:151], v[188:191], v[32:35]
	v_mfma_f32_16x16x32_bf16 v[24:27], v[156:159], v[188:191], v[24:27]
	v_mfma_f32_16x16x32_bf16 v[16:19], v[148:151], v[196:199], v[16:19]
	v_mfma_f32_16x16x32_bf16 v[8:11], v[156:159], v[196:199], v[8:11]
	s_setprio 0
	s_barrier
	s_add_u32 s16, s34, 0xb0080
	s_addc_u32 s17, s35, 0
	s_add_i32 s20, s21, s40
	s_mov_b32 m0, s20
	s_nop 0
	global_load_lds_dwordx4 v132, s[16:17]
	s_add_i32 m0, s20, 0x2000
	s_nop 0
	global_load_lds_dwordx4 v128, s[16:17]
	s_waitcnt vmcnt(10)
	s_barrier
	s_setprio 1
	v_mfma_f32_16x16x32_bf16 v[52:55], v[202:205], v[168:171], v[52:55]
	v_mfma_f32_16x16x32_bf16 v[44:47], v[210:213], v[168:171], v[44:47]
	v_mfma_f32_16x16x32_bf16 v[36:39], v[202:205], v[176:179], v[36:39]
	v_mfma_f32_16x16x32_bf16 v[28:31], v[210:213], v[176:179], v[28:31]
	v_mfma_f32_16x16x32_bf16 v[20:23], v[202:205], v[184:187], v[20:23]
	v_mfma_f32_16x16x32_bf16 v[12:15], v[210:213], v[184:187], v[12:15]
	v_mfma_f32_16x16x32_bf16 v[4:7], v[202:205], v[192:195], v[4:7]
	v_mfma_f32_16x16x32_bf16 v[0:3], v[210:213], v[192:195], v[0:3]
	v_mfma_f32_16x16x32_bf16 v[52:55], v[206:209], v[172:175], v[52:55]
	v_mfma_f32_16x16x32_bf16 v[44:47], v[214:217], v[172:175], v[44:47]
	v_mfma_f32_16x16x32_bf16 v[36:39], v[206:209], v[180:183], v[36:39]
	v_mfma_f32_16x16x32_bf16 v[28:31], v[214:217], v[180:183], v[28:31]
	v_mfma_f32_16x16x32_bf16 v[20:23], v[206:209], v[188:191], v[20:23]
	v_mfma_f32_16x16x32_bf16 v[12:15], v[214:217], v[188:191], v[12:15]
	v_mfma_f32_16x16x32_bf16 v[4:7], v[206:209], v[196:199], v[4:7]
	v_mfma_f32_16x16x32_bf16 v[0:3], v[214:217], v[196:199], v[0:3]
	s_setprio 0
	s_add_i32 s68, s68, 2
	s_add_u32 s0, s0, 0x100
	s_addc_u32 s67, s67, 0
	s_cmp_gt_u32 s68, 41
	s_mov_b64 s[26:27], s[28:29]
	s_barrier

; #define PG8_STAGE(bufoff, gbase, voff) do { _Pragma("unroll") for (int _i = 0; _i < 2; ++_i) \
;         __builtin_amdgcn_global_load_lds((const unsigned*)((const char*)(gbase) + (voff)[_i]), (LAS unsigned*)(lds + (bufoff) + ldsw + _i * 8192), 16, 0, 0); } while (0)
; #define PG8_WAIT_V(n) asm volatile("s_waitcnt vmcnt(" #n ")" ::: "memory")
; #define PG8_BAR __builtin_amdgcn_s_barrier()
; template <class Epi, class Sched>
; __device__ __forceinline__ void gemm_phase(LAS unsigned char* lds, const Gemm g, const Sched& S, const Epi& E) {
;     ...
;     const char* cA = (const char*)g.A + (size_t)cur.pm * tstep; const char* cB = (const char*)g.Bt + (size_t)cur.pn * tstep;
;     PG8_STAGE(PG8_SB(0, 0), cB, voffB); PG8_STAGE(PG8_SA(0, 0), cA, voffA); PG8_STAGE(PG8_SB(0, 1), cB + hstep, voffB); PG8_STAGE(PG8_SA(0, 1), cA + hstep, voffA);
;     if (wr == 1) PG8_BAR;
;     PG8_WAIT_V(4); PG8_BAR;
;     PG8_STAGE(PG8_SB(1, 0), cB + kstep, voffB); PG8_STAGE(PG8_SA(1, 0), cA + kstep, voffA); PG8_STAGE(PG8_SB(1, 1), cB + hstep + kstep, voffB);
;     PG8_WAIT_V(6); PG8_BAR;
.LBB0_573:
	s_and_b32 s1, s3, 3
	s_lshl_b32 s42, s0, 6
	s_lshl_b32 s5, s0, 13
	s_lshl_b32 s43, s1, 5
	s_lshl_b32 s18, s1, 12
	s_mov_b64 s[0:1], 0x80
	s_add_i32 m0, s37, 0x18000
	v_lshl_add_u64 v[6:7], v[6:7], 0, s[0:1]
	s_waitcnt vmcnt(4)
	s_barrier
	global_load_lds_dwordx4 v[6:7], off
	v_lshl_add_u64 v[4:5], v[4:5], 0, s[0:1]
	s_add_i32 m0, s37, 0x1a000
	s_add_i32 s44, s37, 0x8000
	s_add_i32 s45, s37, 0xa000
	global_load_lds_dwordx4 v[4:5], off
	v_lshl_add_u64 v[2:3], v[2:3], 0, s[0:1]
	s_mov_b32 m0, s44
	s_add_u32 s8, s26, 0x40080
	global_load_lds_dwordx4 v[2:3], off
	v_lshl_add_u64 v[0:1], v[0:1], 0, s[0:1]
	s_mov_b32 m0, s45
	s_addc_u32 s9, s27, 0
	global_load_lds_dwordx4 v[0:1], off
	s_add_i32 m0, s37, 0x1c000
	v_lshl_add_u64 v[0:1], s[8:9], 0, v[146:147]
	global_load_lds_dwordx4 v[0:1], off
	v_lshl_add_u64 v[0:1], s[8:9], 0, v[142:143]
	s_add_i32 m0, s37, 0x1e000
	v_bfe_u32 v165, v10, 4, 2
	global_load_lds_dwordx4 v[0:1], off
	v_and_b32_e32 v164, 15, v10
	v_lshlrev_b32_e32 v0, 4, v165
	v_lshlrev_b32_e32 v1, 2, v10
	v_lshl_or_b32 v0, v164, 6, v0
	v_and_b32_e32 v1, 32, v1
	v_bitop3_b32 v2, v0, s5, v1 bitop3:0xde
	v_bitop3_b32 v166, v0, s18, v1 bitop3:0xde
	v_lshlrev_b32_e32 v0, 14, v13
	v_and_b32_e32 v0, 0xffff8000, v0
	v_lshl_add_u32 v0, v12, 11, v0
	v_and_b32_e32 v1, 1, v13
	v_lshl_or_b32 v0, v1, 6, v0
	s_sext_i32_i8 s52, s2
	s_lshl_b32 s2, s3, 2
	v_lshl_add_u32 v152, v14, 1, v0
	v_lshlrev_b32_e32 v0, 14, v8
	s_and_b32 s46, s2, 4
	s_ashr_i32 s47, s76, 31
	v_and_b32_e32 v0, 0xffff8000, v0
	s_waitcnt vmcnt(0)
	s_add_u32 s8, s72, 0x33aa000
	v_lshl_add_u32 v0, v9, 11, v0
	v_and_b32_e32 v1, 1, v8
	s_addc_u32 s9, s73, 0
	v_lshl_or_b32 v0, v1, 6, v0
	s_add_i32 s48, 0, 0x10000
	s_add_i32 s49, 0, 0x14000
	v_mov_b32_e32 v153, v151
	v_lshl_add_u32 v154, v11, 1, v0
	v_mov_b32_e32 v155, v151
	v_mov_b64_e32 v[156:157], 0x600
	v_mov_b64_e32 v[158:159], 0x5ff
	v_add_u32_e32 v167, s48, v166
	v_add_u32_e32 v168, 0, v2
	v_add_u32_e32 v169, s49, v166
	s_movk_i32 s51, 0xc00
	s_barrier
	s_branch .LBB0_575

; #define PG8_STAGE(bufoff, gbase, voff) do { _Pragma("unroll") for (int _i = 0; _i < 2; ++_i) \
;         __builtin_amdgcn_global_load_lds((const unsigned*)((const char*)(gbase) + (voff)[_i]), (LAS unsigned*)(lds + (bufoff) + ldsw + _i * 8192), 16, 0, 0); } while (0)
; #define PG8_LDA(dst, b, h) do { _Pragma("unroll") for (int m = 0; m < 4; ++m) _Pragma("unroll") for (int k = 0; k < 2; ++k) dst[m][k] = *(const LAS bf16x8*)(lds + PG8_SA(b, h) + aoff + m * 2048 + k * 1024); } while (0)
; #define PG8_LDB(dst, b, h) do { _Pragma("unroll") for (int n = 0; n < 2; ++n) _Pragma("unroll") for (int k = 0; k < 2; ++k) dst[n][k] = *(const LAS bf16x8*)(lds + PG8_SB(b, h) + boff + n * 2048 + k * 1024); } while (0)
; #define PG8_MMA(ai, bj, At, Bt) do { __builtin_amdgcn_s_setprio(1); _Pragma("unroll") for (int m = 0; m < 4; ++m) _Pragma("unroll") for (int n = 0; n < 2; ++n) _Pragma("unroll") for (int k = 0; k < 2; ++k) \
;         acc[ai][bj][m][n] = __builtin_amdgcn_mfma_f32_16x16x32_bf16(Bt[n][k], At[m][k], acc[ai][bj][m][n], 0, 0, 0); __builtin_amdgcn_s_setprio(0); } while (0)
; #define PG8_WAIT_L(n) asm volatile("s_waitcnt lgkmcnt(" #n ")" ::: "memory")
; template <class Epi, class Sched>
; __device__ __forceinline__ void gemm_phase(LAS unsigned char* lds, const Gemm g, const Sched& S, const Epi& E) {
;     ...
;         const bool has_next = S.next(ui + 1, nxt);
;         const char* nA = has_next ? (const char*)g.A + (size_t)nxt.pm * tstep : cA; const char* nB = has_next ? (const char*)g.Bt + (size_t)nxt.pn * tstep : cB;
;         for (int t = 0; t < nt; t += 2) {
;             const bool last = (t == nt - 2);
;             const char* a1 = cA + (size_t)(t + 1) * kstep;
;             const char* a2 = last ? nA : cA + (size_t)(t + 2) * kstep; const char* b2 = last ? nB : cB + (size_t)(t + 2) * kstep;
;             const char* a3 = a2 + kstep; const char* b3 = b2 + kstep;
;             PG8_LDB(B0, 0, 0); PG8_SCHED; PG8_LDA(At, 0, 0); PG8_STAGE(PG8_SA(1, 1), a1 + hstep, voffA);
;             PG8_WAIT_L(8); PG8_BAR; PG8_WAIT_L(0); PG8_MMA(0, 0, At, B0); PG8_BAR; PG8_SCHED;
;             PG8_LDB(B1, 0, 1); PG8_STAGE(PG8_SB(0, 0), b2, voffB);
;             PG8_BAR; PG8_WAIT_L(0); PG8_MMA(0, 1, At, B1); PG8_BAR;
;             PG8_LDA(At, 0, 1); PG8_STAGE(PG8_SA(0, 0), a2, voffA);
;             PG8_BAR; PG8_WAIT_L(0); PG8_MMA(1, 0, At, B0); PG8_BAR; PG8_SCHED;
.LBB0_577:
	s_ashr_i32 s21, s20, 31
	v_cmp_lt_i64_e32 vcc, s[22:23], v[156:157]
	s_lshl_b64 s[22:23], s[20:21], 19
	s_add_u32 s22, s96, s22
	s_addc_u32 s23, s97, s23
	s_and_b64 s[24:25], vcc, exec
	s_cselect_b32 s5, s23, s7
	s_cselect_b32 s21, s22, s6
	s_ashr_i32 s19, s18, 31
	s_lshl_b64 s[24:25], s[18:19], 19
	s_add_u32 s24, s31, s24
	s_addc_u32 s25, s33, s25
	s_and_b64 s[28:29], vcc, exec
	s_cselect_b32 s19, s25, s27
	s_cselect_b32 s53, s24, s26
	s_add_u32 s6, s6, 0x40080
	s_addc_u32 s7, s7, 0
	s_add_u32 s54, s26, 0x100
	s_addc_u32 s55, s27, 0
	s_mov_b32 s56, -2
	s_waitcnt lgkmcnt(0)
	ds_read_b128 v[128:131], v167
	ds_read_b128 v[132:135], v167 offset:1024
	ds_read_b128 v[136:139], v167 offset:2048
	ds_read_b128 v[160:163], v167 offset:3072
	s_add_u32 s26, s6, 0xfffc0080
	s_addc_u32 s27, s7, -1
	s_cmp_eq_u32 s56, 12
	s_cselect_b32 s29, s5, s27
	s_cselect_b32 s28, s21, s26
	s_cselect_b32 s27, s19, s55
	s_cselect_b32 s26, s53, s54
	s_add_i32 m0, s37, 0xc000
	ds_read_b128 v[170:173], v168
	ds_read_b128 v[174:177], v168 offset:1024
	ds_read_b128 v[178:181], v168 offset:2048
	ds_read_b128 v[182:185], v168 offset:3072
	ds_read_b128 v[186:189], v168 offset:4096
	ds_read_b128 v[190:193], v168 offset:5120
	ds_read_b128 v[194:197], v168 offset:6144
	ds_read_b128 v[202:205], v168 offset:7168
	global_load_lds_dwordx4 v152, s[6:7]
	s_add_i32 m0, s37, 0xe000
	s_nop 0
	global_load_lds_dwordx4 v154, s[6:7]
	s_waitcnt lgkmcnt(8)
	s_waitcnt vmcnt(26)
	s_barrier
	s_waitcnt lgkmcnt(0)
	s_setprio 1
	s_waitcnt lgkmcnt(0)
	v_mfma_f32_16x16x32_bf16 v[124:127], v[128:131], v[170:173], 0
	v_mfma_f32_16x16x32_bf16 v[120:123], v[136:139], v[170:173], 0
	v_mfma_f32_16x16x32_bf16 v[108:111], v[128:131], v[178:181], 0
	v_mfma_f32_16x16x32_bf16 v[104:107], v[136:139], v[178:181], 0
	v_mfma_f32_16x16x32_bf16 v[92:95], v[128:131], v[186:189], 0
	v_mfma_f32_16x16x32_bf16 v[88:91], v[136:139], v[186:189], 0
	v_mfma_f32_16x16x32_bf16 v[76:79], v[128:131], v[194:197], 0
	v_mfma_f32_16x16x32_bf16 v[72:75], v[136:139], v[194:197], 0
	v_mfma_f32_16x16x32_bf16 v[124:127], v[132:135], v[174:177], v[124:127]
	v_mfma_f32_16x16x32_bf16 v[120:123], v[160:163], v[174:177], v[120:123]
	v_mfma_f32_16x16x32_bf16 v[108:111], v[132:135], v[182:185], v[108:111]
	v_mfma_f32_16x16x32_bf16 v[104:107], v[160:163], v[182:185], v[104:107]
	v_mfma_f32_16x16x32_bf16 v[92:95], v[132:135], v[190:193], v[92:95]
	v_mfma_f32_16x16x32_bf16 v[88:91], v[160:163], v[190:193], v[88:91]
	v_mfma_f32_16x16x32_bf16 v[76:79], v[132:135], v[202:205], v[76:79]
	v_mfma_f32_16x16x32_bf16 v[72:75], v[160:163], v[202:205], v[72:75]
	s_setprio 0
	s_barrier
	s_add_i32 s57, s48, s34
	s_mov_b32 m0, s57
	ds_read_b128 v[206:209], v169
	ds_read_b128 v[210:213], v169 offset:1024
	ds_read_b128 v[214:217], v169 offset:2048
	ds_read_b128 v[218:221], v169 offset:3072
	global_load_lds_dwordx4 v146, s[26:27]
	s_add_i32 m0, s57, 0x2000
	s_nop 0
	global_load_lds_dwordx4 v142, s[26:27]
	s_waitcnt vmcnt(26)
	s_barrier
	s_waitcnt lgkmcnt(0)
	s_setprio 1
	s_waitcnt lgkmcnt(0)
	v_mfma_f32_16x16x32_bf16 v[116:119], v[206:209], v[170:173], 0
	v_mfma_f32_16x16x32_bf16 v[112:115], v[214:217], v[170:173], 0
	v_mfma_f32_16x16x32_bf16 v[100:103], v[206:209], v[178:181], 0
	v_mfma_f32_16x16x32_bf16 v[96:99], v[214:217], v[178:181], 0
	v_mfma_f32_16x16x32_bf16 v[84:87], v[206:209], v[186:189], 0
	v_mfma_f32_16x16x32_bf16 v[80:83], v[214:217], v[186:189], 0
	v_mfma_f32_16x16x32_bf16 v[68:71], v[206:209], v[194:197], 0
	v_mfma_f32_16x16x32_bf16 v[64:67], v[214:217], v[194:197], 0
	v_mfma_f32_16x16x32_bf16 v[116:119], v[210:213], v[174:177], v[116:119]
	v_mfma_f32_16x16x32_bf16 v[112:115], v[218:221], v[174:177], v[112:115]
	v_mfma_f32_16x16x32_bf16 v[100:103], v[210:213], v[182:185], v[100:103]
	v_mfma_f32_16x16x32_bf16 v[96:99], v[218:221], v[182:185], v[96:99]
	v_mfma_f32_16x16x32_bf16 v[84:87], v[210:213], v[190:193], v[84:87]
	v_mfma_f32_16x16x32_bf16 v[80:83], v[218:221], v[190:193], v[80:83]
	v_mfma_f32_16x16x32_bf16 v[68:71], v[210:213], v[202:205], v[68:71]
	v_mfma_f32_16x16x32_bf16 v[64:67], v[218:221], v[202:205], v[64:67]
	s_setprio 0
	s_mov_b32 m0, s37
	v_lshl_add_u64 v[222:223], s[28:29], 0, v[148:149]
	s_barrier
	ds_read_b128 v[170:173], v168 offset:16384
	ds_read_b128 v[174:177], v168 offset:17408
	ds_read_b128 v[178:181], v168 offset:18432
	ds_read_b128 v[182:185], v168 offset:19456
	ds_read_b128 v[186:189], v168 offset:20480
	ds_read_b128 v[190:193], v168 offset:21504
	ds_read_b128 v[194:197], v168 offset:22528
	ds_read_b128 v[202:205], v168 offset:23552
	global_load_lds_dwordx4 v148, s[28:29]
	v_lshl_add_u64 v[224:225], s[28:29], 0, v[144:145]
	s_mov_b32 m0, s38
	s_nop 0
	global_load_lds_dwordx4 v144, s[28:29]
	s_barrier
	s_waitcnt lgkmcnt(0)
	s_setprio 1
	s_waitcnt lgkmcnt(0)
	v_mfma_f32_16x16x32_bf16 v[60:63], v[128:131], v[170:173], 0
	v_mfma_f32_16x16x32_bf16 v[56:59], v[136:139], v[170:173], 0
	v_mfma_f32_16x16x32_bf16 v[44:47], v[128:131], v[178:181], 0
	v_mfma_f32_16x16x32_bf16 v[40:43], v[136:139], v[178:181], 0
	v_mfma_f32_16x16x32_bf16 v[28:31], v[128:131], v[186:189], 0
	v_mfma_f32_16x16x32_bf16 v[24:27], v[136:139], v[186:189], 0
	v_mfma_f32_16x16x32_bf16 v[12:15], v[128:131], v[194:197], 0
	v_mfma_f32_16x16x32_bf16 v[8:11], v[136:139], v[194:197], 0
	v_mfma_f32_16x16x32_bf16 v[60:63], v[132:135], v[174:177], v[60:63]
	v_mfma_f32_16x16x32_bf16 v[56:59], v[160:163], v[174:177], v[56:59]
	v_mfma_f32_16x16x32_bf16 v[44:47], v[132:135], v[182:185], v[44:47]
	v_mfma_f32_16x16x32_bf16 v[40:43], v[160:163], v[182:185], v[40:43]
	v_mfma_f32_16x16x32_bf16 v[28:31], v[132:135], v[190:193], v[28:31]
	v_mfma_f32_16x16x32_bf16 v[24:27], v[160:163], v[190:193], v[24:27]
	v_mfma_f32_16x16x32_bf16 v[12:15], v[132:135], v[202:205], v[12:15]
	v_mfma_f32_16x16x32_bf16 v[8:11], v[160:163], v[202:205], v[8:11]
	s_setprio 0
	s_barrier
; #define PG8_STAGE(bufoff, gbase, voff) do { _Pragma("unroll") for (int _i = 0; _i < 2; ++_i) \
;         __builtin_amdgcn_global_load_lds((const unsigned*)((const char*)(gbase) + (voff)[_i]), (LAS unsigned*)(lds + (bufoff) + ldsw + _i * 8192), 16, 0, 0); } while (0)
; #define PG8_LDA(dst, b, h) do { _Pragma("unroll") for (int m = 0; m < 4; ++m) _Pragma("unroll") for (int k = 0; k < 2; ++k) dst[m][k] = *(const LAS bf16x8*)(lds + PG8_SA(b, h) + aoff + m * 2048 + k * 1024); } while (0)
; #define PG8_LDB(dst, b, h) do { _Pragma("unroll") for (int n = 0; n < 2; ++n) _Pragma("unroll") for (int k = 0; k < 2; ++k) dst[n][k] = *(const LAS bf16x8*)(lds + PG8_SB(b, h) + boff + n * 2048 + k * 1024); } while (0)
; #define PG8_MMA(ai, bj, At, Bt) do { __builtin_amdgcn_s_setprio(1); _Pragma("unroll") for (int m = 0; m < 4; ++m) _Pragma("unroll") for (int n = 0; n < 2; ++n) _Pragma("unroll") for (int k = 0; k < 2; ++k) \
;         acc[ai][bj][m][n] = __builtin_amdgcn_mfma_f32_16x16x32_bf16(Bt[n][k], At[m][k], acc[ai][bj][m][n], 0, 0, 0); __builtin_amdgcn_s_setprio(0); } while (0)
; #define PG8_WAIT_V(n) asm volatile("s_waitcnt vmcnt(" #n ")" ::: "memory")
; #define PG8_WAIT_L(n) asm volatile("s_waitcnt lgkmcnt(" #n ")" ::: "memory")
; #define PG8_BAR __builtin_amdgcn_s_barrier()
; #define PG8_SCHED __builtin_amdgcn_sched_barrier(0)
; template <class Epi, class Sched>
; __device__ __forceinline__ void gemm_phase(LAS unsigned char* lds, const Gemm g, const Sched& S, const Epi& E) {
;     ...
;             PG8_BAR; PG8_WAIT_L(0); PG8_MMA(1, 0, At, B0); PG8_BAR; PG8_SCHED;
;             PG8_STAGE(PG8_SB(0, 1), b2 + hstep, voffB);
;             PG8_WAIT_V(6); PG8_BAR; PG8_MMA(1, 1, At, B1); PG8_BAR;
;             PG8_LDB(B0, 1, 0); PG8_SCHED; PG8_LDA(At, 1, 0); PG8_STAGE(PG8_SA(0, 1), a2 + hstep, voffA);
;             PG8_WAIT_L(8); PG8_BAR; PG8_WAIT_L(0); PG8_MMA(0, 0, At, B0); PG8_BAR; PG8_SCHED;
;             PG8_LDB(B1, 1, 1); PG8_STAGE(PG8_SB(1, 0), b3, voffB);
;             PG8_BAR; PG8_WAIT_L(0); PG8_MMA(0, 1, At, B1); PG8_BAR;
;             PG8_LDA(At, 1, 1); PG8_STAGE(PG8_SA(1, 0), a3, voffA);
;             PG8_BAR; PG8_WAIT_L(0); PG8_MMA(1, 0, At, B0); PG8_BAR; PG8_SCHED;
	s_add_u32 s58, s26, 0x40000
	s_addc_u32 s59, s27, 0
	s_add_i32 s57, s49, s34
	s_mov_b32 m0, s57
	s_nop 0
	global_load_lds_dwordx4 v146, s[58:59]
	s_add_i32 m0, s57, 0x2000
	s_nop 0
	global_load_lds_dwordx4 v142, s[58:59]
	s_waitcnt vmcnt(26)
	s_barrier
	s_setprio 1
	v_mfma_f32_16x16x32_bf16 v[52:55], v[206:209], v[170:173], 0
	v_mfma_f32_16x16x32_bf16 v[48:51], v[214:217], v[170:173], 0
	v_mfma_f32_16x16x32_bf16 v[36:39], v[206:209], v[178:181], 0
	v_mfma_f32_16x16x32_bf16 v[32:35], v[214:217], v[178:181], 0
	v_mfma_f32_16x16x32_bf16 v[20:23], v[206:209], v[186:189], 0
	v_mfma_f32_16x16x32_bf16 v[16:19], v[214:217], v[186:189], 0
	v_mfma_f32_16x16x32_bf16 v[4:7], v[206:209], v[194:197], 0
	v_mfma_f32_16x16x32_bf16 v[0:3], v[214:217], v[194:197], 0
	v_mfma_f32_16x16x32_bf16 v[52:55], v[210:213], v[174:177], v[52:55]
	v_mfma_f32_16x16x32_bf16 v[48:51], v[218:221], v[174:177], v[48:51]
	v_mfma_f32_16x16x32_bf16 v[36:39], v[210:213], v[182:185], v[36:39]
	v_mfma_f32_16x16x32_bf16 v[32:35], v[218:221], v[182:185], v[32:35]
	v_mfma_f32_16x16x32_bf16 v[20:23], v[210:213], v[190:193], v[20:23]
	v_mfma_f32_16x16x32_bf16 v[16:19], v[218:221], v[190:193], v[16:19]
	v_mfma_f32_16x16x32_bf16 v[4:7], v[210:213], v[202:205], v[4:7]
	v_mfma_f32_16x16x32_bf16 v[0:3], v[218:221], v[202:205], v[0:3]
	s_setprio 0
	s_add_i32 s57, 0, 0x18000
	v_add_u32_e32 v150, s57, v166
	s_barrier
	ds_read_b128 v[128:131], v150
	ds_read_b128 v[132:135], v150 offset:1024
	ds_read_b128 v[136:139], v150 offset:2048
	ds_read_b128 v[160:163], v150 offset:3072
	s_add_u32 s28, s28, 0x40000
	s_addc_u32 s29, s29, 0
	s_mov_b32 m0, s39
	ds_read_b128 v[170:173], v168 offset:32768
	ds_read_b128 v[174:177], v168 offset:33792
	ds_read_b128 v[178:181], v168 offset:34816
	ds_read_b128 v[182:185], v168 offset:35840
	ds_read_b128 v[186:189], v168 offset:36864
	ds_read_b128 v[190:193], v168 offset:37888
	ds_read_b128 v[194:197], v168 offset:38912
	ds_read_b128 v[202:205], v168 offset:39936
	global_load_lds_dwordx4 v148, s[28:29]
	s_mov_b32 m0, s40
	s_nop 0
	global_load_lds_dwordx4 v144, s[28:29]
	s_waitcnt lgkmcnt(8)
	s_waitcnt vmcnt(26)
	s_barrier
	s_waitcnt lgkmcnt(0)
	s_setprio 1
	s_waitcnt lgkmcnt(0)
	v_mfma_f32_16x16x32_bf16 v[124:127], v[128:131], v[170:173], v[124:127]
	v_mfma_f32_16x16x32_bf16 v[120:123], v[136:139], v[170:173], v[120:123]
	v_mfma_f32_16x16x32_bf16 v[108:111], v[128:131], v[178:181], v[108:111]
	v_mfma_f32_16x16x32_bf16 v[104:107], v[136:139], v[178:181], v[104:107]
	v_mfma_f32_16x16x32_bf16 v[92:95], v[128:131], v[186:189], v[92:95]
	v_mfma_f32_16x16x32_bf16 v[88:91], v[136:139], v[186:189], v[88:91]
	v_mfma_f32_16x16x32_bf16 v[76:79], v[128:131], v[194:197], v[76:79]
	v_mfma_f32_16x16x32_bf16 v[72:75], v[136:139], v[194:197], v[72:75]
	v_mfma_f32_16x16x32_bf16 v[124:127], v[132:135], v[174:177], v[124:127]
	v_mfma_f32_16x16x32_bf16 v[120:123], v[160:163], v[174:177], v[120:123]
	v_mfma_f32_16x16x32_bf16 v[108:111], v[132:135], v[182:185], v[108:111]
	v_mfma_f32_16x16x32_bf16 v[104:107], v[160:163], v[182:185], v[104:107]
	v_mfma_f32_16x16x32_bf16 v[92:95], v[132:135], v[190:193], v[92:95]
	v_mfma_f32_16x16x32_bf16 v[88:91], v[160:163], v[190:193], v[88:91]
	v_mfma_f32_16x16x32_bf16 v[76:79], v[132:135], v[202:205], v[76:79]
	v_mfma_f32_16x16x32_bf16 v[72:75], v[160:163], v[202:205], v[72:75]
	s_setprio 0
	s_barrier
	s_add_i32 s28, 0, 0x1c000
	s_add_i32 s29, s57, s34
	v_add_u32_e32 v150, s28, v166
	s_add_u32 s0, s26, 0x80
	s_addc_u32 s1, s27, 0
	s_mov_b32 m0, s29
	ds_read_b128 v[206:209], v150
	ds_read_b128 v[210:213], v150 offset:1024
	ds_read_b128 v[214:217], v150 offset:2048
	ds_read_b128 v[218:221], v150 offset:3072
	global_load_lds_dwordx4 v146, s[0:1]
	s_add_i32 m0, s29, 0x2000
	s_nop 0
	global_load_lds_dwordx4 v142, s[0:1]
	s_waitcnt vmcnt(10)
	s_barrier
; #define PG8_STAGE(bufoff, gbase, voff) do { _Pragma("unroll") for (int _i = 0; _i < 2; ++_i) \
;         __builtin_amdgcn_global_load_lds((const unsigned*)((const char*)(gbase) + (voff)[_i]), (LAS unsigned*)(lds + (bufoff) + ldsw + _i * 8192), 16, 0, 0); } while (0)
; #define PG8_MMA(ai, bj, At, Bt) do { __builtin_amdgcn_s_setprio(1); _Pragma("unroll") for (int m = 0; m < 4; ++m) _Pragma("unroll") for (int n = 0; n < 2; ++n) _Pragma("unroll") for (int k = 0; k < 2; ++k) \
;         acc[ai][bj][m][n] = __builtin_amdgcn_mfma_f32_16x16x32_bf16(Bt[n][k], At[m][k], acc[ai][bj][m][n], 0, 0, 0); __builtin_amdgcn_s_setprio(0); } while (0)
; #define PG8_WAIT_V(n) asm volatile("s_waitcnt vmcnt(" #n ")" ::: "memory")
; #define PG8_WAIT_L(n) asm volatile("s_waitcnt lgkmcnt(" #n ")" ::: "memory")
; #define PG8_BAR __builtin_amdgcn_s_barrier()
; #define PG8_SCHED __builtin_amdgcn_sched_barrier(0)
; template <class Epi, class Sched>
; __device__ __forceinline__ void gemm_phase(LAS unsigned char* lds, const Gemm g, const Sched& S, const Epi& E) {
;     ...
;             PG8_BAR; PG8_WAIT_L(0); PG8_MMA(1, 0, At, B0); PG8_BAR; PG8_SCHED;
;             PG8_STAGE(PG8_SB(1, 1), b3 + hstep, voffB);
;             PG8_WAIT_V(6); PG8_BAR; PG8_MMA(1, 1, At, B1); PG8_BAR;
;         }
	s_waitcnt lgkmcnt(0)
	s_setprio 1
	s_waitcnt lgkmcnt(0)
	v_mfma_f32_16x16x32_bf16 v[116:119], v[206:209], v[170:173], v[116:119]
	v_mfma_f32_16x16x32_bf16 v[112:115], v[214:217], v[170:173], v[112:115]
	v_mfma_f32_16x16x32_bf16 v[100:103], v[206:209], v[178:181], v[100:103]
	v_mfma_f32_16x16x32_bf16 v[96:99], v[214:217], v[178:181], v[96:99]
	v_mfma_f32_16x16x32_bf16 v[84:87], v[206:209], v[186:189], v[84:87]
	v_mfma_f32_16x16x32_bf16 v[80:83], v[214:217], v[186:189], v[80:83]
	v_mfma_f32_16x16x32_bf16 v[68:71], v[206:209], v[194:197], v[68:71]
	v_mfma_f32_16x16x32_bf16 v[64:67], v[214:217], v[194:197], v[64:67]
	v_mfma_f32_16x16x32_bf16 v[116:119], v[210:213], v[174:177], v[116:119]
	v_mfma_f32_16x16x32_bf16 v[112:115], v[218:221], v[174:177], v[112:115]
	v_mfma_f32_16x16x32_bf16 v[100:103], v[210:213], v[182:185], v[100:103]
	v_mfma_f32_16x16x32_bf16 v[96:99], v[218:221], v[182:185], v[96:99]
	v_mfma_f32_16x16x32_bf16 v[84:87], v[210:213], v[190:193], v[84:87]
	v_mfma_f32_16x16x32_bf16 v[80:83], v[218:221], v[190:193], v[80:83]
	v_mfma_f32_16x16x32_bf16 v[68:71], v[210:213], v[202:205], v[68:71]
	v_mfma_f32_16x16x32_bf16 v[64:67], v[218:221], v[202:205], v[64:67]
	s_setprio 0
	s_mov_b32 m0, s44
	s_mov_b64 s[0:1], 0x80
	v_lshl_add_u64 v[140:141], v[222:223], 0, s[0:1]
	s_barrier
	ds_read_b128 v[170:173], v168 offset:49152
	ds_read_b128 v[174:177], v168 offset:50176
	ds_read_b128 v[178:181], v168 offset:51200
	ds_read_b128 v[182:185], v168 offset:52224
	ds_read_b128 v[186:189], v168 offset:53248
	ds_read_b128 v[190:193], v168 offset:54272
	ds_read_b128 v[194:197], v168 offset:55296
	ds_read_b128 v[202:205], v168 offset:56320
	global_load_lds_dwordx4 v[140:141], off
	v_lshl_add_u64 v[140:141], v[224:225], 0, s[0:1]
	s_mov_b32 m0, s45
	s_nop 0
	global_load_lds_dwordx4 v[140:141], off
	s_barrier
	s_waitcnt lgkmcnt(0)
	s_setprio 1
	s_waitcnt lgkmcnt(0)
	v_mfma_f32_16x16x32_bf16 v[60:63], v[128:131], v[170:173], v[60:63]
	v_mfma_f32_16x16x32_bf16 v[56:59], v[136:139], v[170:173], v[56:59]
	v_mfma_f32_16x16x32_bf16 v[44:47], v[128:131], v[178:181], v[44:47]
	v_mfma_f32_16x16x32_bf16 v[40:43], v[136:139], v[178:181], v[40:43]
	v_mfma_f32_16x16x32_bf16 v[28:31], v[128:131], v[186:189], v[28:31]
	v_mfma_f32_16x16x32_bf16 v[24:27], v[136:139], v[186:189], v[24:27]
	v_mfma_f32_16x16x32_bf16 v[12:15], v[128:131], v[194:197], v[12:15]
	v_mfma_f32_16x16x32_bf16 v[8:11], v[136:139], v[194:197], v[8:11]
	v_mfma_f32_16x16x32_bf16 v[60:63], v[132:135], v[174:177], v[60:63]
	v_mfma_f32_16x16x32_bf16 v[56:59], v[160:163], v[174:177], v[56:59]
	v_mfma_f32_16x16x32_bf16 v[44:47], v[132:135], v[182:185], v[44:47]
	v_mfma_f32_16x16x32_bf16 v[40:43], v[160:163], v[182:185], v[40:43]
	v_mfma_f32_16x16x32_bf16 v[28:31], v[132:135], v[190:193], v[28:31]
	v_mfma_f32_16x16x32_bf16 v[24:27], v[160:163], v[190:193], v[24:27]
	v_mfma_f32_16x16x32_bf16 v[12:15], v[132:135], v[202:205], v[12:15]
	v_mfma_f32_16x16x32_bf16 v[8:11], v[160:163], v[202:205], v[8:11]
	s_setprio 0
	s_barrier
	s_add_u32 s26, s26, 0x40080
	s_addc_u32 s27, s27, 0
	s_add_i32 s28, s28, s34
	s_mov_b32 m0, s28
	s_nop 0
	global_load_lds_dwordx4 v146, s[26:27]
	s_add_i32 m0, s28, 0x2000
	s_nop 0
	global_load_lds_dwordx4 v142, s[26:27]
	s_waitcnt vmcnt(10)
	s_barrier
	s_setprio 1
	v_mfma_f32_16x16x32_bf16 v[52:55], v[206:209], v[170:173], v[52:55]
	v_mfma_f32_16x16x32_bf16 v[48:51], v[214:217], v[170:173], v[48:51]
	v_mfma_f32_16x16x32_bf16 v[36:39], v[206:209], v[178:181], v[36:39]
	v_mfma_f32_16x16x32_bf16 v[32:35], v[214:217], v[178:181], v[32:35]
	v_mfma_f32_16x16x32_bf16 v[20:23], v[206:209], v[186:189], v[20:23]
	v_mfma_f32_16x16x32_bf16 v[16:19], v[214:217], v[186:189], v[16:19]
	v_mfma_f32_16x16x32_bf16 v[4:7], v[206:209], v[194:197], v[4:7]
	v_mfma_f32_16x16x32_bf16 v[0:3], v[214:217], v[194:197], v[0:3]
	v_mfma_f32_16x16x32_bf16 v[52:55], v[210:213], v[174:177], v[52:55]
	v_mfma_f32_16x16x32_bf16 v[48:51], v[218:221], v[174:177], v[48:51]
	v_mfma_f32_16x16x32_bf16 v[36:39], v[210:213], v[182:185], v[36:39]
	v_mfma_f32_16x16x32_bf16 v[32:35], v[218:221], v[182:185], v[32:35]
	v_mfma_f32_16x16x32_bf16 v[20:23], v[210:213], v[190:193], v[20:23]
	v_mfma_f32_16x16x32_bf16 v[16:19], v[218:221], v[190:193], v[16:19]
	v_mfma_f32_16x16x32_bf16 v[4:7], v[210:213], v[202:205], v[4:7]
	v_mfma_f32_16x16x32_bf16 v[0:3], v[218:221], v[202:205], v[0:3]
	s_setprio 0
	s_add_i32 s56, s56, 2
	s_add_u32 s6, s6, 0x100
	s_addc_u32 s7, s7, 0
	s_add_u32 s54, s54, 0x100
	s_addc_u32 s55, s55, 0
	s_cmp_gt_u32 s56, 13
	s_barrier

; #define PG8_STAGE(bufoff, gbase, voff) do { _Pragma("unroll") for (int _i = 0; _i < 2; ++_i) \
;         __builtin_amdgcn_global_load_lds((const unsigned*)((const char*)(gbase) + (voff)[_i]), (LAS unsigned*)(lds + (bufoff) + ldsw + _i * 8192), 16, 0, 0); } while (0)
; #define PG8_WAIT_V(n) asm volatile("s_waitcnt vmcnt(" #n ")" ::: "memory")
; #define PG8_BAR __builtin_amdgcn_s_barrier()
; template <class Epi, class Sched>
; __device__ __forceinline__ void gemm_phase(LAS unsigned char* lds, const Gemm g, const Sched& S, const Epi& E) {
;     ...
;     const char* cA = (const char*)g.A + (size_t)cur.pm * tstep; const char* cB = (const char*)g.Bt + (size_t)cur.pn * tstep;
;     PG8_STAGE(PG8_SB(0, 0), cB, voffB); PG8_STAGE(PG8_SA(0, 0), cA, voffA); PG8_STAGE(PG8_SB(0, 1), cB + hstep, voffB); PG8_STAGE(PG8_SA(0, 1), cA + hstep, voffA);
;     if (wr == 1) PG8_BAR;
;     PG8_WAIT_V(4); PG8_BAR;
;     PG8_STAGE(PG8_SB(1, 0), cB + kstep, voffB); PG8_STAGE(PG8_SA(1, 0), cA + kstep, voffA); PG8_STAGE(PG8_SB(1, 1), cB + hstep + kstep, voffB);
;     PG8_WAIT_V(6); PG8_BAR;
.LBB0_605:
	s_lshl_b32 s3, s3, 5
	s_mov_b64 s[20:21], 0x80
	s_and_b32 s53, s3, 0x60
	s_add_i32 m0, s45, 0x18000
	v_lshl_add_u64 v[6:7], v[6:7], 0, s[20:21]
	s_lshl_b32 s52, s2, 6
	s_lshl_b32 s7, s2, 13
	s_lshl_b32 s3, s53, 7
	s_waitcnt vmcnt(4)
	s_barrier
	global_load_lds_dwordx4 v[6:7], off
	v_lshl_add_u64 v[4:5], v[4:5], 0, s[20:21]
	s_add_i32 m0, s45, 0x1a000
	s_add_i32 s54, s45, 0x8000
	s_add_i32 s55, s45, 0xa000
	global_load_lds_dwordx4 v[4:5], off
	v_lshl_add_u64 v[2:3], v[2:3], 0, s[20:21]
	s_mov_b32 m0, s54
	s_add_u32 s8, s4, 0x40080
	global_load_lds_dwordx4 v[2:3], off
	v_lshl_add_u64 v[0:1], v[0:1], 0, s[20:21]
	s_mov_b32 m0, s55
	s_addc_u32 s9, s5, 0
	global_load_lds_dwordx4 v[0:1], off
	s_add_i32 m0, s45, 0x1c000
	v_lshl_add_u64 v[0:1], s[8:9], 0, v[130:131]
	global_load_lds_dwordx4 v[0:1], off
	v_lshl_add_u64 v[0:1], s[8:9], 0, v[134:135]
	s_add_i32 m0, s45, 0x1e000
	v_bfe_u32 v169, v8, 4, 2
	global_load_lds_dwordx4 v[0:1], off
	v_and_b32_e32 v168, 15, v8
	v_lshlrev_b32_e32 v0, 4, v169
	v_lshlrev_b32_e32 v1, 2, v8
	v_lshl_or_b32 v0, v168, 6, v0
	v_and_b32_e32 v1, 32, v1
	v_bitop3_b32 v2, v0, s7, v1 bitop3:0xde
	v_bitop3_b32 v170, v0, s3, v1 bitop3:0xde
	v_lshlrev_b32_e32 v0, 14, v9
	v_readlane_b32 s80, v254, 0
	v_and_b32_e32 v0, 0xffff8000, v0
	s_ashr_i32 s3, s2, 31
	v_readlane_b32 s86, v254, 6
	v_readlane_b32 s87, v254, 7
	v_lshl_add_u32 v0, v10, 11, v0
	v_and_b32_e32 v1, 1, v9
	s_ashr_i32 s56, s76, 31
	s_lshl_b64 s[2:3], s[2:3], 2
	s_mov_b64 s[22:23], s[86:87]
	v_lshl_or_b32 v0, v1, 6, v0
	s_add_u32 s22, s22, s2
	v_lshl_add_u32 v138, v11, 1, v0
	v_lshlrev_b32_e32 v0, 14, v12
	s_addc_u32 s23, s23, s3
	v_and_b32_e32 v0, 0xffff8000, v0
	s_waitcnt vmcnt(0)
	v_readlane_b32 s81, v254, 1
	v_readlane_b32 s82, v254, 2
	v_readlane_b32 s83, v254, 3
	s_add_u32 s24, s72, 0x33ab000
	v_lshl_add_u32 v0, v13, 11, v0
	v_and_b32_e32 v1, 1, v12
	s_addc_u32 s25, s73, 0
	v_lshl_or_b32 v0, v1, 6, v0
	s_add_i32 s57, 0, 0x10000
	s_add_i32 s58, 0, 0x14000
	v_readlane_b32 s82, v254, 59
	v_readlane_b32 s80, v254, 55
	s_sext_i32_i16 s33, s6
	v_mov_b32_e32 v139, v137
	v_lshl_add_u32 v140, v14, 1, v0
	v_mov_b32_e32 v141, v137
	v_mov_b64_e32 v[142:143], 0x100
	v_mov_b64_e32 v[144:145], 0xff
	v_add_u32_e32 v171, s57, v170
	v_add_u32_e32 v172, 0, v2
	v_add_u32_e32 v173, s58, v170
	v_mbcnt_hi_u32_b32 v174, -1, v201
	s_mov_b32 s59, 0xc2fc0000
	s_mov_b32 s60, 0x42fc0000
	s_movk_i32 s61, 0x1000
	s_movk_i32 s62, 0x3000
	s_mov_b64 s[26:27], 0x1600000
	s_mov_b32 s63, 0x1600000
	s_mov_b64 s[28:29], 0x3600000
	s_mov_b32 s64, 0x3600000
	v_not_b32_e32 v175, 63
	v_mov_b32_e32 v176, 0x42800000
	v_readlane_b32 s83, v254, 60
	v_readlane_b32 s74, v254, 43
	v_readlane_b32 s81, v254, 56
	s_barrier
	v_readlane_b32 s84, v254, 4
	v_readlane_b32 s85, v254, 5
	v_readlane_b32 s88, v254, 8
	v_readlane_b32 s89, v254, 9
	v_readlane_b32 s90, v254, 10
	v_readlane_b32 s91, v254, 11
	v_readlane_b32 s92, v254, 12
	v_readlane_b32 s93, v254, 13
	v_readlane_b32 s94, v254, 14
	v_readlane_b32 s95, v254, 15

; #define PG8_STAGE(bufoff, gbase, voff) do { _Pragma("unroll") for (int _i = 0; _i < 2; ++_i) \
;         __builtin_amdgcn_global_load_lds((const unsigned*)((const char*)(gbase) + (voff)[_i]), (LAS unsigned*)(lds + (bufoff) + ldsw + _i * 8192), 16, 0, 0); } while (0)
; #define PG8_LDA(dst, b, h) do { _Pragma("unroll") for (int m = 0; m < 4; ++m) _Pragma("unroll") for (int k = 0; k < 2; ++k) dst[m][k] = *(const LAS bf16x8*)(lds + PG8_SA(b, h) + aoff + m * 2048 + k * 1024); } while (0)
; #define PG8_LDB(dst, b, h) do { _Pragma("unroll") for (int n = 0; n < 2; ++n) _Pragma("unroll") for (int k = 0; k < 2; ++k) dst[n][k] = *(const LAS bf16x8*)(lds + PG8_SB(b, h) + boff + n * 2048 + k * 1024); } while (0)
; #define PG8_MMA(ai, bj, At, Bt) do { __builtin_amdgcn_s_setprio(1); _Pragma("unroll") for (int m = 0; m < 4; ++m) _Pragma("unroll") for (int n = 0; n < 2; ++n) _Pragma("unroll") for (int k = 0; k < 2; ++k) \
;         acc[ai][bj][m][n] = __builtin_amdgcn_mfma_f32_16x16x32_bf16(Bt[n][k], At[m][k], acc[ai][bj][m][n], 0, 0, 0); __builtin_amdgcn_s_setprio(0); } while (0)
; #define PG8_WAIT_L(n) asm volatile("s_waitcnt lgkmcnt(" #n ")" ::: "memory")
; template <class Epi, class Sched>
; __device__ __forceinline__ void gemm_phase(LAS unsigned char* lds, const Gemm g, const Sched& S, const Epi& E) {
;     ...
;         const bool has_next = S.next(ui + 1, nxt);
;         const char* nA = has_next ? (const char*)g.A + (size_t)nxt.pm * tstep : cA; const char* nB = has_next ? (const char*)g.Bt + (size_t)nxt.pn * tstep : cB;
;         for (int t = 0; t < nt; t += 2) {
;             const bool last = (t == nt - 2);
;             const char* a1 = cA + (size_t)(t + 1) * kstep;
;             const char* a2 = last ? nA : cA + (size_t)(t + 2) * kstep; const char* b2 = last ? nB : cB + (size_t)(t + 2) * kstep;
;             const char* a3 = a2 + kstep; const char* b3 = b2 + kstep;
;             PG8_LDB(B0, 0, 0); PG8_SCHED; PG8_LDA(At, 0, 0); PG8_STAGE(PG8_SA(1, 1), a1 + hstep, voffA);
;             PG8_WAIT_L(8); PG8_BAR; PG8_WAIT_L(0); PG8_MMA(0, 0, At, B0); PG8_BAR; PG8_SCHED;
;             PG8_LDB(B1, 0, 1); PG8_STAGE(PG8_SB(0, 0), b2, voffB);
;             PG8_BAR; PG8_WAIT_L(0); PG8_MMA(0, 1, At, B1); PG8_BAR;
;             PG8_LDA(At, 0, 1); PG8_STAGE(PG8_SA(0, 0), a2, voffA);
;             PG8_BAR; PG8_WAIT_L(0); PG8_MMA(1, 0, At, B0); PG8_BAR; PG8_SCHED;
.LBB0_612:
	s_ashr_i32 s35, s34, 31
	v_cmp_lt_i64_e32 vcc, s[6:7], v[142:143]
	s_lshl_b64 s[6:7], s[34:35], 19
	s_add_u32 s36, s40, s6
	s_addc_u32 s37, s41, s7
	s_and_b64 s[6:7], vcc, exec
	s_cselect_b32 s8, s37, s1
	s_cselect_b32 s9, s36, s0
	s_ashr_i32 s31, s30, 31
	s_lshl_b64 s[6:7], s[30:31], 19
	s_add_u32 s38, s96, s6
	s_addc_u32 s39, s97, s7
	s_and_b64 s[6:7], vcc, exec
	s_cselect_b32 s31, s39, s5
	s_cselect_b32 s35, s38, s4
	s_add_u32 s0, s0, 0x40080
	s_addc_u32 s1, s1, 0
	s_add_u32 s65, s4, 0x100
	s_addc_u32 s66, s5, 0
	s_mov_b32 s67, -2
	s_waitcnt lgkmcnt(0)
	ds_read_b128 v[146:149], v171
	ds_read_b128 v[150:153], v171 offset:1024
	ds_read_b128 v[154:157], v171 offset:2048
	ds_read_b128 v[158:161], v171 offset:3072
	s_add_u32 s4, s0, 0xfffc0080
	s_addc_u32 s5, s1, -1
	s_cmp_eq_u32 s67, 12
	s_cselect_b32 s7, s8, s5
	s_cselect_b32 s6, s9, s4
	s_cselect_b32 s5, s31, s66
	s_cselect_b32 s4, s35, s65
	s_add_i32 m0, s45, 0xc000
	ds_read_b128 v[162:165], v172
	ds_read_b128 v[178:181], v172 offset:1024
	ds_read_b128 v[182:185], v172 offset:2048
	ds_read_b128 v[186:189], v172 offset:3072
	ds_read_b128 v[190:193], v172 offset:4096
	ds_read_b128 v[194:197], v172 offset:5120
	ds_read_b128 v[202:205], v172 offset:6144
	ds_read_b128 v[206:209], v172 offset:7168
	global_load_lds_dwordx4 v138, s[0:1]
	s_add_i32 m0, s45, 0xe000
	s_nop 0
	global_load_lds_dwordx4 v140, s[0:1]
	s_waitcnt lgkmcnt(8)
	s_waitcnt vmcnt(26)
	s_barrier
	s_waitcnt lgkmcnt(0)
	s_setprio 1
	s_waitcnt lgkmcnt(0)
	v_mfma_f32_16x16x32_bf16 v[124:127], v[146:149], v[162:165], 0
	v_mfma_f32_16x16x32_bf16 v[120:123], v[154:157], v[162:165], 0
	v_mfma_f32_16x16x32_bf16 v[108:111], v[146:149], v[182:185], 0
	v_mfma_f32_16x16x32_bf16 v[104:107], v[154:157], v[182:185], 0
	v_mfma_f32_16x16x32_bf16 v[92:95], v[146:149], v[190:193], 0
	v_mfma_f32_16x16x32_bf16 v[88:91], v[154:157], v[190:193], 0
	v_mfma_f32_16x16x32_bf16 v[76:79], v[146:149], v[202:205], 0
	v_mfma_f32_16x16x32_bf16 v[72:75], v[154:157], v[202:205], 0
	v_mfma_f32_16x16x32_bf16 v[124:127], v[150:153], v[178:181], v[124:127]
	v_mfma_f32_16x16x32_bf16 v[120:123], v[158:161], v[178:181], v[120:123]
	v_mfma_f32_16x16x32_bf16 v[108:111], v[150:153], v[186:189], v[108:111]
	v_mfma_f32_16x16x32_bf16 v[104:107], v[158:161], v[186:189], v[104:107]
	v_mfma_f32_16x16x32_bf16 v[92:95], v[150:153], v[194:197], v[92:95]
	v_mfma_f32_16x16x32_bf16 v[88:91], v[158:161], v[194:197], v[88:91]
	v_mfma_f32_16x16x32_bf16 v[76:79], v[150:153], v[206:209], v[76:79]
	v_mfma_f32_16x16x32_bf16 v[72:75], v[158:161], v[206:209], v[72:75]
	s_setprio 0
	s_barrier
	s_add_i32 s68, s57, s44
	s_mov_b32 m0, s68
	ds_read_b128 v[210:213], v173
	ds_read_b128 v[214:217], v173 offset:1024
	ds_read_b128 v[218:221], v173 offset:2048
	ds_read_b128 v[222:225], v173 offset:3072
	global_load_lds_dwordx4 v130, s[4:5]
	s_add_i32 m0, s68, 0x2000
	s_nop 0
	global_load_lds_dwordx4 v134, s[4:5]
	s_waitcnt vmcnt(26)
	s_barrier
	s_waitcnt lgkmcnt(0)
	s_setprio 1
	s_waitcnt lgkmcnt(0)
	v_mfma_f32_16x16x32_bf16 v[116:119], v[210:213], v[162:165], 0
	v_mfma_f32_16x16x32_bf16 v[112:115], v[218:221], v[162:165], 0
	v_mfma_f32_16x16x32_bf16 v[100:103], v[210:213], v[182:185], 0
	v_mfma_f32_16x16x32_bf16 v[96:99], v[218:221], v[182:185], 0
	v_mfma_f32_16x16x32_bf16 v[84:87], v[210:213], v[190:193], 0
	v_mfma_f32_16x16x32_bf16 v[80:83], v[218:221], v[190:193], 0
	v_mfma_f32_16x16x32_bf16 v[68:71], v[210:213], v[202:205], 0
	v_mfma_f32_16x16x32_bf16 v[64:67], v[218:221], v[202:205], 0
	v_mfma_f32_16x16x32_bf16 v[116:119], v[214:217], v[178:181], v[116:119]
	v_mfma_f32_16x16x32_bf16 v[112:115], v[222:225], v[178:181], v[112:115]
	v_mfma_f32_16x16x32_bf16 v[100:103], v[214:217], v[186:189], v[100:103]
	v_mfma_f32_16x16x32_bf16 v[96:99], v[222:225], v[186:189], v[96:99]
	v_mfma_f32_16x16x32_bf16 v[84:87], v[214:217], v[194:197], v[84:87]
	v_mfma_f32_16x16x32_bf16 v[80:83], v[222:225], v[194:197], v[80:83]
	v_mfma_f32_16x16x32_bf16 v[68:71], v[214:217], v[206:209], v[68:71]
	v_mfma_f32_16x16x32_bf16 v[64:67], v[222:225], v[206:209], v[64:67]
	s_setprio 0
	s_mov_b32 m0, s45
	v_lshl_add_u64 v[226:227], s[6:7], 0, v[128:129]
	s_barrier
	ds_read_b128 v[162:165], v172 offset:16384
	ds_read_b128 v[178:181], v172 offset:17408
	ds_read_b128 v[182:185], v172 offset:18432
	ds_read_b128 v[186:189], v172 offset:19456
	ds_read_b128 v[190:193], v172 offset:20480
	ds_read_b128 v[194:197], v172 offset:21504
	ds_read_b128 v[202:205], v172 offset:22528
	ds_read_b128 v[206:209], v172 offset:23552
	global_load_lds_dwordx4 v128, s[6:7]
	v_lshl_add_u64 v[228:229], s[6:7], 0, v[132:133]
	s_mov_b32 m0, s46
	s_nop 0
	global_load_lds_dwordx4 v132, s[6:7]
	s_barrier
	s_waitcnt lgkmcnt(0)
	s_setprio 1
	s_waitcnt lgkmcnt(0)
	v_mfma_f32_16x16x32_bf16 v[60:63], v[146:149], v[162:165], 0
	v_mfma_f32_16x16x32_bf16 v[56:59], v[154:157], v[162:165], 0
	v_mfma_f32_16x16x32_bf16 v[44:47], v[146:149], v[182:185], 0
	v_mfma_f32_16x16x32_bf16 v[40:43], v[154:157], v[182:185], 0
	v_mfma_f32_16x16x32_bf16 v[28:31], v[146:149], v[190:193], 0
	v_mfma_f32_16x16x32_bf16 v[24:27], v[154:157], v[190:193], 0
	v_mfma_f32_16x16x32_bf16 v[12:15], v[146:149], v[202:205], 0
	v_mfma_f32_16x16x32_bf16 v[8:11], v[154:157], v[202:205], 0
	v_mfma_f32_16x16x32_bf16 v[60:63], v[150:153], v[178:181], v[60:63]
	v_mfma_f32_16x16x32_bf16 v[56:59], v[158:161], v[178:181], v[56:59]
	v_mfma_f32_16x16x32_bf16 v[44:47], v[150:153], v[186:189], v[44:47]
	v_mfma_f32_16x16x32_bf16 v[40:43], v[158:161], v[186:189], v[40:43]
	v_mfma_f32_16x16x32_bf16 v[28:31], v[150:153], v[194:197], v[28:31]
	v_mfma_f32_16x16x32_bf16 v[24:27], v[158:161], v[194:197], v[24:27]
	v_mfma_f32_16x16x32_bf16 v[12:15], v[150:153], v[206:209], v[12:15]
	v_mfma_f32_16x16x32_bf16 v[8:11], v[158:161], v[206:209], v[8:11]
	s_setprio 0
	s_barrier
; #define PG8_STAGE(bufoff, gbase, voff) do { _Pragma("unroll") for (int _i = 0; _i < 2; ++_i) \
;         __builtin_amdgcn_global_load_lds((const unsigned*)((const char*)(gbase) + (voff)[_i]), (LAS unsigned*)(lds + (bufoff) + ldsw + _i * 8192), 16, 0, 0); } while (0)
; #define PG8_LDA(dst, b, h) do { _Pragma("unroll") for (int m = 0; m < 4; ++m) _Pragma("unroll") for (int k = 0; k < 2; ++k) dst[m][k] = *(const LAS bf16x8*)(lds + PG8_SA(b, h) + aoff + m * 2048 + k * 1024); } while (0)
; #define PG8_LDB(dst, b, h) do { _Pragma("unroll") for (int n = 0; n < 2; ++n) _Pragma("unroll") for (int k = 0; k < 2; ++k) dst[n][k] = *(const LAS bf16x8*)(lds + PG8_SB(b, h) + boff + n * 2048 + k * 1024); } while (0)
; #define PG8_MMA(ai, bj, At, Bt) do { __builtin_amdgcn_s_setprio(1); _Pragma("unroll") for (int m = 0; m < 4; ++m) _Pragma("unroll") for (int n = 0; n < 2; ++n) _Pragma("unroll") for (int k = 0; k < 2; ++k) \
;         acc[ai][bj][m][n] = __builtin_amdgcn_mfma_f32_16x16x32_bf16(Bt[n][k], At[m][k], acc[ai][bj][m][n], 0, 0, 0); __builtin_amdgcn_s_setprio(0); } while (0)
; #define PG8_WAIT_V(n) asm volatile("s_waitcnt vmcnt(" #n ")" ::: "memory")
; #define PG8_WAIT_L(n) asm volatile("s_waitcnt lgkmcnt(" #n ")" ::: "memory")
; #define PG8_BAR __builtin_amdgcn_s_barrier()
; #define PG8_SCHED __builtin_amdgcn_sched_barrier(0)
; template <class Epi, class Sched>
; __device__ __forceinline__ void gemm_phase(LAS unsigned char* lds, const Gemm g, const Sched& S, const Epi& E) {
;     ...
;             PG8_BAR; PG8_WAIT_L(0); PG8_MMA(1, 0, At, B0); PG8_BAR; PG8_SCHED;
;             PG8_STAGE(PG8_SB(0, 1), b2 + hstep, voffB);
;             PG8_WAIT_V(6); PG8_BAR; PG8_MMA(1, 1, At, B1); PG8_BAR;
;             PG8_LDB(B0, 1, 0); PG8_SCHED; PG8_LDA(At, 1, 0); PG8_STAGE(PG8_SA(0, 1), a2 + hstep, voffA);
;             PG8_WAIT_L(8); PG8_BAR; PG8_WAIT_L(0); PG8_MMA(0, 0, At, B0); PG8_BAR; PG8_SCHED;
;             PG8_LDB(B1, 1, 1); PG8_STAGE(PG8_SB(1, 0), b3, voffB);
;             PG8_BAR; PG8_WAIT_L(0); PG8_MMA(0, 1, At, B1); PG8_BAR;
;             PG8_LDA(At, 1, 1); PG8_STAGE(PG8_SA(1, 0), a3, voffA);
;             PG8_BAR; PG8_WAIT_L(0); PG8_MMA(1, 0, At, B0); PG8_BAR; PG8_SCHED;
	s_add_u32 s68, s4, 0x40000
	s_addc_u32 s69, s5, 0
	s_add_i32 s70, s58, s44
	s_mov_b32 m0, s70
	s_nop 0
	global_load_lds_dwordx4 v130, s[68:69]
	s_add_i32 m0, s70, 0x2000
	s_nop 0
	global_load_lds_dwordx4 v134, s[68:69]
	s_waitcnt vmcnt(26)
	s_barrier
	s_setprio 1
	v_mfma_f32_16x16x32_bf16 v[52:55], v[210:213], v[162:165], 0
	v_mfma_f32_16x16x32_bf16 v[48:51], v[218:221], v[162:165], 0
	v_mfma_f32_16x16x32_bf16 v[36:39], v[210:213], v[182:185], 0
	v_mfma_f32_16x16x32_bf16 v[32:35], v[218:221], v[182:185], 0
	v_mfma_f32_16x16x32_bf16 v[20:23], v[210:213], v[190:193], 0
	v_mfma_f32_16x16x32_bf16 v[16:19], v[218:221], v[190:193], 0
	v_mfma_f32_16x16x32_bf16 v[4:7], v[210:213], v[202:205], 0
	v_mfma_f32_16x16x32_bf16 v[0:3], v[218:221], v[202:205], 0
	v_mfma_f32_16x16x32_bf16 v[52:55], v[214:217], v[178:181], v[52:55]
	v_mfma_f32_16x16x32_bf16 v[48:51], v[222:225], v[178:181], v[48:51]
	v_mfma_f32_16x16x32_bf16 v[36:39], v[214:217], v[186:189], v[36:39]
	v_mfma_f32_16x16x32_bf16 v[32:35], v[222:225], v[186:189], v[32:35]
	v_mfma_f32_16x16x32_bf16 v[20:23], v[214:217], v[194:197], v[20:23]
	v_mfma_f32_16x16x32_bf16 v[16:19], v[222:225], v[194:197], v[16:19]
	v_mfma_f32_16x16x32_bf16 v[4:7], v[214:217], v[206:209], v[4:7]
	v_mfma_f32_16x16x32_bf16 v[0:3], v[222:225], v[206:209], v[0:3]
	s_setprio 0
	s_add_i32 s68, 0, 0x18000
	v_add_u32_e32 v136, s68, v170
	s_barrier
	ds_read_b128 v[146:149], v136
	ds_read_b128 v[150:153], v136 offset:1024
	ds_read_b128 v[154:157], v136 offset:2048
	ds_read_b128 v[158:161], v136 offset:3072
	s_add_u32 s6, s6, 0x40000
	s_addc_u32 s7, s7, 0
	s_mov_b32 m0, s47
	ds_read_b128 v[162:165], v172 offset:32768
	ds_read_b128 v[178:181], v172 offset:33792
	ds_read_b128 v[182:185], v172 offset:34816
	ds_read_b128 v[186:189], v172 offset:35840
	ds_read_b128 v[190:193], v172 offset:36864
	ds_read_b128 v[194:197], v172 offset:37888
	ds_read_b128 v[202:205], v172 offset:38912
	ds_read_b128 v[206:209], v172 offset:39936
	global_load_lds_dwordx4 v128, s[6:7]
	s_mov_b32 m0, s48
	s_nop 0
	global_load_lds_dwordx4 v132, s[6:7]
	s_waitcnt lgkmcnt(8)
	s_waitcnt vmcnt(26)
	s_barrier
	s_waitcnt lgkmcnt(0)
	s_setprio 1
	s_waitcnt lgkmcnt(0)
	v_mfma_f32_16x16x32_bf16 v[124:127], v[146:149], v[162:165], v[124:127]
	v_mfma_f32_16x16x32_bf16 v[120:123], v[154:157], v[162:165], v[120:123]
	v_mfma_f32_16x16x32_bf16 v[108:111], v[146:149], v[182:185], v[108:111]
	v_mfma_f32_16x16x32_bf16 v[104:107], v[154:157], v[182:185], v[104:107]
	v_mfma_f32_16x16x32_bf16 v[92:95], v[146:149], v[190:193], v[92:95]
	v_mfma_f32_16x16x32_bf16 v[88:91], v[154:157], v[190:193], v[88:91]
	v_mfma_f32_16x16x32_bf16 v[76:79], v[146:149], v[202:205], v[76:79]
	v_mfma_f32_16x16x32_bf16 v[72:75], v[154:157], v[202:205], v[72:75]
	v_mfma_f32_16x16x32_bf16 v[124:127], v[150:153], v[178:181], v[124:127]
	v_mfma_f32_16x16x32_bf16 v[120:123], v[158:161], v[178:181], v[120:123]
	v_mfma_f32_16x16x32_bf16 v[108:111], v[150:153], v[186:189], v[108:111]
	v_mfma_f32_16x16x32_bf16 v[104:107], v[158:161], v[186:189], v[104:107]
	v_mfma_f32_16x16x32_bf16 v[92:95], v[150:153], v[194:197], v[92:95]
	v_mfma_f32_16x16x32_bf16 v[88:91], v[158:161], v[194:197], v[88:91]
	v_mfma_f32_16x16x32_bf16 v[76:79], v[150:153], v[206:209], v[76:79]
	v_mfma_f32_16x16x32_bf16 v[72:75], v[158:161], v[206:209], v[72:75]
	s_setprio 0
	s_barrier
	s_add_i32 s6, 0, 0x1c000
	s_add_i32 s7, s68, s44
	v_add_u32_e32 v136, s6, v170
	s_add_u32 s20, s4, 0x80
	s_addc_u32 s21, s5, 0
	s_mov_b32 m0, s7
	ds_read_b128 v[210:213], v136
	ds_read_b128 v[214:217], v136 offset:1024
	ds_read_b128 v[218:221], v136 offset:2048
	ds_read_b128 v[222:225], v136 offset:3072
	global_load_lds_dwordx4 v130, s[20:21]
	s_add_i32 m0, s7, 0x2000
	s_nop 0
	global_load_lds_dwordx4 v134, s[20:21]
	s_waitcnt vmcnt(10)
	s_barrier
; #define PG8_STAGE(bufoff, gbase, voff) do { _Pragma("unroll") for (int _i = 0; _i < 2; ++_i) \
;         __builtin_amdgcn_global_load_lds((const unsigned*)((const char*)(gbase) + (voff)[_i]), (LAS unsigned*)(lds + (bufoff) + ldsw + _i * 8192), 16, 0, 0); } while (0)
; #define PG8_MMA(ai, bj, At, Bt) do { __builtin_amdgcn_s_setprio(1); _Pragma("unroll") for (int m = 0; m < 4; ++m) _Pragma("unroll") for (int n = 0; n < 2; ++n) _Pragma("unroll") for (int k = 0; k < 2; ++k) \
;         acc[ai][bj][m][n] = __builtin_amdgcn_mfma_f32_16x16x32_bf16(Bt[n][k], At[m][k], acc[ai][bj][m][n], 0, 0, 0); __builtin_amdgcn_s_setprio(0); } while (0)
; #define PG8_WAIT_V(n) asm volatile("s_waitcnt vmcnt(" #n ")" ::: "memory")
; #define PG8_WAIT_L(n) asm volatile("s_waitcnt lgkmcnt(" #n ")" ::: "memory")
; #define PG8_BAR __builtin_amdgcn_s_barrier()
; #define PG8_SCHED __builtin_amdgcn_sched_barrier(0)
; template <class Epi, class Sched>
; __device__ __forceinline__ void gemm_phase(LAS unsigned char* lds, const Gemm g, const Sched& S, const Epi& E) {
;     ...
;             PG8_BAR; PG8_WAIT_L(0); PG8_MMA(1, 0, At, B0); PG8_BAR; PG8_SCHED;
;             PG8_STAGE(PG8_SB(1, 1), b3 + hstep, voffB);
;             PG8_WAIT_V(6); PG8_BAR; PG8_MMA(1, 1, At, B1); PG8_BAR;
;         }
	s_waitcnt lgkmcnt(0)
	s_setprio 1
	s_waitcnt lgkmcnt(0)
	v_mfma_f32_16x16x32_bf16 v[116:119], v[210:213], v[162:165], v[116:119]
	v_mfma_f32_16x16x32_bf16 v[112:115], v[218:221], v[162:165], v[112:115]
	v_mfma_f32_16x16x32_bf16 v[100:103], v[210:213], v[182:185], v[100:103]
	v_mfma_f32_16x16x32_bf16 v[96:99], v[218:221], v[182:185], v[96:99]
	v_mfma_f32_16x16x32_bf16 v[84:87], v[210:213], v[190:193], v[84:87]
	v_mfma_f32_16x16x32_bf16 v[80:83], v[218:221], v[190:193], v[80:83]
	v_mfma_f32_16x16x32_bf16 v[68:71], v[210:213], v[202:205], v[68:71]
	v_mfma_f32_16x16x32_bf16 v[64:67], v[218:221], v[202:205], v[64:67]
	v_mfma_f32_16x16x32_bf16 v[116:119], v[214:217], v[178:181], v[116:119]
	v_mfma_f32_16x16x32_bf16 v[112:115], v[222:225], v[178:181], v[112:115]
	v_mfma_f32_16x16x32_bf16 v[100:103], v[214:217], v[186:189], v[100:103]
	v_mfma_f32_16x16x32_bf16 v[96:99], v[222:225], v[186:189], v[96:99]
	v_mfma_f32_16x16x32_bf16 v[84:87], v[214:217], v[194:197], v[84:87]
	v_mfma_f32_16x16x32_bf16 v[80:83], v[222:225], v[194:197], v[80:83]
	v_mfma_f32_16x16x32_bf16 v[68:71], v[214:217], v[206:209], v[68:71]
	v_mfma_f32_16x16x32_bf16 v[64:67], v[222:225], v[206:209], v[64:67]
	s_setprio 0
	s_mov_b32 m0, s54
	s_mov_b64 s[20:21], 0x80
	v_lshl_add_u64 v[166:167], v[226:227], 0, s[20:21]
	s_barrier
	ds_read_b128 v[162:165], v172 offset:49152
	ds_read_b128 v[178:181], v172 offset:50176
	ds_read_b128 v[182:185], v172 offset:51200
	ds_read_b128 v[186:189], v172 offset:52224
	ds_read_b128 v[190:193], v172 offset:53248
	ds_read_b128 v[194:197], v172 offset:54272
	ds_read_b128 v[202:205], v172 offset:55296
	ds_read_b128 v[206:209], v172 offset:56320
	global_load_lds_dwordx4 v[166:167], off
	v_lshl_add_u64 v[166:167], v[228:229], 0, s[20:21]
	s_mov_b32 m0, s55
	s_nop 0
	global_load_lds_dwordx4 v[166:167], off
	s_barrier
	s_waitcnt lgkmcnt(0)
	s_setprio 1
	s_waitcnt lgkmcnt(0)
	v_mfma_f32_16x16x32_bf16 v[60:63], v[146:149], v[162:165], v[60:63]
	v_mfma_f32_16x16x32_bf16 v[56:59], v[154:157], v[162:165], v[56:59]
	v_mfma_f32_16x16x32_bf16 v[44:47], v[146:149], v[182:185], v[44:47]
	v_mfma_f32_16x16x32_bf16 v[40:43], v[154:157], v[182:185], v[40:43]
	v_mfma_f32_16x16x32_bf16 v[28:31], v[146:149], v[190:193], v[28:31]
	v_mfma_f32_16x16x32_bf16 v[24:27], v[154:157], v[190:193], v[24:27]
	v_mfma_f32_16x16x32_bf16 v[12:15], v[146:149], v[202:205], v[12:15]
	v_mfma_f32_16x16x32_bf16 v[8:11], v[154:157], v[202:205], v[8:11]
	v_mfma_f32_16x16x32_bf16 v[60:63], v[150:153], v[178:181], v[60:63]
	v_mfma_f32_16x16x32_bf16 v[56:59], v[158:161], v[178:181], v[56:59]
	v_mfma_f32_16x16x32_bf16 v[44:47], v[150:153], v[186:189], v[44:47]
	v_mfma_f32_16x16x32_bf16 v[40:43], v[158:161], v[186:189], v[40:43]
	v_mfma_f32_16x16x32_bf16 v[28:31], v[150:153], v[194:197], v[28:31]
	v_mfma_f32_16x16x32_bf16 v[24:27], v[158:161], v[194:197], v[24:27]
	v_mfma_f32_16x16x32_bf16 v[12:15], v[150:153], v[206:209], v[12:15]
	v_mfma_f32_16x16x32_bf16 v[8:11], v[158:161], v[206:209], v[8:11]
	s_setprio 0
	s_barrier
	s_add_u32 s4, s4, 0x40080
	s_addc_u32 s5, s5, 0
	s_add_i32 s6, s6, s44
	s_mov_b32 m0, s6
	s_nop 0
	global_load_lds_dwordx4 v130, s[4:5]
	s_add_i32 m0, s6, 0x2000
	s_nop 0
	global_load_lds_dwordx4 v134, s[4:5]
	s_waitcnt vmcnt(10)
	s_barrier
	s_setprio 1
	v_mfma_f32_16x16x32_bf16 v[52:55], v[210:213], v[162:165], v[52:55]
	v_mfma_f32_16x16x32_bf16 v[48:51], v[218:221], v[162:165], v[48:51]
	v_mfma_f32_16x16x32_bf16 v[36:39], v[210:213], v[182:185], v[36:39]
	v_mfma_f32_16x16x32_bf16 v[32:35], v[218:221], v[182:185], v[32:35]
	v_mfma_f32_16x16x32_bf16 v[20:23], v[210:213], v[190:193], v[20:23]
	v_mfma_f32_16x16x32_bf16 v[16:19], v[218:221], v[190:193], v[16:19]
	v_mfma_f32_16x16x32_bf16 v[4:7], v[210:213], v[202:205], v[4:7]
	v_mfma_f32_16x16x32_bf16 v[0:3], v[218:221], v[202:205], v[0:3]
	v_mfma_f32_16x16x32_bf16 v[52:55], v[214:217], v[178:181], v[52:55]
	v_mfma_f32_16x16x32_bf16 v[48:51], v[222:225], v[178:181], v[48:51]
	v_mfma_f32_16x16x32_bf16 v[36:39], v[214:217], v[186:189], v[36:39]
	v_mfma_f32_16x16x32_bf16 v[32:35], v[222:225], v[186:189], v[32:35]
	v_mfma_f32_16x16x32_bf16 v[20:23], v[214:217], v[194:197], v[20:23]
	v_mfma_f32_16x16x32_bf16 v[16:19], v[222:225], v[194:197], v[16:19]
	v_mfma_f32_16x16x32_bf16 v[4:7], v[214:217], v[206:209], v[4:7]
	v_mfma_f32_16x16x32_bf16 v[0:3], v[222:225], v[206:209], v[0:3]
	s_setprio 0
	s_add_i32 s67, s67, 2
	s_add_u32 s0, s0, 0x100
	s_addc_u32 s1, s1, 0
	s_add_u32 s65, s65, 0x100
	s_addc_u32 s66, s66, 0
	s_cmp_gt_u32 s67, 13
	s_barrier

; #define PG8_STAGE(bufoff, gbase, voff) do { _Pragma("unroll") for (int _i = 0; _i < 2; ++_i) \
;         __builtin_amdgcn_global_load_lds((const unsigned*)((const char*)(gbase) + (voff)[_i]), (LAS unsigned*)(lds + (bufoff) + ldsw + _i * 8192), 16, 0, 0); } while (0)
; #define PG8_WAIT_V(n) asm volatile("s_waitcnt vmcnt(" #n ")" ::: "memory")
; #define PG8_BAR __builtin_amdgcn_s_barrier()
; template <class Epi, class Sched>
; __device__ __forceinline__ void gemm_phase(LAS unsigned char* lds, const Gemm g, const Sched& S, const Epi& E) {
;     ...
;     const char* cA = (const char*)g.A + (size_t)cur.pm * tstep; const char* cB = (const char*)g.Bt + (size_t)cur.pn * tstep;
;     PG8_STAGE(PG8_SB(0, 0), cB, voffB); PG8_STAGE(PG8_SA(0, 0), cA, voffA); PG8_STAGE(PG8_SB(0, 1), cB + hstep, voffB); PG8_STAGE(PG8_SA(0, 1), cA + hstep, voffA);
;     if (wr == 1) PG8_BAR;
;     PG8_WAIT_V(4); PG8_BAR;
;     PG8_STAGE(PG8_SB(1, 0), cB + kstep, voffB); PG8_STAGE(PG8_SA(1, 0), cA + kstep, voffA); PG8_STAGE(PG8_SB(1, 1), cB + hstep + kstep, voffB);
;     PG8_WAIT_V(6); PG8_BAR;
.LBB0_625:
	s_add_u32 s0, s72, 0x2fc00000
	s_addc_u32 s1, s73, 0
	s_lshl_b32 s4, s4, 5
	s_and_b32 s49, s4, 0x60
	s_mov_b64 s[4:5], 0x80
	s_add_i32 m0, s29, 0x18000
	v_lshl_add_u64 v[6:7], v[6:7], 0, s[4:5]
	s_lshl_b32 s48, s3, 6
	s_lshl_b32 s3, s3, 13
	s_lshl_b32 s8, s49, 7
	s_waitcnt vmcnt(4)
	s_barrier
	global_load_lds_dwordx4 v[6:7], off
	v_lshl_add_u64 v[4:5], v[4:5], 0, s[4:5]
	s_add_i32 m0, s29, 0x1a000
	s_add_i32 s51, s29, 0x8000
	s_add_i32 s52, s29, 0xa000
	global_load_lds_dwordx4 v[4:5], off
	v_lshl_add_u64 v[2:3], v[2:3], 0, s[4:5]
	s_mov_b32 m0, s51
	s_add_u32 s6, s34, 0x40080
	global_load_lds_dwordx4 v[2:3], off
	v_lshl_add_u64 v[0:1], v[0:1], 0, s[4:5]
	s_mov_b32 m0, s52
	s_addc_u32 s7, s35, 0
	global_load_lds_dwordx4 v[0:1], off
	s_add_i32 m0, s29, 0x1c000
	v_lshl_add_u64 v[0:1], s[6:7], 0, v[130:131]
	global_load_lds_dwordx4 v[0:1], off
	v_lshl_add_u64 v[0:1], s[6:7], 0, v[134:135]
	s_add_i32 m0, s29, 0x1e000
	v_bfe_u32 v145, v8, 4, 2
	global_load_lds_dwordx4 v[0:1], off
	v_and_b32_e32 v144, 15, v8
	v_lshlrev_b32_e32 v0, 4, v145
	v_lshlrev_b32_e32 v1, 2, v8
	v_lshl_or_b32 v0, v144, 6, v0
	v_and_b32_e32 v1, 32, v1
	v_bitop3_b32 v2, v0, s3, v1 bitop3:0xde
	v_bitop3_b32 v146, v0, s8, v1 bitop3:0xde
	v_lshlrev_b32_e32 v0, 14, v9
	v_and_b32_e32 v0, 0xffff8000, v0
	v_lshl_add_u32 v0, v10, 11, v0
	v_and_b32_e32 v1, 1, v9
	v_lshl_or_b32 v0, v1, 6, v0
	v_lshl_add_u32 v136, v11, 1, v0
	v_lshlrev_b32_e32 v0, 14, v12
	v_and_b32_e32 v0, 0xffff8000, v0
	s_waitcnt vmcnt(0)
	v_lshl_add_u32 v0, v13, 11, v0
	v_and_b32_e32 v1, 1, v12
	v_lshl_or_b32 v0, v1, 6, v0
	s_add_i32 s54, 0, 0x10000
	s_add_i32 s55, 0, 0x14000
	s_sext_i32_i16 s60, s2
	s_ashr_i32 s53, s76, 31
	v_mov_b32_e32 v137, v131
	v_lshl_add_u32 v138, v14, 1, v0
	v_mov_b32_e32 v139, v131
	v_mov_b64_e32 v[140:141], 0x200
	v_mov_b64_e32 v[142:143], 0x1ff
	v_add_u32_e32 v147, s54, v146
	v_add_u32_e32 v148, 0, v2
	v_add_u32_e32 v149, s55, v146
	s_mov_b32 s56, 0x1000000
	s_mov_b64 s[6:7], 0x1200000
	s_mov_b32 s57, 0x1200000
	s_mov_b64 s[8:9], 0x1400000
	s_mov_b32 s58, 0x1400000
	s_mov_b64 s[16:17], 0x1600000
	s_mov_b32 s59, 0x1600000
	s_barrier

; #define PG8_STAGE(bufoff, gbase, voff) do { _Pragma("unroll") for (int _i = 0; _i < 2; ++_i) \
;         __builtin_amdgcn_global_load_lds((const unsigned*)((const char*)(gbase) + (voff)[_i]), (LAS unsigned*)(lds + (bufoff) + ldsw + _i * 8192), 16, 0, 0); } while (0)
; #define PG8_LDA(dst, b, h) do { _Pragma("unroll") for (int m = 0; m < 4; ++m) _Pragma("unroll") for (int k = 0; k < 2; ++k) dst[m][k] = *(const LAS bf16x8*)(lds + PG8_SA(b, h) + aoff + m * 2048 + k * 1024); } while (0)
; #define PG8_LDB(dst, b, h) do { _Pragma("unroll") for (int n = 0; n < 2; ++n) _Pragma("unroll") for (int k = 0; k < 2; ++k) dst[n][k] = *(const LAS bf16x8*)(lds + PG8_SB(b, h) + boff + n * 2048 + k * 1024); } while (0)
; #define PG8_MMA(ai, bj, At, Bt) do { __builtin_amdgcn_s_setprio(1); _Pragma("unroll") for (int m = 0; m < 4; ++m) _Pragma("unroll") for (int n = 0; n < 2; ++n) _Pragma("unroll") for (int k = 0; k < 2; ++k) \
;         acc[ai][bj][m][n] = __builtin_amdgcn_mfma_f32_16x16x32_bf16(Bt[n][k], At[m][k], acc[ai][bj][m][n], 0, 0, 0); __builtin_amdgcn_s_setprio(0); } while (0)
; #define PG8_WAIT_L(n) asm volatile("s_waitcnt lgkmcnt(" #n ")" ::: "memory")
; template <class Epi, class Sched>
; __device__ __forceinline__ void gemm_phase(LAS unsigned char* lds, const Gemm g, const Sched& S, const Epi& E) {
;     ...
;         const bool has_next = S.next(ui + 1, nxt);
;         const char* nA = has_next ? (const char*)g.A + (size_t)nxt.pm * tstep : cA; const char* nB = has_next ? (const char*)g.Bt + (size_t)nxt.pn * tstep : cB;
;         for (int t = 0; t < nt; t += 2) {
;             const bool last = (t == nt - 2);
;             const char* a1 = cA + (size_t)(t + 1) * kstep;
;             const char* a2 = last ? nA : cA + (size_t)(t + 2) * kstep; const char* b2 = last ? nB : cB + (size_t)(t + 2) * kstep;
;             const char* a3 = a2 + kstep; const char* b3 = b2 + kstep;
;             PG8_LDB(B0, 0, 0); PG8_SCHED; PG8_LDA(At, 0, 0); PG8_STAGE(PG8_SA(1, 1), a1 + hstep, voffA);
;             PG8_WAIT_L(8); PG8_BAR; PG8_WAIT_L(0); PG8_MMA(0, 0, At, B0); PG8_BAR; PG8_SCHED;
;             PG8_LDB(B1, 0, 1); PG8_STAGE(PG8_SB(0, 0), b2, voffB);
;             PG8_BAR; PG8_WAIT_L(0); PG8_MMA(0, 1, At, B1); PG8_BAR;
;             PG8_LDA(At, 0, 1); PG8_STAGE(PG8_SA(0, 0), a2, voffA);
;             PG8_BAR; PG8_WAIT_L(0); PG8_MMA(1, 0, At, B0); PG8_BAR; PG8_SCHED;
.LBB0_632:
	s_ashr_i32 s23, s22, 31
	v_cmp_lt_i64_e32 vcc, s[24:25], v[140:141]
	s_lshl_b64 s[24:25], s[22:23], 19
	s_add_u32 s24, s38, s24
	s_addc_u32 s25, s39, s25
	s_and_b64 s[26:27], vcc, exec
	s_cselect_b32 s23, s25, s31
	s_cselect_b32 s61, s24, s30
	s_ashr_i32 s21, s20, 31
	s_lshl_b64 s[26:27], s[20:21], 19
	s_add_u32 s26, s96, s26
	s_addc_u32 s27, s97, s27
	s_and_b64 s[36:37], vcc, exec
	s_cselect_b32 s21, s27, s35
	s_cselect_b32 s62, s26, s34
	s_add_u32 s30, s30, 0x40080
	s_addc_u32 s31, s31, 0
	s_add_u32 s63, s34, 0x100
	s_addc_u32 s64, s35, 0
	s_mov_b32 s65, -2
	s_waitcnt lgkmcnt(0)
	ds_read_b128 v[150:153], v147
	ds_read_b128 v[154:157], v147 offset:1024
	ds_read_b128 v[158:161], v147 offset:2048
	ds_read_b128 v[162:165], v147 offset:3072
	s_add_u32 s34, s30, 0xfffc0080
	s_addc_u32 s35, s31, -1
	s_cmp_eq_u32 s65, 12
	s_cselect_b32 s37, s23, s35
	s_cselect_b32 s36, s61, s34
	s_cselect_b32 s35, s21, s64
	s_cselect_b32 s34, s62, s63
	s_add_i32 m0, s29, 0xc000
	ds_read_b128 v[166:169], v148
	ds_read_b128 v[170:173], v148 offset:1024
	ds_read_b128 v[174:177], v148 offset:2048
	ds_read_b128 v[178:181], v148 offset:3072
	ds_read_b128 v[182:185], v148 offset:4096
	ds_read_b128 v[186:189], v148 offset:5120
	ds_read_b128 v[190:193], v148 offset:6144
	ds_read_b128 v[194:197], v148 offset:7168
	global_load_lds_dwordx4 v136, s[30:31]
	s_add_i32 m0, s29, 0xe000
	s_nop 0
	global_load_lds_dwordx4 v138, s[30:31]
	s_waitcnt lgkmcnt(8)
	s_waitcnt vmcnt(26)
	s_barrier
	s_waitcnt lgkmcnt(0)
	s_setprio 1
	s_waitcnt lgkmcnt(0)
	v_mfma_f32_16x16x32_bf16 v[124:127], v[150:153], v[166:169], 0
	v_mfma_f32_16x16x32_bf16 v[120:123], v[158:161], v[166:169], 0
	v_mfma_f32_16x16x32_bf16 v[116:119], v[150:153], v[174:177], 0
	v_mfma_f32_16x16x32_bf16 v[108:111], v[158:161], v[174:177], 0
	v_mfma_f32_16x16x32_bf16 v[100:103], v[150:153], v[182:185], 0
	v_mfma_f32_16x16x32_bf16 v[92:95], v[158:161], v[182:185], 0
	v_mfma_f32_16x16x32_bf16 v[84:87], v[150:153], v[190:193], 0
	v_mfma_f32_16x16x32_bf16 v[76:79], v[158:161], v[190:193], 0
	v_mfma_f32_16x16x32_bf16 v[124:127], v[154:157], v[170:173], v[124:127]
	v_mfma_f32_16x16x32_bf16 v[120:123], v[162:165], v[170:173], v[120:123]
	v_mfma_f32_16x16x32_bf16 v[116:119], v[154:157], v[178:181], v[116:119]
	v_mfma_f32_16x16x32_bf16 v[108:111], v[162:165], v[178:181], v[108:111]
	v_mfma_f32_16x16x32_bf16 v[100:103], v[154:157], v[186:189], v[100:103]
	v_mfma_f32_16x16x32_bf16 v[92:95], v[162:165], v[186:189], v[92:95]
	v_mfma_f32_16x16x32_bf16 v[84:87], v[154:157], v[194:197], v[84:87]
	v_mfma_f32_16x16x32_bf16 v[76:79], v[162:165], v[194:197], v[76:79]
	s_setprio 0
	s_barrier
	s_add_i32 s66, s54, s43
	s_mov_b32 m0, s66
	ds_read_b128 v[202:205], v149
	ds_read_b128 v[206:209], v149 offset:1024
	ds_read_b128 v[210:213], v149 offset:2048
	ds_read_b128 v[214:217], v149 offset:3072
	global_load_lds_dwordx4 v130, s[34:35]
	s_add_i32 m0, s66, 0x2000
	s_nop 0
	global_load_lds_dwordx4 v134, s[34:35]
	s_waitcnt vmcnt(26)
	s_barrier
	s_waitcnt lgkmcnt(0)
	s_setprio 1
	s_waitcnt lgkmcnt(0)
	v_mfma_f32_16x16x32_bf16 v[112:115], v[202:205], v[166:169], 0
	v_mfma_f32_16x16x32_bf16 v[104:107], v[210:213], v[166:169], 0
	v_mfma_f32_16x16x32_bf16 v[96:99], v[202:205], v[174:177], 0
	v_mfma_f32_16x16x32_bf16 v[88:91], v[210:213], v[174:177], 0
	v_mfma_f32_16x16x32_bf16 v[80:83], v[202:205], v[182:185], 0
	v_mfma_f32_16x16x32_bf16 v[72:75], v[210:213], v[182:185], 0
	v_mfma_f32_16x16x32_bf16 v[68:71], v[202:205], v[190:193], 0
	v_mfma_f32_16x16x32_bf16 v[64:67], v[210:213], v[190:193], 0
	v_mfma_f32_16x16x32_bf16 v[112:115], v[206:209], v[170:173], v[112:115]
	v_mfma_f32_16x16x32_bf16 v[104:107], v[214:217], v[170:173], v[104:107]
	v_mfma_f32_16x16x32_bf16 v[96:99], v[206:209], v[178:181], v[96:99]
	v_mfma_f32_16x16x32_bf16 v[88:91], v[214:217], v[178:181], v[88:91]
	v_mfma_f32_16x16x32_bf16 v[80:83], v[206:209], v[186:189], v[80:83]
	v_mfma_f32_16x16x32_bf16 v[72:75], v[214:217], v[186:189], v[72:75]
	v_mfma_f32_16x16x32_bf16 v[68:71], v[206:209], v[194:197], v[68:71]
	v_mfma_f32_16x16x32_bf16 v[64:67], v[214:217], v[194:197], v[64:67]
	s_setprio 0
	s_mov_b32 m0, s29
	v_lshl_add_u64 v[220:221], s[36:37], 0, v[128:129]
	s_barrier
	ds_read_b128 v[166:169], v148 offset:16384
	ds_read_b128 v[170:173], v148 offset:17408
	ds_read_b128 v[174:177], v148 offset:18432
	ds_read_b128 v[178:181], v148 offset:19456
	ds_read_b128 v[182:185], v148 offset:20480
	ds_read_b128 v[186:189], v148 offset:21504
	ds_read_b128 v[190:193], v148 offset:22528
	ds_read_b128 v[194:197], v148 offset:23552
	global_load_lds_dwordx4 v128, s[36:37]
	v_lshl_add_u64 v[222:223], s[36:37], 0, v[132:133]
	s_mov_b32 m0, s44
	s_nop 0
	global_load_lds_dwordx4 v132, s[36:37]
	s_barrier
	s_waitcnt lgkmcnt(0)
	s_setprio 1
	s_waitcnt lgkmcnt(0)
	v_mfma_f32_16x16x32_bf16 v[60:63], v[150:153], v[166:169], 0
	v_mfma_f32_16x16x32_bf16 v[56:59], v[158:161], v[166:169], 0
	v_mfma_f32_16x16x32_bf16 v[52:55], v[150:153], v[174:177], 0
	v_mfma_f32_16x16x32_bf16 v[44:47], v[158:161], v[174:177], 0
	v_mfma_f32_16x16x32_bf16 v[36:39], v[150:153], v[182:185], 0
	v_mfma_f32_16x16x32_bf16 v[28:31], v[158:161], v[182:185], 0
	v_mfma_f32_16x16x32_bf16 v[20:23], v[150:153], v[190:193], 0
	v_mfma_f32_16x16x32_bf16 v[12:15], v[158:161], v[190:193], 0
	v_mfma_f32_16x16x32_bf16 v[60:63], v[154:157], v[170:173], v[60:63]
	v_mfma_f32_16x16x32_bf16 v[56:59], v[162:165], v[170:173], v[56:59]
	v_mfma_f32_16x16x32_bf16 v[52:55], v[154:157], v[178:181], v[52:55]
	v_mfma_f32_16x16x32_bf16 v[44:47], v[162:165], v[178:181], v[44:47]
	v_mfma_f32_16x16x32_bf16 v[36:39], v[154:157], v[186:189], v[36:39]
	v_mfma_f32_16x16x32_bf16 v[28:31], v[162:165], v[186:189], v[28:31]
	v_mfma_f32_16x16x32_bf16 v[20:23], v[154:157], v[194:197], v[20:23]
	v_mfma_f32_16x16x32_bf16 v[12:15], v[162:165], v[194:197], v[12:15]
	s_setprio 0
	s_barrier
; #define PG8_STAGE(bufoff, gbase, voff) do { _Pragma("unroll") for (int _i = 0; _i < 2; ++_i) \
;         __builtin_amdgcn_global_load_lds((const unsigned*)((const char*)(gbase) + (voff)[_i]), (LAS unsigned*)(lds + (bufoff) + ldsw + _i * 8192), 16, 0, 0); } while (0)
; #define PG8_LDA(dst, b, h) do { _Pragma("unroll") for (int m = 0; m < 4; ++m) _Pragma("unroll") for (int k = 0; k < 2; ++k) dst[m][k] = *(const LAS bf16x8*)(lds + PG8_SA(b, h) + aoff + m * 2048 + k * 1024); } while (0)
; #define PG8_LDB(dst, b, h) do { _Pragma("unroll") for (int n = 0; n < 2; ++n) _Pragma("unroll") for (int k = 0; k < 2; ++k) dst[n][k] = *(const LAS bf16x8*)(lds + PG8_SB(b, h) + boff + n * 2048 + k * 1024); } while (0)
; #define PG8_MMA(ai, bj, At, Bt) do { __builtin_amdgcn_s_setprio(1); _Pragma("unroll") for (int m = 0; m < 4; ++m) _Pragma("unroll") for (int n = 0; n < 2; ++n) _Pragma("unroll") for (int k = 0; k < 2; ++k) \
;         acc[ai][bj][m][n] = __builtin_amdgcn_mfma_f32_16x16x32_bf16(Bt[n][k], At[m][k], acc[ai][bj][m][n], 0, 0, 0); __builtin_amdgcn_s_setprio(0); } while (0)
; #define PG8_WAIT_V(n) asm volatile("s_waitcnt vmcnt(" #n ")" ::: "memory")
; #define PG8_WAIT_L(n) asm volatile("s_waitcnt lgkmcnt(" #n ")" ::: "memory")
; #define PG8_BAR __builtin_amdgcn_s_barrier()
; #define PG8_SCHED __builtin_amdgcn_sched_barrier(0)
; template <class Epi, class Sched>
; __device__ __forceinline__ void gemm_phase(LAS unsigned char* lds, const Gemm g, const Sched& S, const Epi& E) {
;     ...
;             PG8_BAR; PG8_WAIT_L(0); PG8_MMA(1, 0, At, B0); PG8_BAR; PG8_SCHED;
;             PG8_STAGE(PG8_SB(0, 1), b2 + hstep, voffB);
;             PG8_WAIT_V(6); PG8_BAR; PG8_MMA(1, 1, At, B1); PG8_BAR;
;             PG8_LDB(B0, 1, 0); PG8_SCHED; PG8_LDA(At, 1, 0); PG8_STAGE(PG8_SA(0, 1), a2 + hstep, voffA);
;             PG8_WAIT_L(8); PG8_BAR; PG8_WAIT_L(0); PG8_MMA(0, 0, At, B0); PG8_BAR; PG8_SCHED;
;             PG8_LDB(B1, 1, 1); PG8_STAGE(PG8_SB(1, 0), b3, voffB);
;             PG8_BAR; PG8_WAIT_L(0); PG8_MMA(0, 1, At, B1); PG8_BAR;
;             PG8_LDA(At, 1, 1); PG8_STAGE(PG8_SA(1, 0), a3, voffA);
;             PG8_BAR; PG8_WAIT_L(0); PG8_MMA(1, 0, At, B0); PG8_BAR; PG8_SCHED;
	s_add_u32 s66, s34, 0x40000
	s_addc_u32 s67, s35, 0
	s_add_i32 s68, s55, s43
	s_mov_b32 m0, s68
	s_nop 0
	global_load_lds_dwordx4 v130, s[66:67]
	s_add_i32 m0, s68, 0x2000
	s_nop 0
	global_load_lds_dwordx4 v134, s[66:67]
	s_waitcnt vmcnt(26)
	s_barrier
	s_setprio 1
	v_mfma_f32_16x16x32_bf16 v[48:51], v[202:205], v[166:169], 0
	v_mfma_f32_16x16x32_bf16 v[40:43], v[210:213], v[166:169], 0
	v_mfma_f32_16x16x32_bf16 v[32:35], v[202:205], v[174:177], 0
	v_mfma_f32_16x16x32_bf16 v[24:27], v[210:213], v[174:177], 0
	v_mfma_f32_16x16x32_bf16 v[16:19], v[202:205], v[182:185], 0
	v_mfma_f32_16x16x32_bf16 v[8:11], v[210:213], v[182:185], 0
	v_mfma_f32_16x16x32_bf16 v[4:7], v[202:205], v[190:193], 0
	v_mfma_f32_16x16x32_bf16 v[0:3], v[210:213], v[190:193], 0
	v_mfma_f32_16x16x32_bf16 v[48:51], v[206:209], v[170:173], v[48:51]
	v_mfma_f32_16x16x32_bf16 v[40:43], v[214:217], v[170:173], v[40:43]
	v_mfma_f32_16x16x32_bf16 v[32:35], v[206:209], v[178:181], v[32:35]
	v_mfma_f32_16x16x32_bf16 v[24:27], v[214:217], v[178:181], v[24:27]
	v_mfma_f32_16x16x32_bf16 v[16:19], v[206:209], v[186:189], v[16:19]
	v_mfma_f32_16x16x32_bf16 v[8:11], v[214:217], v[186:189], v[8:11]
	v_mfma_f32_16x16x32_bf16 v[4:7], v[206:209], v[194:197], v[4:7]
	v_mfma_f32_16x16x32_bf16 v[0:3], v[214:217], v[194:197], v[0:3]
	s_setprio 0
	s_add_i32 s66, 0, 0x18000
	v_add_u32_e32 v162, s66, v146
	s_barrier
	ds_read_b128 v[150:153], v162
	ds_read_b128 v[154:157], v162 offset:1024
	ds_read_b128 v[158:161], v162 offset:2048
	ds_read_b128 v[162:165], v162 offset:3072
	s_add_u32 s36, s36, 0x40000
	s_addc_u32 s37, s37, 0
	s_mov_b32 m0, s45
	ds_read_b128 v[166:169], v148 offset:32768
	ds_read_b128 v[170:173], v148 offset:33792
	ds_read_b128 v[174:177], v148 offset:34816
	ds_read_b128 v[178:181], v148 offset:35840
	ds_read_b128 v[182:185], v148 offset:36864
	ds_read_b128 v[186:189], v148 offset:37888
	ds_read_b128 v[190:193], v148 offset:38912
	ds_read_b128 v[194:197], v148 offset:39936
	global_load_lds_dwordx4 v128, s[36:37]
	s_mov_b32 m0, s46
	s_nop 0
	global_load_lds_dwordx4 v132, s[36:37]
	s_waitcnt lgkmcnt(8)
	s_waitcnt vmcnt(26)
	s_barrier
	s_waitcnt lgkmcnt(0)
	s_setprio 1
	s_waitcnt lgkmcnt(0)
	v_mfma_f32_16x16x32_bf16 v[124:127], v[150:153], v[166:169], v[124:127]
	v_mfma_f32_16x16x32_bf16 v[120:123], v[158:161], v[166:169], v[120:123]
	v_mfma_f32_16x16x32_bf16 v[116:119], v[150:153], v[174:177], v[116:119]
	v_mfma_f32_16x16x32_bf16 v[108:111], v[158:161], v[174:177], v[108:111]
	v_mfma_f32_16x16x32_bf16 v[100:103], v[150:153], v[182:185], v[100:103]
	v_mfma_f32_16x16x32_bf16 v[92:95], v[158:161], v[182:185], v[92:95]
	v_mfma_f32_16x16x32_bf16 v[84:87], v[150:153], v[190:193], v[84:87]
	v_mfma_f32_16x16x32_bf16 v[76:79], v[158:161], v[190:193], v[76:79]
	v_mfma_f32_16x16x32_bf16 v[124:127], v[154:157], v[170:173], v[124:127]
	v_mfma_f32_16x16x32_bf16 v[120:123], v[162:165], v[170:173], v[120:123]
	v_mfma_f32_16x16x32_bf16 v[116:119], v[154:157], v[178:181], v[116:119]
	v_mfma_f32_16x16x32_bf16 v[108:111], v[162:165], v[178:181], v[108:111]
	v_mfma_f32_16x16x32_bf16 v[100:103], v[154:157], v[186:189], v[100:103]
	v_mfma_f32_16x16x32_bf16 v[92:95], v[162:165], v[186:189], v[92:95]
	v_mfma_f32_16x16x32_bf16 v[84:87], v[154:157], v[194:197], v[84:87]
	v_mfma_f32_16x16x32_bf16 v[76:79], v[162:165], v[194:197], v[76:79]
	s_setprio 0
	s_barrier
	s_add_i32 s36, 0, 0x1c000
	s_add_i32 s37, s66, s43
	v_add_u32_e32 v214, s36, v146
	s_add_u32 s4, s34, 0x80
	s_addc_u32 s5, s35, 0
	s_mov_b32 m0, s37
	ds_read_b128 v[202:205], v214
	ds_read_b128 v[206:209], v214 offset:1024
	ds_read_b128 v[210:213], v214 offset:2048
	ds_read_b128 v[214:217], v214 offset:3072
	global_load_lds_dwordx4 v130, s[4:5]
	s_add_i32 m0, s37, 0x2000
	s_nop 0
	global_load_lds_dwordx4 v134, s[4:5]
	s_waitcnt vmcnt(10)
	s_barrier
; #define PG8_STAGE(bufoff, gbase, voff) do { _Pragma("unroll") for (int _i = 0; _i < 2; ++_i) \
;         __builtin_amdgcn_global_load_lds((const unsigned*)((const char*)(gbase) + (voff)[_i]), (LAS unsigned*)(lds + (bufoff) + ldsw + _i * 8192), 16, 0, 0); } while (0)
; #define PG8_MMA(ai, bj, At, Bt) do { __builtin_amdgcn_s_setprio(1); _Pragma("unroll") for (int m = 0; m < 4; ++m) _Pragma("unroll") for (int n = 0; n < 2; ++n) _Pragma("unroll") for (int k = 0; k < 2; ++k) \
;         acc[ai][bj][m][n] = __builtin_amdgcn_mfma_f32_16x16x32_bf16(Bt[n][k], At[m][k], acc[ai][bj][m][n], 0, 0, 0); __builtin_amdgcn_s_setprio(0); } while (0)
; #define PG8_WAIT_V(n) asm volatile("s_waitcnt vmcnt(" #n ")" ::: "memory")
; #define PG8_WAIT_L(n) asm volatile("s_waitcnt lgkmcnt(" #n ")" ::: "memory")
; #define PG8_BAR __builtin_amdgcn_s_barrier()
; #define PG8_SCHED __builtin_amdgcn_sched_barrier(0)
; template <class Epi, class Sched>
; __device__ __forceinline__ void gemm_phase(LAS unsigned char* lds, const Gemm g, const Sched& S, const Epi& E) {
;     ...
;             PG8_BAR; PG8_WAIT_L(0); PG8_MMA(1, 0, At, B0); PG8_BAR; PG8_SCHED;
;             PG8_STAGE(PG8_SB(1, 1), b3 + hstep, voffB);
;             PG8_WAIT_V(6); PG8_BAR; PG8_MMA(1, 1, At, B1); PG8_BAR;
;         }
	s_waitcnt lgkmcnt(0)
	s_setprio 1
	s_waitcnt lgkmcnt(0)
	v_mfma_f32_16x16x32_bf16 v[112:115], v[202:205], v[166:169], v[112:115]
	v_mfma_f32_16x16x32_bf16 v[104:107], v[210:213], v[166:169], v[104:107]
	v_mfma_f32_16x16x32_bf16 v[96:99], v[202:205], v[174:177], v[96:99]
	v_mfma_f32_16x16x32_bf16 v[88:91], v[210:213], v[174:177], v[88:91]
	v_mfma_f32_16x16x32_bf16 v[80:83], v[202:205], v[182:185], v[80:83]
	v_mfma_f32_16x16x32_bf16 v[72:75], v[210:213], v[182:185], v[72:75]
	v_mfma_f32_16x16x32_bf16 v[68:71], v[202:205], v[190:193], v[68:71]
	v_mfma_f32_16x16x32_bf16 v[64:67], v[210:213], v[190:193], v[64:67]
	v_mfma_f32_16x16x32_bf16 v[112:115], v[206:209], v[170:173], v[112:115]
	v_mfma_f32_16x16x32_bf16 v[104:107], v[214:217], v[170:173], v[104:107]
	v_mfma_f32_16x16x32_bf16 v[96:99], v[206:209], v[178:181], v[96:99]
	v_mfma_f32_16x16x32_bf16 v[88:91], v[214:217], v[178:181], v[88:91]
	v_mfma_f32_16x16x32_bf16 v[80:83], v[206:209], v[186:189], v[80:83]
	v_mfma_f32_16x16x32_bf16 v[72:75], v[214:217], v[186:189], v[72:75]
	v_mfma_f32_16x16x32_bf16 v[68:71], v[206:209], v[194:197], v[68:71]
	v_mfma_f32_16x16x32_bf16 v[64:67], v[214:217], v[194:197], v[64:67]
	s_setprio 0
	s_mov_b32 m0, s51
	s_mov_b64 s[4:5], 0x80
	v_lshl_add_u64 v[198:199], v[220:221], 0, s[4:5]
	s_barrier
	ds_read_b128 v[166:169], v148 offset:49152
	ds_read_b128 v[170:173], v148 offset:50176
	ds_read_b128 v[174:177], v148 offset:51200
	ds_read_b128 v[178:181], v148 offset:52224
	ds_read_b128 v[182:185], v148 offset:53248
	ds_read_b128 v[186:189], v148 offset:54272
	ds_read_b128 v[190:193], v148 offset:55296
	ds_read_b128 v[194:197], v148 offset:56320
	global_load_lds_dwordx4 v[198:199], off
	v_lshl_add_u64 v[198:199], v[222:223], 0, s[4:5]
	s_mov_b32 m0, s52
	s_nop 0
	global_load_lds_dwordx4 v[198:199], off
	s_barrier
	s_waitcnt lgkmcnt(0)
	s_setprio 1
	s_waitcnt lgkmcnt(0)
	v_mfma_f32_16x16x32_bf16 v[60:63], v[150:153], v[166:169], v[60:63]
	v_mfma_f32_16x16x32_bf16 v[56:59], v[158:161], v[166:169], v[56:59]
	v_mfma_f32_16x16x32_bf16 v[52:55], v[150:153], v[174:177], v[52:55]
	v_mfma_f32_16x16x32_bf16 v[44:47], v[158:161], v[174:177], v[44:47]
	v_mfma_f32_16x16x32_bf16 v[36:39], v[150:153], v[182:185], v[36:39]
	v_mfma_f32_16x16x32_bf16 v[28:31], v[158:161], v[182:185], v[28:31]
	v_mfma_f32_16x16x32_bf16 v[20:23], v[150:153], v[190:193], v[20:23]
	v_mfma_f32_16x16x32_bf16 v[12:15], v[158:161], v[190:193], v[12:15]
	v_mfma_f32_16x16x32_bf16 v[60:63], v[154:157], v[170:173], v[60:63]
	v_mfma_f32_16x16x32_bf16 v[56:59], v[162:165], v[170:173], v[56:59]
	v_mfma_f32_16x16x32_bf16 v[52:55], v[154:157], v[178:181], v[52:55]
	v_mfma_f32_16x16x32_bf16 v[44:47], v[162:165], v[178:181], v[44:47]
	v_mfma_f32_16x16x32_bf16 v[36:39], v[154:157], v[186:189], v[36:39]
	v_mfma_f32_16x16x32_bf16 v[28:31], v[162:165], v[186:189], v[28:31]
	v_mfma_f32_16x16x32_bf16 v[20:23], v[154:157], v[194:197], v[20:23]
	v_mfma_f32_16x16x32_bf16 v[12:15], v[162:165], v[194:197], v[12:15]
	s_setprio 0
	s_barrier
	s_add_u32 s34, s34, 0x40080
	s_addc_u32 s35, s35, 0
	s_add_i32 s36, s36, s43
	s_mov_b32 m0, s36
	s_nop 0
	global_load_lds_dwordx4 v130, s[34:35]
	s_add_i32 m0, s36, 0x2000
	s_nop 0
	global_load_lds_dwordx4 v134, s[34:35]
	s_waitcnt vmcnt(10)
	s_barrier
	s_setprio 1
	v_mfma_f32_16x16x32_bf16 v[48:51], v[202:205], v[166:169], v[48:51]
	v_mfma_f32_16x16x32_bf16 v[40:43], v[210:213], v[166:169], v[40:43]
	v_mfma_f32_16x16x32_bf16 v[32:35], v[202:205], v[174:177], v[32:35]
	v_mfma_f32_16x16x32_bf16 v[24:27], v[210:213], v[174:177], v[24:27]
	v_mfma_f32_16x16x32_bf16 v[16:19], v[202:205], v[182:185], v[16:19]
	v_mfma_f32_16x16x32_bf16 v[8:11], v[210:213], v[182:185], v[8:11]
	v_mfma_f32_16x16x32_bf16 v[4:7], v[202:205], v[190:193], v[4:7]
	v_mfma_f32_16x16x32_bf16 v[0:3], v[210:213], v[190:193], v[0:3]
	v_mfma_f32_16x16x32_bf16 v[48:51], v[206:209], v[170:173], v[48:51]
	v_mfma_f32_16x16x32_bf16 v[40:43], v[214:217], v[170:173], v[40:43]
	v_mfma_f32_16x16x32_bf16 v[32:35], v[206:209], v[178:181], v[32:35]
	v_mfma_f32_16x16x32_bf16 v[24:27], v[214:217], v[178:181], v[24:27]
	v_mfma_f32_16x16x32_bf16 v[16:19], v[206:209], v[186:189], v[16:19]
	v_mfma_f32_16x16x32_bf16 v[8:11], v[214:217], v[186:189], v[8:11]
	v_mfma_f32_16x16x32_bf16 v[4:7], v[206:209], v[194:197], v[4:7]
	v_mfma_f32_16x16x32_bf16 v[0:3], v[214:217], v[194:197], v[0:3]
	s_setprio 0
	s_add_i32 s65, s65, 2
	s_add_u32 s30, s30, 0x100
	s_addc_u32 s31, s31, 0
	s_add_u32 s63, s63, 0x100
	s_addc_u32 s64, s64, 0
	s_cmp_gt_u32 s65, 13
	s_barrier

; #define PG8_STAGE(bufoff, gbase, voff) do { _Pragma("unroll") for (int _i = 0; _i < 2; ++_i) \
;         __builtin_amdgcn_global_load_lds((const unsigned*)((const char*)(gbase) + (voff)[_i]), (LAS unsigned*)(lds + (bufoff) + ldsw + _i * 8192), 16, 0, 0); } while (0)
; #define PG8_WAIT_V(n) asm volatile("s_waitcnt vmcnt(" #n ")" ::: "memory")
; #define PG8_BAR __builtin_amdgcn_s_barrier()
; template <class Epi, class Sched>
; __device__ __forceinline__ void gemm_phase(LAS unsigned char* lds, const Gemm g, const Sched& S, const Epi& E) {
;     ...
;     const char* cA = (const char*)g.A + (size_t)cur.pm * tstep; const char* cB = (const char*)g.Bt + (size_t)cur.pn * tstep;
;     PG8_STAGE(PG8_SB(0, 0), cB, voffB); PG8_STAGE(PG8_SA(0, 0), cA, voffA); PG8_STAGE(PG8_SB(0, 1), cB + hstep, voffB); PG8_STAGE(PG8_SA(0, 1), cA + hstep, voffA);
;     if (wr == 1) PG8_BAR;
;     PG8_WAIT_V(4); PG8_BAR;
;     PG8_STAGE(PG8_SB(1, 0), cB + kstep, voffB); PG8_STAGE(PG8_SA(1, 0), cA + kstep, voffA); PG8_STAGE(PG8_SB(1, 1), cB + hstep + kstep, voffB);
;     PG8_WAIT_V(6); PG8_BAR;
.LBB0_645:
	s_lshl_b32 s36, s0, 6
	s_lshl_b32 s5, s0, 13
	s_lshl_b32 s0, s1, 5
	s_and_b32 s37, s0, 0x60
	s_mov_b64 s[0:1], 0x80
	s_add_i32 m0, s21, 0x18000
	v_lshl_add_u64 v[6:7], v[6:7], 0, s[0:1]
	s_lshl_b32 s8, s37, 7
	s_waitcnt vmcnt(4)
	s_barrier
	global_load_lds_dwordx4 v[6:7], off
	v_lshl_add_u64 v[4:5], v[4:5], 0, s[0:1]
	s_add_i32 m0, s21, 0x1a000
	s_add_i32 s42, s21, 0x8000
	s_add_i32 s43, s21, 0xa000
	global_load_lds_dwordx4 v[4:5], off
	v_lshl_add_u64 v[2:3], v[2:3], 0, s[0:1]
	s_mov_b32 m0, s42
	s_add_u32 s6, s24, 0x40080
	global_load_lds_dwordx4 v[2:3], off
	v_lshl_add_u64 v[0:1], v[0:1], 0, s[0:1]
	s_mov_b32 m0, s43
	s_addc_u32 s7, s25, 0
	global_load_lds_dwordx4 v[0:1], off
	s_add_i32 m0, s21, 0x1c000
	v_lshl_add_u64 v[0:1], s[6:7], 0, v[130:131]
	global_load_lds_dwordx4 v[0:1], off
	v_lshl_add_u64 v[0:1], s[6:7], 0, v[134:135]
	s_add_i32 m0, s21, 0x1e000
	v_bfe_u32 v147, v8, 4, 2
	global_load_lds_dwordx4 v[0:1], off
	v_and_b32_e32 v146, 15, v8
	v_lshlrev_b32_e32 v0, 4, v147
	v_lshlrev_b32_e32 v1, 2, v8
	v_lshl_or_b32 v0, v146, 6, v0
	v_and_b32_e32 v1, 32, v1
	v_bitop3_b32 v2, v0, s5, v1 bitop3:0xde
	v_bitop3_b32 v148, v0, s8, v1 bitop3:0xde
	v_lshlrev_b32_e32 v0, 14, v9
	v_and_b32_e32 v0, 0xffff8000, v0
	v_lshl_add_u32 v0, v10, 11, v0
	v_and_b32_e32 v1, 1, v9
	v_lshl_or_b32 v0, v1, 6, v0
	v_lshl_add_u32 v138, v11, 1, v0
	v_lshlrev_b32_e32 v0, 14, v12
	v_and_b32_e32 v0, 0xffff8000, v0
	s_waitcnt vmcnt(0)
	v_lshl_add_u32 v0, v13, 11, v0
	v_and_b32_e32 v1, 1, v12
	v_lshl_or_b32 v0, v1, 6, v0
	s_add_i32 s45, 0, 0x10000
	s_add_i32 s46, 0, 0x14000
	s_sext_i32_i16 s47, s4
	s_ashr_i32 s44, s76, 31
	v_mov_b32_e32 v139, v137
	v_lshl_add_u32 v140, v14, 1, v0
	v_mov_b32_e32 v141, v137
	v_mov_b64_e32 v[142:143], 0x100
	v_mov_b64_e32 v[144:145], 0xff
	v_add_u32_e32 v149, s45, v148
	v_add_u32_e32 v150, 0, v2
	v_add_u32_e32 v151, s46, v148
	s_barrier

; #define PG8_STAGE(bufoff, gbase, voff) do { _Pragma("unroll") for (int _i = 0; _i < 2; ++_i) \
;         __builtin_amdgcn_global_load_lds((const unsigned*)((const char*)(gbase) + (voff)[_i]), (LAS unsigned*)(lds + (bufoff) + ldsw + _i * 8192), 16, 0, 0); } while (0)
; #define PG8_LDA(dst, b, h) do { _Pragma("unroll") for (int m = 0; m < 4; ++m) _Pragma("unroll") for (int k = 0; k < 2; ++k) dst[m][k] = *(const LAS bf16x8*)(lds + PG8_SA(b, h) + aoff + m * 2048 + k * 1024); } while (0)
; #define PG8_LDB(dst, b, h) do { _Pragma("unroll") for (int n = 0; n < 2; ++n) _Pragma("unroll") for (int k = 0; k < 2; ++k) dst[n][k] = *(const LAS bf16x8*)(lds + PG8_SB(b, h) + boff + n * 2048 + k * 1024); } while (0)
; #define PG8_MMA(ai, bj, At, Bt) do { __builtin_amdgcn_s_setprio(1); _Pragma("unroll") for (int m = 0; m < 4; ++m) _Pragma("unroll") for (int n = 0; n < 2; ++n) _Pragma("unroll") for (int k = 0; k < 2; ++k) \
;         acc[ai][bj][m][n] = __builtin_amdgcn_mfma_f32_16x16x32_bf16(Bt[n][k], At[m][k], acc[ai][bj][m][n], 0, 0, 0); __builtin_amdgcn_s_setprio(0); } while (0)
; #define PG8_WAIT_L(n) asm volatile("s_waitcnt lgkmcnt(" #n ")" ::: "memory")
; template <class Epi, class Sched>
; __device__ __forceinline__ void gemm_phase(LAS unsigned char* lds, const Gemm g, const Sched& S, const Epi& E) {
;     ...
;         const bool has_next = S.next(ui + 1, nxt);
;         const char* nA = has_next ? (const char*)g.A + (size_t)nxt.pm * tstep : cA; const char* nB = has_next ? (const char*)g.Bt + (size_t)nxt.pn * tstep : cB;
;         for (int t = 0; t < nt; t += 2) {
;             const bool last = (t == nt - 2);
;             const char* a1 = cA + (size_t)(t + 1) * kstep;
;             const char* a2 = last ? nA : cA + (size_t)(t + 2) * kstep; const char* b2 = last ? nB : cB + (size_t)(t + 2) * kstep;
;             const char* a3 = a2 + kstep; const char* b3 = b2 + kstep;
;             PG8_LDB(B0, 0, 0); PG8_SCHED; PG8_LDA(At, 0, 0); PG8_STAGE(PG8_SA(1, 1), a1 + hstep, voffA);
;             PG8_WAIT_L(8); PG8_BAR; PG8_WAIT_L(0); PG8_MMA(0, 0, At, B0); PG8_BAR; PG8_SCHED;
;             PG8_LDB(B1, 0, 1); PG8_STAGE(PG8_SB(0, 0), b2, voffB);
;             PG8_BAR; PG8_WAIT_L(0); PG8_MMA(0, 1, At, B1); PG8_BAR;
;             PG8_LDA(At, 0, 1); PG8_STAGE(PG8_SA(0, 0), a2, voffA);
;             PG8_BAR; PG8_WAIT_L(0); PG8_MMA(1, 0, At, B0); PG8_BAR; PG8_SCHED;
.LBB0_652:
	s_ashr_i32 s9, s8, 31
	v_cmp_lt_i64_e32 vcc, s[16:17], v[142:143]
	s_lshl_b64 s[16:17], s[8:9], 19
	s_add_u32 s16, s14, s16
	s_addc_u32 s17, s15, s17
	s_and_b64 s[18:19], vcc, exec
	s_cselect_b32 s9, s17, s23
	s_cselect_b32 s48, s16, s22
	s_ashr_i32 s7, s6, 31
	s_lshl_b64 s[18:19], s[6:7], 19
	s_add_u32 s18, s12, s18
	s_addc_u32 s19, s13, s19
	s_and_b64 s[26:27], vcc, exec
	s_cselect_b32 s7, s19, s25
	s_cselect_b32 s49, s18, s24
	s_add_u32 s22, s22, 0x40080
	s_addc_u32 s23, s23, 0
	s_add_u32 s51, s24, 0x100
	s_addc_u32 s52, s25, 0
	s_mov_b32 s53, -2
	s_waitcnt lgkmcnt(0)
	ds_read_b128 v[152:155], v149
	ds_read_b128 v[156:159], v149 offset:1024
	ds_read_b128 v[160:163], v149 offset:2048
	ds_read_b128 v[164:167], v149 offset:3072
	s_add_u32 s24, s22, 0xfffc0080
	s_addc_u32 s25, s23, -1
	s_cmp_eq_u32 s53, 12
	s_cselect_b32 s27, s9, s25
	s_cselect_b32 s26, s48, s24
	s_cselect_b32 s25, s7, s52
	s_cselect_b32 s24, s49, s51
	s_add_i32 m0, s21, 0xc000
	ds_read_b128 v[168:171], v150
	ds_read_b128 v[172:175], v150 offset:1024
	ds_read_b128 v[176:179], v150 offset:2048
	ds_read_b128 v[180:183], v150 offset:3072
	ds_read_b128 v[184:187], v150 offset:4096
	ds_read_b128 v[188:191], v150 offset:5120
	ds_read_b128 v[192:195], v150 offset:6144
	ds_read_b128 v[196:199], v150 offset:7168
	global_load_lds_dwordx4 v138, s[22:23]
	s_add_i32 m0, s21, 0xe000
	s_nop 0
	global_load_lds_dwordx4 v140, s[22:23]
	s_waitcnt lgkmcnt(8)
	s_waitcnt vmcnt(26)
	s_barrier
	s_waitcnt lgkmcnt(0)
	s_setprio 1
	s_waitcnt lgkmcnt(0)
	v_mfma_f32_16x16x32_bf16 v[124:127], v[152:155], v[168:171], 0
	v_mfma_f32_16x16x32_bf16 v[120:123], v[160:163], v[168:171], 0
	v_mfma_f32_16x16x32_bf16 v[112:115], v[152:155], v[176:179], 0
	v_mfma_f32_16x16x32_bf16 v[104:107], v[160:163], v[176:179], 0
	v_mfma_f32_16x16x32_bf16 v[96:99], v[152:155], v[184:187], 0
	v_mfma_f32_16x16x32_bf16 v[88:91], v[160:163], v[184:187], 0
	v_mfma_f32_16x16x32_bf16 v[80:83], v[152:155], v[192:195], 0
	v_mfma_f32_16x16x32_bf16 v[72:75], v[160:163], v[192:195], 0
	v_mfma_f32_16x16x32_bf16 v[124:127], v[156:159], v[172:175], v[124:127]
	v_mfma_f32_16x16x32_bf16 v[120:123], v[164:167], v[172:175], v[120:123]
	v_mfma_f32_16x16x32_bf16 v[112:115], v[156:159], v[180:183], v[112:115]
	v_mfma_f32_16x16x32_bf16 v[104:107], v[164:167], v[180:183], v[104:107]
	v_mfma_f32_16x16x32_bf16 v[96:99], v[156:159], v[188:191], v[96:99]
	v_mfma_f32_16x16x32_bf16 v[88:91], v[164:167], v[188:191], v[88:91]
	v_mfma_f32_16x16x32_bf16 v[80:83], v[156:159], v[196:199], v[80:83]
	v_mfma_f32_16x16x32_bf16 v[72:75], v[164:167], v[196:199], v[72:75]
	s_setprio 0
	s_barrier
	s_add_i32 s54, s45, s30
	s_mov_b32 m0, s54
	ds_read_b128 v[202:205], v151
	ds_read_b128 v[206:209], v151 offset:1024
	ds_read_b128 v[210:213], v151 offset:2048
	ds_read_b128 v[214:217], v151 offset:3072
	global_load_lds_dwordx4 v130, s[24:25]
	s_add_i32 m0, s54, 0x2000
	s_nop 0
	global_load_lds_dwordx4 v134, s[24:25]
	s_waitcnt vmcnt(26)
	s_barrier
	s_waitcnt lgkmcnt(0)
	s_setprio 1
	s_waitcnt lgkmcnt(0)
	v_mfma_f32_16x16x32_bf16 v[116:119], v[202:205], v[168:171], 0
	v_mfma_f32_16x16x32_bf16 v[108:111], v[210:213], v[168:171], 0
	v_mfma_f32_16x16x32_bf16 v[100:103], v[202:205], v[176:179], 0
	v_mfma_f32_16x16x32_bf16 v[92:95], v[210:213], v[176:179], 0
	v_mfma_f32_16x16x32_bf16 v[84:87], v[202:205], v[184:187], 0
	v_mfma_f32_16x16x32_bf16 v[76:79], v[210:213], v[184:187], 0
	v_mfma_f32_16x16x32_bf16 v[68:71], v[202:205], v[192:195], 0
	v_mfma_f32_16x16x32_bf16 v[64:67], v[210:213], v[192:195], 0
	v_mfma_f32_16x16x32_bf16 v[116:119], v[206:209], v[172:175], v[116:119]
	v_mfma_f32_16x16x32_bf16 v[108:111], v[214:217], v[172:175], v[108:111]
	v_mfma_f32_16x16x32_bf16 v[100:103], v[206:209], v[180:183], v[100:103]
	v_mfma_f32_16x16x32_bf16 v[92:95], v[214:217], v[180:183], v[92:95]
	v_mfma_f32_16x16x32_bf16 v[84:87], v[206:209], v[188:191], v[84:87]
	v_mfma_f32_16x16x32_bf16 v[76:79], v[214:217], v[188:191], v[76:79]
	v_mfma_f32_16x16x32_bf16 v[68:71], v[206:209], v[196:199], v[68:71]
	v_mfma_f32_16x16x32_bf16 v[64:67], v[214:217], v[196:199], v[64:67]
	s_setprio 0
	s_mov_b32 m0, s21
	v_lshl_add_u64 v[222:223], s[26:27], 0, v[128:129]
	s_barrier
	ds_read_b128 v[168:171], v150 offset:16384
	ds_read_b128 v[172:175], v150 offset:17408
	ds_read_b128 v[176:179], v150 offset:18432
	ds_read_b128 v[180:183], v150 offset:19456
	ds_read_b128 v[184:187], v150 offset:20480
	ds_read_b128 v[188:191], v150 offset:21504
	ds_read_b128 v[192:195], v150 offset:22528
	ds_read_b128 v[196:199], v150 offset:23552
	global_load_lds_dwordx4 v128, s[26:27]
	v_lshl_add_u64 v[224:225], s[26:27], 0, v[132:133]
	s_mov_b32 m0, s31
	s_nop 0
	global_load_lds_dwordx4 v132, s[26:27]
	s_barrier
	s_waitcnt lgkmcnt(0)
	s_setprio 1
	s_waitcnt lgkmcnt(0)
	v_mfma_f32_16x16x32_bf16 v[60:63], v[152:155], v[168:171], 0
	v_mfma_f32_16x16x32_bf16 v[56:59], v[160:163], v[168:171], 0
	v_mfma_f32_16x16x32_bf16 v[48:51], v[152:155], v[176:179], 0
	v_mfma_f32_16x16x32_bf16 v[40:43], v[160:163], v[176:179], 0
	v_mfma_f32_16x16x32_bf16 v[32:35], v[152:155], v[184:187], 0
	v_mfma_f32_16x16x32_bf16 v[24:27], v[160:163], v[184:187], 0
	v_mfma_f32_16x16x32_bf16 v[16:19], v[152:155], v[192:195], 0
	v_mfma_f32_16x16x32_bf16 v[8:11], v[160:163], v[192:195], 0
	v_mfma_f32_16x16x32_bf16 v[60:63], v[156:159], v[172:175], v[60:63]
	v_mfma_f32_16x16x32_bf16 v[56:59], v[164:167], v[172:175], v[56:59]
	v_mfma_f32_16x16x32_bf16 v[48:51], v[156:159], v[180:183], v[48:51]
	v_mfma_f32_16x16x32_bf16 v[40:43], v[164:167], v[180:183], v[40:43]
	v_mfma_f32_16x16x32_bf16 v[32:35], v[156:159], v[188:191], v[32:35]
	v_mfma_f32_16x16x32_bf16 v[24:27], v[164:167], v[188:191], v[24:27]
	v_mfma_f32_16x16x32_bf16 v[16:19], v[156:159], v[196:199], v[16:19]
	v_mfma_f32_16x16x32_bf16 v[8:11], v[164:167], v[196:199], v[8:11]
	s_setprio 0
	s_barrier
; #define PG8_STAGE(bufoff, gbase, voff) do { _Pragma("unroll") for (int _i = 0; _i < 2; ++_i) \
;         __builtin_amdgcn_global_load_lds((const unsigned*)((const char*)(gbase) + (voff)[_i]), (LAS unsigned*)(lds + (bufoff) + ldsw + _i * 8192), 16, 0, 0); } while (0)
; #define PG8_LDA(dst, b, h) do { _Pragma("unroll") for (int m = 0; m < 4; ++m) _Pragma("unroll") for (int k = 0; k < 2; ++k) dst[m][k] = *(const LAS bf16x8*)(lds + PG8_SA(b, h) + aoff + m * 2048 + k * 1024); } while (0)
; #define PG8_LDB(dst, b, h) do { _Pragma("unroll") for (int n = 0; n < 2; ++n) _Pragma("unroll") for (int k = 0; k < 2; ++k) dst[n][k] = *(const LAS bf16x8*)(lds + PG8_SB(b, h) + boff + n * 2048 + k * 1024); } while (0)
; #define PG8_MMA(ai, bj, At, Bt) do { __builtin_amdgcn_s_setprio(1); _Pragma("unroll") for (int m = 0; m < 4; ++m) _Pragma("unroll") for (int n = 0; n < 2; ++n) _Pragma("unroll") for (int k = 0; k < 2; ++k) \
;         acc[ai][bj][m][n] = __builtin_amdgcn_mfma_f32_16x16x32_bf16(Bt[n][k], At[m][k], acc[ai][bj][m][n], 0, 0, 0); __builtin_amdgcn_s_setprio(0); } while (0)
; #define PG8_WAIT_V(n) asm volatile("s_waitcnt vmcnt(" #n ")" ::: "memory")
; #define PG8_WAIT_L(n) asm volatile("s_waitcnt lgkmcnt(" #n ")" ::: "memory")
; #define PG8_BAR __builtin_amdgcn_s_barrier()
; #define PG8_SCHED __builtin_amdgcn_sched_barrier(0)
; template <class Epi, class Sched>
; __device__ __forceinline__ void gemm_phase(LAS unsigned char* lds, const Gemm g, const Sched& S, const Epi& E) {
;     ...
;             PG8_BAR; PG8_WAIT_L(0); PG8_MMA(1, 0, At, B0); PG8_BAR; PG8_SCHED;
;             PG8_STAGE(PG8_SB(0, 1), b2 + hstep, voffB);
;             PG8_WAIT_V(6); PG8_BAR; PG8_MMA(1, 1, At, B1); PG8_BAR;
;             PG8_LDB(B0, 1, 0); PG8_SCHED; PG8_LDA(At, 1, 0); PG8_STAGE(PG8_SA(0, 1), a2 + hstep, voffA);
;             PG8_WAIT_L(8); PG8_BAR; PG8_WAIT_L(0); PG8_MMA(0, 0, At, B0); PG8_BAR; PG8_SCHED;
;             PG8_LDB(B1, 1, 1); PG8_STAGE(PG8_SB(1, 0), b3, voffB);
;             PG8_BAR; PG8_WAIT_L(0); PG8_MMA(0, 1, At, B1); PG8_BAR;
;             PG8_LDA(At, 1, 1); PG8_STAGE(PG8_SA(1, 0), a3, voffA);
;             PG8_BAR; PG8_WAIT_L(0); PG8_MMA(1, 0, At, B0); PG8_BAR; PG8_SCHED;
	s_add_u32 s54, s24, 0x40000
	s_addc_u32 s55, s25, 0
	s_add_i32 s56, s46, s30
	s_mov_b32 m0, s56
	s_nop 0
	global_load_lds_dwordx4 v130, s[54:55]
	s_add_i32 m0, s56, 0x2000
	s_nop 0
	global_load_lds_dwordx4 v134, s[54:55]
	s_waitcnt vmcnt(26)
	s_barrier
	s_setprio 1
	v_mfma_f32_16x16x32_bf16 v[52:55], v[202:205], v[168:171], 0
	v_mfma_f32_16x16x32_bf16 v[44:47], v[210:213], v[168:171], 0
	v_mfma_f32_16x16x32_bf16 v[36:39], v[202:205], v[176:179], 0
	v_mfma_f32_16x16x32_bf16 v[28:31], v[210:213], v[176:179], 0
	v_mfma_f32_16x16x32_bf16 v[20:23], v[202:205], v[184:187], 0
	v_mfma_f32_16x16x32_bf16 v[12:15], v[210:213], v[184:187], 0
	v_mfma_f32_16x16x32_bf16 v[4:7], v[202:205], v[192:195], 0
	v_mfma_f32_16x16x32_bf16 v[0:3], v[210:213], v[192:195], 0
	v_mfma_f32_16x16x32_bf16 v[52:55], v[206:209], v[172:175], v[52:55]
	v_mfma_f32_16x16x32_bf16 v[44:47], v[214:217], v[172:175], v[44:47]
	v_mfma_f32_16x16x32_bf16 v[36:39], v[206:209], v[180:183], v[36:39]
	v_mfma_f32_16x16x32_bf16 v[28:31], v[214:217], v[180:183], v[28:31]
	v_mfma_f32_16x16x32_bf16 v[20:23], v[206:209], v[188:191], v[20:23]
	v_mfma_f32_16x16x32_bf16 v[12:15], v[214:217], v[188:191], v[12:15]
	v_mfma_f32_16x16x32_bf16 v[4:7], v[206:209], v[196:199], v[4:7]
	v_mfma_f32_16x16x32_bf16 v[0:3], v[214:217], v[196:199], v[0:3]
	s_setprio 0
	s_add_i32 s54, 0, 0x18000
	v_add_u32_e32 v136, s54, v148
	s_barrier
	ds_read_b128 v[152:155], v136
	ds_read_b128 v[156:159], v136 offset:1024
	ds_read_b128 v[160:163], v136 offset:2048
	ds_read_b128 v[164:167], v136 offset:3072
	s_add_u32 s26, s26, 0x40000
	s_addc_u32 s27, s27, 0
	s_mov_b32 m0, s33
	ds_read_b128 v[168:171], v150 offset:32768
	ds_read_b128 v[172:175], v150 offset:33792
	ds_read_b128 v[176:179], v150 offset:34816
	ds_read_b128 v[180:183], v150 offset:35840
	ds_read_b128 v[184:187], v150 offset:36864
	ds_read_b128 v[188:191], v150 offset:37888
	ds_read_b128 v[192:195], v150 offset:38912
	ds_read_b128 v[196:199], v150 offset:39936
	global_load_lds_dwordx4 v128, s[26:27]
	s_mov_b32 m0, s34
	s_nop 0
	global_load_lds_dwordx4 v132, s[26:27]
	s_waitcnt lgkmcnt(8)
	s_waitcnt vmcnt(26)
	s_barrier
	s_waitcnt lgkmcnt(0)
	s_setprio 1
	s_waitcnt lgkmcnt(0)
	v_mfma_f32_16x16x32_bf16 v[124:127], v[152:155], v[168:171], v[124:127]
	v_mfma_f32_16x16x32_bf16 v[120:123], v[160:163], v[168:171], v[120:123]
	v_mfma_f32_16x16x32_bf16 v[112:115], v[152:155], v[176:179], v[112:115]
	v_mfma_f32_16x16x32_bf16 v[104:107], v[160:163], v[176:179], v[104:107]
	v_mfma_f32_16x16x32_bf16 v[96:99], v[152:155], v[184:187], v[96:99]
	v_mfma_f32_16x16x32_bf16 v[88:91], v[160:163], v[184:187], v[88:91]
	v_mfma_f32_16x16x32_bf16 v[80:83], v[152:155], v[192:195], v[80:83]
	v_mfma_f32_16x16x32_bf16 v[72:75], v[160:163], v[192:195], v[72:75]
	v_mfma_f32_16x16x32_bf16 v[124:127], v[156:159], v[172:175], v[124:127]
	v_mfma_f32_16x16x32_bf16 v[120:123], v[164:167], v[172:175], v[120:123]
	v_mfma_f32_16x16x32_bf16 v[112:115], v[156:159], v[180:183], v[112:115]
	v_mfma_f32_16x16x32_bf16 v[104:107], v[164:167], v[180:183], v[104:107]
	v_mfma_f32_16x16x32_bf16 v[96:99], v[156:159], v[188:191], v[96:99]
	v_mfma_f32_16x16x32_bf16 v[88:91], v[164:167], v[188:191], v[88:91]
	v_mfma_f32_16x16x32_bf16 v[80:83], v[156:159], v[196:199], v[80:83]
	v_mfma_f32_16x16x32_bf16 v[72:75], v[164:167], v[196:199], v[72:75]
	s_setprio 0
	s_barrier
	s_add_i32 s26, 0, 0x1c000
	s_add_i32 s27, s54, s30
	v_add_u32_e32 v136, s26, v148
	s_add_u32 s0, s24, 0x80
	s_addc_u32 s1, s25, 0
	s_mov_b32 m0, s27
	ds_read_b128 v[202:205], v136
	ds_read_b128 v[206:209], v136 offset:1024
	ds_read_b128 v[210:213], v136 offset:2048
	ds_read_b128 v[214:217], v136 offset:3072
	global_load_lds_dwordx4 v130, s[0:1]
	s_add_i32 m0, s27, 0x2000
	s_nop 0
	global_load_lds_dwordx4 v134, s[0:1]
	s_waitcnt vmcnt(10)
	s_barrier
; #define PG8_STAGE(bufoff, gbase, voff) do { _Pragma("unroll") for (int _i = 0; _i < 2; ++_i) \
;         __builtin_amdgcn_global_load_lds((const unsigned*)((const char*)(gbase) + (voff)[_i]), (LAS unsigned*)(lds + (bufoff) + ldsw + _i * 8192), 16, 0, 0); } while (0)
; #define PG8_LDA(dst, b, h) do { _Pragma("unroll") for (int m = 0; m < 4; ++m) _Pragma("unroll") for (int k = 0; k < 2; ++k) dst[m][k] = *(const LAS bf16x8*)(lds + PG8_SA(b, h) + aoff + m * 2048 + k * 1024); } while (0)
; #define PG8_MMA(ai, bj, At, Bt) do { __builtin_amdgcn_s_setprio(1); _Pragma("unroll") for (int m = 0; m < 4; ++m) _Pragma("unroll") for (int n = 0; n < 2; ++n) _Pragma("unroll") for (int k = 0; k < 2; ++k) \
;         acc[ai][bj][m][n] = __builtin_amdgcn_mfma_f32_16x16x32_bf16(Bt[n][k], At[m][k], acc[ai][bj][m][n], 0, 0, 0); __builtin_amdgcn_s_setprio(0); } while (0)
; #define PG8_WAIT_V(n) asm volatile("s_waitcnt vmcnt(" #n ")" ::: "memory")
; #define PG8_WAIT_L(n) asm volatile("s_waitcnt lgkmcnt(" #n ")" ::: "memory")
; #define PG8_BAR __builtin_amdgcn_s_barrier()
; #define PG8_SCHED __builtin_amdgcn_sched_barrier(0)
; template <class Epi, class Sched>
; __device__ __forceinline__ void gemm_phase(LAS unsigned char* lds, const Gemm g, const Sched& S, const Epi& E) {
;     ...
;             PG8_BAR; PG8_WAIT_L(0); PG8_MMA(0, 1, At, B1); PG8_BAR;
;             PG8_LDA(At, 1, 1); PG8_STAGE(PG8_SA(1, 0), a3, voffA);
;             PG8_BAR; PG8_WAIT_L(0); PG8_MMA(1, 0, At, B0); PG8_BAR; PG8_SCHED;
;             PG8_STAGE(PG8_SB(1, 1), b3 + hstep, voffB);
;             PG8_WAIT_V(6); PG8_BAR; PG8_MMA(1, 1, At, B1); PG8_BAR;
;         }
	s_waitcnt lgkmcnt(0)
	s_setprio 1
	s_waitcnt lgkmcnt(0)
	v_mfma_f32_16x16x32_bf16 v[116:119], v[202:205], v[168:171], v[116:119]
	v_mfma_f32_16x16x32_bf16 v[108:111], v[210:213], v[168:171], v[108:111]
	v_mfma_f32_16x16x32_bf16 v[100:103], v[202:205], v[176:179], v[100:103]
	v_mfma_f32_16x16x32_bf16 v[92:95], v[210:213], v[176:179], v[92:95]
	v_mfma_f32_16x16x32_bf16 v[84:87], v[202:205], v[184:187], v[84:87]
	v_mfma_f32_16x16x32_bf16 v[76:79], v[210:213], v[184:187], v[76:79]
	v_mfma_f32_16x16x32_bf16 v[68:71], v[202:205], v[192:195], v[68:71]
	v_mfma_f32_16x16x32_bf16 v[64:67], v[210:213], v[192:195], v[64:67]
	v_mfma_f32_16x16x32_bf16 v[116:119], v[206:209], v[172:175], v[116:119]
	v_mfma_f32_16x16x32_bf16 v[108:111], v[214:217], v[172:175], v[108:111]
	v_mfma_f32_16x16x32_bf16 v[100:103], v[206:209], v[180:183], v[100:103]
	v_mfma_f32_16x16x32_bf16 v[92:95], v[214:217], v[180:183], v[92:95]
	v_mfma_f32_16x16x32_bf16 v[84:87], v[206:209], v[188:191], v[84:87]
	v_mfma_f32_16x16x32_bf16 v[76:79], v[214:217], v[188:191], v[76:79]
	v_mfma_f32_16x16x32_bf16 v[68:71], v[206:209], v[196:199], v[68:71]
	v_mfma_f32_16x16x32_bf16 v[64:67], v[214:217], v[196:199], v[64:67]
	s_setprio 0
	s_mov_b32 m0, s42
	s_mov_b64 s[0:1], 0x80
	v_lshl_add_u64 v[218:219], v[222:223], 0, s[0:1]
	s_barrier
	ds_read_b128 v[168:171], v150 offset:49152
	ds_read_b128 v[172:175], v150 offset:50176
	ds_read_b128 v[176:179], v150 offset:51200
	ds_read_b128 v[180:183], v150 offset:52224
	ds_read_b128 v[184:187], v150 offset:53248
	ds_read_b128 v[188:191], v150 offset:54272
	ds_read_b128 v[192:195], v150 offset:55296
	ds_read_b128 v[196:199], v150 offset:56320
	global_load_lds_dwordx4 v[218:219], off
	v_lshl_add_u64 v[218:219], v[224:225], 0, s[0:1]
	s_mov_b32 m0, s43
	s_nop 0
	global_load_lds_dwordx4 v[218:219], off
	s_barrier
	s_waitcnt lgkmcnt(0)
	s_setprio 1
	s_waitcnt lgkmcnt(0)
	v_mfma_f32_16x16x32_bf16 v[60:63], v[152:155], v[168:171], v[60:63]
	v_mfma_f32_16x16x32_bf16 v[56:59], v[160:163], v[168:171], v[56:59]
	v_mfma_f32_16x16x32_bf16 v[48:51], v[152:155], v[176:179], v[48:51]
	v_mfma_f32_16x16x32_bf16 v[40:43], v[160:163], v[176:179], v[40:43]
	v_mfma_f32_16x16x32_bf16 v[32:35], v[152:155], v[184:187], v[32:35]
	v_mfma_f32_16x16x32_bf16 v[24:27], v[160:163], v[184:187], v[24:27]
	v_mfma_f32_16x16x32_bf16 v[16:19], v[152:155], v[192:195], v[16:19]
	v_mfma_f32_16x16x32_bf16 v[8:11], v[160:163], v[192:195], v[8:11]
	v_mfma_f32_16x16x32_bf16 v[60:63], v[156:159], v[172:175], v[60:63]
	v_mfma_f32_16x16x32_bf16 v[56:59], v[164:167], v[172:175], v[56:59]
	v_mfma_f32_16x16x32_bf16 v[48:51], v[156:159], v[180:183], v[48:51]
	v_mfma_f32_16x16x32_bf16 v[40:43], v[164:167], v[180:183], v[40:43]
	v_mfma_f32_16x16x32_bf16 v[32:35], v[156:159], v[188:191], v[32:35]
	v_mfma_f32_16x16x32_bf16 v[24:27], v[164:167], v[188:191], v[24:27]
	v_mfma_f32_16x16x32_bf16 v[16:19], v[156:159], v[196:199], v[16:19]
	v_mfma_f32_16x16x32_bf16 v[8:11], v[164:167], v[196:199], v[8:11]
	s_setprio 0
	s_barrier
	s_add_u32 s24, s24, 0x40080
	s_addc_u32 s25, s25, 0
	s_add_i32 s26, s26, s30
	s_mov_b32 m0, s26
	s_nop 0
	global_load_lds_dwordx4 v130, s[24:25]
	s_add_i32 m0, s26, 0x2000
	s_nop 0
	global_load_lds_dwordx4 v134, s[24:25]
	s_waitcnt vmcnt(10)
	s_barrier
	s_setprio 1
	v_mfma_f32_16x16x32_bf16 v[52:55], v[202:205], v[168:171], v[52:55]
	v_mfma_f32_16x16x32_bf16 v[44:47], v[210:213], v[168:171], v[44:47]
	v_mfma_f32_16x16x32_bf16 v[36:39], v[202:205], v[176:179], v[36:39]
	v_mfma_f32_16x16x32_bf16 v[28:31], v[210:213], v[176:179], v[28:31]
	v_mfma_f32_16x16x32_bf16 v[20:23], v[202:205], v[184:187], v[20:23]
	v_mfma_f32_16x16x32_bf16 v[12:15], v[210:213], v[184:187], v[12:15]
	v_mfma_f32_16x16x32_bf16 v[4:7], v[202:205], v[192:195], v[4:7]
	v_mfma_f32_16x16x32_bf16 v[0:3], v[210:213], v[192:195], v[0:3]
	v_mfma_f32_16x16x32_bf16 v[52:55], v[206:209], v[172:175], v[52:55]
	v_mfma_f32_16x16x32_bf16 v[44:47], v[214:217], v[172:175], v[44:47]
	v_mfma_f32_16x16x32_bf16 v[36:39], v[206:209], v[180:183], v[36:39]
	v_mfma_f32_16x16x32_bf16 v[28:31], v[214:217], v[180:183], v[28:31]
	v_mfma_f32_16x16x32_bf16 v[20:23], v[206:209], v[188:191], v[20:23]
	v_mfma_f32_16x16x32_bf16 v[12:15], v[214:217], v[188:191], v[12:15]
	v_mfma_f32_16x16x32_bf16 v[4:7], v[206:209], v[196:199], v[4:7]
	v_mfma_f32_16x16x32_bf16 v[0:3], v[214:217], v[196:199], v[0:3]
	s_setprio 0
	s_add_i32 s53, s53, 2
	s_add_u32 s22, s22, 0x100
	s_addc_u32 s23, s23, 0
	s_add_u32 s51, s51, 0x100
	s_addc_u32 s52, s52, 0
	s_cmp_gt_u32 s53, 13
	s_barrier

; #define PG8_STAGE(bufoff, gbase, voff) do { _Pragma("unroll") for (int _i = 0; _i < 2; ++_i) \
;         __builtin_amdgcn_global_load_lds((const unsigned*)((const char*)(gbase) + (voff)[_i]), (LAS unsigned*)(lds + (bufoff) + ldsw + _i * 8192), 16, 0, 0); } while (0)
; #define PG8_WAIT_V(n) asm volatile("s_waitcnt vmcnt(" #n ")" ::: "memory")
; #define PG8_BAR __builtin_amdgcn_s_barrier()
; template <class Epi, class Sched>
; __device__ __forceinline__ void gemm_phase(LAS unsigned char* lds, const Gemm g, const Sched& S, const Epi& E) {
;     ...
;     for (int i = 0; i < 2; ++i) { int R, C; stage_rc(tid * 16 + i * 8192, R, C); const int Rb = Epi::PERM ? ((R & ~31) + perm32(R & 31)) : R;
;         voffA[i] = (unsigned)(R * K + C) * 2u; voffB[i] = (unsigned)(Rb * K + C) * 2u; }
;     const size_t kstep = (size_t)(BK * 2);
;     const size_t hstep = (size_t)HALF * K * 2;
;     const size_t tstep = 2 * hstep;
;     const unsigned ldsw = (unsigned)wid * 1024u;
;     const int aoff = lds_byte(wr * 64 + fr, fq * 8), boff = lds_byte(wc * 32 + fr, fq * 8);
;     ...
;     PG8_WAIT_V(4); PG8_BAR;
;     PG8_STAGE(PG8_SB(1, 0), cB + kstep, voffB); PG8_STAGE(PG8_SA(1, 0), cA + kstep, voffA); PG8_STAGE(PG8_SB(1, 1), cB + hstep + kstep, voffB);
;     PG8_WAIT_V(6); PG8_BAR;
.LBB0_665:
	s_lshl_b32 s34, s0, 6
	s_lshl_b32 s3, s0, 13
	s_lshl_b32 s0, s1, 5
	s_and_b32 s35, s0, 0x60
	s_mov_b64 s[0:1], 0x80
	s_add_i32 m0, s17, 0x18000
	v_lshl_add_u64 v[6:7], v[6:7], 0, s[0:1]
	s_lshl_b32 s6, s35, 7
	s_waitcnt vmcnt(4)
	s_barrier
	global_load_lds_dwordx4 v[6:7], off
	v_lshl_add_u64 v[4:5], v[4:5], 0, s[0:1]
	s_add_i32 m0, s17, 0x1a000
	s_add_i32 s36, s17, 0x8000
	s_add_i32 s37, s17, 0xa000
	global_load_lds_dwordx4 v[4:5], off
	v_lshl_add_u64 v[2:3], v[2:3], 0, s[0:1]
	s_mov_b32 m0, s36
	s_add_u32 s4, s20, 0x40080
	global_load_lds_dwordx4 v[2:3], off
	v_lshl_add_u64 v[0:1], v[0:1], 0, s[0:1]
	s_mov_b32 m0, s37
	s_addc_u32 s5, s21, 0
	global_load_lds_dwordx4 v[0:1], off
	s_add_i32 m0, s17, 0x1c000
	v_lshl_add_u64 v[0:1], s[4:5], 0, v[130:131]
	global_load_lds_dwordx4 v[0:1], off
	v_lshl_add_u64 v[0:1], s[4:5], 0, v[134:135]
	s_add_i32 m0, s17, 0x1e000
	v_bfe_u32 v147, v8, 4, 2
	global_load_lds_dwordx4 v[0:1], off
	v_and_b32_e32 v146, 15, v8
	v_lshlrev_b32_e32 v0, 4, v147
	v_lshlrev_b32_e32 v1, 2, v8
	v_lshl_or_b32 v0, v146, 6, v0
	v_and_b32_e32 v1, 32, v1
	v_bitop3_b32 v2, v0, s3, v1 bitop3:0xde
	v_bitop3_b32 v148, v0, s6, v1 bitop3:0xde
	v_lshlrev_b32_e32 v0, 14, v9
	v_and_b32_e32 v0, 0xffff8000, v0
	v_lshl_add_u32 v0, v10, 11, v0
	v_and_b32_e32 v1, 1, v9
	v_lshl_or_b32 v0, v1, 6, v0
	v_lshl_add_u32 v138, v11, 1, v0
	v_lshlrev_b32_e32 v0, 14, v12
	s_ashr_i32 s42, s76, 31
	v_and_b32_e32 v0, 0xffff8000, v0
	s_waitcnt vmcnt(0)
	s_add_u32 s4, s72, 0x1d000800
	v_lshl_add_u32 v0, v13, 11, v0
	v_and_b32_e32 v1, 1, v12
	s_addc_u32 s5, s73, 0
	v_lshl_or_b32 v0, v1, 6, v0
	s_add_i32 s43, 0, 0x10000
	s_add_i32 s44, 0, 0x14000
	s_sext_i32_i16 s45, s2
	v_mov_b32_e32 v139, v137
	v_lshl_add_u32 v140, v14, 1, v0
	v_mov_b32_e32 v141, v137
	v_mov_b64_e32 v[142:143], 0x100
	v_mov_b64_e32 v[144:145], 0xff
	v_add_u32_e32 v149, s43, v148
	v_add_u32_e32 v150, 0, v2
	v_add_u32_e32 v151, s44, v148
	s_barrier

; #define PG8_STAGE(bufoff, gbase, voff) do { _Pragma("unroll") for (int _i = 0; _i < 2; ++_i) \
;         __builtin_amdgcn_global_load_lds((const unsigned*)((const char*)(gbase) + (voff)[_i]), (LAS unsigned*)(lds + (bufoff) + ldsw + _i * 8192), 16, 0, 0); } while (0)
; #define PG8_LDA(dst, b, h) do { _Pragma("unroll") for (int m = 0; m < 4; ++m) _Pragma("unroll") for (int k = 0; k < 2; ++k) dst[m][k] = *(const LAS bf16x8*)(lds + PG8_SA(b, h) + aoff + m * 2048 + k * 1024); } while (0)
; #define PG8_LDB(dst, b, h) do { _Pragma("unroll") for (int n = 0; n < 2; ++n) _Pragma("unroll") for (int k = 0; k < 2; ++k) dst[n][k] = *(const LAS bf16x8*)(lds + PG8_SB(b, h) + boff + n * 2048 + k * 1024); } while (0)
; #define PG8_MMA(ai, bj, At, Bt) do { __builtin_amdgcn_s_setprio(1); _Pragma("unroll") for (int m = 0; m < 4; ++m) _Pragma("unroll") for (int n = 0; n < 2; ++n) _Pragma("unroll") for (int k = 0; k < 2; ++k) \
;         acc[ai][bj][m][n] = __builtin_amdgcn_mfma_f32_16x16x32_bf16(Bt[n][k], At[m][k], acc[ai][bj][m][n], 0, 0, 0); __builtin_amdgcn_s_setprio(0); } while (0)
; #define PG8_WAIT_L(n) asm volatile("s_waitcnt lgkmcnt(" #n ")" ::: "memory")
; template <class Epi, class Sched>
; __device__ __forceinline__ void gemm_phase(LAS unsigned char* lds, const Gemm g, const Sched& S, const Epi& E) {
;     ...
;         const bool has_next = S.next(ui + 1, nxt);
;         const char* nA = has_next ? (const char*)g.A + (size_t)nxt.pm * tstep : cA; const char* nB = has_next ? (const char*)g.Bt + (size_t)nxt.pn * tstep : cB;
;         for (int t = 0; t < nt; t += 2) {
;             const bool last = (t == nt - 2);
;             const char* a1 = cA + (size_t)(t + 1) * kstep;
;             const char* a2 = last ? nA : cA + (size_t)(t + 2) * kstep; const char* b2 = last ? nB : cB + (size_t)(t + 2) * kstep;
;             const char* a3 = a2 + kstep; const char* b3 = b2 + kstep;
;             PG8_LDB(B0, 0, 0); PG8_SCHED; PG8_LDA(At, 0, 0); PG8_STAGE(PG8_SA(1, 1), a1 + hstep, voffA);
;             PG8_WAIT_L(8); PG8_BAR; PG8_WAIT_L(0); PG8_MMA(0, 0, At, B0); PG8_BAR; PG8_SCHED;
;             PG8_LDB(B1, 0, 1); PG8_STAGE(PG8_SB(0, 0), b2, voffB);
;             PG8_BAR; PG8_WAIT_L(0); PG8_MMA(0, 1, At, B1); PG8_BAR;
;             PG8_LDA(At, 0, 1); PG8_STAGE(PG8_SA(0, 0), a2, voffA);
;             PG8_BAR; PG8_WAIT_L(0); PG8_MMA(1, 0, At, B0); PG8_BAR; PG8_SCHED;
.LBB0_672:
	s_ashr_i32 s9, s8, 31
	v_cmp_lt_i64_e32 vcc, s[12:13], v[142:143]
	s_lshl_b64 s[12:13], s[8:9], 19
	s_add_u32 s12, s26, s12
	s_addc_u32 s13, s27, s13
	s_and_b64 s[14:15], vcc, exec
	s_cselect_b32 s9, s13, s19
	s_cselect_b32 s46, s12, s18
	s_ashr_i32 s7, s6, 31
	s_lshl_b64 s[14:15], s[6:7], 19
	s_add_u32 s14, s10, s14
	s_addc_u32 s15, s11, s15
	s_and_b64 s[22:23], vcc, exec
	s_cselect_b32 s7, s15, s21
	s_cselect_b32 s47, s14, s20
	s_add_u32 s18, s18, 0x40080
	s_addc_u32 s19, s19, 0
	s_add_u32 s48, s20, 0x100
	s_addc_u32 s49, s21, 0
	s_mov_b32 s51, -2
	s_waitcnt lgkmcnt(0)
	ds_read_b128 v[152:155], v149
	ds_read_b128 v[156:159], v149 offset:1024
	ds_read_b128 v[160:163], v149 offset:2048
	ds_read_b128 v[164:167], v149 offset:3072
	s_add_u32 s20, s18, 0xfffc0080
	s_addc_u32 s21, s19, -1
	s_cmp_eq_u32 s51, 12
	s_cselect_b32 s23, s9, s21
	s_cselect_b32 s22, s46, s20
	s_cselect_b32 s21, s7, s49
	s_cselect_b32 s20, s47, s48
	s_add_i32 m0, s17, 0xc000
	ds_read_b128 v[168:171], v150
	ds_read_b128 v[172:175], v150 offset:1024
	ds_read_b128 v[176:179], v150 offset:2048
	ds_read_b128 v[180:183], v150 offset:3072
	ds_read_b128 v[184:187], v150 offset:4096
	ds_read_b128 v[188:191], v150 offset:5120
	ds_read_b128 v[192:195], v150 offset:6144
	ds_read_b128 v[196:199], v150 offset:7168
	global_load_lds_dwordx4 v138, s[18:19]
	s_add_i32 m0, s17, 0xe000
	s_nop 0
	global_load_lds_dwordx4 v140, s[18:19]
	s_waitcnt lgkmcnt(8)
	s_waitcnt vmcnt(26)
	s_barrier
	s_waitcnt lgkmcnt(0)
	s_setprio 1
	s_waitcnt lgkmcnt(0)
	v_mfma_f32_16x16x32_bf16 v[124:127], v[152:155], v[168:171], 0
	v_mfma_f32_16x16x32_bf16 v[120:123], v[160:163], v[168:171], 0
	v_mfma_f32_16x16x32_bf16 v[112:115], v[152:155], v[176:179], 0
	v_mfma_f32_16x16x32_bf16 v[104:107], v[160:163], v[176:179], 0
	v_mfma_f32_16x16x32_bf16 v[96:99], v[152:155], v[184:187], 0
	v_mfma_f32_16x16x32_bf16 v[88:91], v[160:163], v[184:187], 0
	v_mfma_f32_16x16x32_bf16 v[80:83], v[152:155], v[192:195], 0
	v_mfma_f32_16x16x32_bf16 v[72:75], v[160:163], v[192:195], 0
	v_mfma_f32_16x16x32_bf16 v[124:127], v[156:159], v[172:175], v[124:127]
	v_mfma_f32_16x16x32_bf16 v[120:123], v[164:167], v[172:175], v[120:123]
	v_mfma_f32_16x16x32_bf16 v[112:115], v[156:159], v[180:183], v[112:115]
	v_mfma_f32_16x16x32_bf16 v[104:107], v[164:167], v[180:183], v[104:107]
	v_mfma_f32_16x16x32_bf16 v[96:99], v[156:159], v[188:191], v[96:99]
	v_mfma_f32_16x16x32_bf16 v[88:91], v[164:167], v[188:191], v[88:91]
	v_mfma_f32_16x16x32_bf16 v[80:83], v[156:159], v[196:199], v[80:83]
	v_mfma_f32_16x16x32_bf16 v[72:75], v[164:167], v[196:199], v[72:75]
	s_setprio 0
	s_barrier
	s_add_i32 s52, s43, s28
	s_mov_b32 m0, s52
	ds_read_b128 v[202:205], v151
	ds_read_b128 v[206:209], v151 offset:1024
	ds_read_b128 v[210:213], v151 offset:2048
	ds_read_b128 v[214:217], v151 offset:3072
	global_load_lds_dwordx4 v130, s[20:21]
	s_add_i32 m0, s52, 0x2000
	s_nop 0
	global_load_lds_dwordx4 v134, s[20:21]
	s_waitcnt vmcnt(26)
	s_barrier
	s_waitcnt lgkmcnt(0)
	s_setprio 1
	s_waitcnt lgkmcnt(0)
	v_mfma_f32_16x16x32_bf16 v[116:119], v[202:205], v[168:171], 0
	v_mfma_f32_16x16x32_bf16 v[108:111], v[210:213], v[168:171], 0
	v_mfma_f32_16x16x32_bf16 v[100:103], v[202:205], v[176:179], 0
	v_mfma_f32_16x16x32_bf16 v[92:95], v[210:213], v[176:179], 0
	v_mfma_f32_16x16x32_bf16 v[84:87], v[202:205], v[184:187], 0
	v_mfma_f32_16x16x32_bf16 v[76:79], v[210:213], v[184:187], 0
	v_mfma_f32_16x16x32_bf16 v[68:71], v[202:205], v[192:195], 0
	v_mfma_f32_16x16x32_bf16 v[64:67], v[210:213], v[192:195], 0
	v_mfma_f32_16x16x32_bf16 v[116:119], v[206:209], v[172:175], v[116:119]
	v_mfma_f32_16x16x32_bf16 v[108:111], v[214:217], v[172:175], v[108:111]
	v_mfma_f32_16x16x32_bf16 v[100:103], v[206:209], v[180:183], v[100:103]
	v_mfma_f32_16x16x32_bf16 v[92:95], v[214:217], v[180:183], v[92:95]
	v_mfma_f32_16x16x32_bf16 v[84:87], v[206:209], v[188:191], v[84:87]
	v_mfma_f32_16x16x32_bf16 v[76:79], v[214:217], v[188:191], v[76:79]
	v_mfma_f32_16x16x32_bf16 v[68:71], v[206:209], v[196:199], v[68:71]
	v_mfma_f32_16x16x32_bf16 v[64:67], v[214:217], v[196:199], v[64:67]
	s_setprio 0
	s_mov_b32 m0, s17
	v_lshl_add_u64 v[222:223], s[22:23], 0, v[128:129]
	s_barrier
	ds_read_b128 v[168:171], v150 offset:16384
	ds_read_b128 v[172:175], v150 offset:17408
	ds_read_b128 v[176:179], v150 offset:18432
	ds_read_b128 v[180:183], v150 offset:19456
	ds_read_b128 v[184:187], v150 offset:20480
	ds_read_b128 v[188:191], v150 offset:21504
	ds_read_b128 v[192:195], v150 offset:22528
	ds_read_b128 v[196:199], v150 offset:23552
	global_load_lds_dwordx4 v128, s[22:23]
	v_lshl_add_u64 v[224:225], s[22:23], 0, v[132:133]
	s_mov_b32 m0, s29
	s_nop 0
	global_load_lds_dwordx4 v132, s[22:23]
	s_barrier
	s_waitcnt lgkmcnt(0)
	s_setprio 1
	s_waitcnt lgkmcnt(0)
	v_mfma_f32_16x16x32_bf16 v[60:63], v[152:155], v[168:171], 0
	v_mfma_f32_16x16x32_bf16 v[56:59], v[160:163], v[168:171], 0
	v_mfma_f32_16x16x32_bf16 v[48:51], v[152:155], v[176:179], 0
	v_mfma_f32_16x16x32_bf16 v[40:43], v[160:163], v[176:179], 0
	v_mfma_f32_16x16x32_bf16 v[32:35], v[152:155], v[184:187], 0
	v_mfma_f32_16x16x32_bf16 v[24:27], v[160:163], v[184:187], 0
	v_mfma_f32_16x16x32_bf16 v[16:19], v[152:155], v[192:195], 0
	v_mfma_f32_16x16x32_bf16 v[8:11], v[160:163], v[192:195], 0
	v_mfma_f32_16x16x32_bf16 v[60:63], v[156:159], v[172:175], v[60:63]
	v_mfma_f32_16x16x32_bf16 v[56:59], v[164:167], v[172:175], v[56:59]
	v_mfma_f32_16x16x32_bf16 v[48:51], v[156:159], v[180:183], v[48:51]
	v_mfma_f32_16x16x32_bf16 v[40:43], v[164:167], v[180:183], v[40:43]
	v_mfma_f32_16x16x32_bf16 v[32:35], v[156:159], v[188:191], v[32:35]
	v_mfma_f32_16x16x32_bf16 v[24:27], v[164:167], v[188:191], v[24:27]
	v_mfma_f32_16x16x32_bf16 v[16:19], v[156:159], v[196:199], v[16:19]
	v_mfma_f32_16x16x32_bf16 v[8:11], v[164:167], v[196:199], v[8:11]
	s_setprio 0
	s_barrier
; #define PG8_STAGE(bufoff, gbase, voff) do { _Pragma("unroll") for (int _i = 0; _i < 2; ++_i) \
;         __builtin_amdgcn_global_load_lds((const unsigned*)((const char*)(gbase) + (voff)[_i]), (LAS unsigned*)(lds + (bufoff) + ldsw + _i * 8192), 16, 0, 0); } while (0)
; #define PG8_LDA(dst, b, h) do { _Pragma("unroll") for (int m = 0; m < 4; ++m) _Pragma("unroll") for (int k = 0; k < 2; ++k) dst[m][k] = *(const LAS bf16x8*)(lds + PG8_SA(b, h) + aoff + m * 2048 + k * 1024); } while (0)
; #define PG8_LDB(dst, b, h) do { _Pragma("unroll") for (int n = 0; n < 2; ++n) _Pragma("unroll") for (int k = 0; k < 2; ++k) dst[n][k] = *(const LAS bf16x8*)(lds + PG8_SB(b, h) + boff + n * 2048 + k * 1024); } while (0)
; #define PG8_MMA(ai, bj, At, Bt) do { __builtin_amdgcn_s_setprio(1); _Pragma("unroll") for (int m = 0; m < 4; ++m) _Pragma("unroll") for (int n = 0; n < 2; ++n) _Pragma("unroll") for (int k = 0; k < 2; ++k) \
;         acc[ai][bj][m][n] = __builtin_amdgcn_mfma_f32_16x16x32_bf16(Bt[n][k], At[m][k], acc[ai][bj][m][n], 0, 0, 0); __builtin_amdgcn_s_setprio(0); } while (0)
; #define PG8_WAIT_V(n) asm volatile("s_waitcnt vmcnt(" #n ")" ::: "memory")
; #define PG8_WAIT_L(n) asm volatile("s_waitcnt lgkmcnt(" #n ")" ::: "memory")
; #define PG8_BAR __builtin_amdgcn_s_barrier()
; #define PG8_SCHED __builtin_amdgcn_sched_barrier(0)
; template <class Epi, class Sched>
; __device__ __forceinline__ void gemm_phase(LAS unsigned char* lds, const Gemm g, const Sched& S, const Epi& E) {
;     ...
;             PG8_STAGE(PG8_SB(0, 1), b2 + hstep, voffB);
;             PG8_WAIT_V(6); PG8_BAR; PG8_MMA(1, 1, At, B1); PG8_BAR;
;             PG8_LDB(B0, 1, 0); PG8_SCHED; PG8_LDA(At, 1, 0); PG8_STAGE(PG8_SA(0, 1), a2 + hstep, voffA);
;             PG8_WAIT_L(8); PG8_BAR; PG8_WAIT_L(0); PG8_MMA(0, 0, At, B0); PG8_BAR; PG8_SCHED;
;             PG8_LDB(B1, 1, 1); PG8_STAGE(PG8_SB(1, 0), b3, voffB);
;             PG8_BAR; PG8_WAIT_L(0); PG8_MMA(0, 1, At, B1); PG8_BAR;
	s_add_u32 s52, s20, 0x40000
	s_addc_u32 s53, s21, 0
	s_add_i32 s54, s44, s28
	s_mov_b32 m0, s54
	s_nop 0
	global_load_lds_dwordx4 v130, s[52:53]
	s_add_i32 m0, s54, 0x2000
	s_nop 0
	global_load_lds_dwordx4 v134, s[52:53]
	s_waitcnt vmcnt(26)
	s_barrier
	s_setprio 1
	v_mfma_f32_16x16x32_bf16 v[52:55], v[202:205], v[168:171], 0
	v_mfma_f32_16x16x32_bf16 v[44:47], v[210:213], v[168:171], 0
	v_mfma_f32_16x16x32_bf16 v[36:39], v[202:205], v[176:179], 0
	v_mfma_f32_16x16x32_bf16 v[28:31], v[210:213], v[176:179], 0
	v_mfma_f32_16x16x32_bf16 v[20:23], v[202:205], v[184:187], 0
	v_mfma_f32_16x16x32_bf16 v[12:15], v[210:213], v[184:187], 0
	v_mfma_f32_16x16x32_bf16 v[4:7], v[202:205], v[192:195], 0
	v_mfma_f32_16x16x32_bf16 v[0:3], v[210:213], v[192:195], 0
	v_mfma_f32_16x16x32_bf16 v[52:55], v[206:209], v[172:175], v[52:55]
	v_mfma_f32_16x16x32_bf16 v[44:47], v[214:217], v[172:175], v[44:47]
	v_mfma_f32_16x16x32_bf16 v[36:39], v[206:209], v[180:183], v[36:39]
	v_mfma_f32_16x16x32_bf16 v[28:31], v[214:217], v[180:183], v[28:31]
	v_mfma_f32_16x16x32_bf16 v[20:23], v[206:209], v[188:191], v[20:23]
	v_mfma_f32_16x16x32_bf16 v[12:15], v[214:217], v[188:191], v[12:15]
	v_mfma_f32_16x16x32_bf16 v[4:7], v[206:209], v[196:199], v[4:7]
	v_mfma_f32_16x16x32_bf16 v[0:3], v[214:217], v[196:199], v[0:3]
	s_setprio 0
	s_add_i32 s52, 0, 0x18000
	v_add_u32_e32 v136, s52, v148
	s_barrier
	ds_read_b128 v[152:155], v136
	ds_read_b128 v[156:159], v136 offset:1024
	ds_read_b128 v[160:163], v136 offset:2048
	ds_read_b128 v[164:167], v136 offset:3072
	s_add_u32 s22, s22, 0x40000
	s_addc_u32 s23, s23, 0
	s_mov_b32 m0, s30
	ds_read_b128 v[168:171], v150 offset:32768
	ds_read_b128 v[172:175], v150 offset:33792
	ds_read_b128 v[176:179], v150 offset:34816
	ds_read_b128 v[180:183], v150 offset:35840
	ds_read_b128 v[184:187], v150 offset:36864
	ds_read_b128 v[188:191], v150 offset:37888
	ds_read_b128 v[192:195], v150 offset:38912
	ds_read_b128 v[196:199], v150 offset:39936
	global_load_lds_dwordx4 v128, s[22:23]
	s_mov_b32 m0, s31
	s_nop 0
	global_load_lds_dwordx4 v132, s[22:23]
	s_waitcnt lgkmcnt(8)
	s_waitcnt vmcnt(26)
	s_barrier
	s_waitcnt lgkmcnt(0)
	s_setprio 1
	s_waitcnt lgkmcnt(0)
	v_mfma_f32_16x16x32_bf16 v[124:127], v[152:155], v[168:171], v[124:127]
	v_mfma_f32_16x16x32_bf16 v[120:123], v[160:163], v[168:171], v[120:123]
	v_mfma_f32_16x16x32_bf16 v[112:115], v[152:155], v[176:179], v[112:115]
	v_mfma_f32_16x16x32_bf16 v[104:107], v[160:163], v[176:179], v[104:107]
	v_mfma_f32_16x16x32_bf16 v[96:99], v[152:155], v[184:187], v[96:99]
	v_mfma_f32_16x16x32_bf16 v[88:91], v[160:163], v[184:187], v[88:91]
	v_mfma_f32_16x16x32_bf16 v[80:83], v[152:155], v[192:195], v[80:83]
	v_mfma_f32_16x16x32_bf16 v[72:75], v[160:163], v[192:195], v[72:75]
	v_mfma_f32_16x16x32_bf16 v[124:127], v[156:159], v[172:175], v[124:127]
	v_mfma_f32_16x16x32_bf16 v[120:123], v[164:167], v[172:175], v[120:123]
	v_mfma_f32_16x16x32_bf16 v[112:115], v[156:159], v[180:183], v[112:115]
	v_mfma_f32_16x16x32_bf16 v[104:107], v[164:167], v[180:183], v[104:107]
	v_mfma_f32_16x16x32_bf16 v[96:99], v[156:159], v[188:191], v[96:99]
	v_mfma_f32_16x16x32_bf16 v[88:91], v[164:167], v[188:191], v[88:91]
	v_mfma_f32_16x16x32_bf16 v[80:83], v[156:159], v[196:199], v[80:83]
	v_mfma_f32_16x16x32_bf16 v[72:75], v[164:167], v[196:199], v[72:75]
	s_setprio 0
	s_barrier
	s_add_i32 s22, 0, 0x1c000
	s_add_i32 s23, s52, s28
	v_add_u32_e32 v136, s22, v148
	s_add_u32 s0, s20, 0x80
	s_addc_u32 s1, s21, 0
	s_mov_b32 m0, s23
	ds_read_b128 v[202:205], v136
	ds_read_b128 v[206:209], v136 offset:1024
	ds_read_b128 v[210:213], v136 offset:2048
	ds_read_b128 v[214:217], v136 offset:3072
	global_load_lds_dwordx4 v130, s[0:1]
	s_add_i32 m0, s23, 0x2000
	s_nop 0
	global_load_lds_dwordx4 v134, s[0:1]
	s_waitcnt vmcnt(10)
	s_barrier
; #define PG8_STAGE(bufoff, gbase, voff) do { _Pragma("unroll") for (int _i = 0; _i < 2; ++_i) \
;         __builtin_amdgcn_global_load_lds((const unsigned*)((const char*)(gbase) + (voff)[_i]), (LAS unsigned*)(lds + (bufoff) + ldsw + _i * 8192), 16, 0, 0); } while (0)
; #define PG8_LDA(dst, b, h) do { _Pragma("unroll") for (int m = 0; m < 4; ++m) _Pragma("unroll") for (int k = 0; k < 2; ++k) dst[m][k] = *(const LAS bf16x8*)(lds + PG8_SA(b, h) + aoff + m * 2048 + k * 1024); } while (0)
; #define PG8_MMA(ai, bj, At, Bt) do { __builtin_amdgcn_s_setprio(1); _Pragma("unroll") for (int m = 0; m < 4; ++m) _Pragma("unroll") for (int n = 0; n < 2; ++n) _Pragma("unroll") for (int k = 0; k < 2; ++k) \
;         acc[ai][bj][m][n] = __builtin_amdgcn_mfma_f32_16x16x32_bf16(Bt[n][k], At[m][k], acc[ai][bj][m][n], 0, 0, 0); __builtin_amdgcn_s_setprio(0); } while (0)
; #define PG8_WAIT_V(n) asm volatile("s_waitcnt vmcnt(" #n ")" ::: "memory")
; #define PG8_WAIT_L(n) asm volatile("s_waitcnt lgkmcnt(" #n ")" ::: "memory")
; #define PG8_BAR __builtin_amdgcn_s_barrier()
; #define PG8_SCHED __builtin_amdgcn_sched_barrier(0)
; template <class Epi, class Sched>
; __device__ __forceinline__ void gemm_phase(LAS unsigned char* lds, const Gemm g, const Sched& S, const Epi& E) {
;     ...
;             PG8_BAR; PG8_WAIT_L(0); PG8_MMA(0, 1, At, B1); PG8_BAR;
;             PG8_LDA(At, 1, 1); PG8_STAGE(PG8_SA(1, 0), a3, voffA);
;             PG8_BAR; PG8_WAIT_L(0); PG8_MMA(1, 0, At, B0); PG8_BAR; PG8_SCHED;
;             PG8_STAGE(PG8_SB(1, 1), b3 + hstep, voffB);
;             PG8_WAIT_V(6); PG8_BAR; PG8_MMA(1, 1, At, B1); PG8_BAR;
;         }
	s_waitcnt lgkmcnt(0)
	s_setprio 1
	s_waitcnt lgkmcnt(0)
	v_mfma_f32_16x16x32_bf16 v[116:119], v[202:205], v[168:171], v[116:119]
	v_mfma_f32_16x16x32_bf16 v[108:111], v[210:213], v[168:171], v[108:111]
	v_mfma_f32_16x16x32_bf16 v[100:103], v[202:205], v[176:179], v[100:103]
	v_mfma_f32_16x16x32_bf16 v[92:95], v[210:213], v[176:179], v[92:95]
	v_mfma_f32_16x16x32_bf16 v[84:87], v[202:205], v[184:187], v[84:87]
	v_mfma_f32_16x16x32_bf16 v[76:79], v[210:213], v[184:187], v[76:79]
	v_mfma_f32_16x16x32_bf16 v[68:71], v[202:205], v[192:195], v[68:71]
	v_mfma_f32_16x16x32_bf16 v[64:67], v[210:213], v[192:195], v[64:67]
	v_mfma_f32_16x16x32_bf16 v[116:119], v[206:209], v[172:175], v[116:119]
	v_mfma_f32_16x16x32_bf16 v[108:111], v[214:217], v[172:175], v[108:111]
	v_mfma_f32_16x16x32_bf16 v[100:103], v[206:209], v[180:183], v[100:103]
	v_mfma_f32_16x16x32_bf16 v[92:95], v[214:217], v[180:183], v[92:95]
	v_mfma_f32_16x16x32_bf16 v[84:87], v[206:209], v[188:191], v[84:87]
	v_mfma_f32_16x16x32_bf16 v[76:79], v[214:217], v[188:191], v[76:79]
	v_mfma_f32_16x16x32_bf16 v[68:71], v[206:209], v[196:199], v[68:71]
	v_mfma_f32_16x16x32_bf16 v[64:67], v[214:217], v[196:199], v[64:67]
	s_setprio 0
	s_mov_b32 m0, s36
	s_mov_b64 s[0:1], 0x80
	v_lshl_add_u64 v[218:219], v[222:223], 0, s[0:1]
	s_barrier
	ds_read_b128 v[168:171], v150 offset:49152
	ds_read_b128 v[172:175], v150 offset:50176
	ds_read_b128 v[176:179], v150 offset:51200
	ds_read_b128 v[180:183], v150 offset:52224
	ds_read_b128 v[184:187], v150 offset:53248
	ds_read_b128 v[188:191], v150 offset:54272
	ds_read_b128 v[192:195], v150 offset:55296
	ds_read_b128 v[196:199], v150 offset:56320
	global_load_lds_dwordx4 v[218:219], off
	v_lshl_add_u64 v[218:219], v[224:225], 0, s[0:1]
	s_mov_b32 m0, s37
	s_nop 0
	global_load_lds_dwordx4 v[218:219], off
	s_barrier
	s_waitcnt lgkmcnt(0)
	s_setprio 1
	s_waitcnt lgkmcnt(0)
	v_mfma_f32_16x16x32_bf16 v[60:63], v[152:155], v[168:171], v[60:63]
	v_mfma_f32_16x16x32_bf16 v[56:59], v[160:163], v[168:171], v[56:59]
	v_mfma_f32_16x16x32_bf16 v[48:51], v[152:155], v[176:179], v[48:51]
	v_mfma_f32_16x16x32_bf16 v[40:43], v[160:163], v[176:179], v[40:43]
	v_mfma_f32_16x16x32_bf16 v[32:35], v[152:155], v[184:187], v[32:35]
	v_mfma_f32_16x16x32_bf16 v[24:27], v[160:163], v[184:187], v[24:27]
	v_mfma_f32_16x16x32_bf16 v[16:19], v[152:155], v[192:195], v[16:19]
	v_mfma_f32_16x16x32_bf16 v[8:11], v[160:163], v[192:195], v[8:11]
	v_mfma_f32_16x16x32_bf16 v[60:63], v[156:159], v[172:175], v[60:63]
	v_mfma_f32_16x16x32_bf16 v[56:59], v[164:167], v[172:175], v[56:59]
	v_mfma_f32_16x16x32_bf16 v[48:51], v[156:159], v[180:183], v[48:51]
	v_mfma_f32_16x16x32_bf16 v[40:43], v[164:167], v[180:183], v[40:43]
	v_mfma_f32_16x16x32_bf16 v[32:35], v[156:159], v[188:191], v[32:35]
	v_mfma_f32_16x16x32_bf16 v[24:27], v[164:167], v[188:191], v[24:27]
	v_mfma_f32_16x16x32_bf16 v[16:19], v[156:159], v[196:199], v[16:19]
	v_mfma_f32_16x16x32_bf16 v[8:11], v[164:167], v[196:199], v[8:11]
	s_setprio 0
	s_barrier
	s_add_u32 s20, s20, 0x40080
	s_addc_u32 s21, s21, 0
	s_add_i32 s22, s22, s28
	s_mov_b32 m0, s22
	s_nop 0
	global_load_lds_dwordx4 v130, s[20:21]
	s_add_i32 m0, s22, 0x2000
	s_nop 0
	global_load_lds_dwordx4 v134, s[20:21]
	s_waitcnt vmcnt(10)
	s_barrier
	s_setprio 1
	v_mfma_f32_16x16x32_bf16 v[52:55], v[202:205], v[168:171], v[52:55]
	v_mfma_f32_16x16x32_bf16 v[44:47], v[210:213], v[168:171], v[44:47]
	v_mfma_f32_16x16x32_bf16 v[36:39], v[202:205], v[176:179], v[36:39]
	v_mfma_f32_16x16x32_bf16 v[28:31], v[210:213], v[176:179], v[28:31]
	v_mfma_f32_16x16x32_bf16 v[20:23], v[202:205], v[184:187], v[20:23]
	v_mfma_f32_16x16x32_bf16 v[12:15], v[210:213], v[184:187], v[12:15]
	v_mfma_f32_16x16x32_bf16 v[4:7], v[202:205], v[192:195], v[4:7]
	v_mfma_f32_16x16x32_bf16 v[0:3], v[210:213], v[192:195], v[0:3]
	v_mfma_f32_16x16x32_bf16 v[52:55], v[206:209], v[172:175], v[52:55]
	v_mfma_f32_16x16x32_bf16 v[44:47], v[214:217], v[172:175], v[44:47]
	v_mfma_f32_16x16x32_bf16 v[36:39], v[206:209], v[180:183], v[36:39]
	v_mfma_f32_16x16x32_bf16 v[28:31], v[214:217], v[180:183], v[28:31]
	v_mfma_f32_16x16x32_bf16 v[20:23], v[206:209], v[188:191], v[20:23]
	v_mfma_f32_16x16x32_bf16 v[12:15], v[214:217], v[188:191], v[12:15]
	v_mfma_f32_16x16x32_bf16 v[4:7], v[206:209], v[196:199], v[4:7]
	v_mfma_f32_16x16x32_bf16 v[0:3], v[214:217], v[196:199], v[0:3]
	s_setprio 0
	s_add_i32 s51, s51, 2
	s_add_u32 s18, s18, 0x100
	s_addc_u32 s19, s19, 0
	s_add_u32 s48, s48, 0x100
	s_addc_u32 s49, s49, 0
	s_cmp_gt_u32 s51, 13
	s_barrier

; #define PG8_STAGE(bufoff, gbase, voff) do { _Pragma("unroll") for (int _i = 0; _i < 2; ++_i) \
;         __builtin_amdgcn_global_load_lds((const unsigned*)((const char*)(gbase) + (voff)[_i]), (LAS unsigned*)(lds + (bufoff) + ldsw + _i * 8192), 16, 0, 0); } while (0)
; #define PG8_WAIT_V(n) asm volatile("s_waitcnt vmcnt(" #n ")" ::: "memory")
; #define PG8_BAR __builtin_amdgcn_s_barrier()
; template <class Epi, class Sched>
; __device__ __forceinline__ void gemm_phase(LAS unsigned char* lds, const Gemm g, const Sched& S, const Epi& E) {
;     ...
;     for (int i = 0; i < 2; ++i) { int R, C; stage_rc(tid * 16 + i * 8192, R, C); const int Rb = Epi::PERM ? ((R & ~31) + perm32(R & 31)) : R;
;         voffA[i] = (unsigned)(R * K + C) * 2u; voffB[i] = (unsigned)(Rb * K + C) * 2u; }
;     const size_t kstep = (size_t)(BK * 2);
;     const size_t hstep = (size_t)HALF * K * 2;
;     const size_t tstep = 2 * hstep;
;     const unsigned ldsw = (unsigned)wid * 1024u;
;     const int aoff = lds_byte(wr * 64 + fr, fq * 8), boff = lds_byte(wc * 32 + fr, fq * 8);
;     ...
;     PG8_WAIT_V(4); PG8_BAR;
;     PG8_STAGE(PG8_SB(1, 0), cB + kstep, voffB); PG8_STAGE(PG8_SA(1, 0), cA + kstep, voffA); PG8_STAGE(PG8_SB(1, 1), cB + hstep + kstep, voffB);
;     PG8_WAIT_V(6); PG8_BAR;
.LBB0_685:
	s_lshl_b32 s0, s0, 5
	s_and_b32 s43, s0, 0x60
	s_mov_b64 s[0:1], 0x80
	s_add_i32 m0, s33, 0x18000
	v_lshl_add_u64 v[6:7], v[6:7], 0, s[0:1]
	s_lshl_b32 s42, s6, 6
	s_lshl_b32 s7, s6, 13
	s_lshl_b32 s9, s43, 7
	s_waitcnt vmcnt(4)
	s_barrier
	global_load_lds_dwordx4 v[6:7], off
	v_lshl_add_u64 v[4:5], v[4:5], 0, s[0:1]
	s_add_i32 m0, s33, 0x1a000
	s_add_i32 s44, s33, 0x8000
	s_add_i32 s45, s33, 0xa000
	global_load_lds_dwordx4 v[4:5], off
	v_lshl_add_u64 v[0:1], v[0:1], 0, s[0:1]
	s_mov_b32 m0, s44
	s_add_u32 s10, s4, 0x40080
	global_load_lds_dwordx4 v[0:1], off
	v_lshl_add_u64 v[0:1], v[2:3], 0, s[0:1]
	s_mov_b32 m0, s45
	s_addc_u32 s11, s5, 0
	global_load_lds_dwordx4 v[0:1], off
	s_add_i32 m0, s33, 0x1c000
	v_lshl_add_u64 v[0:1], s[10:11], 0, v[130:131]
	global_load_lds_dwordx4 v[0:1], off
	v_lshl_add_u64 v[0:1], s[10:11], 0, v[134:135]
	s_add_i32 m0, s33, 0x1e000
	v_bfe_u32 v147, v9, 4, 2
	global_load_lds_dwordx4 v[0:1], off
	v_and_b32_e32 v146, 15, v9
	v_lshlrev_b32_e32 v0, 4, v147
	v_lshlrev_b32_e32 v1, 2, v9
	v_lshl_or_b32 v0, v146, 6, v0
	v_and_b32_e32 v1, 32, v1
	v_bitop3_b32 v2, v0, s7, v1 bitop3:0xde
	v_bitop3_b32 v148, v0, s9, v1 bitop3:0xde
	v_lshlrev_b32_e32 v0, 14, v8
	v_and_b32_e32 v0, 0xffff8000, v0
	v_lshl_add_u32 v0, v10, 11, v0
	v_and_b32_e32 v1, 1, v8
	s_sext_i32_i16 s56, s8
	v_readlane_b32 s8, v254, 0
	v_lshl_or_b32 v0, v1, 6, v0
	s_ashr_i32 s7, s6, 31
	v_readlane_b32 s10, v254, 2
	v_readlane_b32 s11, v254, 3
	v_readlane_b32 s14, v254, 6
	v_readlane_b32 s15, v254, 7
	v_lshl_add_u32 v136, v11, 1, v0
	v_lshlrev_b32_e32 v0, 14, v12
	s_ashr_i32 s46, s76, 31
	s_lshl_b64 s[6:7], s[6:7], 2
	s_mov_b64 s[10:11], s[14:15]
	v_and_b32_e32 v0, 0xffff8000, v0
	s_waitcnt vmcnt(0)
	s_add_u32 s6, s10, s6
	v_lshl_add_u32 v0, v13, 11, v0
	v_and_b32_e32 v1, 1, v12
	v_readlane_b32 s9, v254, 1
	v_readlane_b32 s12, v254, 4
	v_readlane_b32 s13, v254, 5
	s_addc_u32 s7, s11, s7
	v_lshl_or_b32 v0, v1, 6, v0
	s_add_i32 s47, 0, 0x10000
	s_add_i32 s48, 0, 0x14000
	v_readlane_b32 s16, v254, 8
	v_readlane_b32 s18, v254, 10
	v_mov_b32_e32 v137, v131
	v_lshl_add_u32 v138, v14, 1, v0
	v_mov_b32_e32 v139, v131
	v_add_u32_e32 v149, s47, v148
	v_add_u32_e32 v150, 0, v2
	v_add_u32_e32 v151, s48, v148
	s_mov_b32 s49, 0xc2fc0000
	s_mov_b32 s51, 0x42fc0000
	s_mov_b32 s52, 0x280000
	s_mov_b64 s[8:9], 0x680000
	s_mov_b32 s53, 0x680000
	s_mov_b64 s[10:11], 0x2c0000
	s_mov_b32 s54, 0x2c0000
	s_mov_b64 s[12:13], 0x6c0000
	s_mov_b32 s55, 0x6c0000
	v_not_b32_e32 v152, 63
	v_mov_b32_e32 v153, 0x42800000
	s_barrier
	v_readlane_b32 s17, v254, 9
	v_readlane_b32 s19, v254, 11
	v_readlane_b32 s20, v254, 12
	v_readlane_b32 s21, v254, 13
	v_readlane_b32 s22, v254, 14
	v_readlane_b32 s23, v254, 15

; #define PG8_STAGE(bufoff, gbase, voff) do { _Pragma("unroll") for (int _i = 0; _i < 2; ++_i) \
;         __builtin_amdgcn_global_load_lds((const unsigned*)((const char*)(gbase) + (voff)[_i]), (LAS unsigned*)(lds + (bufoff) + ldsw + _i * 8192), 16, 0, 0); } while (0)
; #define PG8_LDA(dst, b, h) do { _Pragma("unroll") for (int m = 0; m < 4; ++m) _Pragma("unroll") for (int k = 0; k < 2; ++k) dst[m][k] = *(const LAS bf16x8*)(lds + PG8_SA(b, h) + aoff + m * 2048 + k * 1024); } while (0)
; #define PG8_LDB(dst, b, h) do { _Pragma("unroll") for (int n = 0; n < 2; ++n) _Pragma("unroll") for (int k = 0; k < 2; ++k) dst[n][k] = *(const LAS bf16x8*)(lds + PG8_SB(b, h) + boff + n * 2048 + k * 1024); } while (0)
; #define PG8_MMA(ai, bj, At, Bt) do { __builtin_amdgcn_s_setprio(1); _Pragma("unroll") for (int m = 0; m < 4; ++m) _Pragma("unroll") for (int n = 0; n < 2; ++n) _Pragma("unroll") for (int k = 0; k < 2; ++k) \
;         acc[ai][bj][m][n] = __builtin_amdgcn_mfma_f32_16x16x32_bf16(Bt[n][k], At[m][k], acc[ai][bj][m][n], 0, 0, 0); __builtin_amdgcn_s_setprio(0); } while (0)
; #define PG8_WAIT_L(n) asm volatile("s_waitcnt lgkmcnt(" #n ")" ::: "memory")
; template <class Epi, class Sched>
; __device__ __forceinline__ void gemm_phase(LAS unsigned char* lds, const Gemm g, const Sched& S, const Epi& E) {
;     ...
;         const bool has_next = S.next(ui + 1, nxt);
;         const char* nA = has_next ? (const char*)g.A + (size_t)nxt.pm * tstep : cA; const char* nB = has_next ? (const char*)g.Bt + (size_t)nxt.pn * tstep : cB;
;         for (int t = 0; t < nt; t += 2) {
;             const bool last = (t == nt - 2);
;             const char* a1 = cA + (size_t)(t + 1) * kstep;
;             const char* a2 = last ? nA : cA + (size_t)(t + 2) * kstep; const char* b2 = last ? nB : cB + (size_t)(t + 2) * kstep;
;             const char* a3 = a2 + kstep; const char* b3 = b2 + kstep;
;             PG8_LDB(B0, 0, 0); PG8_SCHED; PG8_LDA(At, 0, 0); PG8_STAGE(PG8_SA(1, 1), a1 + hstep, voffA);
;             PG8_WAIT_L(8); PG8_BAR; PG8_WAIT_L(0); PG8_MMA(0, 0, At, B0); PG8_BAR; PG8_SCHED;
;             PG8_LDB(B1, 0, 1); PG8_STAGE(PG8_SB(0, 0), b2, voffB);
;             PG8_BAR; PG8_WAIT_L(0); PG8_MMA(0, 1, At, B1); PG8_BAR;
;             PG8_LDA(At, 0, 1); PG8_STAGE(PG8_SA(0, 0), a2, voffA);
;             PG8_BAR; PG8_WAIT_L(0); PG8_MMA(1, 0, At, B0); PG8_BAR; PG8_SCHED;
.LBB0_692:
	s_ashr_i32 s19, s18, 31
	v_cmp_lt_i64_e64 s[24:25], s[20:21], 32
	s_lshl_b64 s[20:21], s[18:19], 19
	s_add_u32 s20, s40, s20
	s_addc_u32 s21, s41, s21
	s_and_b64 s[22:23], s[24:25], exec
	s_cselect_b32 s19, s21, s3
	s_cselect_b32 s57, s20, s2
	s_ashr_i32 s17, s16, 31
	s_lshl_b64 s[22:23], s[16:17], 19
	s_add_u32 s22, s28, s22
	s_addc_u32 s23, s29, s23
	s_and_b64 s[24:25], s[24:25], exec
	s_cselect_b32 s17, s23, s5
	s_cselect_b32 s58, s22, s4
	s_add_u32 s2, s2, 0x40080
	s_addc_u32 s3, s3, 0
	s_add_u32 s59, s4, 0x100
	s_addc_u32 s60, s5, 0
	s_mov_b32 s61, -2
	s_waitcnt lgkmcnt(0)
	ds_read_b128 v[140:143], v149
	ds_read_b128 v[154:157], v149 offset:1024
	ds_read_b128 v[158:161], v149 offset:2048
	ds_read_b128 v[162:165], v149 offset:3072
	s_add_u32 s4, s2, 0xfffc0080
	s_addc_u32 s5, s3, -1
	s_cmp_eq_u32 s61, 12
	s_cselect_b32 s25, s19, s5
	s_cselect_b32 s24, s57, s4
	s_cselect_b32 s5, s17, s60
	s_cselect_b32 s4, s58, s59
	s_add_i32 m0, s33, 0xc000
	ds_read_b128 v[166:169], v150
	ds_read_b128 v[170:173], v150 offset:1024
	ds_read_b128 v[174:177], v150 offset:2048
	ds_read_b128 v[178:181], v150 offset:3072
	ds_read_b128 v[182:185], v150 offset:4096
	ds_read_b128 v[186:189], v150 offset:5120
	ds_read_b128 v[190:193], v150 offset:6144
	ds_read_b128 v[194:197], v150 offset:7168
	global_load_lds_dwordx4 v136, s[2:3]
	s_add_i32 m0, s33, 0xe000
	s_nop 0
	global_load_lds_dwordx4 v138, s[2:3]
	s_waitcnt lgkmcnt(8)
	s_waitcnt vmcnt(26)
	s_barrier
	s_waitcnt lgkmcnt(0)
	s_setprio 1
	s_waitcnt lgkmcnt(0)
	v_mfma_f32_16x16x32_bf16 v[124:127], v[140:143], v[166:169], 0
	v_mfma_f32_16x16x32_bf16 v[120:123], v[158:161], v[166:169], 0
	v_mfma_f32_16x16x32_bf16 v[108:111], v[140:143], v[174:177], 0
	v_mfma_f32_16x16x32_bf16 v[104:107], v[158:161], v[174:177], 0
	v_mfma_f32_16x16x32_bf16 v[92:95], v[140:143], v[182:185], 0
	v_mfma_f32_16x16x32_bf16 v[88:91], v[158:161], v[182:185], 0
	v_mfma_f32_16x16x32_bf16 v[76:79], v[140:143], v[190:193], 0
	v_mfma_f32_16x16x32_bf16 v[72:75], v[158:161], v[190:193], 0
	v_mfma_f32_16x16x32_bf16 v[124:127], v[154:157], v[170:173], v[124:127]
	v_mfma_f32_16x16x32_bf16 v[120:123], v[162:165], v[170:173], v[120:123]
	v_mfma_f32_16x16x32_bf16 v[108:111], v[154:157], v[178:181], v[108:111]
	v_mfma_f32_16x16x32_bf16 v[104:107], v[162:165], v[178:181], v[104:107]
	v_mfma_f32_16x16x32_bf16 v[92:95], v[154:157], v[186:189], v[92:95]
	v_mfma_f32_16x16x32_bf16 v[88:91], v[162:165], v[186:189], v[88:91]
	v_mfma_f32_16x16x32_bf16 v[76:79], v[154:157], v[194:197], v[76:79]
	v_mfma_f32_16x16x32_bf16 v[72:75], v[162:165], v[194:197], v[72:75]
	s_setprio 0
	s_barrier
	s_add_i32 s62, s47, s31
	s_mov_b32 m0, s62
	ds_read_b128 v[202:205], v151
	ds_read_b128 v[206:209], v151 offset:1024
	ds_read_b128 v[210:213], v151 offset:2048
	ds_read_b128 v[214:217], v151 offset:3072
	global_load_lds_dwordx4 v130, s[4:5]
	s_add_i32 m0, s62, 0x2000
	s_nop 0
	global_load_lds_dwordx4 v134, s[4:5]
	s_waitcnt vmcnt(26)
	s_barrier
	s_waitcnt lgkmcnt(0)
	s_setprio 1
	s_waitcnt lgkmcnt(0)
	v_mfma_f32_16x16x32_bf16 v[116:119], v[202:205], v[166:169], 0
	v_mfma_f32_16x16x32_bf16 v[112:115], v[210:213], v[166:169], 0
	v_mfma_f32_16x16x32_bf16 v[100:103], v[202:205], v[174:177], 0
	v_mfma_f32_16x16x32_bf16 v[96:99], v[210:213], v[174:177], 0
	v_mfma_f32_16x16x32_bf16 v[84:87], v[202:205], v[182:185], 0
	v_mfma_f32_16x16x32_bf16 v[80:83], v[210:213], v[182:185], 0
	v_mfma_f32_16x16x32_bf16 v[68:71], v[202:205], v[190:193], 0
	v_mfma_f32_16x16x32_bf16 v[64:67], v[210:213], v[190:193], 0
	v_mfma_f32_16x16x32_bf16 v[116:119], v[206:209], v[170:173], v[116:119]
	v_mfma_f32_16x16x32_bf16 v[112:115], v[214:217], v[170:173], v[112:115]
	v_mfma_f32_16x16x32_bf16 v[100:103], v[206:209], v[178:181], v[100:103]
	v_mfma_f32_16x16x32_bf16 v[96:99], v[214:217], v[178:181], v[96:99]
	v_mfma_f32_16x16x32_bf16 v[84:87], v[206:209], v[186:189], v[84:87]
	v_mfma_f32_16x16x32_bf16 v[80:83], v[214:217], v[186:189], v[80:83]
	v_mfma_f32_16x16x32_bf16 v[68:71], v[206:209], v[194:197], v[68:71]
	v_mfma_f32_16x16x32_bf16 v[64:67], v[214:217], v[194:197], v[64:67]
	s_setprio 0
	s_mov_b32 m0, s33
	v_lshl_add_u64 v[218:219], s[24:25], 0, v[128:129]
	s_barrier
	ds_read_b128 v[166:169], v150 offset:16384
	ds_read_b128 v[170:173], v150 offset:17408
	ds_read_b128 v[174:177], v150 offset:18432
	ds_read_b128 v[178:181], v150 offset:19456
	ds_read_b128 v[182:185], v150 offset:20480
	ds_read_b128 v[186:189], v150 offset:21504
	ds_read_b128 v[190:193], v150 offset:22528
	ds_read_b128 v[194:197], v150 offset:23552
	global_load_lds_dwordx4 v128, s[24:25]
	v_lshl_add_u64 v[220:221], s[24:25], 0, v[132:133]
	s_mov_b32 m0, s34
	s_nop 0
	global_load_lds_dwordx4 v132, s[24:25]
	s_barrier
	s_waitcnt lgkmcnt(0)
	s_setprio 1
	s_waitcnt lgkmcnt(0)
	v_mfma_f32_16x16x32_bf16 v[60:63], v[140:143], v[166:169], 0
	v_mfma_f32_16x16x32_bf16 v[56:59], v[158:161], v[166:169], 0
	v_mfma_f32_16x16x32_bf16 v[44:47], v[140:143], v[174:177], 0
	v_mfma_f32_16x16x32_bf16 v[40:43], v[158:161], v[174:177], 0
	v_mfma_f32_16x16x32_bf16 v[28:31], v[140:143], v[182:185], 0
	v_mfma_f32_16x16x32_bf16 v[24:27], v[158:161], v[182:185], 0
	v_mfma_f32_16x16x32_bf16 v[12:15], v[140:143], v[190:193], 0
	v_mfma_f32_16x16x32_bf16 v[8:11], v[158:161], v[190:193], 0
	v_mfma_f32_16x16x32_bf16 v[60:63], v[154:157], v[170:173], v[60:63]
	v_mfma_f32_16x16x32_bf16 v[56:59], v[162:165], v[170:173], v[56:59]
	v_mfma_f32_16x16x32_bf16 v[44:47], v[154:157], v[178:181], v[44:47]
	v_mfma_f32_16x16x32_bf16 v[40:43], v[162:165], v[178:181], v[40:43]
	v_mfma_f32_16x16x32_bf16 v[28:31], v[154:157], v[186:189], v[28:31]
	v_mfma_f32_16x16x32_bf16 v[24:27], v[162:165], v[186:189], v[24:27]
	v_mfma_f32_16x16x32_bf16 v[12:15], v[154:157], v[194:197], v[12:15]
	v_mfma_f32_16x16x32_bf16 v[8:11], v[162:165], v[194:197], v[8:11]
	s_setprio 0
	s_barrier
; #define PG8_STAGE(bufoff, gbase, voff) do { _Pragma("unroll") for (int _i = 0; _i < 2; ++_i) \
;         __builtin_amdgcn_global_load_lds((const unsigned*)((const char*)(gbase) + (voff)[_i]), (LAS unsigned*)(lds + (bufoff) + ldsw + _i * 8192), 16, 0, 0); } while (0)
; #define PG8_LDA(dst, b, h) do { _Pragma("unroll") for (int m = 0; m < 4; ++m) _Pragma("unroll") for (int k = 0; k < 2; ++k) dst[m][k] = *(const LAS bf16x8*)(lds + PG8_SA(b, h) + aoff + m * 2048 + k * 1024); } while (0)
; #define PG8_LDB(dst, b, h) do { _Pragma("unroll") for (int n = 0; n < 2; ++n) _Pragma("unroll") for (int k = 0; k < 2; ++k) dst[n][k] = *(const LAS bf16x8*)(lds + PG8_SB(b, h) + boff + n * 2048 + k * 1024); } while (0)
; #define PG8_MMA(ai, bj, At, Bt) do { __builtin_amdgcn_s_setprio(1); _Pragma("unroll") for (int m = 0; m < 4; ++m) _Pragma("unroll") for (int n = 0; n < 2; ++n) _Pragma("unroll") for (int k = 0; k < 2; ++k) \
;         acc[ai][bj][m][n] = __builtin_amdgcn_mfma_f32_16x16x32_bf16(Bt[n][k], At[m][k], acc[ai][bj][m][n], 0, 0, 0); __builtin_amdgcn_s_setprio(0); } while (0)
; #define PG8_WAIT_V(n) asm volatile("s_waitcnt vmcnt(" #n ")" ::: "memory")
; #define PG8_WAIT_L(n) asm volatile("s_waitcnt lgkmcnt(" #n ")" ::: "memory")
; #define PG8_BAR __builtin_amdgcn_s_barrier()
; #define PG8_SCHED __builtin_amdgcn_sched_barrier(0)
; template <class Epi, class Sched>
; __device__ __forceinline__ void gemm_phase(LAS unsigned char* lds, const Gemm g, const Sched& S, const Epi& E) {
;     ...
;             PG8_STAGE(PG8_SB(0, 1), b2 + hstep, voffB);
;             PG8_WAIT_V(6); PG8_BAR; PG8_MMA(1, 1, At, B1); PG8_BAR;
;             PG8_LDB(B0, 1, 0); PG8_SCHED; PG8_LDA(At, 1, 0); PG8_STAGE(PG8_SA(0, 1), a2 + hstep, voffA);
;             PG8_WAIT_L(8); PG8_BAR; PG8_WAIT_L(0); PG8_MMA(0, 0, At, B0); PG8_BAR; PG8_SCHED;
;             PG8_LDB(B1, 1, 1); PG8_STAGE(PG8_SB(1, 0), b3, voffB);
;             PG8_BAR; PG8_WAIT_L(0); PG8_MMA(0, 1, At, B1); PG8_BAR;
	s_add_u32 s62, s4, 0x40000
	s_addc_u32 s63, s5, 0
	s_add_i32 s64, s48, s31
	s_mov_b32 m0, s64
	s_nop 0
	global_load_lds_dwordx4 v130, s[62:63]
	s_add_i32 m0, s64, 0x2000
	s_nop 0
	global_load_lds_dwordx4 v134, s[62:63]
	s_waitcnt vmcnt(26)
	s_barrier
	s_setprio 1
	v_mfma_f32_16x16x32_bf16 v[52:55], v[202:205], v[166:169], 0
	v_mfma_f32_16x16x32_bf16 v[48:51], v[210:213], v[166:169], 0
	v_mfma_f32_16x16x32_bf16 v[36:39], v[202:205], v[174:177], 0
	v_mfma_f32_16x16x32_bf16 v[32:35], v[210:213], v[174:177], 0
	v_mfma_f32_16x16x32_bf16 v[20:23], v[202:205], v[182:185], 0
	v_mfma_f32_16x16x32_bf16 v[16:19], v[210:213], v[182:185], 0
	v_mfma_f32_16x16x32_bf16 v[4:7], v[202:205], v[190:193], 0
	v_mfma_f32_16x16x32_bf16 v[0:3], v[210:213], v[190:193], 0
	v_mfma_f32_16x16x32_bf16 v[52:55], v[206:209], v[170:173], v[52:55]
	v_mfma_f32_16x16x32_bf16 v[48:51], v[214:217], v[170:173], v[48:51]
	v_mfma_f32_16x16x32_bf16 v[36:39], v[206:209], v[178:181], v[36:39]
	v_mfma_f32_16x16x32_bf16 v[32:35], v[214:217], v[178:181], v[32:35]
	v_mfma_f32_16x16x32_bf16 v[20:23], v[206:209], v[186:189], v[20:23]
	v_mfma_f32_16x16x32_bf16 v[16:19], v[214:217], v[186:189], v[16:19]
	v_mfma_f32_16x16x32_bf16 v[4:7], v[206:209], v[194:197], v[4:7]
	v_mfma_f32_16x16x32_bf16 v[0:3], v[214:217], v[194:197], v[0:3]
	s_setprio 0
	s_add_i32 s62, 0, 0x18000
	v_add_u32_e32 v162, s62, v148
	s_barrier
	ds_read_b128 v[140:143], v162
	ds_read_b128 v[154:157], v162 offset:1024
	ds_read_b128 v[158:161], v162 offset:2048
	ds_read_b128 v[162:165], v162 offset:3072
	s_add_u32 s24, s24, 0x40000
	s_addc_u32 s25, s25, 0
	s_mov_b32 m0, s35
	ds_read_b128 v[166:169], v150 offset:32768
	ds_read_b128 v[170:173], v150 offset:33792
	ds_read_b128 v[174:177], v150 offset:34816
	ds_read_b128 v[178:181], v150 offset:35840
	ds_read_b128 v[182:185], v150 offset:36864
	ds_read_b128 v[186:189], v150 offset:37888
	ds_read_b128 v[190:193], v150 offset:38912
	ds_read_b128 v[194:197], v150 offset:39936
	global_load_lds_dwordx4 v128, s[24:25]
	s_mov_b32 m0, s36
	s_nop 0
	global_load_lds_dwordx4 v132, s[24:25]
	s_waitcnt lgkmcnt(8)
	s_waitcnt vmcnt(26)
	s_barrier
	s_waitcnt lgkmcnt(0)
	s_setprio 1
	s_waitcnt lgkmcnt(0)
	v_mfma_f32_16x16x32_bf16 v[124:127], v[140:143], v[166:169], v[124:127]
	v_mfma_f32_16x16x32_bf16 v[120:123], v[158:161], v[166:169], v[120:123]
	v_mfma_f32_16x16x32_bf16 v[108:111], v[140:143], v[174:177], v[108:111]
	v_mfma_f32_16x16x32_bf16 v[104:107], v[158:161], v[174:177], v[104:107]
	v_mfma_f32_16x16x32_bf16 v[92:95], v[140:143], v[182:185], v[92:95]
	v_mfma_f32_16x16x32_bf16 v[88:91], v[158:161], v[182:185], v[88:91]
	v_mfma_f32_16x16x32_bf16 v[76:79], v[140:143], v[190:193], v[76:79]
	v_mfma_f32_16x16x32_bf16 v[72:75], v[158:161], v[190:193], v[72:75]
	v_mfma_f32_16x16x32_bf16 v[124:127], v[154:157], v[170:173], v[124:127]
	v_mfma_f32_16x16x32_bf16 v[120:123], v[162:165], v[170:173], v[120:123]
	v_mfma_f32_16x16x32_bf16 v[108:111], v[154:157], v[178:181], v[108:111]
	v_mfma_f32_16x16x32_bf16 v[104:107], v[162:165], v[178:181], v[104:107]
	v_mfma_f32_16x16x32_bf16 v[92:95], v[154:157], v[186:189], v[92:95]
	v_mfma_f32_16x16x32_bf16 v[88:91], v[162:165], v[186:189], v[88:91]
	v_mfma_f32_16x16x32_bf16 v[76:79], v[154:157], v[194:197], v[76:79]
	v_mfma_f32_16x16x32_bf16 v[72:75], v[162:165], v[194:197], v[72:75]
	s_setprio 0
	s_barrier
	s_add_i32 s24, 0, 0x1c000
	s_add_i32 s25, s62, s31
	v_add_u32_e32 v214, s24, v148
	s_add_u32 s0, s4, 0x80
	s_addc_u32 s1, s5, 0
	s_mov_b32 m0, s25
	ds_read_b128 v[202:205], v214
	ds_read_b128 v[206:209], v214 offset:1024
	ds_read_b128 v[210:213], v214 offset:2048
	ds_read_b128 v[214:217], v214 offset:3072
	global_load_lds_dwordx4 v130, s[0:1]
	s_add_i32 m0, s25, 0x2000
	s_nop 0
	global_load_lds_dwordx4 v134, s[0:1]
	s_waitcnt vmcnt(10)
	s_barrier
; #define PG8_STAGE(bufoff, gbase, voff) do { _Pragma("unroll") for (int _i = 0; _i < 2; ++_i) \
;         __builtin_amdgcn_global_load_lds((const unsigned*)((const char*)(gbase) + (voff)[_i]), (LAS unsigned*)(lds + (bufoff) + ldsw + _i * 8192), 16, 0, 0); } while (0)
; #define PG8_LDA(dst, b, h) do { _Pragma("unroll") for (int m = 0; m < 4; ++m) _Pragma("unroll") for (int k = 0; k < 2; ++k) dst[m][k] = *(const LAS bf16x8*)(lds + PG8_SA(b, h) + aoff + m * 2048 + k * 1024); } while (0)
; #define PG8_MMA(ai, bj, At, Bt) do { __builtin_amdgcn_s_setprio(1); _Pragma("unroll") for (int m = 0; m < 4; ++m) _Pragma("unroll") for (int n = 0; n < 2; ++n) _Pragma("unroll") for (int k = 0; k < 2; ++k) \
;         acc[ai][bj][m][n] = __builtin_amdgcn_mfma_f32_16x16x32_bf16(Bt[n][k], At[m][k], acc[ai][bj][m][n], 0, 0, 0); __builtin_amdgcn_s_setprio(0); } while (0)
; #define PG8_WAIT_V(n) asm volatile("s_waitcnt vmcnt(" #n ")" ::: "memory")
; #define PG8_WAIT_L(n) asm volatile("s_waitcnt lgkmcnt(" #n ")" ::: "memory")
; #define PG8_BAR __builtin_amdgcn_s_barrier()
; #define PG8_SCHED __builtin_amdgcn_sched_barrier(0)
; template <class Epi, class Sched>
; __device__ __forceinline__ void gemm_phase(LAS unsigned char* lds, const Gemm g, const Sched& S, const Epi& E) {
;     ...
;             PG8_BAR; PG8_WAIT_L(0); PG8_MMA(0, 1, At, B1); PG8_BAR;
;             PG8_LDA(At, 1, 1); PG8_STAGE(PG8_SA(1, 0), a3, voffA);
;             PG8_BAR; PG8_WAIT_L(0); PG8_MMA(1, 0, At, B0); PG8_BAR; PG8_SCHED;
;             PG8_STAGE(PG8_SB(1, 1), b3 + hstep, voffB);
;             PG8_WAIT_V(6); PG8_BAR; PG8_MMA(1, 1, At, B1); PG8_BAR;
;         }
	s_waitcnt lgkmcnt(0)
	s_setprio 1
	s_waitcnt lgkmcnt(0)
	v_mfma_f32_16x16x32_bf16 v[116:119], v[202:205], v[166:169], v[116:119]
	v_mfma_f32_16x16x32_bf16 v[112:115], v[210:213], v[166:169], v[112:115]
	v_mfma_f32_16x16x32_bf16 v[100:103], v[202:205], v[174:177], v[100:103]
	v_mfma_f32_16x16x32_bf16 v[96:99], v[210:213], v[174:177], v[96:99]
	v_mfma_f32_16x16x32_bf16 v[84:87], v[202:205], v[182:185], v[84:87]
	v_mfma_f32_16x16x32_bf16 v[80:83], v[210:213], v[182:185], v[80:83]
	v_mfma_f32_16x16x32_bf16 v[68:71], v[202:205], v[190:193], v[68:71]
	v_mfma_f32_16x16x32_bf16 v[64:67], v[210:213], v[190:193], v[64:67]
	v_mfma_f32_16x16x32_bf16 v[116:119], v[206:209], v[170:173], v[116:119]
	v_mfma_f32_16x16x32_bf16 v[112:115], v[214:217], v[170:173], v[112:115]
	v_mfma_f32_16x16x32_bf16 v[100:103], v[206:209], v[178:181], v[100:103]
	v_mfma_f32_16x16x32_bf16 v[96:99], v[214:217], v[178:181], v[96:99]
	v_mfma_f32_16x16x32_bf16 v[84:87], v[206:209], v[186:189], v[84:87]
	v_mfma_f32_16x16x32_bf16 v[80:83], v[214:217], v[186:189], v[80:83]
	v_mfma_f32_16x16x32_bf16 v[68:71], v[206:209], v[194:197], v[68:71]
	v_mfma_f32_16x16x32_bf16 v[64:67], v[214:217], v[194:197], v[64:67]
	s_setprio 0
	s_mov_b32 m0, s44
	s_mov_b64 s[0:1], 0x80
	v_lshl_add_u64 v[144:145], v[218:219], 0, s[0:1]
	s_barrier
	ds_read_b128 v[166:169], v150 offset:49152
	ds_read_b128 v[170:173], v150 offset:50176
	ds_read_b128 v[174:177], v150 offset:51200
	ds_read_b128 v[178:181], v150 offset:52224
	ds_read_b128 v[182:185], v150 offset:53248
	ds_read_b128 v[186:189], v150 offset:54272
	ds_read_b128 v[190:193], v150 offset:55296
	ds_read_b128 v[194:197], v150 offset:56320
	global_load_lds_dwordx4 v[144:145], off
	v_lshl_add_u64 v[144:145], v[220:221], 0, s[0:1]
	s_mov_b32 m0, s45
	s_nop 0
	global_load_lds_dwordx4 v[144:145], off
	s_barrier
	s_waitcnt lgkmcnt(0)
	s_setprio 1
	s_waitcnt lgkmcnt(0)
	v_mfma_f32_16x16x32_bf16 v[60:63], v[140:143], v[166:169], v[60:63]
	v_mfma_f32_16x16x32_bf16 v[56:59], v[158:161], v[166:169], v[56:59]
	v_mfma_f32_16x16x32_bf16 v[44:47], v[140:143], v[174:177], v[44:47]
	v_mfma_f32_16x16x32_bf16 v[40:43], v[158:161], v[174:177], v[40:43]
	v_mfma_f32_16x16x32_bf16 v[28:31], v[140:143], v[182:185], v[28:31]
	v_mfma_f32_16x16x32_bf16 v[24:27], v[158:161], v[182:185], v[24:27]
	v_mfma_f32_16x16x32_bf16 v[12:15], v[140:143], v[190:193], v[12:15]
	v_mfma_f32_16x16x32_bf16 v[8:11], v[158:161], v[190:193], v[8:11]
	v_mfma_f32_16x16x32_bf16 v[60:63], v[154:157], v[170:173], v[60:63]
	v_mfma_f32_16x16x32_bf16 v[56:59], v[162:165], v[170:173], v[56:59]
	v_mfma_f32_16x16x32_bf16 v[44:47], v[154:157], v[178:181], v[44:47]
	v_mfma_f32_16x16x32_bf16 v[40:43], v[162:165], v[178:181], v[40:43]
	v_mfma_f32_16x16x32_bf16 v[28:31], v[154:157], v[186:189], v[28:31]
	v_mfma_f32_16x16x32_bf16 v[24:27], v[162:165], v[186:189], v[24:27]
	v_mfma_f32_16x16x32_bf16 v[12:15], v[154:157], v[194:197], v[12:15]
	v_mfma_f32_16x16x32_bf16 v[8:11], v[162:165], v[194:197], v[8:11]
	s_setprio 0
	s_barrier
	s_add_u32 s4, s4, 0x40080
	s_addc_u32 s5, s5, 0
	s_add_i32 s24, s24, s31
	s_mov_b32 m0, s24
	s_nop 0
	global_load_lds_dwordx4 v130, s[4:5]
	s_add_i32 m0, s24, 0x2000
	s_nop 0
	global_load_lds_dwordx4 v134, s[4:5]
	s_waitcnt vmcnt(10)
	s_barrier
	s_setprio 1
	v_mfma_f32_16x16x32_bf16 v[52:55], v[202:205], v[166:169], v[52:55]
	v_mfma_f32_16x16x32_bf16 v[48:51], v[210:213], v[166:169], v[48:51]
	v_mfma_f32_16x16x32_bf16 v[36:39], v[202:205], v[174:177], v[36:39]
	v_mfma_f32_16x16x32_bf16 v[32:35], v[210:213], v[174:177], v[32:35]
	v_mfma_f32_16x16x32_bf16 v[20:23], v[202:205], v[182:185], v[20:23]
	v_mfma_f32_16x16x32_bf16 v[16:19], v[210:213], v[182:185], v[16:19]
	v_mfma_f32_16x16x32_bf16 v[4:7], v[202:205], v[190:193], v[4:7]
	v_mfma_f32_16x16x32_bf16 v[0:3], v[210:213], v[190:193], v[0:3]
	v_mfma_f32_16x16x32_bf16 v[52:55], v[206:209], v[170:173], v[52:55]
	v_mfma_f32_16x16x32_bf16 v[48:51], v[214:217], v[170:173], v[48:51]
	v_mfma_f32_16x16x32_bf16 v[36:39], v[206:209], v[178:181], v[36:39]
	v_mfma_f32_16x16x32_bf16 v[32:35], v[214:217], v[178:181], v[32:35]
	v_mfma_f32_16x16x32_bf16 v[20:23], v[206:209], v[186:189], v[20:23]
	v_mfma_f32_16x16x32_bf16 v[16:19], v[214:217], v[186:189], v[16:19]
	v_mfma_f32_16x16x32_bf16 v[4:7], v[206:209], v[194:197], v[4:7]
	v_mfma_f32_16x16x32_bf16 v[0:3], v[214:217], v[194:197], v[0:3]
	s_setprio 0
	s_add_i32 s61, s61, 2
	s_add_u32 s2, s2, 0x100
	s_addc_u32 s3, s3, 0
	s_add_u32 s59, s59, 0x100
	s_addc_u32 s60, s60, 0
	s_cmp_gt_u32 s61, 13
	s_barrier

; #define PG8_STAGE(bufoff, gbase, voff) do { _Pragma("unroll") for (int _i = 0; _i < 2; ++_i) \
;         __builtin_amdgcn_global_load_lds((const unsigned*)((const char*)(gbase) + (voff)[_i]), (LAS unsigned*)(lds + (bufoff) + ldsw + _i * 8192), 16, 0, 0); } while (0)
; #define PG8_WAIT_V(n) asm volatile("s_waitcnt vmcnt(" #n ")" ::: "memory")
; #define PG8_BAR __builtin_amdgcn_s_barrier()
; template <class Epi, class Sched>
; __device__ __forceinline__ void gemm_phase(LAS unsigned char* lds, const Gemm g, const Sched& S, const Epi& E) {
;     ...
;     for (int i = 0; i < 2; ++i) { int R, C; stage_rc(tid * 16 + i * 8192, R, C); const int Rb = Epi::PERM ? ((R & ~31) + perm32(R & 31)) : R;
;         voffA[i] = (unsigned)(R * K + C) * 2u; voffB[i] = (unsigned)(Rb * K + C) * 2u; }
;     const size_t kstep = (size_t)(BK * 2);
;     const size_t hstep = (size_t)HALF * K * 2;
;     const size_t tstep = 2 * hstep;
;     const unsigned ldsw = (unsigned)wid * 1024u;
;     const int aoff = lds_byte(wr * 64 + fr, fq * 8), boff = lds_byte(wc * 32 + fr, fq * 8);
;     ...
;     PG8_WAIT_V(4); PG8_BAR;
;     PG8_STAGE(PG8_SB(1, 0), cB + kstep, voffB); PG8_STAGE(PG8_SA(1, 0), cA + kstep, voffA); PG8_STAGE(PG8_SB(1, 1), cB + hstep + kstep, voffB);
;     PG8_WAIT_V(6); PG8_BAR;
.LBB0_705:
	s_lshl_b32 s41, s0, 6
	s_lshl_b32 s3, s0, 13
	s_lshl_b32 s0, s1, 5
	s_and_b32 s42, s0, 0x60
	s_mov_b64 s[0:1], 0x80
	s_add_i32 m0, s21, 0x18000
	v_lshl_add_u64 v[6:7], v[6:7], 0, s[0:1]
	s_lshl_b32 s6, s42, 7
	s_waitcnt vmcnt(4)
	s_barrier
	global_load_lds_dwordx4 v[6:7], off
	v_lshl_add_u64 v[4:5], v[4:5], 0, s[0:1]
	s_add_i32 m0, s21, 0x1a000
	s_add_i32 s43, s21, 0x8000
	s_add_i32 s44, s21, 0xa000
	global_load_lds_dwordx4 v[4:5], off
	v_lshl_add_u64 v[0:1], v[0:1], 0, s[0:1]
	s_mov_b32 m0, s43
	s_add_u32 s4, s24, 0x40080
	global_load_lds_dwordx4 v[0:1], off
	v_lshl_add_u64 v[0:1], v[2:3], 0, s[0:1]
	s_mov_b32 m0, s44
	s_addc_u32 s5, s25, 0
	global_load_lds_dwordx4 v[0:1], off
	s_add_i32 m0, s21, 0x1c000
	v_lshl_add_u64 v[0:1], s[4:5], 0, v[130:131]
	global_load_lds_dwordx4 v[0:1], off
	v_lshl_add_u64 v[0:1], s[4:5], 0, v[134:135]
	s_add_i32 m0, s21, 0x1e000
	v_bfe_u32 v141, v8, 4, 2
	global_load_lds_dwordx4 v[0:1], off
	v_and_b32_e32 v140, 15, v8
	v_lshlrev_b32_e32 v0, 4, v141
	v_lshlrev_b32_e32 v1, 2, v8
	v_lshl_or_b32 v0, v140, 6, v0
	v_and_b32_e32 v1, 32, v1
	v_bitop3_b32 v2, v0, s3, v1 bitop3:0xde
	v_bitop3_b32 v142, v0, s6, v1 bitop3:0xde
	v_lshlrev_b32_e32 v0, 14, v9
	v_and_b32_e32 v0, 0xffff8000, v0
	v_lshl_add_u32 v0, v10, 11, v0
	v_and_b32_e32 v1, 1, v9
	v_lshl_or_b32 v0, v1, 6, v0
	v_lshl_add_u32 v136, v11, 1, v0
	v_lshlrev_b32_e32 v0, 14, v12
	v_and_b32_e32 v0, 0xffff8000, v0
	s_waitcnt vmcnt(0)
	v_lshl_add_u32 v0, v13, 11, v0
	v_and_b32_e32 v1, 1, v12
	v_lshl_or_b32 v0, v1, 6, v0
	s_add_i32 s46, 0, 0x10000
	s_add_i32 s47, 0, 0x14000
	s_sext_i32_i16 s53, s2
	s_ashr_i32 s45, s76, 31
	v_mov_b32_e32 v137, v131
	v_lshl_add_u32 v138, v14, 1, v0
	v_mov_b32_e32 v139, v131
	v_add_u32_e32 v143, s46, v142
	v_add_u32_e32 v144, 0, v2
	v_add_u32_e32 v145, s47, v142
	s_mov_b32 s48, 0xc0000
	s_mov_b64 s[2:3], 0x200000
	s_mov_b32 s49, 0x200000
	s_mov_b64 s[4:5], 0x240000
	s_mov_b32 s50, 0x240000
	s_mov_b64 s[6:7], 0x280000
	s_mov_b32 s51, 0x280000
	s_mov_b64 s[8:9], 0x2c0000
	s_mov_b32 s52, 0x2c0000
	s_barrier

; #define PG8_STAGE(bufoff, gbase, voff) do { _Pragma("unroll") for (int _i = 0; _i < 2; ++_i) \
;         __builtin_amdgcn_global_load_lds((const unsigned*)((const char*)(gbase) + (voff)[_i]), (LAS unsigned*)(lds + (bufoff) + ldsw + _i * 8192), 16, 0, 0); } while (0)
; #define PG8_LDA(dst, b, h) do { _Pragma("unroll") for (int m = 0; m < 4; ++m) _Pragma("unroll") for (int k = 0; k < 2; ++k) dst[m][k] = *(const LAS bf16x8*)(lds + PG8_SA(b, h) + aoff + m * 2048 + k * 1024); } while (0)
; #define PG8_LDB(dst, b, h) do { _Pragma("unroll") for (int n = 0; n < 2; ++n) _Pragma("unroll") for (int k = 0; k < 2; ++k) dst[n][k] = *(const LAS bf16x8*)(lds + PG8_SB(b, h) + boff + n * 2048 + k * 1024); } while (0)
; #define PG8_MMA(ai, bj, At, Bt) do { __builtin_amdgcn_s_setprio(1); _Pragma("unroll") for (int m = 0; m < 4; ++m) _Pragma("unroll") for (int n = 0; n < 2; ++n) _Pragma("unroll") for (int k = 0; k < 2; ++k) \
;         acc[ai][bj][m][n] = __builtin_amdgcn_mfma_f32_16x16x32_bf16(Bt[n][k], At[m][k], acc[ai][bj][m][n], 0, 0, 0); __builtin_amdgcn_s_setprio(0); } while (0)
; #define PG8_WAIT_L(n) asm volatile("s_waitcnt lgkmcnt(" #n ")" ::: "memory")
; template <class Epi, class Sched>
; __device__ __forceinline__ void gemm_phase(LAS unsigned char* lds, const Gemm g, const Sched& S, const Epi& E) {
;     ...
;         const bool has_next = S.next(ui + 1, nxt);
;         const char* nA = has_next ? (const char*)g.A + (size_t)nxt.pm * tstep : cA; const char* nB = has_next ? (const char*)g.Bt + (size_t)nxt.pn * tstep : cB;
;         for (int t = 0; t < nt; t += 2) {
;             const bool last = (t == nt - 2);
;             const char* a1 = cA + (size_t)(t + 1) * kstep;
;             const char* a2 = last ? nA : cA + (size_t)(t + 2) * kstep; const char* b2 = last ? nB : cB + (size_t)(t + 2) * kstep;
;             const char* a3 = a2 + kstep; const char* b3 = b2 + kstep;
;             PG8_LDB(B0, 0, 0); PG8_SCHED; PG8_LDA(At, 0, 0); PG8_STAGE(PG8_SA(1, 1), a1 + hstep, voffA);
;             PG8_WAIT_L(8); PG8_BAR; PG8_WAIT_L(0); PG8_MMA(0, 0, At, B0); PG8_BAR; PG8_SCHED;
;             PG8_LDB(B1, 0, 1); PG8_STAGE(PG8_SB(0, 0), b2, voffB);
;             PG8_BAR; PG8_WAIT_L(0); PG8_MMA(0, 1, At, B1); PG8_BAR;
;             PG8_LDA(At, 0, 1); PG8_STAGE(PG8_SA(0, 0), a2, voffA);
;             PG8_BAR; PG8_WAIT_L(0); PG8_MMA(1, 0, At, B0); PG8_BAR; PG8_SCHED;
.LBB0_712:
	s_ashr_i32 s15, s14, 31
	v_cmp_lt_i64_e64 s[26:27], s[16:17], 64
	s_lshl_b64 s[16:17], s[14:15], 19
	s_add_u32 s16, s38, s16
	s_addc_u32 s17, s39, s17
	s_and_b64 s[18:19], s[26:27], exec
	s_cselect_b32 s15, s17, s23
	s_cselect_b32 s54, s16, s22
	s_ashr_i32 s13, s12, 31
	s_lshl_b64 s[18:19], s[12:13], 19
	s_add_u32 s18, s28, s18
	s_addc_u32 s19, s29, s19
	s_and_b64 s[26:27], s[26:27], exec
	s_cselect_b32 s13, s19, s25
	s_cselect_b32 s55, s18, s24
	s_add_u32 s22, s22, 0x40080
	s_addc_u32 s23, s23, 0
	s_add_u32 s56, s24, 0x100
	s_addc_u32 s57, s25, 0
	s_mov_b32 s58, -2
	s_waitcnt lgkmcnt(0)
	ds_read_b128 v[146:149], v143
	ds_read_b128 v[150:153], v143 offset:1024
	ds_read_b128 v[154:157], v143 offset:2048
	ds_read_b128 v[158:161], v143 offset:3072
	s_add_u32 s24, s22, 0xfffc0080
	s_addc_u32 s25, s23, -1
	s_cmp_eq_u32 s58, 12
	s_cselect_b32 s27, s15, s25
	s_cselect_b32 s26, s54, s24
	s_cselect_b32 s25, s13, s57
	s_cselect_b32 s24, s55, s56
	s_add_i32 m0, s21, 0xc000
	ds_read_b128 v[162:165], v144
	ds_read_b128 v[166:169], v144 offset:1024
	ds_read_b128 v[170:173], v144 offset:2048
	ds_read_b128 v[174:177], v144 offset:3072
	ds_read_b128 v[178:181], v144 offset:4096
	ds_read_b128 v[182:185], v144 offset:5120
	ds_read_b128 v[186:189], v144 offset:6144
	ds_read_b128 v[190:193], v144 offset:7168
	global_load_lds_dwordx4 v136, s[22:23]
	s_add_i32 m0, s21, 0xe000
	s_nop 0
	global_load_lds_dwordx4 v138, s[22:23]
	s_waitcnt lgkmcnt(8)
	s_waitcnt vmcnt(26)
	s_barrier
	s_waitcnt lgkmcnt(0)
	s_setprio 1
	s_waitcnt lgkmcnt(0)
	v_mfma_f32_16x16x32_bf16 v[124:127], v[146:149], v[162:165], 0
	v_mfma_f32_16x16x32_bf16 v[120:123], v[154:157], v[162:165], 0
	v_mfma_f32_16x16x32_bf16 v[116:119], v[146:149], v[170:173], 0
	v_mfma_f32_16x16x32_bf16 v[108:111], v[154:157], v[170:173], 0
	v_mfma_f32_16x16x32_bf16 v[100:103], v[146:149], v[178:181], 0
	v_mfma_f32_16x16x32_bf16 v[92:95], v[154:157], v[178:181], 0
	v_mfma_f32_16x16x32_bf16 v[84:87], v[146:149], v[186:189], 0
	v_mfma_f32_16x16x32_bf16 v[76:79], v[154:157], v[186:189], 0
	v_mfma_f32_16x16x32_bf16 v[124:127], v[150:153], v[166:169], v[124:127]
	v_mfma_f32_16x16x32_bf16 v[120:123], v[158:161], v[166:169], v[120:123]
	v_mfma_f32_16x16x32_bf16 v[116:119], v[150:153], v[174:177], v[116:119]
	v_mfma_f32_16x16x32_bf16 v[108:111], v[158:161], v[174:177], v[108:111]
	v_mfma_f32_16x16x32_bf16 v[100:103], v[150:153], v[182:185], v[100:103]
	v_mfma_f32_16x16x32_bf16 v[92:95], v[158:161], v[182:185], v[92:95]
	v_mfma_f32_16x16x32_bf16 v[84:87], v[150:153], v[190:193], v[84:87]
	v_mfma_f32_16x16x32_bf16 v[76:79], v[158:161], v[190:193], v[76:79]
	s_setprio 0
	s_barrier
	s_add_i32 s59, s46, s34
	s_mov_b32 m0, s59
	ds_read_b128 v[194:197], v145
	ds_read_b128 v[202:205], v145 offset:1024
	ds_read_b128 v[206:209], v145 offset:2048
	ds_read_b128 v[210:213], v145 offset:3072
	global_load_lds_dwordx4 v130, s[24:25]
	s_add_i32 m0, s59, 0x2000
	s_nop 0
	global_load_lds_dwordx4 v134, s[24:25]
	s_waitcnt vmcnt(26)
	s_barrier
	s_waitcnt lgkmcnt(0)
	s_setprio 1
	s_waitcnt lgkmcnt(0)
	v_mfma_f32_16x16x32_bf16 v[112:115], v[194:197], v[162:165], 0
	v_mfma_f32_16x16x32_bf16 v[104:107], v[206:209], v[162:165], 0
	v_mfma_f32_16x16x32_bf16 v[96:99], v[194:197], v[170:173], 0
	v_mfma_f32_16x16x32_bf16 v[88:91], v[206:209], v[170:173], 0
	v_mfma_f32_16x16x32_bf16 v[80:83], v[194:197], v[178:181], 0
	v_mfma_f32_16x16x32_bf16 v[72:75], v[206:209], v[178:181], 0
	v_mfma_f32_16x16x32_bf16 v[68:71], v[194:197], v[186:189], 0
	v_mfma_f32_16x16x32_bf16 v[64:67], v[206:209], v[186:189], 0
	v_mfma_f32_16x16x32_bf16 v[112:115], v[202:205], v[166:169], v[112:115]
	v_mfma_f32_16x16x32_bf16 v[104:107], v[210:213], v[166:169], v[104:107]
	v_mfma_f32_16x16x32_bf16 v[96:99], v[202:205], v[174:177], v[96:99]
	v_mfma_f32_16x16x32_bf16 v[88:91], v[210:213], v[174:177], v[88:91]
	v_mfma_f32_16x16x32_bf16 v[80:83], v[202:205], v[182:185], v[80:83]
	v_mfma_f32_16x16x32_bf16 v[72:75], v[210:213], v[182:185], v[72:75]
	v_mfma_f32_16x16x32_bf16 v[68:71], v[202:205], v[190:193], v[68:71]
	v_mfma_f32_16x16x32_bf16 v[64:67], v[210:213], v[190:193], v[64:67]
	s_setprio 0
	s_mov_b32 m0, s21
	v_lshl_add_u64 v[216:217], s[26:27], 0, v[128:129]
	s_barrier
	ds_read_b128 v[162:165], v144 offset:16384
	ds_read_b128 v[166:169], v144 offset:17408
	ds_read_b128 v[170:173], v144 offset:18432
	ds_read_b128 v[174:177], v144 offset:19456
	ds_read_b128 v[178:181], v144 offset:20480
	ds_read_b128 v[182:185], v144 offset:21504
	ds_read_b128 v[186:189], v144 offset:22528
	ds_read_b128 v[190:193], v144 offset:23552
	global_load_lds_dwordx4 v128, s[26:27]
	v_lshl_add_u64 v[218:219], s[26:27], 0, v[132:133]
	s_mov_b32 m0, s35
	s_nop 0
	global_load_lds_dwordx4 v132, s[26:27]
	s_barrier
	s_waitcnt lgkmcnt(0)
	s_setprio 1
	s_waitcnt lgkmcnt(0)
	v_mfma_f32_16x16x32_bf16 v[60:63], v[146:149], v[162:165], 0
	v_mfma_f32_16x16x32_bf16 v[56:59], v[154:157], v[162:165], 0
	v_mfma_f32_16x16x32_bf16 v[52:55], v[146:149], v[170:173], 0
	v_mfma_f32_16x16x32_bf16 v[44:47], v[154:157], v[170:173], 0
	v_mfma_f32_16x16x32_bf16 v[36:39], v[146:149], v[178:181], 0
	v_mfma_f32_16x16x32_bf16 v[28:31], v[154:157], v[178:181], 0
	v_mfma_f32_16x16x32_bf16 v[20:23], v[146:149], v[186:189], 0
	v_mfma_f32_16x16x32_bf16 v[12:15], v[154:157], v[186:189], 0
	v_mfma_f32_16x16x32_bf16 v[60:63], v[150:153], v[166:169], v[60:63]
	v_mfma_f32_16x16x32_bf16 v[56:59], v[158:161], v[166:169], v[56:59]
	v_mfma_f32_16x16x32_bf16 v[52:55], v[150:153], v[174:177], v[52:55]
	v_mfma_f32_16x16x32_bf16 v[44:47], v[158:161], v[174:177], v[44:47]
	v_mfma_f32_16x16x32_bf16 v[36:39], v[150:153], v[182:185], v[36:39]
	v_mfma_f32_16x16x32_bf16 v[28:31], v[158:161], v[182:185], v[28:31]
	v_mfma_f32_16x16x32_bf16 v[20:23], v[150:153], v[190:193], v[20:23]
	v_mfma_f32_16x16x32_bf16 v[12:15], v[158:161], v[190:193], v[12:15]
	s_setprio 0
	s_barrier
; #define PG8_STAGE(bufoff, gbase, voff) do { _Pragma("unroll") for (int _i = 0; _i < 2; ++_i) \
;         __builtin_amdgcn_global_load_lds((const unsigned*)((const char*)(gbase) + (voff)[_i]), (LAS unsigned*)(lds + (bufoff) + ldsw + _i * 8192), 16, 0, 0); } while (0)
; #define PG8_LDA(dst, b, h) do { _Pragma("unroll") for (int m = 0; m < 4; ++m) _Pragma("unroll") for (int k = 0; k < 2; ++k) dst[m][k] = *(const LAS bf16x8*)(lds + PG8_SA(b, h) + aoff + m * 2048 + k * 1024); } while (0)
; #define PG8_LDB(dst, b, h) do { _Pragma("unroll") for (int n = 0; n < 2; ++n) _Pragma("unroll") for (int k = 0; k < 2; ++k) dst[n][k] = *(const LAS bf16x8*)(lds + PG8_SB(b, h) + boff + n * 2048 + k * 1024); } while (0)
; #define PG8_MMA(ai, bj, At, Bt) do { __builtin_amdgcn_s_setprio(1); _Pragma("unroll") for (int m = 0; m < 4; ++m) _Pragma("unroll") for (int n = 0; n < 2; ++n) _Pragma("unroll") for (int k = 0; k < 2; ++k) \
;         acc[ai][bj][m][n] = __builtin_amdgcn_mfma_f32_16x16x32_bf16(Bt[n][k], At[m][k], acc[ai][bj][m][n], 0, 0, 0); __builtin_amdgcn_s_setprio(0); } while (0)
; #define PG8_WAIT_V(n) asm volatile("s_waitcnt vmcnt(" #n ")" ::: "memory")
; #define PG8_WAIT_L(n) asm volatile("s_waitcnt lgkmcnt(" #n ")" ::: "memory")
; #define PG8_BAR __builtin_amdgcn_s_barrier()
; #define PG8_SCHED __builtin_amdgcn_sched_barrier(0)
; template <class Epi, class Sched>
; __device__ __forceinline__ void gemm_phase(LAS unsigned char* lds, const Gemm g, const Sched& S, const Epi& E) {
;     ...
;             PG8_STAGE(PG8_SB(0, 1), b2 + hstep, voffB);
;             PG8_WAIT_V(6); PG8_BAR; PG8_MMA(1, 1, At, B1); PG8_BAR;
;             PG8_LDB(B0, 1, 0); PG8_SCHED; PG8_LDA(At, 1, 0); PG8_STAGE(PG8_SA(0, 1), a2 + hstep, voffA);
;             PG8_WAIT_L(8); PG8_BAR; PG8_WAIT_L(0); PG8_MMA(0, 0, At, B0); PG8_BAR; PG8_SCHED;
;             PG8_LDB(B1, 1, 1); PG8_STAGE(PG8_SB(1, 0), b3, voffB);
;             PG8_BAR; PG8_WAIT_L(0); PG8_MMA(0, 1, At, B1); PG8_BAR;
	s_add_u32 s60, s24, 0x40000
	s_addc_u32 s61, s25, 0
	s_add_i32 s59, s47, s34
	s_mov_b32 m0, s59
	s_nop 0
	global_load_lds_dwordx4 v130, s[60:61]
	s_add_i32 m0, s59, 0x2000
	s_nop 0
	global_load_lds_dwordx4 v134, s[60:61]
	s_waitcnt vmcnt(26)
	s_barrier
	s_setprio 1
	v_mfma_f32_16x16x32_bf16 v[48:51], v[194:197], v[162:165], 0
	v_mfma_f32_16x16x32_bf16 v[40:43], v[206:209], v[162:165], 0
	v_mfma_f32_16x16x32_bf16 v[32:35], v[194:197], v[170:173], 0
	v_mfma_f32_16x16x32_bf16 v[24:27], v[206:209], v[170:173], 0
	v_mfma_f32_16x16x32_bf16 v[16:19], v[194:197], v[178:181], 0
	v_mfma_f32_16x16x32_bf16 v[8:11], v[206:209], v[178:181], 0
	v_mfma_f32_16x16x32_bf16 v[4:7], v[194:197], v[186:189], 0
	v_mfma_f32_16x16x32_bf16 v[0:3], v[206:209], v[186:189], 0
	v_mfma_f32_16x16x32_bf16 v[48:51], v[202:205], v[166:169], v[48:51]
	v_mfma_f32_16x16x32_bf16 v[40:43], v[210:213], v[166:169], v[40:43]
	v_mfma_f32_16x16x32_bf16 v[32:35], v[202:205], v[174:177], v[32:35]
	v_mfma_f32_16x16x32_bf16 v[24:27], v[210:213], v[174:177], v[24:27]
	v_mfma_f32_16x16x32_bf16 v[16:19], v[202:205], v[182:185], v[16:19]
	v_mfma_f32_16x16x32_bf16 v[8:11], v[210:213], v[182:185], v[8:11]
	v_mfma_f32_16x16x32_bf16 v[4:7], v[202:205], v[190:193], v[4:7]
	v_mfma_f32_16x16x32_bf16 v[0:3], v[210:213], v[190:193], v[0:3]
	s_setprio 0
	s_add_i32 s59, 0, 0x18000
	v_add_u32_e32 v158, s59, v142
	s_barrier
	ds_read_b128 v[146:149], v158
	ds_read_b128 v[150:153], v158 offset:1024
	ds_read_b128 v[154:157], v158 offset:2048
	ds_read_b128 v[158:161], v158 offset:3072
	s_add_u32 s26, s26, 0x40000
	s_addc_u32 s27, s27, 0
	s_mov_b32 m0, s36
	ds_read_b128 v[162:165], v144 offset:32768
	ds_read_b128 v[166:169], v144 offset:33792
	ds_read_b128 v[170:173], v144 offset:34816
	ds_read_b128 v[174:177], v144 offset:35840
	ds_read_b128 v[178:181], v144 offset:36864
	ds_read_b128 v[182:185], v144 offset:37888
	ds_read_b128 v[186:189], v144 offset:38912
	ds_read_b128 v[190:193], v144 offset:39936
	global_load_lds_dwordx4 v128, s[26:27]
	s_mov_b32 m0, s37
	s_nop 0
	global_load_lds_dwordx4 v132, s[26:27]
	s_waitcnt lgkmcnt(8)
	s_waitcnt vmcnt(26)
	s_barrier
	s_waitcnt lgkmcnt(0)
	s_setprio 1
	s_waitcnt lgkmcnt(0)
	v_mfma_f32_16x16x32_bf16 v[124:127], v[146:149], v[162:165], v[124:127]
	v_mfma_f32_16x16x32_bf16 v[120:123], v[154:157], v[162:165], v[120:123]
	v_mfma_f32_16x16x32_bf16 v[116:119], v[146:149], v[170:173], v[116:119]
	v_mfma_f32_16x16x32_bf16 v[108:111], v[154:157], v[170:173], v[108:111]
	v_mfma_f32_16x16x32_bf16 v[100:103], v[146:149], v[178:181], v[100:103]
	v_mfma_f32_16x16x32_bf16 v[92:95], v[154:157], v[178:181], v[92:95]
	v_mfma_f32_16x16x32_bf16 v[84:87], v[146:149], v[186:189], v[84:87]
	v_mfma_f32_16x16x32_bf16 v[76:79], v[154:157], v[186:189], v[76:79]
	v_mfma_f32_16x16x32_bf16 v[124:127], v[150:153], v[166:169], v[124:127]
	v_mfma_f32_16x16x32_bf16 v[120:123], v[158:161], v[166:169], v[120:123]
	v_mfma_f32_16x16x32_bf16 v[116:119], v[150:153], v[174:177], v[116:119]
	v_mfma_f32_16x16x32_bf16 v[108:111], v[158:161], v[174:177], v[108:111]
	v_mfma_f32_16x16x32_bf16 v[100:103], v[150:153], v[182:185], v[100:103]
	v_mfma_f32_16x16x32_bf16 v[92:95], v[158:161], v[182:185], v[92:95]
	v_mfma_f32_16x16x32_bf16 v[84:87], v[150:153], v[190:193], v[84:87]
	v_mfma_f32_16x16x32_bf16 v[76:79], v[158:161], v[190:193], v[76:79]
	s_setprio 0
	s_barrier
	s_add_i32 s26, 0, 0x1c000
	s_add_i32 s27, s59, s34
	v_add_u32_e32 v210, s26, v142
	s_add_u32 s0, s24, 0x80
	s_addc_u32 s1, s25, 0
	s_mov_b32 m0, s27
	ds_read_b128 v[194:197], v210
	ds_read_b128 v[202:205], v210 offset:1024
	ds_read_b128 v[206:209], v210 offset:2048
	ds_read_b128 v[210:213], v210 offset:3072
	global_load_lds_dwordx4 v130, s[0:1]
	s_add_i32 m0, s27, 0x2000
	s_nop 0
	global_load_lds_dwordx4 v134, s[0:1]
	s_waitcnt vmcnt(10)
	s_barrier
; #define PG8_STAGE(bufoff, gbase, voff) do { _Pragma("unroll") for (int _i = 0; _i < 2; ++_i) \
;         __builtin_amdgcn_global_load_lds((const unsigned*)((const char*)(gbase) + (voff)[_i]), (LAS unsigned*)(lds + (bufoff) + ldsw + _i * 8192), 16, 0, 0); } while (0)
; #define PG8_LDA(dst, b, h) do { _Pragma("unroll") for (int m = 0; m < 4; ++m) _Pragma("unroll") for (int k = 0; k < 2; ++k) dst[m][k] = *(const LAS bf16x8*)(lds + PG8_SA(b, h) + aoff + m * 2048 + k * 1024); } while (0)
; #define PG8_MMA(ai, bj, At, Bt) do { __builtin_amdgcn_s_setprio(1); _Pragma("unroll") for (int m = 0; m < 4; ++m) _Pragma("unroll") for (int n = 0; n < 2; ++n) _Pragma("unroll") for (int k = 0; k < 2; ++k) \
;         acc[ai][bj][m][n] = __builtin_amdgcn_mfma_f32_16x16x32_bf16(Bt[n][k], At[m][k], acc[ai][bj][m][n], 0, 0, 0); __builtin_amdgcn_s_setprio(0); } while (0)
; #define PG8_WAIT_V(n) asm volatile("s_waitcnt vmcnt(" #n ")" ::: "memory")
; #define PG8_WAIT_L(n) asm volatile("s_waitcnt lgkmcnt(" #n ")" ::: "memory")
; #define PG8_BAR __builtin_amdgcn_s_barrier()
; #define PG8_SCHED __builtin_amdgcn_sched_barrier(0)
; template <class Epi, class Sched>
; __device__ __forceinline__ void gemm_phase(LAS unsigned char* lds, const Gemm g, const Sched& S, const Epi& E) {
;     ...
;             PG8_BAR; PG8_WAIT_L(0); PG8_MMA(0, 1, At, B1); PG8_BAR;
;             PG8_LDA(At, 1, 1); PG8_STAGE(PG8_SA(1, 0), a3, voffA);
;             PG8_BAR; PG8_WAIT_L(0); PG8_MMA(1, 0, At, B0); PG8_BAR; PG8_SCHED;
;             PG8_STAGE(PG8_SB(1, 1), b3 + hstep, voffB);
;             PG8_WAIT_V(6); PG8_BAR; PG8_MMA(1, 1, At, B1); PG8_BAR;
;         }
	s_waitcnt lgkmcnt(0)
	s_setprio 1
	s_waitcnt lgkmcnt(0)
	v_mfma_f32_16x16x32_bf16 v[112:115], v[194:197], v[162:165], v[112:115]
	v_mfma_f32_16x16x32_bf16 v[104:107], v[206:209], v[162:165], v[104:107]
	v_mfma_f32_16x16x32_bf16 v[96:99], v[194:197], v[170:173], v[96:99]
	v_mfma_f32_16x16x32_bf16 v[88:91], v[206:209], v[170:173], v[88:91]
	v_mfma_f32_16x16x32_bf16 v[80:83], v[194:197], v[178:181], v[80:83]
	v_mfma_f32_16x16x32_bf16 v[72:75], v[206:209], v[178:181], v[72:75]
	v_mfma_f32_16x16x32_bf16 v[68:71], v[194:197], v[186:189], v[68:71]
	v_mfma_f32_16x16x32_bf16 v[64:67], v[206:209], v[186:189], v[64:67]
	v_mfma_f32_16x16x32_bf16 v[112:115], v[202:205], v[166:169], v[112:115]
	v_mfma_f32_16x16x32_bf16 v[104:107], v[210:213], v[166:169], v[104:107]
	v_mfma_f32_16x16x32_bf16 v[96:99], v[202:205], v[174:177], v[96:99]
	v_mfma_f32_16x16x32_bf16 v[88:91], v[210:213], v[174:177], v[88:91]
	v_mfma_f32_16x16x32_bf16 v[80:83], v[202:205], v[182:185], v[80:83]
	v_mfma_f32_16x16x32_bf16 v[72:75], v[210:213], v[182:185], v[72:75]
	v_mfma_f32_16x16x32_bf16 v[68:71], v[202:205], v[190:193], v[68:71]
	v_mfma_f32_16x16x32_bf16 v[64:67], v[210:213], v[190:193], v[64:67]
	s_setprio 0
	s_mov_b32 m0, s43
	s_mov_b64 s[0:1], 0x80
	v_lshl_add_u64 v[198:199], v[216:217], 0, s[0:1]
	s_barrier
	ds_read_b128 v[162:165], v144 offset:49152
	ds_read_b128 v[166:169], v144 offset:50176
	ds_read_b128 v[170:173], v144 offset:51200
	ds_read_b128 v[174:177], v144 offset:52224
	ds_read_b128 v[178:181], v144 offset:53248
	ds_read_b128 v[182:185], v144 offset:54272
	ds_read_b128 v[186:189], v144 offset:55296
	ds_read_b128 v[190:193], v144 offset:56320
	global_load_lds_dwordx4 v[198:199], off
	v_lshl_add_u64 v[198:199], v[218:219], 0, s[0:1]
	s_mov_b32 m0, s44
	s_nop 0
	global_load_lds_dwordx4 v[198:199], off
	s_barrier
	s_waitcnt lgkmcnt(0)
	s_setprio 1
	s_waitcnt lgkmcnt(0)
	v_mfma_f32_16x16x32_bf16 v[60:63], v[146:149], v[162:165], v[60:63]
	v_mfma_f32_16x16x32_bf16 v[56:59], v[154:157], v[162:165], v[56:59]
	v_mfma_f32_16x16x32_bf16 v[52:55], v[146:149], v[170:173], v[52:55]
	v_mfma_f32_16x16x32_bf16 v[44:47], v[154:157], v[170:173], v[44:47]
	v_mfma_f32_16x16x32_bf16 v[36:39], v[146:149], v[178:181], v[36:39]
	v_mfma_f32_16x16x32_bf16 v[28:31], v[154:157], v[178:181], v[28:31]
	v_mfma_f32_16x16x32_bf16 v[20:23], v[146:149], v[186:189], v[20:23]
	v_mfma_f32_16x16x32_bf16 v[12:15], v[154:157], v[186:189], v[12:15]
	v_mfma_f32_16x16x32_bf16 v[60:63], v[150:153], v[166:169], v[60:63]
	v_mfma_f32_16x16x32_bf16 v[56:59], v[158:161], v[166:169], v[56:59]
	v_mfma_f32_16x16x32_bf16 v[52:55], v[150:153], v[174:177], v[52:55]
	v_mfma_f32_16x16x32_bf16 v[44:47], v[158:161], v[174:177], v[44:47]
	v_mfma_f32_16x16x32_bf16 v[36:39], v[150:153], v[182:185], v[36:39]
	v_mfma_f32_16x16x32_bf16 v[28:31], v[158:161], v[182:185], v[28:31]
	v_mfma_f32_16x16x32_bf16 v[20:23], v[150:153], v[190:193], v[20:23]
	v_mfma_f32_16x16x32_bf16 v[12:15], v[158:161], v[190:193], v[12:15]
	s_setprio 0
	s_barrier
	s_add_u32 s24, s24, 0x40080
	s_addc_u32 s25, s25, 0
	s_add_i32 s26, s26, s34
	s_mov_b32 m0, s26
	s_nop 0
	global_load_lds_dwordx4 v130, s[24:25]
	s_add_i32 m0, s26, 0x2000
	s_nop 0
	global_load_lds_dwordx4 v134, s[24:25]
	s_waitcnt vmcnt(10)
	s_barrier
	s_setprio 1
	v_mfma_f32_16x16x32_bf16 v[48:51], v[194:197], v[162:165], v[48:51]
	v_mfma_f32_16x16x32_bf16 v[40:43], v[206:209], v[162:165], v[40:43]
	v_mfma_f32_16x16x32_bf16 v[32:35], v[194:197], v[170:173], v[32:35]
	v_mfma_f32_16x16x32_bf16 v[24:27], v[206:209], v[170:173], v[24:27]
	v_mfma_f32_16x16x32_bf16 v[16:19], v[194:197], v[178:181], v[16:19]
	v_mfma_f32_16x16x32_bf16 v[8:11], v[206:209], v[178:181], v[8:11]
	v_mfma_f32_16x16x32_bf16 v[4:7], v[194:197], v[186:189], v[4:7]
	v_mfma_f32_16x16x32_bf16 v[0:3], v[206:209], v[186:189], v[0:3]
	v_mfma_f32_16x16x32_bf16 v[48:51], v[202:205], v[166:169], v[48:51]
	v_mfma_f32_16x16x32_bf16 v[40:43], v[210:213], v[166:169], v[40:43]
	v_mfma_f32_16x16x32_bf16 v[32:35], v[202:205], v[174:177], v[32:35]
	v_mfma_f32_16x16x32_bf16 v[24:27], v[210:213], v[174:177], v[24:27]
	v_mfma_f32_16x16x32_bf16 v[16:19], v[202:205], v[182:185], v[16:19]
	v_mfma_f32_16x16x32_bf16 v[8:11], v[210:213], v[182:185], v[8:11]
	v_mfma_f32_16x16x32_bf16 v[4:7], v[202:205], v[190:193], v[4:7]
	v_mfma_f32_16x16x32_bf16 v[0:3], v[210:213], v[190:193], v[0:3]
	s_setprio 0
	s_add_i32 s58, s58, 2
	s_add_u32 s22, s22, 0x100
	s_addc_u32 s23, s23, 0
	s_add_u32 s56, s56, 0x100
	s_addc_u32 s57, s57, 0
	s_cmp_gt_u32 s58, 13
	s_barrier

; #define PG8_STAGE(bufoff, gbase, voff) do { _Pragma("unroll") for (int _i = 0; _i < 2; ++_i) \
;         __builtin_amdgcn_global_load_lds((const unsigned*)((const char*)(gbase) + (voff)[_i]), (LAS unsigned*)(lds + (bufoff) + ldsw + _i * 8192), 16, 0, 0); } while (0)
; #define PG8_WAIT_V(n) asm volatile("s_waitcnt vmcnt(" #n ")" ::: "memory")
; #define PG8_BAR __builtin_amdgcn_s_barrier()
; template <class Epi, class Sched>
; __device__ __forceinline__ void gemm_phase(LAS unsigned char* lds, const Gemm g, const Sched& S, const Epi& E) {
;     ...
;     for (int i = 0; i < 2; ++i) { int R, C; stage_rc(tid * 16 + i * 8192, R, C); const int Rb = Epi::PERM ? ((R & ~31) + perm32(R & 31)) : R;
;         voffA[i] = (unsigned)(R * K + C) * 2u; voffB[i] = (unsigned)(Rb * K + C) * 2u; }
;     const size_t kstep = (size_t)(BK * 2);
;     const size_t hstep = (size_t)HALF * K * 2;
;     const size_t tstep = 2 * hstep;
;     const unsigned ldsw = (unsigned)wid * 1024u;
;     const int aoff = lds_byte(wr * 64 + fr, fq * 8), boff = lds_byte(wc * 32 + fr, fq * 8);
;     ...
;     PG8_WAIT_V(4); PG8_BAR;
;     PG8_STAGE(PG8_SB(1, 0), cB + kstep, voffB); PG8_STAGE(PG8_SA(1, 0), cA + kstep, voffA); PG8_STAGE(PG8_SB(1, 1), cB + hstep + kstep, voffB);
;     PG8_WAIT_V(6); PG8_BAR;
.LBB0_818:
	s_lshl_b32 s29, s0, 6
	s_lshl_b32 s3, s0, 13
	s_lshl_b32 s0, s1, 5
	s_and_b32 s30, s0, 0x60
	s_mov_b64 s[0:1], 0x80
	s_add_i32 m0, s13, 0x18000
	v_lshl_add_u64 v[6:7], v[6:7], 0, s[0:1]
	s_lshl_b32 s6, s30, 7
	s_waitcnt vmcnt(4)
	s_barrier
	global_load_lds_dwordx4 v[6:7], off
	v_lshl_add_u64 v[4:5], v[4:5], 0, s[0:1]
	s_add_i32 m0, s13, 0x1a000
	s_add_i32 s31, s13, 0x8000
	s_add_i32 s33, s13, 0xa000
	global_load_lds_dwordx4 v[4:5], off
	v_lshl_add_u64 v[2:3], v[2:3], 0, s[0:1]
	s_mov_b32 m0, s31
	s_add_u32 s4, s16, 0x80080
	global_load_lds_dwordx4 v[2:3], off
	v_lshl_add_u64 v[0:1], v[0:1], 0, s[0:1]
	s_mov_b32 m0, s33
	s_addc_u32 s5, s17, 0
	global_load_lds_dwordx4 v[0:1], off
	s_add_i32 m0, s13, 0x1c000
	v_lshl_add_u64 v[0:1], s[4:5], 0, v[146:147]
	global_load_lds_dwordx4 v[0:1], off
	v_lshl_add_u64 v[0:1], s[4:5], 0, v[150:151]
	s_add_i32 m0, s13, 0x1e000
	v_bfe_u32 v166, v8, 4, 2
	global_load_lds_dwordx4 v[0:1], off
	v_and_b32_e32 v161, 15, v8
	v_lshlrev_b32_e32 v0, 4, v166
	v_lshlrev_b32_e32 v1, 2, v8
	v_lshl_or_b32 v0, v161, 6, v0
	v_and_b32_e32 v1, 32, v1
	v_bitop3_b32 v2, v0, s3, v1 bitop3:0xde
	v_bitop3_b32 v167, v0, s6, v1 bitop3:0xde
	v_lshlrev_b32_e32 v0, 15, v9
	v_and_b32_e32 v0, 0xffff0000, v0
	v_lshl_add_u32 v0, v10, 12, v0
	v_and_b32_e32 v1, 1, v9
	v_lshl_or_b32 v0, v1, 6, v0
	v_lshl_add_u32 v152, v11, 1, v0
	v_lshlrev_b32_e32 v0, 15, v12
	v_and_b32_e32 v0, 0xffff0000, v0
	s_waitcnt vmcnt(0)
	v_lshl_add_u32 v0, v13, 12, v0
	v_and_b32_e32 v1, 1, v12
	v_lshl_or_b32 v0, v1, 6, v0
	s_add_i32 s35, 0, 0x10000
	s_add_i32 s36, 0, 0x14000
	s_sext_i32_i16 s38, s2
	s_ashr_i32 s34, s76, 31
	v_mov_b32_e32 v153, v147
	v_lshl_add_u32 v154, v14, 1, v0
	v_mov_b32_e32 v155, v147
	v_mov_b64_e32 v[156:157], 0x200
	v_mov_b64_e32 v[158:159], 0x1ff
	v_add_u32_e32 v168, s35, v167
	v_add_u32_e32 v169, 0, v2
	v_add_u32_e32 v170, s36, v167
	s_movk_i32 s37, 0xc00
	s_barrier

; #define PG8_STAGE(bufoff, gbase, voff) do { _Pragma("unroll") for (int _i = 0; _i < 2; ++_i) \
;         __builtin_amdgcn_global_load_lds((const unsigned*)((const char*)(gbase) + (voff)[_i]), (LAS unsigned*)(lds + (bufoff) + ldsw + _i * 8192), 16, 0, 0); } while (0)
; #define PG8_LDA(dst, b, h) do { _Pragma("unroll") for (int m = 0; m < 4; ++m) _Pragma("unroll") for (int k = 0; k < 2; ++k) dst[m][k] = *(const LAS bf16x8*)(lds + PG8_SA(b, h) + aoff + m * 2048 + k * 1024); } while (0)
; #define PG8_LDB(dst, b, h) do { _Pragma("unroll") for (int n = 0; n < 2; ++n) _Pragma("unroll") for (int k = 0; k < 2; ++k) dst[n][k] = *(const LAS bf16x8*)(lds + PG8_SB(b, h) + boff + n * 2048 + k * 1024); } while (0)
; #define PG8_MMA(ai, bj, At, Bt) do { __builtin_amdgcn_s_setprio(1); _Pragma("unroll") for (int m = 0; m < 4; ++m) _Pragma("unroll") for (int n = 0; n < 2; ++n) _Pragma("unroll") for (int k = 0; k < 2; ++k) \
;         acc[ai][bj][m][n] = __builtin_amdgcn_mfma_f32_16x16x32_bf16(Bt[n][k], At[m][k], acc[ai][bj][m][n], 0, 0, 0); __builtin_amdgcn_s_setprio(0); } while (0)
; #define PG8_WAIT_L(n) asm volatile("s_waitcnt lgkmcnt(" #n ")" ::: "memory")
; template <class Epi, class Sched>
; __device__ __forceinline__ void gemm_phase(LAS unsigned char* lds, const Gemm g, const Sched& S, const Epi& E) {
;     ...
;         const bool has_next = S.next(ui + 1, nxt);
;         const char* nA = has_next ? (const char*)g.A + (size_t)nxt.pm * tstep : cA; const char* nB = has_next ? (const char*)g.Bt + (size_t)nxt.pn * tstep : cB;
;         for (int t = 0; t < nt; t += 2) {
;             const bool last = (t == nt - 2);
;             const char* a1 = cA + (size_t)(t + 1) * kstep;
;             const char* a2 = last ? nA : cA + (size_t)(t + 2) * kstep; const char* b2 = last ? nB : cB + (size_t)(t + 2) * kstep;
;             const char* a3 = a2 + kstep; const char* b3 = b2 + kstep;
;             PG8_LDB(B0, 0, 0); PG8_SCHED; PG8_LDA(At, 0, 0); PG8_STAGE(PG8_SA(1, 1), a1 + hstep, voffA);
;             PG8_WAIT_L(8); PG8_BAR; PG8_WAIT_L(0); PG8_MMA(0, 0, At, B0); PG8_BAR; PG8_SCHED;
;             PG8_LDB(B1, 0, 1); PG8_STAGE(PG8_SB(0, 0), b2, voffB);
;             PG8_BAR; PG8_WAIT_L(0); PG8_MMA(0, 1, At, B1); PG8_BAR;
;             PG8_LDA(At, 0, 1); PG8_STAGE(PG8_SA(0, 0), a2, voffA);
;             PG8_BAR; PG8_WAIT_L(0); PG8_MMA(1, 0, At, B0); PG8_BAR; PG8_SCHED;
.LBB0_825:
	s_ashr_i32 s7, s6, 31
	v_cmp_lt_i64_e32 vcc, s[8:9], v[156:157]
	s_lshl_b64 s[8:9], s[6:7], 20
	s_add_u32 s8, s22, s8
	s_addc_u32 s9, s23, s9
	s_and_b64 s[10:11], vcc, exec
	s_cselect_b32 s7, s9, s15
	s_cselect_b32 s39, s8, s14
	s_ashr_i32 s5, s4, 31
	s_lshl_b64 s[10:11], s[4:5], 20
	s_add_u32 s10, s50, s10
	s_addc_u32 s11, s51, s11
	s_and_b64 s[18:19], vcc, exec
	s_cselect_b32 s5, s11, s17
	s_cselect_b32 s40, s10, s16
	s_add_u32 s14, s14, 0x80080
	s_addc_u32 s15, s15, 0
	s_add_u32 s41, s16, 0x100
	s_addc_u32 s42, s17, 0
	s_mov_b32 s43, -2
	ds_read_b128 v[128:131], v168
	ds_read_b128 v[132:135], v168 offset:1024
	ds_read_b128 v[136:139], v168 offset:2048
	ds_read_b128 v[140:143], v168 offset:3072
	s_add_u32 s16, s14, 0xfff80080
	s_addc_u32 s17, s15, -1
	s_cmp_eq_u32 s43, 28
	s_cselect_b32 s19, s7, s17
	s_cselect_b32 s18, s39, s16
	s_cselect_b32 s17, s5, s42
	s_cselect_b32 s16, s40, s41
	s_add_i32 m0, s13, 0xc000
	ds_read_b128 v[162:165], v169
	ds_read_b128 v[172:175], v169 offset:1024
	ds_read_b128 v[176:179], v169 offset:2048
	ds_read_b128 v[180:183], v169 offset:3072
	ds_read_b128 v[184:187], v169 offset:4096
	ds_read_b128 v[188:191], v169 offset:5120
	ds_read_b128 v[192:195], v169 offset:6144
	ds_read_b128 v[196:199], v169 offset:7168
	global_load_lds_dwordx4 v152, s[14:15]
	s_add_i32 m0, s13, 0xe000
	s_nop 0
	global_load_lds_dwordx4 v154, s[14:15]
	s_waitcnt lgkmcnt(8)
	s_waitcnt vmcnt(26)
	s_barrier
	s_waitcnt lgkmcnt(0)
	s_setprio 1
	s_waitcnt lgkmcnt(0)
	v_mfma_f32_16x16x32_bf16 v[124:127], v[128:131], v[162:165], 0
	v_mfma_f32_16x16x32_bf16 v[120:123], v[136:139], v[162:165], 0
	v_mfma_f32_16x16x32_bf16 v[116:119], v[128:131], v[176:179], 0
	v_mfma_f32_16x16x32_bf16 v[112:115], v[136:139], v[176:179], 0
	v_mfma_f32_16x16x32_bf16 v[108:111], v[128:131], v[184:187], 0
	v_mfma_f32_16x16x32_bf16 v[100:103], v[136:139], v[184:187], 0
	v_mfma_f32_16x16x32_bf16 v[76:79], v[128:131], v[192:195], 0
	v_mfma_f32_16x16x32_bf16 v[72:75], v[136:139], v[192:195], 0
	v_mfma_f32_16x16x32_bf16 v[124:127], v[132:135], v[172:175], v[124:127]
	v_mfma_f32_16x16x32_bf16 v[120:123], v[140:143], v[172:175], v[120:123]
	v_mfma_f32_16x16x32_bf16 v[116:119], v[132:135], v[180:183], v[116:119]
	v_mfma_f32_16x16x32_bf16 v[112:115], v[140:143], v[180:183], v[112:115]
	v_mfma_f32_16x16x32_bf16 v[108:111], v[132:135], v[188:191], v[108:111]
	v_mfma_f32_16x16x32_bf16 v[100:103], v[140:143], v[188:191], v[100:103]
	v_mfma_f32_16x16x32_bf16 v[76:79], v[132:135], v[196:199], v[76:79]
	v_mfma_f32_16x16x32_bf16 v[72:75], v[140:143], v[196:199], v[72:75]
	s_setprio 0
	s_barrier
	s_add_i32 s44, s35, s24
	s_mov_b32 m0, s44
	ds_read_b128 v[202:205], v170
	ds_read_b128 v[206:209], v170 offset:1024
	ds_read_b128 v[210:213], v170 offset:2048
	ds_read_b128 v[214:217], v170 offset:3072
	global_load_lds_dwordx4 v146, s[16:17]
	s_add_i32 m0, s44, 0x2000
	s_nop 0
	global_load_lds_dwordx4 v150, s[16:17]
	s_waitcnt vmcnt(26)
	s_barrier
	s_waitcnt lgkmcnt(0)
	s_setprio 1
	s_waitcnt lgkmcnt(0)
	v_mfma_f32_16x16x32_bf16 v[104:107], v[202:205], v[162:165], 0
	v_mfma_f32_16x16x32_bf16 v[96:99], v[210:213], v[162:165], 0
	v_mfma_f32_16x16x32_bf16 v[92:95], v[202:205], v[176:179], 0
	v_mfma_f32_16x16x32_bf16 v[88:91], v[210:213], v[176:179], 0
	v_mfma_f32_16x16x32_bf16 v[84:87], v[202:205], v[184:187], 0
	v_mfma_f32_16x16x32_bf16 v[80:83], v[210:213], v[184:187], 0
	v_mfma_f32_16x16x32_bf16 v[68:71], v[202:205], v[192:195], 0
	v_mfma_f32_16x16x32_bf16 v[64:67], v[210:213], v[192:195], 0
	v_mfma_f32_16x16x32_bf16 v[104:107], v[206:209], v[172:175], v[104:107]
	v_mfma_f32_16x16x32_bf16 v[96:99], v[214:217], v[172:175], v[96:99]
	v_mfma_f32_16x16x32_bf16 v[92:95], v[206:209], v[180:183], v[92:95]
	v_mfma_f32_16x16x32_bf16 v[88:91], v[214:217], v[180:183], v[88:91]
	v_mfma_f32_16x16x32_bf16 v[84:87], v[206:209], v[188:191], v[84:87]
	v_mfma_f32_16x16x32_bf16 v[80:83], v[214:217], v[188:191], v[80:83]
	v_mfma_f32_16x16x32_bf16 v[68:71], v[206:209], v[196:199], v[68:71]
	v_mfma_f32_16x16x32_bf16 v[64:67], v[214:217], v[196:199], v[64:67]
	s_setprio 0
	s_mov_b32 m0, s13
	v_lshl_add_u64 v[222:223], s[18:19], 0, v[144:145]
	s_barrier
	ds_read_b128 v[162:165], v169 offset:16384
	ds_read_b128 v[172:175], v169 offset:17408
	ds_read_b128 v[176:179], v169 offset:18432
	ds_read_b128 v[180:183], v169 offset:19456
	ds_read_b128 v[184:187], v169 offset:20480
	ds_read_b128 v[188:191], v169 offset:21504
	ds_read_b128 v[192:195], v169 offset:22528
	ds_read_b128 v[196:199], v169 offset:23552
	global_load_lds_dwordx4 v144, s[18:19]
	v_lshl_add_u64 v[224:225], s[18:19], 0, v[148:149]
	s_mov_b32 m0, s25
	s_nop 0
	global_load_lds_dwordx4 v148, s[18:19]
	s_barrier
	s_waitcnt lgkmcnt(0)
	s_setprio 1
	s_waitcnt lgkmcnt(0)
	v_mfma_f32_16x16x32_bf16 v[60:63], v[128:131], v[162:165], 0
	v_mfma_f32_16x16x32_bf16 v[56:59], v[136:139], v[162:165], 0
	v_mfma_f32_16x16x32_bf16 v[48:51], v[128:131], v[176:179], 0
	v_mfma_f32_16x16x32_bf16 v[40:43], v[136:139], v[176:179], 0
	v_mfma_f32_16x16x32_bf16 v[32:35], v[128:131], v[184:187], 0
	v_mfma_f32_16x16x32_bf16 v[24:27], v[136:139], v[184:187], 0
	v_mfma_f32_16x16x32_bf16 v[16:19], v[128:131], v[192:195], 0
	v_mfma_f32_16x16x32_bf16 v[8:11], v[136:139], v[192:195], 0
	v_mfma_f32_16x16x32_bf16 v[60:63], v[132:135], v[172:175], v[60:63]
	v_mfma_f32_16x16x32_bf16 v[56:59], v[140:143], v[172:175], v[56:59]
	v_mfma_f32_16x16x32_bf16 v[48:51], v[132:135], v[180:183], v[48:51]
	v_mfma_f32_16x16x32_bf16 v[40:43], v[140:143], v[180:183], v[40:43]
	v_mfma_f32_16x16x32_bf16 v[32:35], v[132:135], v[188:191], v[32:35]
	v_mfma_f32_16x16x32_bf16 v[24:27], v[140:143], v[188:191], v[24:27]
	v_mfma_f32_16x16x32_bf16 v[16:19], v[132:135], v[196:199], v[16:19]
	v_mfma_f32_16x16x32_bf16 v[8:11], v[140:143], v[196:199], v[8:11]
	s_setprio 0
	s_barrier
; #define PG8_STAGE(bufoff, gbase, voff) do { _Pragma("unroll") for (int _i = 0; _i < 2; ++_i) \
;         __builtin_amdgcn_global_load_lds((const unsigned*)((const char*)(gbase) + (voff)[_i]), (LAS unsigned*)(lds + (bufoff) + ldsw + _i * 8192), 16, 0, 0); } while (0)
; #define PG8_LDA(dst, b, h) do { _Pragma("unroll") for (int m = 0; m < 4; ++m) _Pragma("unroll") for (int k = 0; k < 2; ++k) dst[m][k] = *(const LAS bf16x8*)(lds + PG8_SA(b, h) + aoff + m * 2048 + k * 1024); } while (0)
; #define PG8_LDB(dst, b, h) do { _Pragma("unroll") for (int n = 0; n < 2; ++n) _Pragma("unroll") for (int k = 0; k < 2; ++k) dst[n][k] = *(const LAS bf16x8*)(lds + PG8_SB(b, h) + boff + n * 2048 + k * 1024); } while (0)
; #define PG8_MMA(ai, bj, At, Bt) do { __builtin_amdgcn_s_setprio(1); _Pragma("unroll") for (int m = 0; m < 4; ++m) _Pragma("unroll") for (int n = 0; n < 2; ++n) _Pragma("unroll") for (int k = 0; k < 2; ++k) \
;         acc[ai][bj][m][n] = __builtin_amdgcn_mfma_f32_16x16x32_bf16(Bt[n][k], At[m][k], acc[ai][bj][m][n], 0, 0, 0); __builtin_amdgcn_s_setprio(0); } while (0)
; #define PG8_WAIT_V(n) asm volatile("s_waitcnt vmcnt(" #n ")" ::: "memory")
; #define PG8_WAIT_L(n) asm volatile("s_waitcnt lgkmcnt(" #n ")" ::: "memory")
; #define PG8_BAR __builtin_amdgcn_s_barrier()
; #define PG8_SCHED __builtin_amdgcn_sched_barrier(0)
; template <class Epi, class Sched>
; __device__ __forceinline__ void gemm_phase(LAS unsigned char* lds, const Gemm g, const Sched& S, const Epi& E) {
;     ...
;             PG8_STAGE(PG8_SB(0, 1), b2 + hstep, voffB);
;             PG8_WAIT_V(6); PG8_BAR; PG8_MMA(1, 1, At, B1); PG8_BAR;
;             PG8_LDB(B0, 1, 0); PG8_SCHED; PG8_LDA(At, 1, 0); PG8_STAGE(PG8_SA(0, 1), a2 + hstep, voffA);
;             PG8_WAIT_L(8); PG8_BAR; PG8_WAIT_L(0); PG8_MMA(0, 0, At, B0); PG8_BAR; PG8_SCHED;
;             PG8_LDB(B1, 1, 1); PG8_STAGE(PG8_SB(1, 0), b3, voffB);
;             PG8_BAR; PG8_WAIT_L(0); PG8_MMA(0, 1, At, B1); PG8_BAR;
	s_add_u32 s44, s16, 0x80000
	s_addc_u32 s45, s17, 0
	s_add_i32 s46, s36, s24
	s_mov_b32 m0, s46
	s_nop 0
	global_load_lds_dwordx4 v146, s[44:45]
	s_add_i32 m0, s46, 0x2000
	s_nop 0
	global_load_lds_dwordx4 v150, s[44:45]
	s_waitcnt vmcnt(26)
	s_barrier
	s_setprio 1
	v_mfma_f32_16x16x32_bf16 v[52:55], v[202:205], v[162:165], 0
	v_mfma_f32_16x16x32_bf16 v[44:47], v[210:213], v[162:165], 0
	v_mfma_f32_16x16x32_bf16 v[36:39], v[202:205], v[176:179], 0
	v_mfma_f32_16x16x32_bf16 v[28:31], v[210:213], v[176:179], 0
	v_mfma_f32_16x16x32_bf16 v[20:23], v[202:205], v[184:187], 0
	v_mfma_f32_16x16x32_bf16 v[12:15], v[210:213], v[184:187], 0
	v_mfma_f32_16x16x32_bf16 v[4:7], v[202:205], v[192:195], 0
	v_mfma_f32_16x16x32_bf16 v[0:3], v[210:213], v[192:195], 0
	v_mfma_f32_16x16x32_bf16 v[52:55], v[206:209], v[172:175], v[52:55]
	v_mfma_f32_16x16x32_bf16 v[44:47], v[214:217], v[172:175], v[44:47]
	v_mfma_f32_16x16x32_bf16 v[36:39], v[206:209], v[180:183], v[36:39]
	v_mfma_f32_16x16x32_bf16 v[28:31], v[214:217], v[180:183], v[28:31]
	v_mfma_f32_16x16x32_bf16 v[20:23], v[206:209], v[188:191], v[20:23]
	v_mfma_f32_16x16x32_bf16 v[12:15], v[214:217], v[188:191], v[12:15]
	v_mfma_f32_16x16x32_bf16 v[4:7], v[206:209], v[196:199], v[4:7]
	v_mfma_f32_16x16x32_bf16 v[0:3], v[214:217], v[196:199], v[0:3]
	s_setprio 0
	s_add_i32 s44, 0, 0x18000
	v_add_u32_e32 v140, s44, v167
	s_barrier
	ds_read_b128 v[128:131], v140
	ds_read_b128 v[132:135], v140 offset:1024
	ds_read_b128 v[136:139], v140 offset:2048
	ds_read_b128 v[140:143], v140 offset:3072
	s_add_u32 s18, s18, 0x80000
	s_addc_u32 s19, s19, 0
	s_mov_b32 m0, s26
	ds_read_b128 v[162:165], v169 offset:32768
	ds_read_b128 v[172:175], v169 offset:33792
	ds_read_b128 v[176:179], v169 offset:34816
	ds_read_b128 v[180:183], v169 offset:35840
	ds_read_b128 v[184:187], v169 offset:36864
	ds_read_b128 v[188:191], v169 offset:37888
	ds_read_b128 v[192:195], v169 offset:38912
	ds_read_b128 v[196:199], v169 offset:39936
	global_load_lds_dwordx4 v144, s[18:19]
	s_mov_b32 m0, s27
	s_nop 0
	global_load_lds_dwordx4 v148, s[18:19]
	s_waitcnt lgkmcnt(8)
	s_waitcnt vmcnt(26)
	s_barrier
	s_waitcnt lgkmcnt(0)
	s_setprio 1
	s_waitcnt lgkmcnt(0)
	v_mfma_f32_16x16x32_bf16 v[124:127], v[128:131], v[162:165], v[124:127]
	v_mfma_f32_16x16x32_bf16 v[120:123], v[136:139], v[162:165], v[120:123]
	v_mfma_f32_16x16x32_bf16 v[116:119], v[128:131], v[176:179], v[116:119]
	v_mfma_f32_16x16x32_bf16 v[112:115], v[136:139], v[176:179], v[112:115]
	v_mfma_f32_16x16x32_bf16 v[108:111], v[128:131], v[184:187], v[108:111]
	v_mfma_f32_16x16x32_bf16 v[100:103], v[136:139], v[184:187], v[100:103]
	v_mfma_f32_16x16x32_bf16 v[76:79], v[128:131], v[192:195], v[76:79]
	v_mfma_f32_16x16x32_bf16 v[72:75], v[136:139], v[192:195], v[72:75]
	v_mfma_f32_16x16x32_bf16 v[124:127], v[132:135], v[172:175], v[124:127]
	v_mfma_f32_16x16x32_bf16 v[120:123], v[140:143], v[172:175], v[120:123]
	v_mfma_f32_16x16x32_bf16 v[116:119], v[132:135], v[180:183], v[116:119]
	v_mfma_f32_16x16x32_bf16 v[112:115], v[140:143], v[180:183], v[112:115]
	v_mfma_f32_16x16x32_bf16 v[108:111], v[132:135], v[188:191], v[108:111]
	v_mfma_f32_16x16x32_bf16 v[100:103], v[140:143], v[188:191], v[100:103]
	v_mfma_f32_16x16x32_bf16 v[76:79], v[132:135], v[196:199], v[76:79]
	v_mfma_f32_16x16x32_bf16 v[72:75], v[140:143], v[196:199], v[72:75]
	s_setprio 0
	s_barrier
	s_add_i32 s18, 0, 0x1c000
	s_add_i32 s19, s44, s24
	v_add_u32_e32 v160, s18, v167
	s_add_u32 s0, s16, 0x80
	s_addc_u32 s1, s17, 0
	s_mov_b32 m0, s19
	ds_read_b128 v[202:205], v160
	ds_read_b128 v[206:209], v160 offset:1024
	ds_read_b128 v[210:213], v160 offset:2048
	ds_read_b128 v[214:217], v160 offset:3072
	global_load_lds_dwordx4 v146, s[0:1]
	s_add_i32 m0, s19, 0x2000
	s_nop 0
	global_load_lds_dwordx4 v150, s[0:1]
	s_waitcnt vmcnt(10)
	s_barrier
; #define PG8_STAGE(bufoff, gbase, voff) do { _Pragma("unroll") for (int _i = 0; _i < 2; ++_i) \
;         __builtin_amdgcn_global_load_lds((const unsigned*)((const char*)(gbase) + (voff)[_i]), (LAS unsigned*)(lds + (bufoff) + ldsw + _i * 8192), 16, 0, 0); } while (0)
; #define PG8_LDA(dst, b, h) do { _Pragma("unroll") for (int m = 0; m < 4; ++m) _Pragma("unroll") for (int k = 0; k < 2; ++k) dst[m][k] = *(const LAS bf16x8*)(lds + PG8_SA(b, h) + aoff + m * 2048 + k * 1024); } while (0)
; #define PG8_MMA(ai, bj, At, Bt) do { __builtin_amdgcn_s_setprio(1); _Pragma("unroll") for (int m = 0; m < 4; ++m) _Pragma("unroll") for (int n = 0; n < 2; ++n) _Pragma("unroll") for (int k = 0; k < 2; ++k) \
;         acc[ai][bj][m][n] = __builtin_amdgcn_mfma_f32_16x16x32_bf16(Bt[n][k], At[m][k], acc[ai][bj][m][n], 0, 0, 0); __builtin_amdgcn_s_setprio(0); } while (0)
; #define PG8_WAIT_V(n) asm volatile("s_waitcnt vmcnt(" #n ")" ::: "memory")
; #define PG8_WAIT_L(n) asm volatile("s_waitcnt lgkmcnt(" #n ")" ::: "memory")
; #define PG8_BAR __builtin_amdgcn_s_barrier()
; #define PG8_SCHED __builtin_amdgcn_sched_barrier(0)
; template <class Epi, class Sched>
; __device__ __forceinline__ void gemm_phase(LAS unsigned char* lds, const Gemm g, const Sched& S, const Epi& E) {
;     ...
;             PG8_BAR; PG8_WAIT_L(0); PG8_MMA(0, 1, At, B1); PG8_BAR;
;             PG8_LDA(At, 1, 1); PG8_STAGE(PG8_SA(1, 0), a3, voffA);
;             PG8_BAR; PG8_WAIT_L(0); PG8_MMA(1, 0, At, B0); PG8_BAR; PG8_SCHED;
;             PG8_STAGE(PG8_SB(1, 1), b3 + hstep, voffB);
;             PG8_WAIT_V(6); PG8_BAR; PG8_MMA(1, 1, At, B1); PG8_BAR;
;         }
	s_waitcnt lgkmcnt(0)
	s_setprio 1
	s_waitcnt lgkmcnt(0)
	v_mfma_f32_16x16x32_bf16 v[104:107], v[202:205], v[162:165], v[104:107]
	v_mfma_f32_16x16x32_bf16 v[96:99], v[210:213], v[162:165], v[96:99]
	v_mfma_f32_16x16x32_bf16 v[92:95], v[202:205], v[176:179], v[92:95]
	v_mfma_f32_16x16x32_bf16 v[88:91], v[210:213], v[176:179], v[88:91]
	v_mfma_f32_16x16x32_bf16 v[84:87], v[202:205], v[184:187], v[84:87]
	v_mfma_f32_16x16x32_bf16 v[80:83], v[210:213], v[184:187], v[80:83]
	v_mfma_f32_16x16x32_bf16 v[68:71], v[202:205], v[192:195], v[68:71]
	v_mfma_f32_16x16x32_bf16 v[64:67], v[210:213], v[192:195], v[64:67]
	v_mfma_f32_16x16x32_bf16 v[104:107], v[206:209], v[172:175], v[104:107]
	v_mfma_f32_16x16x32_bf16 v[96:99], v[214:217], v[172:175], v[96:99]
	v_mfma_f32_16x16x32_bf16 v[92:95], v[206:209], v[180:183], v[92:95]
	v_mfma_f32_16x16x32_bf16 v[88:91], v[214:217], v[180:183], v[88:91]
	v_mfma_f32_16x16x32_bf16 v[84:87], v[206:209], v[188:191], v[84:87]
	v_mfma_f32_16x16x32_bf16 v[80:83], v[214:217], v[188:191], v[80:83]
	v_mfma_f32_16x16x32_bf16 v[68:71], v[206:209], v[196:199], v[68:71]
	v_mfma_f32_16x16x32_bf16 v[64:67], v[214:217], v[196:199], v[64:67]
	s_setprio 0
	s_mov_b32 m0, s31
	s_mov_b64 s[0:1], 0x80
	v_lshl_add_u64 v[218:219], v[222:223], 0, s[0:1]
	s_barrier
	ds_read_b128 v[162:165], v169 offset:49152
	ds_read_b128 v[172:175], v169 offset:50176
	ds_read_b128 v[176:179], v169 offset:51200
	ds_read_b128 v[180:183], v169 offset:52224
	ds_read_b128 v[184:187], v169 offset:53248
	ds_read_b128 v[188:191], v169 offset:54272
	ds_read_b128 v[192:195], v169 offset:55296
	ds_read_b128 v[196:199], v169 offset:56320
	global_load_lds_dwordx4 v[218:219], off
	v_lshl_add_u64 v[218:219], v[224:225], 0, s[0:1]
	s_mov_b32 m0, s33
	s_nop 0
	global_load_lds_dwordx4 v[218:219], off
	s_barrier
	s_waitcnt lgkmcnt(0)
	s_setprio 1
	s_waitcnt lgkmcnt(0)
	v_mfma_f32_16x16x32_bf16 v[60:63], v[128:131], v[162:165], v[60:63]
	v_mfma_f32_16x16x32_bf16 v[56:59], v[136:139], v[162:165], v[56:59]
	v_mfma_f32_16x16x32_bf16 v[48:51], v[128:131], v[176:179], v[48:51]
	v_mfma_f32_16x16x32_bf16 v[40:43], v[136:139], v[176:179], v[40:43]
	v_mfma_f32_16x16x32_bf16 v[32:35], v[128:131], v[184:187], v[32:35]
	v_mfma_f32_16x16x32_bf16 v[24:27], v[136:139], v[184:187], v[24:27]
	v_mfma_f32_16x16x32_bf16 v[16:19], v[128:131], v[192:195], v[16:19]
	v_mfma_f32_16x16x32_bf16 v[8:11], v[136:139], v[192:195], v[8:11]
	v_mfma_f32_16x16x32_bf16 v[60:63], v[132:135], v[172:175], v[60:63]
	v_mfma_f32_16x16x32_bf16 v[56:59], v[140:143], v[172:175], v[56:59]
	v_mfma_f32_16x16x32_bf16 v[48:51], v[132:135], v[180:183], v[48:51]
	v_mfma_f32_16x16x32_bf16 v[40:43], v[140:143], v[180:183], v[40:43]
	v_mfma_f32_16x16x32_bf16 v[32:35], v[132:135], v[188:191], v[32:35]
	v_mfma_f32_16x16x32_bf16 v[24:27], v[140:143], v[188:191], v[24:27]
	v_mfma_f32_16x16x32_bf16 v[16:19], v[132:135], v[196:199], v[16:19]
	v_mfma_f32_16x16x32_bf16 v[8:11], v[140:143], v[196:199], v[8:11]
	s_setprio 0
	s_barrier
	s_add_u32 s16, s16, 0x80080
	s_addc_u32 s17, s17, 0
	s_add_i32 s18, s18, s24
	s_mov_b32 m0, s18
	s_nop 0
	global_load_lds_dwordx4 v146, s[16:17]
	s_add_i32 m0, s18, 0x2000
	s_nop 0
	global_load_lds_dwordx4 v150, s[16:17]
	s_waitcnt vmcnt(10)
	s_barrier
	s_setprio 1
	v_mfma_f32_16x16x32_bf16 v[52:55], v[202:205], v[162:165], v[52:55]
	v_mfma_f32_16x16x32_bf16 v[44:47], v[210:213], v[162:165], v[44:47]
	v_mfma_f32_16x16x32_bf16 v[36:39], v[202:205], v[176:179], v[36:39]
	v_mfma_f32_16x16x32_bf16 v[28:31], v[210:213], v[176:179], v[28:31]
	v_mfma_f32_16x16x32_bf16 v[20:23], v[202:205], v[184:187], v[20:23]
	v_mfma_f32_16x16x32_bf16 v[12:15], v[210:213], v[184:187], v[12:15]
	v_mfma_f32_16x16x32_bf16 v[4:7], v[202:205], v[192:195], v[4:7]
	v_mfma_f32_16x16x32_bf16 v[0:3], v[210:213], v[192:195], v[0:3]
	v_mfma_f32_16x16x32_bf16 v[52:55], v[206:209], v[172:175], v[52:55]
	v_mfma_f32_16x16x32_bf16 v[44:47], v[214:217], v[172:175], v[44:47]
	v_mfma_f32_16x16x32_bf16 v[36:39], v[206:209], v[180:183], v[36:39]
	v_mfma_f32_16x16x32_bf16 v[28:31], v[214:217], v[180:183], v[28:31]
	v_mfma_f32_16x16x32_bf16 v[20:23], v[206:209], v[188:191], v[20:23]
	v_mfma_f32_16x16x32_bf16 v[12:15], v[214:217], v[188:191], v[12:15]
	v_mfma_f32_16x16x32_bf16 v[4:7], v[206:209], v[196:199], v[4:7]
	v_mfma_f32_16x16x32_bf16 v[0:3], v[214:217], v[196:199], v[0:3]
	s_setprio 0
	s_add_i32 s43, s43, 2
	s_add_u32 s14, s14, 0x100
	s_addc_u32 s15, s15, 0
	s_add_u32 s41, s41, 0x100
	s_addc_u32 s42, s42, 0
	s_cmp_gt_u32 s43, 29
	s_barrier

; #define PG8_STAGE(bufoff, gbase, voff) do { _Pragma("unroll") for (int _i = 0; _i < 2; ++_i) \
;         __builtin_amdgcn_global_load_lds((const unsigned*)((const char*)(gbase) + (voff)[_i]), (LAS unsigned*)(lds + (bufoff) + ldsw + _i * 8192), 16, 0, 0); } while (0)
; #define PG8_WAIT_V(n) asm volatile("s_waitcnt vmcnt(" #n ")" ::: "memory")
; #define PG8_BAR __builtin_amdgcn_s_barrier()
; template <class Epi, class Sched>
; __device__ __forceinline__ void gemm_phase(LAS unsigned char* lds, const Gemm g, const Sched& S, const Epi& E) {
;     ...
;     for (int i = 0; i < 2; ++i) { int R, C; stage_rc(tid * 16 + i * 8192, R, C); const int Rb = Epi::PERM ? ((R & ~31) + perm32(R & 31)) : R;
;         voffA[i] = (unsigned)(R * K + C) * 2u; voffB[i] = (unsigned)(Rb * K + C) * 2u; }
;     const size_t kstep = (size_t)(BK * 2);
;     const size_t hstep = (size_t)HALF * K * 2;
;     const size_t tstep = 2 * hstep;
;     const unsigned ldsw = (unsigned)wid * 1024u;
;     const int aoff = lds_byte(wr * 64 + fr, fq * 8), boff = lds_byte(wc * 32 + fr, fq * 8);
;     ...
;     PG8_WAIT_V(4); PG8_BAR;
;     PG8_STAGE(PG8_SB(1, 0), cB + kstep, voffB); PG8_STAGE(PG8_SA(1, 0), cA + kstep, voffA); PG8_STAGE(PG8_SB(1, 1), cB + hstep + kstep, voffB);
;     PG8_WAIT_V(6); PG8_BAR;
.LBB0_890:
	s_add_u32 s43, s64, 0x3285000
	s_addc_u32 s44, s65, 0
	s_lshl_b32 s45, s0, 6
	s_lshl_b32 s5, s0, 13
	s_lshl_b32 s0, s1, 5
	s_and_b32 s46, s0, 0x60
	s_mov_b64 s[0:1], 0x80
	s_add_i32 m0, s38, 0x18000
	v_lshl_add_u64 v[6:7], v[6:7], 0, s[0:1]
	s_lshl_b32 s10, s46, 7
	s_waitcnt vmcnt(4)
	s_barrier
	global_load_lds_dwordx4 v[6:7], off
	v_lshl_add_u64 v[4:5], v[4:5], 0, s[0:1]
	s_add_i32 m0, s38, 0x1a000
	s_add_i32 s47, s38, 0x8000
	s_add_i32 s48, s38, 0xa000
	global_load_lds_dwordx4 v[4:5], off
	v_lshl_add_u64 v[2:3], v[2:3], 0, s[0:1]
	s_mov_b32 m0, s47
	s_add_u32 s6, s26, 0x60080
	global_load_lds_dwordx4 v[2:3], off
	v_lshl_add_u64 v[0:1], v[0:1], 0, s[0:1]
	s_mov_b32 m0, s48
	s_addc_u32 s7, s27, 0
	global_load_lds_dwordx4 v[0:1], off
	s_add_i32 m0, s38, 0x1c000
	v_lshl_add_u64 v[0:1], s[6:7], 0, v[204:205]
	global_load_lds_dwordx4 v[0:1], off
	v_lshl_add_u64 v[0:1], s[6:7], 0, v[208:209]
	s_add_i32 m0, s38, 0x1e000
	v_bfe_u32 v234, v8, 4, 2
	global_load_lds_dwordx4 v[0:1], off
	v_and_b32_e32 v235, 15, v8
	v_lshlrev_b32_e32 v0, 4, v234
	v_lshlrev_b32_e32 v1, 2, v8
	v_lshl_or_b32 v0, v235, 6, v0
	v_and_b32_e32 v1, 32, v1
	v_bitop3_b32 v2, v0, s5, v1 bitop3:0xde
	v_bitop3_b32 v236, v0, s10, v1 bitop3:0xde
	v_lshrrev_b32_e32 v1, 1, v9
	v_mul_lo_u32 v0, v10, s2
	v_mad_u64_u32 v[0:1], s[10:11], v1, s4, v[0:1]
	v_or_b32_e32 v0, v0, v11
	s_mov_b64 s[6:7], 0x60080
	v_add_lshl_u32 v0, v0, v12, 1
	v_mov_b32_e32 v1, v205
	v_lshl_add_u64 v[210:211], v[0:1], 0, s[6:7]
	v_lshrrev_b32_e32 v1, 1, v13
	v_mul_lo_u32 v0, v14, s2
	s_sext_i32_i8 s55, s3
	v_mad_u64_u32 v[0:1], s[2:3], v1, s4, v[0:1]
	s_waitcnt vmcnt(0)
	v_or_b32_e32 v0, v0, v15
	v_add_lshl_u32 v0, v0, v16, 1
	v_mov_b32_e32 v1, v205
	s_add_i32 s50, 0, 0x10000
	s_add_i32 s51, 0, 0x14000
	s_ashr_i32 s49, s76, 31
	v_lshl_add_u64 v[212:213], v[0:1], 0, s[6:7]
	v_mov_b64_e32 v[214:215], 0x400
	v_mov_b64_e32 v[216:217], 0x3ff
	v_add_u32_e32 v237, s50, v236
	v_add_u32_e32 v238, 0, v2
	v_add_u32_e32 v239, s51, v236
	s_mov_b64 s[10:11], 0x8000
	s_mov_b64 s[12:13], 0x10000
	s_mov_b64 s[14:15], 0x18000
	s_mov_b64 s[16:17], 0x40000
	s_mov_b64 s[18:19], 0x48000
	s_mov_b64 s[20:21], 0x50000
	s_mov_b64 s[22:23], 0x58000
	s_barrier

; #define PG8_STAGE(bufoff, gbase, voff) do { _Pragma("unroll") for (int _i = 0; _i < 2; ++_i) \
;         __builtin_amdgcn_global_load_lds((const unsigned*)((const char*)(gbase) + (voff)[_i]), (LAS unsigned*)(lds + (bufoff) + ldsw + _i * 8192), 16, 0, 0); } while (0)
; #define PG8_LDA(dst, b, h) do { _Pragma("unroll") for (int m = 0; m < 4; ++m) _Pragma("unroll") for (int k = 0; k < 2; ++k) dst[m][k] = *(const LAS bf16x8*)(lds + PG8_SA(b, h) + aoff + m * 2048 + k * 1024); } while (0)
; #define PG8_LDB(dst, b, h) do { _Pragma("unroll") for (int n = 0; n < 2; ++n) _Pragma("unroll") for (int k = 0; k < 2; ++k) dst[n][k] = *(const LAS bf16x8*)(lds + PG8_SB(b, h) + boff + n * 2048 + k * 1024); } while (0)
; #define PG8_MMA(ai, bj, At, Bt) do { __builtin_amdgcn_s_setprio(1); _Pragma("unroll") for (int m = 0; m < 4; ++m) _Pragma("unroll") for (int n = 0; n < 2; ++n) _Pragma("unroll") for (int k = 0; k < 2; ++k) \
;         acc[ai][bj][m][n] = __builtin_amdgcn_mfma_f32_16x16x32_bf16(Bt[n][k], At[m][k], acc[ai][bj][m][n], 0, 0, 0); __builtin_amdgcn_s_setprio(0); } while (0)
; #define PG8_WAIT_V(n) asm volatile("s_waitcnt vmcnt(" #n ")" ::: "memory")
; #define PG8_WAIT_L(n) asm volatile("s_waitcnt lgkmcnt(" #n ")" ::: "memory")
; template <class Epi, class Sched>
; __device__ __forceinline__ void gemm_phase(LAS unsigned char* lds, const Gemm g, const Sched& S, const Epi& E) {
;     ...
;         for (int t = 0; t < nt; t += 2) {
;             const bool last = (t == nt - 2);
;             const char* a1 = cA + (size_t)(t + 1) * kstep;
;             const char* a2 = last ? nA : cA + (size_t)(t + 2) * kstep; const char* b2 = last ? nB : cB + (size_t)(t + 2) * kstep;
;             const char* a3 = a2 + kstep; const char* b3 = b2 + kstep;
;             PG8_LDB(B0, 0, 0); PG8_SCHED; PG8_LDA(At, 0, 0); PG8_STAGE(PG8_SA(1, 1), a1 + hstep, voffA);
;             PG8_WAIT_L(8); PG8_BAR; PG8_WAIT_L(0); PG8_MMA(0, 0, At, B0); PG8_BAR; PG8_SCHED;
;             PG8_LDB(B1, 0, 1); PG8_STAGE(PG8_SB(0, 0), b2, voffB);
;             PG8_BAR; PG8_WAIT_L(0); PG8_MMA(0, 1, At, B1); PG8_BAR;
;             PG8_LDA(At, 0, 1); PG8_STAGE(PG8_SA(0, 0), a2, voffA);
;             PG8_BAR; PG8_WAIT_L(0); PG8_MMA(1, 0, At, B0); PG8_BAR; PG8_SCHED;
;             PG8_STAGE(PG8_SB(0, 1), b2 + hstep, voffB);
;             PG8_WAIT_V(6); PG8_BAR; PG8_MMA(1, 1, At, B1); PG8_BAR;
.LBB0_901:
	s_add_u32 s56, s26, 0x100
	s_addc_u32 s57, s27, 0
	s_mov_b32 s58, -2
	s_waitcnt vmcnt(0)
	ds_read_b128 v[128:131], v237
	ds_read_b128 v[132:135], v237 offset:1024
	ds_read_b128 v[136:139], v237 offset:2048
	ds_read_b128 v[140:143], v237 offset:3072
	s_add_u32 s26, s24, 0x100
	s_addc_u32 s27, s25, 0
	s_cmp_eq_u32 s58, 20
	s_cselect_b32 s31, s5, s27
	s_cselect_b32 s30, s4, s26
	s_cselect_b32 s29, s7, s57
	s_cselect_b32 s28, s6, s56
	v_lshl_add_u64 v[176:177], s[24:25], 0, v[210:211]
	s_add_i32 m0, s38, 0xc000
	ds_read_b128 v[144:147], v238
	ds_read_b128 v[148:151], v238 offset:1024
	ds_read_b128 v[152:155], v238 offset:2048
	ds_read_b128 v[156:159], v238 offset:3072
	ds_read_b128 v[160:163], v238 offset:4096
	ds_read_b128 v[164:167], v238 offset:5120
	ds_read_b128 v[168:171], v238 offset:6144
	ds_read_b128 v[172:175], v238 offset:7168
	global_load_lds_dwordx4 v[176:177], off
	v_lshl_add_u64 v[176:177], s[24:25], 0, v[212:213]
	s_add_i32 m0, s38, 0xe000
	s_nop 0
	global_load_lds_dwordx4 v[176:177], off
	s_waitcnt lgkmcnt(8)
	s_waitcnt vmcnt(26)
	s_barrier
	s_waitcnt lgkmcnt(0)
	s_setprio 1
	s_waitcnt lgkmcnt(0)
	v_mfma_f32_16x16x32_bf16 v[124:127], v[128:131], v[144:147], 0
	v_mfma_f32_16x16x32_bf16 v[120:123], v[136:139], v[144:147], 0
	v_mfma_f32_16x16x32_bf16 v[108:111], v[128:131], v[152:155], 0
	v_mfma_f32_16x16x32_bf16 v[104:107], v[136:139], v[152:155], 0
	v_mfma_f32_16x16x32_bf16 v[92:95], v[128:131], v[160:163], 0
	v_mfma_f32_16x16x32_bf16 v[88:91], v[136:139], v[160:163], 0
	v_mfma_f32_16x16x32_bf16 v[76:79], v[128:131], v[168:171], 0
	v_mfma_f32_16x16x32_bf16 v[72:75], v[136:139], v[168:171], 0
	v_mfma_f32_16x16x32_bf16 v[124:127], v[132:135], v[148:151], v[124:127]
	v_mfma_f32_16x16x32_bf16 v[120:123], v[140:143], v[148:151], v[120:123]
	v_mfma_f32_16x16x32_bf16 v[108:111], v[132:135], v[156:159], v[108:111]
	v_mfma_f32_16x16x32_bf16 v[104:107], v[140:143], v[156:159], v[104:107]
	v_mfma_f32_16x16x32_bf16 v[92:95], v[132:135], v[164:167], v[92:95]
	v_mfma_f32_16x16x32_bf16 v[88:91], v[140:143], v[164:167], v[88:91]
	v_mfma_f32_16x16x32_bf16 v[76:79], v[132:135], v[172:175], v[76:79]
	v_mfma_f32_16x16x32_bf16 v[72:75], v[140:143], v[172:175], v[72:75]
	s_setprio 0
	s_barrier
	s_add_i32 s24, s50, s37
	s_mov_b32 m0, s24
	ds_read_b128 v[176:179], v239
	ds_read_b128 v[180:183], v239 offset:1024
	ds_read_b128 v[184:187], v239 offset:2048
	ds_read_b128 v[188:191], v239 offset:3072
	global_load_lds_dwordx4 v204, s[28:29]
	s_add_i32 m0, s24, 0x2000
	s_nop 0
	global_load_lds_dwordx4 v208, s[28:29]
	s_waitcnt vmcnt(26)
	s_barrier
	s_waitcnt lgkmcnt(0)
	s_setprio 1
	s_waitcnt lgkmcnt(0)
	v_mfma_f32_16x16x32_bf16 v[116:119], v[176:179], v[144:147], 0
	v_mfma_f32_16x16x32_bf16 v[112:115], v[184:187], v[144:147], 0
	v_mfma_f32_16x16x32_bf16 v[100:103], v[176:179], v[152:155], 0
	v_mfma_f32_16x16x32_bf16 v[96:99], v[184:187], v[152:155], 0
	v_mfma_f32_16x16x32_bf16 v[84:87], v[176:179], v[160:163], 0
	v_mfma_f32_16x16x32_bf16 v[80:83], v[184:187], v[160:163], 0
	v_mfma_f32_16x16x32_bf16 v[68:71], v[176:179], v[168:171], 0
	v_mfma_f32_16x16x32_bf16 v[64:67], v[184:187], v[168:171], 0
	v_mfma_f32_16x16x32_bf16 v[116:119], v[180:183], v[148:151], v[116:119]
	v_mfma_f32_16x16x32_bf16 v[112:115], v[188:191], v[148:151], v[112:115]
	v_mfma_f32_16x16x32_bf16 v[100:103], v[180:183], v[156:159], v[100:103]
	v_mfma_f32_16x16x32_bf16 v[96:99], v[188:191], v[156:159], v[96:99]
	v_mfma_f32_16x16x32_bf16 v[84:87], v[180:183], v[164:167], v[84:87]
	v_mfma_f32_16x16x32_bf16 v[80:83], v[188:191], v[164:167], v[80:83]
	v_mfma_f32_16x16x32_bf16 v[68:71], v[180:183], v[172:175], v[68:71]
	v_mfma_f32_16x16x32_bf16 v[64:67], v[188:191], v[172:175], v[64:67]
	s_setprio 0
	s_mov_b32 m0, s38
	v_lshl_add_u64 v[196:197], s[30:31], 0, v[202:203]
	s_barrier
	ds_read_b128 v[144:147], v238 offset:16384
	ds_read_b128 v[148:151], v238 offset:17408
	ds_read_b128 v[152:155], v238 offset:18432
	ds_read_b128 v[156:159], v238 offset:19456
	ds_read_b128 v[160:163], v238 offset:20480
	ds_read_b128 v[164:167], v238 offset:21504
	ds_read_b128 v[168:171], v238 offset:22528
	ds_read_b128 v[172:175], v238 offset:23552
	global_load_lds_dwordx4 v202, s[30:31]
	v_lshl_add_u64 v[198:199], s[30:31], 0, v[206:207]
	s_mov_b32 m0, s39
	s_nop 0
	global_load_lds_dwordx4 v206, s[30:31]
	s_barrier
	s_waitcnt lgkmcnt(0)
	s_setprio 1
	s_waitcnt lgkmcnt(0)
	v_mfma_f32_16x16x32_bf16 v[60:63], v[128:131], v[144:147], 0
	v_mfma_f32_16x16x32_bf16 v[56:59], v[136:139], v[144:147], 0
	v_mfma_f32_16x16x32_bf16 v[44:47], v[128:131], v[152:155], 0
	v_mfma_f32_16x16x32_bf16 v[40:43], v[136:139], v[152:155], 0
	v_mfma_f32_16x16x32_bf16 v[28:31], v[128:131], v[160:163], 0
	v_mfma_f32_16x16x32_bf16 v[24:27], v[136:139], v[160:163], 0
	v_mfma_f32_16x16x32_bf16 v[12:15], v[128:131], v[168:171], 0
	v_mfma_f32_16x16x32_bf16 v[8:11], v[136:139], v[168:171], 0
	v_mfma_f32_16x16x32_bf16 v[60:63], v[132:135], v[148:151], v[60:63]
	v_mfma_f32_16x16x32_bf16 v[56:59], v[140:143], v[148:151], v[56:59]
	v_mfma_f32_16x16x32_bf16 v[44:47], v[132:135], v[156:159], v[44:47]
	v_mfma_f32_16x16x32_bf16 v[40:43], v[140:143], v[156:159], v[40:43]
	v_mfma_f32_16x16x32_bf16 v[28:31], v[132:135], v[164:167], v[28:31]
	v_mfma_f32_16x16x32_bf16 v[24:27], v[140:143], v[164:167], v[24:27]
	v_mfma_f32_16x16x32_bf16 v[12:15], v[132:135], v[172:175], v[12:15]
	v_mfma_f32_16x16x32_bf16 v[8:11], v[140:143], v[172:175], v[8:11]
	s_setprio 0
	s_barrier
	s_add_u32 s24, s28, 0x60000
	s_addc_u32 s25, s29, 0
	s_add_i32 s59, s51, s37
	s_mov_b32 m0, s59
	s_nop 0
	global_load_lds_dwordx4 v204, s[24:25]
	s_add_i32 m0, s59, 0x2000
	s_nop 0
	global_load_lds_dwordx4 v208, s[24:25]
	s_waitcnt vmcnt(26)
	s_barrier
; #define PG8_STAGE(bufoff, gbase, voff) do { _Pragma("unroll") for (int _i = 0; _i < 2; ++_i) \
;         __builtin_amdgcn_global_load_lds((const unsigned*)((const char*)(gbase) + (voff)[_i]), (LAS unsigned*)(lds + (bufoff) + ldsw + _i * 8192), 16, 0, 0); } while (0)
; #define PG8_LDA(dst, b, h) do { _Pragma("unroll") for (int m = 0; m < 4; ++m) _Pragma("unroll") for (int k = 0; k < 2; ++k) dst[m][k] = *(const LAS bf16x8*)(lds + PG8_SA(b, h) + aoff + m * 2048 + k * 1024); } while (0)
; #define PG8_LDB(dst, b, h) do { _Pragma("unroll") for (int n = 0; n < 2; ++n) _Pragma("unroll") for (int k = 0; k < 2; ++k) dst[n][k] = *(const LAS bf16x8*)(lds + PG8_SB(b, h) + boff + n * 2048 + k * 1024); } while (0)
; #define PG8_MMA(ai, bj, At, Bt) do { __builtin_amdgcn_s_setprio(1); _Pragma("unroll") for (int m = 0; m < 4; ++m) _Pragma("unroll") for (int n = 0; n < 2; ++n) _Pragma("unroll") for (int k = 0; k < 2; ++k) \
;         acc[ai][bj][m][n] = __builtin_amdgcn_mfma_f32_16x16x32_bf16(Bt[n][k], At[m][k], acc[ai][bj][m][n], 0, 0, 0); __builtin_amdgcn_s_setprio(0); } while (0)
; #define PG8_WAIT_V(n) asm volatile("s_waitcnt vmcnt(" #n ")" ::: "memory")
; #define PG8_WAIT_L(n) asm volatile("s_waitcnt lgkmcnt(" #n ")" ::: "memory")
; #define PG8_BAR __builtin_amdgcn_s_barrier()
; #define PG8_SCHED __builtin_amdgcn_sched_barrier(0)
; template <class Epi, class Sched>
; __device__ __forceinline__ void gemm_phase(LAS unsigned char* lds, const Gemm g, const Sched& S, const Epi& E) {
;     ...
;             PG8_WAIT_V(6); PG8_BAR; PG8_MMA(1, 1, At, B1); PG8_BAR;
;             PG8_LDB(B0, 1, 0); PG8_SCHED; PG8_LDA(At, 1, 0); PG8_STAGE(PG8_SA(0, 1), a2 + hstep, voffA);
;             PG8_WAIT_L(8); PG8_BAR; PG8_WAIT_L(0); PG8_MMA(0, 0, At, B0); PG8_BAR; PG8_SCHED;
;             PG8_LDB(B1, 1, 1); PG8_STAGE(PG8_SB(1, 0), b3, voffB);
;             PG8_BAR; PG8_WAIT_L(0); PG8_MMA(0, 1, At, B1); PG8_BAR;
	s_setprio 1
	v_mfma_f32_16x16x32_bf16 v[52:55], v[176:179], v[144:147], 0
	v_mfma_f32_16x16x32_bf16 v[48:51], v[184:187], v[144:147], 0
	v_mfma_f32_16x16x32_bf16 v[36:39], v[176:179], v[152:155], 0
	v_mfma_f32_16x16x32_bf16 v[32:35], v[184:187], v[152:155], 0
	v_mfma_f32_16x16x32_bf16 v[20:23], v[176:179], v[160:163], 0
	v_mfma_f32_16x16x32_bf16 v[16:19], v[184:187], v[160:163], 0
	v_mfma_f32_16x16x32_bf16 v[4:7], v[176:179], v[168:171], 0
	v_mfma_f32_16x16x32_bf16 v[0:3], v[184:187], v[168:171], 0
	v_mfma_f32_16x16x32_bf16 v[52:55], v[180:183], v[148:151], v[52:55]
	v_mfma_f32_16x16x32_bf16 v[48:51], v[188:191], v[148:151], v[48:51]
	v_mfma_f32_16x16x32_bf16 v[36:39], v[180:183], v[156:159], v[36:39]
	v_mfma_f32_16x16x32_bf16 v[32:35], v[188:191], v[156:159], v[32:35]
	v_mfma_f32_16x16x32_bf16 v[20:23], v[180:183], v[164:167], v[20:23]
	v_mfma_f32_16x16x32_bf16 v[16:19], v[188:191], v[164:167], v[16:19]
	v_mfma_f32_16x16x32_bf16 v[4:7], v[180:183], v[172:175], v[4:7]
	v_mfma_f32_16x16x32_bf16 v[0:3], v[188:191], v[172:175], v[0:3]
	s_setprio 0
	s_add_i32 s59, 0, 0x18000
	v_add_u32_e32 v140, s59, v236
	s_barrier
	ds_read_b128 v[128:131], v140
	ds_read_b128 v[132:135], v140 offset:1024
	ds_read_b128 v[136:139], v140 offset:2048
	ds_read_b128 v[140:143], v140 offset:3072
	s_add_u32 s24, s30, 0x60000
	s_addc_u32 s25, s31, 0
	s_mov_b32 m0, s40
	ds_read_b128 v[144:147], v238 offset:32768
	ds_read_b128 v[148:151], v238 offset:33792
	ds_read_b128 v[152:155], v238 offset:34816
	ds_read_b128 v[156:159], v238 offset:35840
	ds_read_b128 v[160:163], v238 offset:36864
	ds_read_b128 v[164:167], v238 offset:37888
	ds_read_b128 v[168:171], v238 offset:38912
	ds_read_b128 v[172:175], v238 offset:39936
	global_load_lds_dwordx4 v202, s[24:25]
	s_mov_b32 m0, s41
	s_nop 0
	global_load_lds_dwordx4 v206, s[24:25]
	s_waitcnt lgkmcnt(8)
	s_waitcnt vmcnt(26)
	s_barrier
	s_waitcnt lgkmcnt(0)
	s_setprio 1
	s_waitcnt lgkmcnt(0)
	v_mfma_f32_16x16x32_bf16 v[124:127], v[128:131], v[144:147], v[124:127]
	v_mfma_f32_16x16x32_bf16 v[120:123], v[136:139], v[144:147], v[120:123]
	v_mfma_f32_16x16x32_bf16 v[108:111], v[128:131], v[152:155], v[108:111]
	v_mfma_f32_16x16x32_bf16 v[104:107], v[136:139], v[152:155], v[104:107]
	v_mfma_f32_16x16x32_bf16 v[92:95], v[128:131], v[160:163], v[92:95]
	v_mfma_f32_16x16x32_bf16 v[88:91], v[136:139], v[160:163], v[88:91]
	v_mfma_f32_16x16x32_bf16 v[76:79], v[128:131], v[168:171], v[76:79]
	v_mfma_f32_16x16x32_bf16 v[72:75], v[136:139], v[168:171], v[72:75]
	v_mfma_f32_16x16x32_bf16 v[124:127], v[132:135], v[148:151], v[124:127]
	v_mfma_f32_16x16x32_bf16 v[120:123], v[140:143], v[148:151], v[120:123]
	v_mfma_f32_16x16x32_bf16 v[108:111], v[132:135], v[156:159], v[108:111]
	v_mfma_f32_16x16x32_bf16 v[104:107], v[140:143], v[156:159], v[104:107]
	v_mfma_f32_16x16x32_bf16 v[92:95], v[132:135], v[164:167], v[92:95]
	v_mfma_f32_16x16x32_bf16 v[88:91], v[140:143], v[164:167], v[88:91]
	v_mfma_f32_16x16x32_bf16 v[76:79], v[132:135], v[172:175], v[76:79]
	v_mfma_f32_16x16x32_bf16 v[72:75], v[140:143], v[172:175], v[72:75]
	s_setprio 0
	s_barrier
	s_add_i32 s30, 0, 0x1c000
	s_add_i32 s24, s59, s37
	v_add_u32_e32 v188, s30, v236
	s_add_u32 s0, s28, 0x80
	s_addc_u32 s1, s29, 0
	s_mov_b32 m0, s24
	ds_read_b128 v[176:179], v188
	ds_read_b128 v[180:183], v188 offset:1024
	ds_read_b128 v[184:187], v188 offset:2048
	ds_read_b128 v[188:191], v188 offset:3072
	global_load_lds_dwordx4 v204, s[0:1]
	s_add_i32 m0, s24, 0x2000
	s_nop 0
	global_load_lds_dwordx4 v208, s[0:1]
	s_waitcnt vmcnt(10)
	s_barrier
; #define PG8_STAGE(bufoff, gbase, voff) do { _Pragma("unroll") for (int _i = 0; _i < 2; ++_i) \
;         __builtin_amdgcn_global_load_lds((const unsigned*)((const char*)(gbase) + (voff)[_i]), (LAS unsigned*)(lds + (bufoff) + ldsw + _i * 8192), 16, 0, 0); } while (0)
; #define PG8_LDA(dst, b, h) do { _Pragma("unroll") for (int m = 0; m < 4; ++m) _Pragma("unroll") for (int k = 0; k < 2; ++k) dst[m][k] = *(const LAS bf16x8*)(lds + PG8_SA(b, h) + aoff + m * 2048 + k * 1024); } while (0)
; #define PG8_MMA(ai, bj, At, Bt) do { __builtin_amdgcn_s_setprio(1); _Pragma("unroll") for (int m = 0; m < 4; ++m) _Pragma("unroll") for (int n = 0; n < 2; ++n) _Pragma("unroll") for (int k = 0; k < 2; ++k) \
;         acc[ai][bj][m][n] = __builtin_amdgcn_mfma_f32_16x16x32_bf16(Bt[n][k], At[m][k], acc[ai][bj][m][n], 0, 0, 0); __builtin_amdgcn_s_setprio(0); } while (0)
; #define PG8_WAIT_V(n) asm volatile("s_waitcnt vmcnt(" #n ")" ::: "memory")
; #define PG8_WAIT_L(n) asm volatile("s_waitcnt lgkmcnt(" #n ")" ::: "memory")
; #define PG8_BAR __builtin_amdgcn_s_barrier()
; #define PG8_SCHED __builtin_amdgcn_sched_barrier(0)
; template <class Epi, class Sched>
; __device__ __forceinline__ void gemm_phase(LAS unsigned char* lds, const Gemm g, const Sched& S, const Epi& E) {
;     ...
;             PG8_BAR; PG8_WAIT_L(0); PG8_MMA(0, 1, At, B1); PG8_BAR;
;             PG8_LDA(At, 1, 1); PG8_STAGE(PG8_SA(1, 0), a3, voffA);
;             PG8_BAR; PG8_WAIT_L(0); PG8_MMA(1, 0, At, B0); PG8_BAR; PG8_SCHED;
;             PG8_STAGE(PG8_SB(1, 1), b3 + hstep, voffB);
;             PG8_WAIT_V(6); PG8_BAR; PG8_MMA(1, 1, At, B1); PG8_BAR;
;         }
	s_waitcnt lgkmcnt(0)
	s_setprio 1
	s_waitcnt lgkmcnt(0)
	v_mfma_f32_16x16x32_bf16 v[116:119], v[176:179], v[144:147], v[116:119]
	v_mfma_f32_16x16x32_bf16 v[112:115], v[184:187], v[144:147], v[112:115]
	v_mfma_f32_16x16x32_bf16 v[100:103], v[176:179], v[152:155], v[100:103]
	v_mfma_f32_16x16x32_bf16 v[96:99], v[184:187], v[152:155], v[96:99]
	v_mfma_f32_16x16x32_bf16 v[84:87], v[176:179], v[160:163], v[84:87]
	v_mfma_f32_16x16x32_bf16 v[80:83], v[184:187], v[160:163], v[80:83]
	v_mfma_f32_16x16x32_bf16 v[68:71], v[176:179], v[168:171], v[68:71]
	v_mfma_f32_16x16x32_bf16 v[64:67], v[184:187], v[168:171], v[64:67]
	v_mfma_f32_16x16x32_bf16 v[116:119], v[180:183], v[148:151], v[116:119]
	v_mfma_f32_16x16x32_bf16 v[112:115], v[188:191], v[148:151], v[112:115]
	v_mfma_f32_16x16x32_bf16 v[100:103], v[180:183], v[156:159], v[100:103]
	v_mfma_f32_16x16x32_bf16 v[96:99], v[188:191], v[156:159], v[96:99]
	v_mfma_f32_16x16x32_bf16 v[84:87], v[180:183], v[164:167], v[84:87]
	v_mfma_f32_16x16x32_bf16 v[80:83], v[188:191], v[164:167], v[80:83]
	v_mfma_f32_16x16x32_bf16 v[68:71], v[180:183], v[172:175], v[68:71]
	v_mfma_f32_16x16x32_bf16 v[64:67], v[188:191], v[172:175], v[64:67]
	s_setprio 0
	s_mov_b32 m0, s47
	s_mov_b64 s[0:1], 0x80
	v_lshl_add_u64 v[192:193], v[196:197], 0, s[0:1]
	s_barrier
	ds_read_b128 v[144:147], v238 offset:49152
	ds_read_b128 v[148:151], v238 offset:50176
	ds_read_b128 v[152:155], v238 offset:51200
	ds_read_b128 v[156:159], v238 offset:52224
	ds_read_b128 v[160:163], v238 offset:53248
	ds_read_b128 v[164:167], v238 offset:54272
	ds_read_b128 v[168:171], v238 offset:55296
	ds_read_b128 v[172:175], v238 offset:56320
	global_load_lds_dwordx4 v[192:193], off
	v_lshl_add_u64 v[192:193], v[198:199], 0, s[0:1]
	s_mov_b32 m0, s48
	s_nop 0
	global_load_lds_dwordx4 v[192:193], off
	s_barrier
	s_waitcnt lgkmcnt(0)
	s_setprio 1
	s_waitcnt lgkmcnt(0)
	v_mfma_f32_16x16x32_bf16 v[60:63], v[128:131], v[144:147], v[60:63]
	v_mfma_f32_16x16x32_bf16 v[56:59], v[136:139], v[144:147], v[56:59]
	v_mfma_f32_16x16x32_bf16 v[44:47], v[128:131], v[152:155], v[44:47]
	v_mfma_f32_16x16x32_bf16 v[40:43], v[136:139], v[152:155], v[40:43]
	v_mfma_f32_16x16x32_bf16 v[28:31], v[128:131], v[160:163], v[28:31]
	v_mfma_f32_16x16x32_bf16 v[24:27], v[136:139], v[160:163], v[24:27]
	v_mfma_f32_16x16x32_bf16 v[12:15], v[128:131], v[168:171], v[12:15]
	v_mfma_f32_16x16x32_bf16 v[8:11], v[136:139], v[168:171], v[8:11]
	v_mfma_f32_16x16x32_bf16 v[60:63], v[132:135], v[148:151], v[60:63]
	v_mfma_f32_16x16x32_bf16 v[56:59], v[140:143], v[148:151], v[56:59]
	v_mfma_f32_16x16x32_bf16 v[44:47], v[132:135], v[156:159], v[44:47]
	v_mfma_f32_16x16x32_bf16 v[40:43], v[140:143], v[156:159], v[40:43]
	v_mfma_f32_16x16x32_bf16 v[28:31], v[132:135], v[164:167], v[28:31]
	v_mfma_f32_16x16x32_bf16 v[24:27], v[140:143], v[164:167], v[24:27]
	v_mfma_f32_16x16x32_bf16 v[12:15], v[132:135], v[172:175], v[12:15]
	v_mfma_f32_16x16x32_bf16 v[8:11], v[140:143], v[172:175], v[8:11]
	s_setprio 0
	s_barrier
	s_add_u32 s24, s28, 0x60080
	s_addc_u32 s25, s29, 0
	s_add_i32 s28, s30, s37
	s_mov_b32 m0, s28
	s_nop 0
	global_load_lds_dwordx4 v204, s[24:25]
	s_add_i32 m0, s28, 0x2000
	s_nop 0
	global_load_lds_dwordx4 v208, s[24:25]
	s_waitcnt vmcnt(10)
	s_barrier
	s_setprio 1
	v_mfma_f32_16x16x32_bf16 v[52:55], v[176:179], v[144:147], v[52:55]
	v_mfma_f32_16x16x32_bf16 v[48:51], v[184:187], v[144:147], v[48:51]
	v_mfma_f32_16x16x32_bf16 v[36:39], v[176:179], v[152:155], v[36:39]
	v_mfma_f32_16x16x32_bf16 v[32:35], v[184:187], v[152:155], v[32:35]
	v_mfma_f32_16x16x32_bf16 v[20:23], v[176:179], v[160:163], v[20:23]
	v_mfma_f32_16x16x32_bf16 v[16:19], v[184:187], v[160:163], v[16:19]
	v_mfma_f32_16x16x32_bf16 v[4:7], v[176:179], v[168:171], v[4:7]
	v_mfma_f32_16x16x32_bf16 v[0:3], v[184:187], v[168:171], v[0:3]
	v_mfma_f32_16x16x32_bf16 v[52:55], v[180:183], v[148:151], v[52:55]
	v_mfma_f32_16x16x32_bf16 v[48:51], v[188:191], v[148:151], v[48:51]
	v_mfma_f32_16x16x32_bf16 v[36:39], v[180:183], v[156:159], v[36:39]
	v_mfma_f32_16x16x32_bf16 v[32:35], v[188:191], v[156:159], v[32:35]
	v_mfma_f32_16x16x32_bf16 v[20:23], v[180:183], v[164:167], v[20:23]
	v_mfma_f32_16x16x32_bf16 v[16:19], v[188:191], v[164:167], v[16:19]
	v_mfma_f32_16x16x32_bf16 v[4:7], v[180:183], v[172:175], v[4:7]
	v_mfma_f32_16x16x32_bf16 v[0:3], v[188:191], v[172:175], v[0:3]
	s_setprio 0
	s_add_i32 s58, s58, 2
	s_add_u32 s56, s56, 0x100
	s_addc_u32 s57, s57, 0
	s_cmp_gt_u32 s58, 21
	s_mov_b64 s[24:25], s[26:27]
	s_barrier

; #define PG8_STAGE(bufoff, gbase, voff) do { _Pragma("unroll") for (int _i = 0; _i < 2; ++_i) \
;         __builtin_amdgcn_global_load_lds((const unsigned*)((const char*)(gbase) + (voff)[_i]), (LAS unsigned*)(lds + (bufoff) + ldsw + _i * 8192), 16, 0, 0); } while (0)
; #define PG8_WAIT_V(n) asm volatile("s_waitcnt vmcnt(" #n ")" ::: "memory")
; #define PG8_BAR __builtin_amdgcn_s_barrier()
; template <class Epi, class Sched>
; __device__ __forceinline__ void gemm_phase(LAS unsigned char* lds, const Gemm g, const Sched& S, const Epi& E) {
;     ...
;     for (int i = 0; i < 2; ++i) { int R, C; stage_rc(tid * 16 + i * 8192, R, C); const int Rb = Epi::PERM ? ((R & ~31) + perm32(R & 31)) : R;
;         voffA[i] = (unsigned)(R * K + C) * 2u; voffB[i] = (unsigned)(Rb * K + C) * 2u; }
;     const size_t kstep = (size_t)(BK * 2);
;     const size_t hstep = (size_t)HALF * K * 2;
;     const size_t tstep = 2 * hstep;
;     const unsigned ldsw = (unsigned)wid * 1024u;
;     const int aoff = lds_byte(wr * 64 + fr, fq * 8), boff = lds_byte(wc * 32 + fr, fq * 8);
;     ...
;     PG8_WAIT_V(4); PG8_BAR;
;     PG8_STAGE(PG8_SB(1, 0), cB + kstep, voffB); PG8_STAGE(PG8_SA(1, 0), cA + kstep, voffA); PG8_STAGE(PG8_SB(1, 1), cB + hstep + kstep, voffB);
;     PG8_WAIT_V(6); PG8_BAR;
.LBB0_1017:
	s_lshl_b32 s0, s0, 5
	s_lshl_b32 s33, s1, 6
	s_lshl_b32 s3, s1, 13
	s_and_b32 s34, s0, 0x60
	s_mov_b64 s[0:1], 0x80
	s_add_i32 m0, s15, 0x18000
	v_lshl_add_u64 v[6:7], v[6:7], 0, s[0:1]
	s_lshl_b32 s6, s34, 7
	s_waitcnt vmcnt(4)
	s_barrier
	global_load_lds_dwordx4 v[6:7], off
	v_lshl_add_u64 v[4:5], v[4:5], 0, s[0:1]
	s_add_i32 m0, s15, 0x1a000
	s_add_i32 s35, s15, 0x8000
	s_add_i32 s36, s15, 0xa000
	global_load_lds_dwordx4 v[4:5], off
	v_lshl_add_u64 v[2:3], v[2:3], 0, s[0:1]
	s_mov_b32 m0, s35
	s_add_u32 s4, s18, 0x40080
	global_load_lds_dwordx4 v[2:3], off
	v_lshl_add_u64 v[0:1], v[0:1], 0, s[0:1]
	s_mov_b32 m0, s36
	s_addc_u32 s5, s19, 0
	global_load_lds_dwordx4 v[0:1], off
	s_add_i32 m0, s15, 0x1c000
	v_lshl_add_u64 v[0:1], s[4:5], 0, v[132:133]
	global_load_lds_dwordx4 v[0:1], off
	v_lshl_add_u64 v[0:1], s[4:5], 0, v[128:129]
	s_add_i32 m0, s15, 0x1e000
	v_bfe_u32 v145, v9, 4, 2
	global_load_lds_dwordx4 v[0:1], off
	v_and_b32_e32 v144, 15, v9
	v_lshlrev_b32_e32 v0, 4, v145
	v_lshlrev_b32_e32 v1, 2, v9
	v_lshl_or_b32 v0, v144, 6, v0
	v_and_b32_e32 v1, 32, v1
	v_bitop3_b32 v2, v0, s3, v1 bitop3:0xde
	s_waitcnt vmcnt(0)
	v_bitop3_b32 v146, v0, s6, v1 bitop3:0xde
	v_lshlrev_b32_e32 v0, 14, v13
	v_and_b32_e32 v0, 0xffff8000, v0
	v_lshl_add_u32 v0, v12, 11, v0
	v_and_b32_e32 v1, 1, v13
	v_lshl_or_b32 v0, v1, 6, v0
	v_lshl_add_u32 v136, v14, 1, v0
	v_lshlrev_b32_e32 v0, 14, v8
	v_and_b32_e32 v0, 0xffff8000, v0
	s_waitcnt vmcnt(0)
	v_lshl_add_u32 v0, v10, 11, v0
	v_and_b32_e32 v1, 1, v8
	v_lshl_or_b32 v0, v1, 6, v0
	s_add_i32 s38, 0, 0x10000
	s_add_i32 s39, 0, 0x14000
	s_sext_i32_i16 s41, s2
	s_ashr_i32 s37, s76, 31
	v_mov_b32_e32 v137, v133
	v_lshl_add_u32 v138, v11, 1, v0
	v_mov_b32_e32 v139, v133
	v_mov_b64_e32 v[140:141], 0x1600
	v_mov_b64_e32 v[142:143], 0x15ff
	v_add_u32_e32 v147, s38, v146
	v_add_u32_e32 v148, 0, v2
	v_add_u32_e32 v149, s39, v146
	s_movk_i32 s40, 0x1600
	s_barrier

; #define PG8_STAGE(bufoff, gbase, voff) do { _Pragma("unroll") for (int _i = 0; _i < 2; ++_i) \
;         __builtin_amdgcn_global_load_lds((const unsigned*)((const char*)(gbase) + (voff)[_i]), (LAS unsigned*)(lds + (bufoff) + ldsw + _i * 8192), 16, 0, 0); } while (0)
; #define PG8_LDA(dst, b, h) do { _Pragma("unroll") for (int m = 0; m < 4; ++m) _Pragma("unroll") for (int k = 0; k < 2; ++k) dst[m][k] = *(const LAS bf16x8*)(lds + PG8_SA(b, h) + aoff + m * 2048 + k * 1024); } while (0)
; #define PG8_LDB(dst, b, h) do { _Pragma("unroll") for (int n = 0; n < 2; ++n) _Pragma("unroll") for (int k = 0; k < 2; ++k) dst[n][k] = *(const LAS bf16x8*)(lds + PG8_SB(b, h) + boff + n * 2048 + k * 1024); } while (0)
; #define PG8_MMA(ai, bj, At, Bt) do { __builtin_amdgcn_s_setprio(1); _Pragma("unroll") for (int m = 0; m < 4; ++m) _Pragma("unroll") for (int n = 0; n < 2; ++n) _Pragma("unroll") for (int k = 0; k < 2; ++k) \
;         acc[ai][bj][m][n] = __builtin_amdgcn_mfma_f32_16x16x32_bf16(Bt[n][k], At[m][k], acc[ai][bj][m][n], 0, 0, 0); __builtin_amdgcn_s_setprio(0); } while (0)
; #define PG8_WAIT_L(n) asm volatile("s_waitcnt lgkmcnt(" #n ")" ::: "memory")
; template <class Epi, class Sched>
; __device__ __forceinline__ void gemm_phase(LAS unsigned char* lds, const Gemm g, const Sched& S, const Epi& E) {
;     ...
;         const bool has_next = S.next(ui + 1, nxt);
;         const char* nA = has_next ? (const char*)g.A + (size_t)nxt.pm * tstep : cA; const char* nB = has_next ? (const char*)g.Bt + (size_t)nxt.pn * tstep : cB;
;         for (int t = 0; t < nt; t += 2) {
;             const bool last = (t == nt - 2);
;             const char* a1 = cA + (size_t)(t + 1) * kstep;
;             const char* a2 = last ? nA : cA + (size_t)(t + 2) * kstep; const char* b2 = last ? nB : cB + (size_t)(t + 2) * kstep;
;             const char* a3 = a2 + kstep; const char* b3 = b2 + kstep;
;             PG8_LDB(B0, 0, 0); PG8_SCHED; PG8_LDA(At, 0, 0); PG8_STAGE(PG8_SA(1, 1), a1 + hstep, voffA);
;             PG8_WAIT_L(8); PG8_BAR; PG8_WAIT_L(0); PG8_MMA(0, 0, At, B0); PG8_BAR; PG8_SCHED;
;             PG8_LDB(B1, 0, 1); PG8_STAGE(PG8_SB(0, 0), b2, voffB);
;             PG8_BAR; PG8_WAIT_L(0); PG8_MMA(0, 1, At, B1); PG8_BAR;
;             PG8_LDA(At, 0, 1); PG8_STAGE(PG8_SA(0, 0), a2, voffA);
;             PG8_BAR; PG8_WAIT_L(0); PG8_MMA(1, 0, At, B0); PG8_BAR; PG8_SCHED;
.LBB0_1020:
	s_ashr_i32 s7, s6, 31
	v_cmp_lt_i64_e32 vcc, s[10:11], v[140:141]
	s_lshl_b64 s[10:11], s[6:7], 19
	s_add_u32 s10, s96, s10
	s_addc_u32 s11, s97, s11
	s_and_b64 s[12:13], vcc, exec
	s_cselect_b32 s7, s11, s17
	s_cselect_b32 s42, s10, s16
	s_ashr_i32 s5, s4, 31
	s_lshl_b64 s[12:13], s[4:5], 19
	s_add_u32 s12, s23, s12
	s_addc_u32 s13, s24, s13
	s_and_b64 s[20:21], vcc, exec
	s_cselect_b32 s5, s13, s19
	s_cselect_b32 s43, s12, s18
	s_add_u32 s16, s16, 0x40080
	s_addc_u32 s17, s17, 0
	s_add_u32 s44, s18, 0x100
	s_addc_u32 s45, s19, 0
	s_mov_b32 s46, -2
	ds_read_b128 v[150:153], v147
	ds_read_b128 v[154:157], v147 offset:1024
	ds_read_b128 v[158:161], v147 offset:2048
	ds_read_b128 v[162:165], v147 offset:3072
	s_add_u32 s18, s16, 0xfffc0080
	s_addc_u32 s19, s17, -1
	s_cmp_eq_u32 s46, 12
	s_cselect_b32 s21, s7, s19
	s_cselect_b32 s20, s42, s18
	s_cselect_b32 s19, s5, s45
	s_cselect_b32 s18, s43, s44
	s_add_i32 m0, s15, 0xc000
	ds_read_b128 v[166:169], v148
	ds_read_b128 v[170:173], v148 offset:1024
	ds_read_b128 v[174:177], v148 offset:2048
	ds_read_b128 v[178:181], v148 offset:3072
	ds_read_b128 v[182:185], v148 offset:4096
	ds_read_b128 v[186:189], v148 offset:5120
	ds_read_b128 v[190:193], v148 offset:6144
	ds_read_b128 v[194:197], v148 offset:7168
	global_load_lds_dwordx4 v136, s[16:17]
	s_add_i32 m0, s15, 0xe000
	s_nop 0
	global_load_lds_dwordx4 v138, s[16:17]
	s_waitcnt lgkmcnt(8)
	s_waitcnt vmcnt(26)
	s_barrier
	s_waitcnt lgkmcnt(0)
	s_setprio 1
	s_waitcnt lgkmcnt(0)
	v_mfma_f32_16x16x32_bf16 v[124:127], v[150:153], v[166:169], 0
	v_mfma_f32_16x16x32_bf16 v[116:119], v[158:161], v[166:169], 0
	v_mfma_f32_16x16x32_bf16 v[108:111], v[150:153], v[174:177], 0
	v_mfma_f32_16x16x32_bf16 v[100:103], v[158:161], v[174:177], 0
	v_mfma_f32_16x16x32_bf16 v[92:95], v[150:153], v[182:185], 0
	v_mfma_f32_16x16x32_bf16 v[84:87], v[158:161], v[182:185], 0
	v_mfma_f32_16x16x32_bf16 v[76:79], v[150:153], v[190:193], 0
	v_mfma_f32_16x16x32_bf16 v[68:71], v[158:161], v[190:193], 0
	v_mfma_f32_16x16x32_bf16 v[124:127], v[154:157], v[170:173], v[124:127]
	v_mfma_f32_16x16x32_bf16 v[116:119], v[162:165], v[170:173], v[116:119]
	v_mfma_f32_16x16x32_bf16 v[108:111], v[154:157], v[178:181], v[108:111]
	v_mfma_f32_16x16x32_bf16 v[100:103], v[162:165], v[178:181], v[100:103]
	v_mfma_f32_16x16x32_bf16 v[92:95], v[154:157], v[186:189], v[92:95]
	v_mfma_f32_16x16x32_bf16 v[84:87], v[162:165], v[186:189], v[84:87]
	v_mfma_f32_16x16x32_bf16 v[76:79], v[154:157], v[194:197], v[76:79]
	v_mfma_f32_16x16x32_bf16 v[68:71], v[162:165], v[194:197], v[68:71]
	s_setprio 0
	s_barrier
	s_add_i32 s47, s38, s25
	s_mov_b32 m0, s47
	ds_read_b128 v[202:205], v149
	ds_read_b128 v[206:209], v149 offset:1024
	ds_read_b128 v[210:213], v149 offset:2048
	ds_read_b128 v[214:217], v149 offset:3072
	global_load_lds_dwordx4 v132, s[18:19]
	s_add_i32 m0, s47, 0x2000
	s_nop 0
	global_load_lds_dwordx4 v128, s[18:19]
	s_waitcnt vmcnt(26)
	s_barrier
	s_waitcnt lgkmcnt(0)
	s_setprio 1
	s_waitcnt lgkmcnt(0)
	v_mfma_f32_16x16x32_bf16 v[120:123], v[202:205], v[166:169], 0
	v_mfma_f32_16x16x32_bf16 v[112:115], v[210:213], v[166:169], 0
	v_mfma_f32_16x16x32_bf16 v[104:107], v[202:205], v[174:177], 0
	v_mfma_f32_16x16x32_bf16 v[96:99], v[210:213], v[174:177], 0
	v_mfma_f32_16x16x32_bf16 v[88:91], v[202:205], v[182:185], 0
	v_mfma_f32_16x16x32_bf16 v[80:83], v[210:213], v[182:185], 0
	v_mfma_f32_16x16x32_bf16 v[72:75], v[202:205], v[190:193], 0
	v_mfma_f32_16x16x32_bf16 v[64:67], v[210:213], v[190:193], 0
	v_mfma_f32_16x16x32_bf16 v[120:123], v[206:209], v[170:173], v[120:123]
	v_mfma_f32_16x16x32_bf16 v[112:115], v[214:217], v[170:173], v[112:115]
	v_mfma_f32_16x16x32_bf16 v[104:107], v[206:209], v[178:181], v[104:107]
	v_mfma_f32_16x16x32_bf16 v[96:99], v[214:217], v[178:181], v[96:99]
	v_mfma_f32_16x16x32_bf16 v[88:91], v[206:209], v[186:189], v[88:91]
	v_mfma_f32_16x16x32_bf16 v[80:83], v[214:217], v[186:189], v[80:83]
	v_mfma_f32_16x16x32_bf16 v[72:75], v[206:209], v[194:197], v[72:75]
	v_mfma_f32_16x16x32_bf16 v[64:67], v[214:217], v[194:197], v[64:67]
	s_setprio 0
	s_mov_b32 m0, s15
	v_lshl_add_u64 v[220:221], s[20:21], 0, v[134:135]
	s_barrier
	ds_read_b128 v[166:169], v148 offset:16384
	ds_read_b128 v[170:173], v148 offset:17408
	ds_read_b128 v[174:177], v148 offset:18432
	ds_read_b128 v[178:181], v148 offset:19456
	ds_read_b128 v[182:185], v148 offset:20480
	ds_read_b128 v[186:189], v148 offset:21504
	ds_read_b128 v[190:193], v148 offset:22528
	ds_read_b128 v[194:197], v148 offset:23552
	global_load_lds_dwordx4 v134, s[20:21]
	v_lshl_add_u64 v[222:223], s[20:21], 0, v[130:131]
	s_mov_b32 m0, s28
	s_nop 0
	global_load_lds_dwordx4 v130, s[20:21]
	s_barrier
	s_waitcnt lgkmcnt(0)
	s_setprio 1
	s_waitcnt lgkmcnt(0)
	v_mfma_f32_16x16x32_bf16 v[60:63], v[150:153], v[166:169], 0
	v_mfma_f32_16x16x32_bf16 v[56:59], v[158:161], v[166:169], 0
	v_mfma_f32_16x16x32_bf16 v[44:47], v[150:153], v[174:177], 0
	v_mfma_f32_16x16x32_bf16 v[40:43], v[158:161], v[174:177], 0
	v_mfma_f32_16x16x32_bf16 v[28:31], v[150:153], v[182:185], 0
	v_mfma_f32_16x16x32_bf16 v[24:27], v[158:161], v[182:185], 0
	v_mfma_f32_16x16x32_bf16 v[12:15], v[150:153], v[190:193], 0
	v_mfma_f32_16x16x32_bf16 v[8:11], v[158:161], v[190:193], 0
	v_mfma_f32_16x16x32_bf16 v[60:63], v[154:157], v[170:173], v[60:63]
	v_mfma_f32_16x16x32_bf16 v[56:59], v[162:165], v[170:173], v[56:59]
	v_mfma_f32_16x16x32_bf16 v[44:47], v[154:157], v[178:181], v[44:47]
	v_mfma_f32_16x16x32_bf16 v[40:43], v[162:165], v[178:181], v[40:43]
	v_mfma_f32_16x16x32_bf16 v[28:31], v[154:157], v[186:189], v[28:31]
	v_mfma_f32_16x16x32_bf16 v[24:27], v[162:165], v[186:189], v[24:27]
	v_mfma_f32_16x16x32_bf16 v[12:15], v[154:157], v[194:197], v[12:15]
	v_mfma_f32_16x16x32_bf16 v[8:11], v[162:165], v[194:197], v[8:11]
	s_setprio 0
	s_barrier
; #define PG8_STAGE(bufoff, gbase, voff) do { _Pragma("unroll") for (int _i = 0; _i < 2; ++_i) \
;         __builtin_amdgcn_global_load_lds((const unsigned*)((const char*)(gbase) + (voff)[_i]), (LAS unsigned*)(lds + (bufoff) + ldsw + _i * 8192), 16, 0, 0); } while (0)
; #define PG8_LDA(dst, b, h) do { _Pragma("unroll") for (int m = 0; m < 4; ++m) _Pragma("unroll") for (int k = 0; k < 2; ++k) dst[m][k] = *(const LAS bf16x8*)(lds + PG8_SA(b, h) + aoff + m * 2048 + k * 1024); } while (0)
; #define PG8_LDB(dst, b, h) do { _Pragma("unroll") for (int n = 0; n < 2; ++n) _Pragma("unroll") for (int k = 0; k < 2; ++k) dst[n][k] = *(const LAS bf16x8*)(lds + PG8_SB(b, h) + boff + n * 2048 + k * 1024); } while (0)
; #define PG8_MMA(ai, bj, At, Bt) do { __builtin_amdgcn_s_setprio(1); _Pragma("unroll") for (int m = 0; m < 4; ++m) _Pragma("unroll") for (int n = 0; n < 2; ++n) _Pragma("unroll") for (int k = 0; k < 2; ++k) \
;         acc[ai][bj][m][n] = __builtin_amdgcn_mfma_f32_16x16x32_bf16(Bt[n][k], At[m][k], acc[ai][bj][m][n], 0, 0, 0); __builtin_amdgcn_s_setprio(0); } while (0)
; #define PG8_WAIT_V(n) asm volatile("s_waitcnt vmcnt(" #n ")" ::: "memory")
; #define PG8_WAIT_L(n) asm volatile("s_waitcnt lgkmcnt(" #n ")" ::: "memory")
; #define PG8_BAR __builtin_amdgcn_s_barrier()
; #define PG8_SCHED __builtin_amdgcn_sched_barrier(0)
; template <class Epi, class Sched>
; __device__ __forceinline__ void gemm_phase(LAS unsigned char* lds, const Gemm g, const Sched& S, const Epi& E) {
;     ...
;             PG8_STAGE(PG8_SB(0, 1), b2 + hstep, voffB);
;             PG8_WAIT_V(6); PG8_BAR; PG8_MMA(1, 1, At, B1); PG8_BAR;
;             PG8_LDB(B0, 1, 0); PG8_SCHED; PG8_LDA(At, 1, 0); PG8_STAGE(PG8_SA(0, 1), a2 + hstep, voffA);
;             PG8_WAIT_L(8); PG8_BAR; PG8_WAIT_L(0); PG8_MMA(0, 0, At, B0); PG8_BAR; PG8_SCHED;
;             PG8_LDB(B1, 1, 1); PG8_STAGE(PG8_SB(1, 0), b3, voffB);
;             PG8_BAR; PG8_WAIT_L(0); PG8_MMA(0, 1, At, B1); PG8_BAR;
	s_add_u32 s48, s18, 0x40000
	s_addc_u32 s49, s19, 0
	s_add_i32 s47, s39, s25
	s_mov_b32 m0, s47
	s_nop 0
	global_load_lds_dwordx4 v132, s[48:49]
	s_add_i32 m0, s47, 0x2000
	s_nop 0
	global_load_lds_dwordx4 v128, s[48:49]
	s_waitcnt vmcnt(26)
	s_barrier
	s_setprio 1
	v_mfma_f32_16x16x32_bf16 v[52:55], v[202:205], v[166:169], 0
	v_mfma_f32_16x16x32_bf16 v[48:51], v[210:213], v[166:169], 0
	v_mfma_f32_16x16x32_bf16 v[36:39], v[202:205], v[174:177], 0
	v_mfma_f32_16x16x32_bf16 v[32:35], v[210:213], v[174:177], 0
	v_mfma_f32_16x16x32_bf16 v[20:23], v[202:205], v[182:185], 0
	v_mfma_f32_16x16x32_bf16 v[16:19], v[210:213], v[182:185], 0
	v_mfma_f32_16x16x32_bf16 v[4:7], v[202:205], v[190:193], 0
	v_mfma_f32_16x16x32_bf16 v[0:3], v[210:213], v[190:193], 0
	v_mfma_f32_16x16x32_bf16 v[52:55], v[206:209], v[170:173], v[52:55]
	v_mfma_f32_16x16x32_bf16 v[48:51], v[214:217], v[170:173], v[48:51]
	v_mfma_f32_16x16x32_bf16 v[36:39], v[206:209], v[178:181], v[36:39]
	v_mfma_f32_16x16x32_bf16 v[32:35], v[214:217], v[178:181], v[32:35]
	v_mfma_f32_16x16x32_bf16 v[20:23], v[206:209], v[186:189], v[20:23]
	v_mfma_f32_16x16x32_bf16 v[16:19], v[214:217], v[186:189], v[16:19]
	v_mfma_f32_16x16x32_bf16 v[4:7], v[206:209], v[194:197], v[4:7]
	v_mfma_f32_16x16x32_bf16 v[0:3], v[214:217], v[194:197], v[0:3]
	s_setprio 0
	s_add_i32 s47, 0, 0x18000
	v_add_u32_e32 v162, s47, v146
	s_barrier
	ds_read_b128 v[150:153], v162
	ds_read_b128 v[154:157], v162 offset:1024
	ds_read_b128 v[158:161], v162 offset:2048
	ds_read_b128 v[162:165], v162 offset:3072
	s_add_u32 s20, s20, 0x40000
	s_addc_u32 s21, s21, 0
	s_mov_b32 m0, s29
	ds_read_b128 v[166:169], v148 offset:32768
	ds_read_b128 v[170:173], v148 offset:33792
	ds_read_b128 v[174:177], v148 offset:34816
	ds_read_b128 v[178:181], v148 offset:35840
	ds_read_b128 v[182:185], v148 offset:36864
	ds_read_b128 v[186:189], v148 offset:37888
	ds_read_b128 v[190:193], v148 offset:38912
	ds_read_b128 v[194:197], v148 offset:39936
	global_load_lds_dwordx4 v134, s[20:21]
	s_mov_b32 m0, s30
	s_nop 0
	global_load_lds_dwordx4 v130, s[20:21]
	s_waitcnt lgkmcnt(8)
	s_waitcnt vmcnt(26)
	s_barrier
	s_waitcnt lgkmcnt(0)
	s_setprio 1
	s_waitcnt lgkmcnt(0)
	v_mfma_f32_16x16x32_bf16 v[124:127], v[150:153], v[166:169], v[124:127]
	v_mfma_f32_16x16x32_bf16 v[116:119], v[158:161], v[166:169], v[116:119]
	v_mfma_f32_16x16x32_bf16 v[108:111], v[150:153], v[174:177], v[108:111]
	v_mfma_f32_16x16x32_bf16 v[100:103], v[158:161], v[174:177], v[100:103]
	v_mfma_f32_16x16x32_bf16 v[92:95], v[150:153], v[182:185], v[92:95]
	v_mfma_f32_16x16x32_bf16 v[84:87], v[158:161], v[182:185], v[84:87]
	v_mfma_f32_16x16x32_bf16 v[76:79], v[150:153], v[190:193], v[76:79]
	v_mfma_f32_16x16x32_bf16 v[68:71], v[158:161], v[190:193], v[68:71]
	v_mfma_f32_16x16x32_bf16 v[124:127], v[154:157], v[170:173], v[124:127]
	v_mfma_f32_16x16x32_bf16 v[116:119], v[162:165], v[170:173], v[116:119]
	v_mfma_f32_16x16x32_bf16 v[108:111], v[154:157], v[178:181], v[108:111]
	v_mfma_f32_16x16x32_bf16 v[100:103], v[162:165], v[178:181], v[100:103]
	v_mfma_f32_16x16x32_bf16 v[92:95], v[154:157], v[186:189], v[92:95]
	v_mfma_f32_16x16x32_bf16 v[84:87], v[162:165], v[186:189], v[84:87]
	v_mfma_f32_16x16x32_bf16 v[76:79], v[154:157], v[194:197], v[76:79]
	v_mfma_f32_16x16x32_bf16 v[68:71], v[162:165], v[194:197], v[68:71]
	s_setprio 0
	s_barrier
	s_add_i32 s20, 0, 0x1c000
	s_add_i32 s21, s47, s25
	v_add_u32_e32 v214, s20, v146
	s_add_u32 s0, s18, 0x80
	s_addc_u32 s1, s19, 0
	s_mov_b32 m0, s21
	ds_read_b128 v[202:205], v214
	ds_read_b128 v[206:209], v214 offset:1024
	ds_read_b128 v[210:213], v214 offset:2048
	ds_read_b128 v[214:217], v214 offset:3072
	global_load_lds_dwordx4 v132, s[0:1]
	s_add_i32 m0, s21, 0x2000
	s_nop 0
	global_load_lds_dwordx4 v128, s[0:1]
	s_waitcnt vmcnt(10)
	s_barrier
; #define PG8_STAGE(bufoff, gbase, voff) do { _Pragma("unroll") for (int _i = 0; _i < 2; ++_i) \
;         __builtin_amdgcn_global_load_lds((const unsigned*)((const char*)(gbase) + (voff)[_i]), (LAS unsigned*)(lds + (bufoff) + ldsw + _i * 8192), 16, 0, 0); } while (0)
; #define PG8_LDA(dst, b, h) do { _Pragma("unroll") for (int m = 0; m < 4; ++m) _Pragma("unroll") for (int k = 0; k < 2; ++k) dst[m][k] = *(const LAS bf16x8*)(lds + PG8_SA(b, h) + aoff + m * 2048 + k * 1024); } while (0)
; #define PG8_MMA(ai, bj, At, Bt) do { __builtin_amdgcn_s_setprio(1); _Pragma("unroll") for (int m = 0; m < 4; ++m) _Pragma("unroll") for (int n = 0; n < 2; ++n) _Pragma("unroll") for (int k = 0; k < 2; ++k) \
;         acc[ai][bj][m][n] = __builtin_amdgcn_mfma_f32_16x16x32_bf16(Bt[n][k], At[m][k], acc[ai][bj][m][n], 0, 0, 0); __builtin_amdgcn_s_setprio(0); } while (0)
; #define PG8_WAIT_V(n) asm volatile("s_waitcnt vmcnt(" #n ")" ::: "memory")
; #define PG8_WAIT_L(n) asm volatile("s_waitcnt lgkmcnt(" #n ")" ::: "memory")
; #define PG8_BAR __builtin_amdgcn_s_barrier()
; #define PG8_SCHED __builtin_amdgcn_sched_barrier(0)
; template <class Epi, class Sched>
; __device__ __forceinline__ void gemm_phase(LAS unsigned char* lds, const Gemm g, const Sched& S, const Epi& E) {
;     ...
;             PG8_BAR; PG8_WAIT_L(0); PG8_MMA(0, 1, At, B1); PG8_BAR;
;             PG8_LDA(At, 1, 1); PG8_STAGE(PG8_SA(1, 0), a3, voffA);
;             PG8_BAR; PG8_WAIT_L(0); PG8_MMA(1, 0, At, B0); PG8_BAR; PG8_SCHED;
;             PG8_STAGE(PG8_SB(1, 1), b3 + hstep, voffB);
;             PG8_WAIT_V(6); PG8_BAR; PG8_MMA(1, 1, At, B1); PG8_BAR;
;         }
	s_waitcnt lgkmcnt(0)
	s_setprio 1
	s_waitcnt lgkmcnt(0)
	v_mfma_f32_16x16x32_bf16 v[120:123], v[202:205], v[166:169], v[120:123]
	v_mfma_f32_16x16x32_bf16 v[112:115], v[210:213], v[166:169], v[112:115]
	v_mfma_f32_16x16x32_bf16 v[104:107], v[202:205], v[174:177], v[104:107]
	v_mfma_f32_16x16x32_bf16 v[96:99], v[210:213], v[174:177], v[96:99]
	v_mfma_f32_16x16x32_bf16 v[88:91], v[202:205], v[182:185], v[88:91]
	v_mfma_f32_16x16x32_bf16 v[80:83], v[210:213], v[182:185], v[80:83]
	v_mfma_f32_16x16x32_bf16 v[72:75], v[202:205], v[190:193], v[72:75]
	v_mfma_f32_16x16x32_bf16 v[64:67], v[210:213], v[190:193], v[64:67]
	v_mfma_f32_16x16x32_bf16 v[120:123], v[206:209], v[170:173], v[120:123]
	v_mfma_f32_16x16x32_bf16 v[112:115], v[214:217], v[170:173], v[112:115]
	v_mfma_f32_16x16x32_bf16 v[104:107], v[206:209], v[178:181], v[104:107]
	v_mfma_f32_16x16x32_bf16 v[96:99], v[214:217], v[178:181], v[96:99]
	v_mfma_f32_16x16x32_bf16 v[88:91], v[206:209], v[186:189], v[88:91]
	v_mfma_f32_16x16x32_bf16 v[80:83], v[214:217], v[186:189], v[80:83]
	v_mfma_f32_16x16x32_bf16 v[72:75], v[206:209], v[194:197], v[72:75]
	v_mfma_f32_16x16x32_bf16 v[64:67], v[214:217], v[194:197], v[64:67]
	s_setprio 0
	s_mov_b32 m0, s35
	s_mov_b64 s[0:1], 0x80
	v_lshl_add_u64 v[198:199], v[220:221], 0, s[0:1]
	s_barrier
	ds_read_b128 v[166:169], v148 offset:49152
	ds_read_b128 v[170:173], v148 offset:50176
	ds_read_b128 v[174:177], v148 offset:51200
	ds_read_b128 v[178:181], v148 offset:52224
	ds_read_b128 v[182:185], v148 offset:53248
	ds_read_b128 v[186:189], v148 offset:54272
	ds_read_b128 v[190:193], v148 offset:55296
	ds_read_b128 v[194:197], v148 offset:56320
	global_load_lds_dwordx4 v[198:199], off
	v_lshl_add_u64 v[198:199], v[222:223], 0, s[0:1]
	s_mov_b32 m0, s36
	s_nop 0
	global_load_lds_dwordx4 v[198:199], off
	s_barrier
	s_waitcnt lgkmcnt(0)
	s_setprio 1
	s_waitcnt lgkmcnt(0)
	v_mfma_f32_16x16x32_bf16 v[60:63], v[150:153], v[166:169], v[60:63]
	v_mfma_f32_16x16x32_bf16 v[56:59], v[158:161], v[166:169], v[56:59]
	v_mfma_f32_16x16x32_bf16 v[44:47], v[150:153], v[174:177], v[44:47]
	v_mfma_f32_16x16x32_bf16 v[40:43], v[158:161], v[174:177], v[40:43]
	v_mfma_f32_16x16x32_bf16 v[28:31], v[150:153], v[182:185], v[28:31]
	v_mfma_f32_16x16x32_bf16 v[24:27], v[158:161], v[182:185], v[24:27]
	v_mfma_f32_16x16x32_bf16 v[12:15], v[150:153], v[190:193], v[12:15]
	v_mfma_f32_16x16x32_bf16 v[8:11], v[158:161], v[190:193], v[8:11]
	v_mfma_f32_16x16x32_bf16 v[60:63], v[154:157], v[170:173], v[60:63]
	v_mfma_f32_16x16x32_bf16 v[56:59], v[162:165], v[170:173], v[56:59]
	v_mfma_f32_16x16x32_bf16 v[44:47], v[154:157], v[178:181], v[44:47]
	v_mfma_f32_16x16x32_bf16 v[40:43], v[162:165], v[178:181], v[40:43]
	v_mfma_f32_16x16x32_bf16 v[28:31], v[154:157], v[186:189], v[28:31]
	v_mfma_f32_16x16x32_bf16 v[24:27], v[162:165], v[186:189], v[24:27]
	v_mfma_f32_16x16x32_bf16 v[12:15], v[154:157], v[194:197], v[12:15]
	v_mfma_f32_16x16x32_bf16 v[8:11], v[162:165], v[194:197], v[8:11]
	s_setprio 0
	s_barrier
	s_add_u32 s18, s18, 0x40080
	s_addc_u32 s19, s19, 0
	s_add_i32 s20, s20, s25
	s_mov_b32 m0, s20
	s_nop 0
	global_load_lds_dwordx4 v132, s[18:19]
	s_add_i32 m0, s20, 0x2000
	s_nop 0
	global_load_lds_dwordx4 v128, s[18:19]
	s_waitcnt vmcnt(10)
	s_barrier
	s_setprio 1
	v_mfma_f32_16x16x32_bf16 v[52:55], v[202:205], v[166:169], v[52:55]
	v_mfma_f32_16x16x32_bf16 v[48:51], v[210:213], v[166:169], v[48:51]
	v_mfma_f32_16x16x32_bf16 v[36:39], v[202:205], v[174:177], v[36:39]
	v_mfma_f32_16x16x32_bf16 v[32:35], v[210:213], v[174:177], v[32:35]
	v_mfma_f32_16x16x32_bf16 v[20:23], v[202:205], v[182:185], v[20:23]
	v_mfma_f32_16x16x32_bf16 v[16:19], v[210:213], v[182:185], v[16:19]
	v_mfma_f32_16x16x32_bf16 v[4:7], v[202:205], v[190:193], v[4:7]
	v_mfma_f32_16x16x32_bf16 v[0:3], v[210:213], v[190:193], v[0:3]
	v_mfma_f32_16x16x32_bf16 v[52:55], v[206:209], v[170:173], v[52:55]
	v_mfma_f32_16x16x32_bf16 v[48:51], v[214:217], v[170:173], v[48:51]
	v_mfma_f32_16x16x32_bf16 v[36:39], v[206:209], v[178:181], v[36:39]
	v_mfma_f32_16x16x32_bf16 v[32:35], v[214:217], v[178:181], v[32:35]
	v_mfma_f32_16x16x32_bf16 v[20:23], v[206:209], v[186:189], v[20:23]
	v_mfma_f32_16x16x32_bf16 v[16:19], v[214:217], v[186:189], v[16:19]
	v_mfma_f32_16x16x32_bf16 v[4:7], v[206:209], v[194:197], v[4:7]
	v_mfma_f32_16x16x32_bf16 v[0:3], v[214:217], v[194:197], v[0:3]
	s_setprio 0
	s_add_i32 s46, s46, 2
	s_add_u32 s16, s16, 0x100
	s_addc_u32 s17, s17, 0
	s_add_u32 s44, s44, 0x100
	s_addc_u32 s45, s45, 0
	s_cmp_gt_u32 s46, 13
	s_barrier

; #define PG8_STAGE(bufoff, gbase, voff) do { _Pragma("unroll") for (int _i = 0; _i < 2; ++_i) \
;         __builtin_amdgcn_global_load_lds((const unsigned*)((const char*)(gbase) + (voff)[_i]), (LAS unsigned*)(lds + (bufoff) + ldsw + _i * 8192), 16, 0, 0); } while (0)
; #define PG8_WAIT_V(n) asm volatile("s_waitcnt vmcnt(" #n ")" ::: "memory")
; #define PG8_BAR __builtin_amdgcn_s_barrier()
; template <class Epi, class Sched>
; __device__ __forceinline__ void gemm_phase(LAS unsigned char* lds, const Gemm g, const Sched& S, const Epi& E) {
;     ...
;     for (int i = 0; i < 2; ++i) { int R, C; stage_rc(tid * 16 + i * 8192, R, C); const int Rb = Epi::PERM ? ((R & ~31) + perm32(R & 31)) : R;
;         voffA[i] = (unsigned)(R * K + C) * 2u; voffB[i] = (unsigned)(Rb * K + C) * 2u; }
;     const size_t kstep = (size_t)(BK * 2);
;     const size_t hstep = (size_t)HALF * K * 2;
;     const size_t tstep = 2 * hstep;
;     const unsigned ldsw = (unsigned)wid * 1024u;
;     const int aoff = lds_byte(wr * 64 + fr, fq * 8), boff = lds_byte(wc * 32 + fr, fq * 8);
;     ...
;     PG8_WAIT_V(4); PG8_BAR;
;     PG8_STAGE(PG8_SB(1, 0), cB + kstep, voffB); PG8_STAGE(PG8_SA(1, 0), cA + kstep, voffA); PG8_STAGE(PG8_SB(1, 1), cB + hstep + kstep, voffB);
;     PG8_WAIT_V(6); PG8_BAR;
.LBB0_1085:
	s_add_u32 s40, s64, 0x3288000
	s_addc_u32 s41, s65, 0
	s_lshl_b32 s42, s0, 6
	s_lshl_b32 s3, s0, 13
	s_lshl_b32 s0, s1, 5
	s_and_b32 s43, s0, 0x60
	s_mov_b64 s[0:1], 0x80
	s_add_i32 m0, s35, 0x18000
	v_lshl_add_u64 v[6:7], v[6:7], 0, s[0:1]
	s_lshl_b32 s6, s43, 7
	s_waitcnt vmcnt(4)
	s_barrier
	global_load_lds_dwordx4 v[6:7], off
	v_lshl_add_u64 v[4:5], v[4:5], 0, s[0:1]
	s_add_i32 m0, s35, 0x1a000
	s_add_i32 s44, s35, 0x8000
	s_add_i32 s45, s35, 0xa000
	global_load_lds_dwordx4 v[4:5], off
	v_lshl_add_u64 v[2:3], v[2:3], 0, s[0:1]
	s_mov_b32 m0, s44
	s_add_u32 s4, s24, 0xb0080
	global_load_lds_dwordx4 v[2:3], off
	v_lshl_add_u64 v[0:1], v[0:1], 0, s[0:1]
	s_mov_b32 m0, s45
	s_addc_u32 s5, s25, 0
	global_load_lds_dwordx4 v[0:1], off
	s_add_i32 m0, s35, 0x1c000
	v_lshl_add_u64 v[0:1], s[4:5], 0, v[190:191]
	global_load_lds_dwordx4 v[0:1], off
	v_lshl_add_u64 v[0:1], s[4:5], 0, v[194:195]
	s_add_i32 m0, s35, 0x1e000
	v_bfe_u32 v238, v8, 4, 2
	global_load_lds_dwordx4 v[0:1], off
	v_and_b32_e32 v239, 15, v8
	v_lshlrev_b32_e32 v0, 4, v238
	v_lshlrev_b32_e32 v1, 2, v8
	v_lshl_or_b32 v0, v239, 6, v0
	v_and_b32_e32 v1, 32, v1
	v_bitop3_b32 v2, v0, s3, v1 bitop3:0xde
	v_bitop3_b32 v240, v0, s6, v1 bitop3:0xde
	v_lshrrev_b32_e32 v1, 1, v9
	v_mul_lo_u32 v0, v11, s2
	s_mov_b32 s3, 0xb000
	v_mad_u64_u32 v[0:1], s[6:7], v1, s3, v[0:1]
	v_or_b32_e32 v0, v0, v10
	s_mov_b64 s[4:5], 0xb0080
	v_add_lshl_u32 v0, v0, v12, 1
	v_mov_b32_e32 v1, v191
	v_lshl_add_u64 v[196:197], v[0:1], 0, s[4:5]
	v_lshrrev_b32_e32 v1, 1, v13
	v_mul_lo_u32 v0, v14, s2
	v_mad_u64_u32 v[0:1], s[2:3], v1, s3, v[0:1]
	s_waitcnt vmcnt(0)
	v_or_b32_e32 v0, v0, v15
	v_add_lshl_u32 v0, v0, v16, 1
	v_mov_b32_e32 v1, v191
	s_add_i32 s48, 0, 0x10000
	s_add_i32 s49, 0, 0x14000
	s_ashr_i32 s46, s76, 31
	s_ashr_i32 s47, s71, 31
	v_lshl_add_u64 v[198:199], v[0:1], 0, s[4:5]
	v_mov_b64_e32 v[202:203], 0x400
	v_mov_b64_e32 v[204:205], 0x3ff
	v_add_u32_e32 v241, s48, v240
	v_add_u32_e32 v242, 0, v2
	v_add_u32_e32 v243, s49, v240
	s_mov_b64 s[8:9], 0x8000
	s_mov_b64 s[10:11], 0x10000
	s_mov_b64 s[12:13], 0x18000
	s_mov_b64 s[14:15], 0x40000
	s_mov_b64 s[16:17], 0x48000
	s_mov_b64 s[18:19], 0x50000
	s_mov_b64 s[20:21], 0x58000
	s_barrier

; #define PG8_STAGE(bufoff, gbase, voff) do { _Pragma("unroll") for (int _i = 0; _i < 2; ++_i) \
;         __builtin_amdgcn_global_load_lds((const unsigned*)((const char*)(gbase) + (voff)[_i]), (LAS unsigned*)(lds + (bufoff) + ldsw + _i * 8192), 16, 0, 0); } while (0)
; #define PG8_LDA(dst, b, h) do { _Pragma("unroll") for (int m = 0; m < 4; ++m) _Pragma("unroll") for (int k = 0; k < 2; ++k) dst[m][k] = *(const LAS bf16x8*)(lds + PG8_SA(b, h) + aoff + m * 2048 + k * 1024); } while (0)
; #define PG8_LDB(dst, b, h) do { _Pragma("unroll") for (int n = 0; n < 2; ++n) _Pragma("unroll") for (int k = 0; k < 2; ++k) dst[n][k] = *(const LAS bf16x8*)(lds + PG8_SB(b, h) + boff + n * 2048 + k * 1024); } while (0)
; #define PG8_MMA(ai, bj, At, Bt) do { __builtin_amdgcn_s_setprio(1); _Pragma("unroll") for (int m = 0; m < 4; ++m) _Pragma("unroll") for (int n = 0; n < 2; ++n) _Pragma("unroll") for (int k = 0; k < 2; ++k) \
;         acc[ai][bj][m][n] = __builtin_amdgcn_mfma_f32_16x16x32_bf16(Bt[n][k], At[m][k], acc[ai][bj][m][n], 0, 0, 0); __builtin_amdgcn_s_setprio(0); } while (0)
; #define PG8_WAIT_V(n) asm volatile("s_waitcnt vmcnt(" #n ")" ::: "memory")
; #define PG8_WAIT_L(n) asm volatile("s_waitcnt lgkmcnt(" #n ")" ::: "memory")
; template <class Epi, class Sched>
; __device__ __forceinline__ void gemm_phase(LAS unsigned char* lds, const Gemm g, const Sched& S, const Epi& E) {
;     ...
;         for (int t = 0; t < nt; t += 2) {
;             const bool last = (t == nt - 2);
;             const char* a1 = cA + (size_t)(t + 1) * kstep;
;             const char* a2 = last ? nA : cA + (size_t)(t + 2) * kstep; const char* b2 = last ? nB : cB + (size_t)(t + 2) * kstep;
;             const char* a3 = a2 + kstep; const char* b3 = b2 + kstep;
;             PG8_LDB(B0, 0, 0); PG8_SCHED; PG8_LDA(At, 0, 0); PG8_STAGE(PG8_SA(1, 1), a1 + hstep, voffA);
;             PG8_WAIT_L(8); PG8_BAR; PG8_WAIT_L(0); PG8_MMA(0, 0, At, B0); PG8_BAR; PG8_SCHED;
;             PG8_LDB(B1, 0, 1); PG8_STAGE(PG8_SB(0, 0), b2, voffB);
;             PG8_BAR; PG8_WAIT_L(0); PG8_MMA(0, 1, At, B1); PG8_BAR;
;             PG8_LDA(At, 0, 1); PG8_STAGE(PG8_SA(0, 0), a2, voffA);
;             PG8_BAR; PG8_WAIT_L(0); PG8_MMA(1, 0, At, B0); PG8_BAR; PG8_SCHED;
;             PG8_STAGE(PG8_SB(0, 1), b2 + hstep, voffB);
;             PG8_WAIT_V(6); PG8_BAR; PG8_MMA(1, 1, At, B1); PG8_BAR;
.LBB0_1096:
	s_add_u32 s54, s24, 0x100
	s_addc_u32 s55, s25, 0
	s_mov_b32 s56, -2
	ds_read_b128 v[128:131], v241
	ds_read_b128 v[132:135], v241 offset:1024
	ds_read_b128 v[136:139], v241 offset:2048
	ds_read_b128 v[140:143], v241 offset:3072
	s_add_u32 s24, s22, 0x100
	s_addc_u32 s25, s23, 0
	s_cmp_eq_u32 s56, 40
	s_cselect_b32 s29, s5, s25
	s_cselect_b32 s28, s4, s24
	s_cselect_b32 s27, s7, s55
	s_cselect_b32 s26, s6, s54
	v_lshl_add_u64 v[176:177], s[22:23], 0, v[196:197]
	s_add_i32 m0, s35, 0xc000
	ds_read_b128 v[144:147], v242
	ds_read_b128 v[148:151], v242 offset:1024
	ds_read_b128 v[152:155], v242 offset:2048
	ds_read_b128 v[156:159], v242 offset:3072
	ds_read_b128 v[160:163], v242 offset:4096
	ds_read_b128 v[164:167], v242 offset:5120
	ds_read_b128 v[168:171], v242 offset:6144
	ds_read_b128 v[172:175], v242 offset:7168
	global_load_lds_dwordx4 v[176:177], off
	v_lshl_add_u64 v[176:177], s[22:23], 0, v[198:199]
	s_add_i32 m0, s35, 0xe000
	s_nop 0
	global_load_lds_dwordx4 v[176:177], off
	s_waitcnt lgkmcnt(8)
	s_waitcnt vmcnt(26)
	s_barrier
	s_waitcnt lgkmcnt(0)
	s_setprio 1
	s_waitcnt lgkmcnt(0)
	v_mfma_f32_16x16x32_bf16 v[124:127], v[128:131], v[144:147], 0
	v_mfma_f32_16x16x32_bf16 v[120:123], v[136:139], v[144:147], 0
	v_mfma_f32_16x16x32_bf16 v[108:111], v[128:131], v[152:155], 0
	v_mfma_f32_16x16x32_bf16 v[104:107], v[136:139], v[152:155], 0
	v_mfma_f32_16x16x32_bf16 v[92:95], v[128:131], v[160:163], 0
	v_mfma_f32_16x16x32_bf16 v[88:91], v[136:139], v[160:163], 0
	v_mfma_f32_16x16x32_bf16 v[76:79], v[128:131], v[168:171], 0
	v_mfma_f32_16x16x32_bf16 v[72:75], v[136:139], v[168:171], 0
	v_mfma_f32_16x16x32_bf16 v[124:127], v[132:135], v[148:151], v[124:127]
	v_mfma_f32_16x16x32_bf16 v[120:123], v[140:143], v[148:151], v[120:123]
	v_mfma_f32_16x16x32_bf16 v[108:111], v[132:135], v[156:159], v[108:111]
	v_mfma_f32_16x16x32_bf16 v[104:107], v[140:143], v[156:159], v[104:107]
	v_mfma_f32_16x16x32_bf16 v[92:95], v[132:135], v[164:167], v[92:95]
	v_mfma_f32_16x16x32_bf16 v[88:91], v[140:143], v[164:167], v[88:91]
	v_mfma_f32_16x16x32_bf16 v[76:79], v[132:135], v[172:175], v[76:79]
	v_mfma_f32_16x16x32_bf16 v[72:75], v[140:143], v[172:175], v[72:75]
	s_setprio 0
	s_barrier
	s_add_i32 s22, s48, s34
	s_mov_b32 m0, s22
	ds_read_b128 v[176:179], v243
	ds_read_b128 v[180:183], v243 offset:1024
	ds_read_b128 v[184:187], v243 offset:2048
	ds_read_b128 v[206:209], v243 offset:3072
	global_load_lds_dwordx4 v190, s[26:27]
	s_add_i32 m0, s22, 0x2000
	s_nop 0
	global_load_lds_dwordx4 v194, s[26:27]
	s_waitcnt vmcnt(26)
	s_barrier
	s_waitcnt lgkmcnt(0)
	s_setprio 1
	s_waitcnt lgkmcnt(0)
	v_mfma_f32_16x16x32_bf16 v[116:119], v[176:179], v[144:147], 0
	v_mfma_f32_16x16x32_bf16 v[112:115], v[184:187], v[144:147], 0
	v_mfma_f32_16x16x32_bf16 v[100:103], v[176:179], v[152:155], 0
	v_mfma_f32_16x16x32_bf16 v[96:99], v[184:187], v[152:155], 0
	v_mfma_f32_16x16x32_bf16 v[84:87], v[176:179], v[160:163], 0
	v_mfma_f32_16x16x32_bf16 v[80:83], v[184:187], v[160:163], 0
	v_mfma_f32_16x16x32_bf16 v[68:71], v[176:179], v[168:171], 0
	v_mfma_f32_16x16x32_bf16 v[64:67], v[184:187], v[168:171], 0
	v_mfma_f32_16x16x32_bf16 v[116:119], v[180:183], v[148:151], v[116:119]
	v_mfma_f32_16x16x32_bf16 v[112:115], v[206:209], v[148:151], v[112:115]
	v_mfma_f32_16x16x32_bf16 v[100:103], v[180:183], v[156:159], v[100:103]
	v_mfma_f32_16x16x32_bf16 v[96:99], v[206:209], v[156:159], v[96:99]
	v_mfma_f32_16x16x32_bf16 v[84:87], v[180:183], v[164:167], v[84:87]
	v_mfma_f32_16x16x32_bf16 v[80:83], v[206:209], v[164:167], v[80:83]
	v_mfma_f32_16x16x32_bf16 v[68:71], v[180:183], v[172:175], v[68:71]
	v_mfma_f32_16x16x32_bf16 v[64:67], v[206:209], v[172:175], v[64:67]
	s_setprio 0
	s_mov_b32 m0, s35
	v_lshl_add_u64 v[214:215], s[28:29], 0, v[188:189]
	s_barrier
	ds_read_b128 v[144:147], v242 offset:16384
	ds_read_b128 v[148:151], v242 offset:17408
	ds_read_b128 v[152:155], v242 offset:18432
	ds_read_b128 v[156:159], v242 offset:19456
	ds_read_b128 v[160:163], v242 offset:20480
	ds_read_b128 v[164:167], v242 offset:21504
	ds_read_b128 v[168:171], v242 offset:22528
	ds_read_b128 v[172:175], v242 offset:23552
	global_load_lds_dwordx4 v188, s[28:29]
	v_lshl_add_u64 v[216:217], s[28:29], 0, v[192:193]
	s_mov_b32 m0, s36
	s_nop 0
	global_load_lds_dwordx4 v192, s[28:29]
	s_barrier
	s_waitcnt lgkmcnt(0)
	s_setprio 1
	s_waitcnt lgkmcnt(0)
	v_mfma_f32_16x16x32_bf16 v[60:63], v[128:131], v[144:147], 0
	v_mfma_f32_16x16x32_bf16 v[56:59], v[136:139], v[144:147], 0
	v_mfma_f32_16x16x32_bf16 v[44:47], v[128:131], v[152:155], 0
	v_mfma_f32_16x16x32_bf16 v[40:43], v[136:139], v[152:155], 0
	v_mfma_f32_16x16x32_bf16 v[28:31], v[128:131], v[160:163], 0
	v_mfma_f32_16x16x32_bf16 v[24:27], v[136:139], v[160:163], 0
	v_mfma_f32_16x16x32_bf16 v[12:15], v[128:131], v[168:171], 0
	v_mfma_f32_16x16x32_bf16 v[8:11], v[136:139], v[168:171], 0
	v_mfma_f32_16x16x32_bf16 v[60:63], v[132:135], v[148:151], v[60:63]
	v_mfma_f32_16x16x32_bf16 v[56:59], v[140:143], v[148:151], v[56:59]
	v_mfma_f32_16x16x32_bf16 v[44:47], v[132:135], v[156:159], v[44:47]
	v_mfma_f32_16x16x32_bf16 v[40:43], v[140:143], v[156:159], v[40:43]
	v_mfma_f32_16x16x32_bf16 v[28:31], v[132:135], v[164:167], v[28:31]
	v_mfma_f32_16x16x32_bf16 v[24:27], v[140:143], v[164:167], v[24:27]
	v_mfma_f32_16x16x32_bf16 v[12:15], v[132:135], v[172:175], v[12:15]
	v_mfma_f32_16x16x32_bf16 v[8:11], v[140:143], v[172:175], v[8:11]
	s_setprio 0
	s_barrier
	s_add_u32 s22, s26, 0xb0000
	s_addc_u32 s23, s27, 0
	s_add_i32 s57, s49, s34
	s_mov_b32 m0, s57
	s_nop 0
	global_load_lds_dwordx4 v190, s[22:23]
	s_add_i32 m0, s57, 0x2000
	s_nop 0
	global_load_lds_dwordx4 v194, s[22:23]
	s_waitcnt vmcnt(26)
	s_barrier
; #define PG8_STAGE(bufoff, gbase, voff) do { _Pragma("unroll") for (int _i = 0; _i < 2; ++_i) \
;         __builtin_amdgcn_global_load_lds((const unsigned*)((const char*)(gbase) + (voff)[_i]), (LAS unsigned*)(lds + (bufoff) + ldsw + _i * 8192), 16, 0, 0); } while (0)
; #define PG8_LDA(dst, b, h) do { _Pragma("unroll") for (int m = 0; m < 4; ++m) _Pragma("unroll") for (int k = 0; k < 2; ++k) dst[m][k] = *(const LAS bf16x8*)(lds + PG8_SA(b, h) + aoff + m * 2048 + k * 1024); } while (0)
; #define PG8_LDB(dst, b, h) do { _Pragma("unroll") for (int n = 0; n < 2; ++n) _Pragma("unroll") for (int k = 0; k < 2; ++k) dst[n][k] = *(const LAS bf16x8*)(lds + PG8_SB(b, h) + boff + n * 2048 + k * 1024); } while (0)
; #define PG8_MMA(ai, bj, At, Bt) do { __builtin_amdgcn_s_setprio(1); _Pragma("unroll") for (int m = 0; m < 4; ++m) _Pragma("unroll") for (int n = 0; n < 2; ++n) _Pragma("unroll") for (int k = 0; k < 2; ++k) \
;         acc[ai][bj][m][n] = __builtin_amdgcn_mfma_f32_16x16x32_bf16(Bt[n][k], At[m][k], acc[ai][bj][m][n], 0, 0, 0); __builtin_amdgcn_s_setprio(0); } while (0)
; #define PG8_WAIT_V(n) asm volatile("s_waitcnt vmcnt(" #n ")" ::: "memory")
; #define PG8_WAIT_L(n) asm volatile("s_waitcnt lgkmcnt(" #n ")" ::: "memory")
; #define PG8_BAR __builtin_amdgcn_s_barrier()
; #define PG8_SCHED __builtin_amdgcn_sched_barrier(0)
; template <class Epi, class Sched>
; __device__ __forceinline__ void gemm_phase(LAS unsigned char* lds, const Gemm g, const Sched& S, const Epi& E) {
;     ...
;             PG8_WAIT_V(6); PG8_BAR; PG8_MMA(1, 1, At, B1); PG8_BAR;
;             PG8_LDB(B0, 1, 0); PG8_SCHED; PG8_LDA(At, 1, 0); PG8_STAGE(PG8_SA(0, 1), a2 + hstep, voffA);
;             PG8_WAIT_L(8); PG8_BAR; PG8_WAIT_L(0); PG8_MMA(0, 0, At, B0); PG8_BAR; PG8_SCHED;
;             PG8_LDB(B1, 1, 1); PG8_STAGE(PG8_SB(1, 0), b3, voffB);
;             PG8_BAR; PG8_WAIT_L(0); PG8_MMA(0, 1, At, B1); PG8_BAR;
	s_setprio 1
	v_mfma_f32_16x16x32_bf16 v[52:55], v[176:179], v[144:147], 0
	v_mfma_f32_16x16x32_bf16 v[48:51], v[184:187], v[144:147], 0
	v_mfma_f32_16x16x32_bf16 v[36:39], v[176:179], v[152:155], 0
	v_mfma_f32_16x16x32_bf16 v[32:35], v[184:187], v[152:155], 0
	v_mfma_f32_16x16x32_bf16 v[20:23], v[176:179], v[160:163], 0
	v_mfma_f32_16x16x32_bf16 v[16:19], v[184:187], v[160:163], 0
	v_mfma_f32_16x16x32_bf16 v[4:7], v[176:179], v[168:171], 0
	v_mfma_f32_16x16x32_bf16 v[0:3], v[184:187], v[168:171], 0
	v_mfma_f32_16x16x32_bf16 v[52:55], v[180:183], v[148:151], v[52:55]
	v_mfma_f32_16x16x32_bf16 v[48:51], v[206:209], v[148:151], v[48:51]
	v_mfma_f32_16x16x32_bf16 v[36:39], v[180:183], v[156:159], v[36:39]
	v_mfma_f32_16x16x32_bf16 v[32:35], v[206:209], v[156:159], v[32:35]
	v_mfma_f32_16x16x32_bf16 v[20:23], v[180:183], v[164:167], v[20:23]
	v_mfma_f32_16x16x32_bf16 v[16:19], v[206:209], v[164:167], v[16:19]
	v_mfma_f32_16x16x32_bf16 v[4:7], v[180:183], v[172:175], v[4:7]
	v_mfma_f32_16x16x32_bf16 v[0:3], v[206:209], v[172:175], v[0:3]
	s_setprio 0
	s_add_i32 s57, 0, 0x18000
	v_add_u32_e32 v140, s57, v240
	s_barrier
	ds_read_b128 v[128:131], v140
	ds_read_b128 v[132:135], v140 offset:1024
	ds_read_b128 v[136:139], v140 offset:2048
	ds_read_b128 v[140:143], v140 offset:3072
	s_add_u32 s22, s28, 0xb0000
	s_addc_u32 s23, s29, 0
	s_mov_b32 m0, s37
	ds_read_b128 v[144:147], v242 offset:32768
	ds_read_b128 v[148:151], v242 offset:33792
	ds_read_b128 v[152:155], v242 offset:34816
	ds_read_b128 v[156:159], v242 offset:35840
	ds_read_b128 v[160:163], v242 offset:36864
	ds_read_b128 v[164:167], v242 offset:37888
	ds_read_b128 v[168:171], v242 offset:38912
	ds_read_b128 v[172:175], v242 offset:39936
	global_load_lds_dwordx4 v188, s[22:23]
	s_mov_b32 m0, s38
	s_nop 0
	global_load_lds_dwordx4 v192, s[22:23]
	s_waitcnt lgkmcnt(8)
	s_waitcnt vmcnt(26)
	s_barrier
	s_waitcnt lgkmcnt(0)
	s_setprio 1
	s_waitcnt lgkmcnt(0)
	v_mfma_f32_16x16x32_bf16 v[124:127], v[128:131], v[144:147], v[124:127]
	v_mfma_f32_16x16x32_bf16 v[120:123], v[136:139], v[144:147], v[120:123]
	v_mfma_f32_16x16x32_bf16 v[108:111], v[128:131], v[152:155], v[108:111]
	v_mfma_f32_16x16x32_bf16 v[104:107], v[136:139], v[152:155], v[104:107]
	v_mfma_f32_16x16x32_bf16 v[92:95], v[128:131], v[160:163], v[92:95]
	v_mfma_f32_16x16x32_bf16 v[88:91], v[136:139], v[160:163], v[88:91]
	v_mfma_f32_16x16x32_bf16 v[76:79], v[128:131], v[168:171], v[76:79]
	v_mfma_f32_16x16x32_bf16 v[72:75], v[136:139], v[168:171], v[72:75]
	v_mfma_f32_16x16x32_bf16 v[124:127], v[132:135], v[148:151], v[124:127]
	v_mfma_f32_16x16x32_bf16 v[120:123], v[140:143], v[148:151], v[120:123]
	v_mfma_f32_16x16x32_bf16 v[108:111], v[132:135], v[156:159], v[108:111]
	v_mfma_f32_16x16x32_bf16 v[104:107], v[140:143], v[156:159], v[104:107]
	v_mfma_f32_16x16x32_bf16 v[92:95], v[132:135], v[164:167], v[92:95]
	v_mfma_f32_16x16x32_bf16 v[88:91], v[140:143], v[164:167], v[88:91]
	v_mfma_f32_16x16x32_bf16 v[76:79], v[132:135], v[172:175], v[76:79]
	v_mfma_f32_16x16x32_bf16 v[72:75], v[140:143], v[172:175], v[72:75]
	s_setprio 0
	s_barrier
	s_add_i32 s28, 0, 0x1c000
	s_add_i32 s22, s57, s34
	v_add_u32_e32 v206, s28, v240
	s_add_u32 s0, s26, 0x80
	s_addc_u32 s1, s27, 0
	s_mov_b32 m0, s22
	ds_read_b128 v[176:179], v206
	ds_read_b128 v[180:183], v206 offset:1024
	ds_read_b128 v[184:187], v206 offset:2048
	ds_read_b128 v[206:209], v206 offset:3072
	global_load_lds_dwordx4 v190, s[0:1]
	s_add_i32 m0, s22, 0x2000
	s_nop 0
	global_load_lds_dwordx4 v194, s[0:1]
	s_waitcnt vmcnt(10)
	s_barrier
; #define PG8_STAGE(bufoff, gbase, voff) do { _Pragma("unroll") for (int _i = 0; _i < 2; ++_i) \
;         __builtin_amdgcn_global_load_lds((const unsigned*)((const char*)(gbase) + (voff)[_i]), (LAS unsigned*)(lds + (bufoff) + ldsw + _i * 8192), 16, 0, 0); } while (0)
; #define PG8_LDA(dst, b, h) do { _Pragma("unroll") for (int m = 0; m < 4; ++m) _Pragma("unroll") for (int k = 0; k < 2; ++k) dst[m][k] = *(const LAS bf16x8*)(lds + PG8_SA(b, h) + aoff + m * 2048 + k * 1024); } while (0)
; #define PG8_MMA(ai, bj, At, Bt) do { __builtin_amdgcn_s_setprio(1); _Pragma("unroll") for (int m = 0; m < 4; ++m) _Pragma("unroll") for (int n = 0; n < 2; ++n) _Pragma("unroll") for (int k = 0; k < 2; ++k) \
;         acc[ai][bj][m][n] = __builtin_amdgcn_mfma_f32_16x16x32_bf16(Bt[n][k], At[m][k], acc[ai][bj][m][n], 0, 0, 0); __builtin_amdgcn_s_setprio(0); } while (0)
; #define PG8_WAIT_V(n) asm volatile("s_waitcnt vmcnt(" #n ")" ::: "memory")
; #define PG8_WAIT_L(n) asm volatile("s_waitcnt lgkmcnt(" #n ")" ::: "memory")
; #define PG8_BAR __builtin_amdgcn_s_barrier()
; #define PG8_SCHED __builtin_amdgcn_sched_barrier(0)
; template <class Epi, class Sched>
; __device__ __forceinline__ void gemm_phase(LAS unsigned char* lds, const Gemm g, const Sched& S, const Epi& E) {
;     ...
;             PG8_BAR; PG8_WAIT_L(0); PG8_MMA(0, 1, At, B1); PG8_BAR;
;             PG8_LDA(At, 1, 1); PG8_STAGE(PG8_SA(1, 0), a3, voffA);
;             PG8_BAR; PG8_WAIT_L(0); PG8_MMA(1, 0, At, B0); PG8_BAR; PG8_SCHED;
;             PG8_STAGE(PG8_SB(1, 1), b3 + hstep, voffB);
;             PG8_WAIT_V(6); PG8_BAR; PG8_MMA(1, 1, At, B1); PG8_BAR;
;         }
	s_waitcnt lgkmcnt(0)
	s_setprio 1
	s_waitcnt lgkmcnt(0)
	v_mfma_f32_16x16x32_bf16 v[116:119], v[176:179], v[144:147], v[116:119]
	v_mfma_f32_16x16x32_bf16 v[112:115], v[184:187], v[144:147], v[112:115]
	v_mfma_f32_16x16x32_bf16 v[100:103], v[176:179], v[152:155], v[100:103]
	v_mfma_f32_16x16x32_bf16 v[96:99], v[184:187], v[152:155], v[96:99]
	v_mfma_f32_16x16x32_bf16 v[84:87], v[176:179], v[160:163], v[84:87]
	v_mfma_f32_16x16x32_bf16 v[80:83], v[184:187], v[160:163], v[80:83]
	v_mfma_f32_16x16x32_bf16 v[68:71], v[176:179], v[168:171], v[68:71]
	v_mfma_f32_16x16x32_bf16 v[64:67], v[184:187], v[168:171], v[64:67]
	v_mfma_f32_16x16x32_bf16 v[116:119], v[180:183], v[148:151], v[116:119]
	v_mfma_f32_16x16x32_bf16 v[112:115], v[206:209], v[148:151], v[112:115]
	v_mfma_f32_16x16x32_bf16 v[100:103], v[180:183], v[156:159], v[100:103]
	v_mfma_f32_16x16x32_bf16 v[96:99], v[206:209], v[156:159], v[96:99]
	v_mfma_f32_16x16x32_bf16 v[84:87], v[180:183], v[164:167], v[84:87]
	v_mfma_f32_16x16x32_bf16 v[80:83], v[206:209], v[164:167], v[80:83]
	v_mfma_f32_16x16x32_bf16 v[68:71], v[180:183], v[172:175], v[68:71]
	v_mfma_f32_16x16x32_bf16 v[64:67], v[206:209], v[172:175], v[64:67]
	s_setprio 0
	s_mov_b32 m0, s44
	s_mov_b64 s[0:1], 0x80
	v_lshl_add_u64 v[210:211], v[214:215], 0, s[0:1]
	s_barrier
	ds_read_b128 v[144:147], v242 offset:49152
	ds_read_b128 v[148:151], v242 offset:50176
	ds_read_b128 v[152:155], v242 offset:51200
	ds_read_b128 v[156:159], v242 offset:52224
	ds_read_b128 v[160:163], v242 offset:53248
	ds_read_b128 v[164:167], v242 offset:54272
	ds_read_b128 v[168:171], v242 offset:55296
	ds_read_b128 v[172:175], v242 offset:56320
	global_load_lds_dwordx4 v[210:211], off
	v_lshl_add_u64 v[210:211], v[216:217], 0, s[0:1]
	s_mov_b32 m0, s45
	s_nop 0
	global_load_lds_dwordx4 v[210:211], off
	s_barrier
	s_waitcnt lgkmcnt(0)
	s_setprio 1
	s_waitcnt lgkmcnt(0)
	v_mfma_f32_16x16x32_bf16 v[60:63], v[128:131], v[144:147], v[60:63]
	v_mfma_f32_16x16x32_bf16 v[56:59], v[136:139], v[144:147], v[56:59]
	v_mfma_f32_16x16x32_bf16 v[44:47], v[128:131], v[152:155], v[44:47]
	v_mfma_f32_16x16x32_bf16 v[40:43], v[136:139], v[152:155], v[40:43]
	v_mfma_f32_16x16x32_bf16 v[28:31], v[128:131], v[160:163], v[28:31]
	v_mfma_f32_16x16x32_bf16 v[24:27], v[136:139], v[160:163], v[24:27]
	v_mfma_f32_16x16x32_bf16 v[12:15], v[128:131], v[168:171], v[12:15]
	v_mfma_f32_16x16x32_bf16 v[8:11], v[136:139], v[168:171], v[8:11]
	v_mfma_f32_16x16x32_bf16 v[60:63], v[132:135], v[148:151], v[60:63]
	v_mfma_f32_16x16x32_bf16 v[56:59], v[140:143], v[148:151], v[56:59]
	v_mfma_f32_16x16x32_bf16 v[44:47], v[132:135], v[156:159], v[44:47]
	v_mfma_f32_16x16x32_bf16 v[40:43], v[140:143], v[156:159], v[40:43]
	v_mfma_f32_16x16x32_bf16 v[28:31], v[132:135], v[164:167], v[28:31]
	v_mfma_f32_16x16x32_bf16 v[24:27], v[140:143], v[164:167], v[24:27]
	v_mfma_f32_16x16x32_bf16 v[12:15], v[132:135], v[172:175], v[12:15]
	v_mfma_f32_16x16x32_bf16 v[8:11], v[140:143], v[172:175], v[8:11]
	s_setprio 0
	s_barrier
	s_add_u32 s22, s26, 0xb0080
	s_addc_u32 s23, s27, 0
	s_add_i32 s26, s28, s34
	s_mov_b32 m0, s26
	s_nop 0
	global_load_lds_dwordx4 v190, s[22:23]
	s_add_i32 m0, s26, 0x2000
	s_nop 0
	global_load_lds_dwordx4 v194, s[22:23]
	s_waitcnt vmcnt(10)
	s_barrier
	s_setprio 1
	v_mfma_f32_16x16x32_bf16 v[52:55], v[176:179], v[144:147], v[52:55]
	v_mfma_f32_16x16x32_bf16 v[48:51], v[184:187], v[144:147], v[48:51]
	v_mfma_f32_16x16x32_bf16 v[36:39], v[176:179], v[152:155], v[36:39]
	v_mfma_f32_16x16x32_bf16 v[32:35], v[184:187], v[152:155], v[32:35]
	v_mfma_f32_16x16x32_bf16 v[20:23], v[176:179], v[160:163], v[20:23]
	v_mfma_f32_16x16x32_bf16 v[16:19], v[184:187], v[160:163], v[16:19]
	v_mfma_f32_16x16x32_bf16 v[4:7], v[176:179], v[168:171], v[4:7]
	v_mfma_f32_16x16x32_bf16 v[0:3], v[184:187], v[168:171], v[0:3]
	v_mfma_f32_16x16x32_bf16 v[52:55], v[180:183], v[148:151], v[52:55]
	v_mfma_f32_16x16x32_bf16 v[48:51], v[206:209], v[148:151], v[48:51]
	v_mfma_f32_16x16x32_bf16 v[36:39], v[180:183], v[156:159], v[36:39]
	v_mfma_f32_16x16x32_bf16 v[32:35], v[206:209], v[156:159], v[32:35]
	v_mfma_f32_16x16x32_bf16 v[20:23], v[180:183], v[164:167], v[20:23]
	v_mfma_f32_16x16x32_bf16 v[16:19], v[206:209], v[164:167], v[16:19]
	v_mfma_f32_16x16x32_bf16 v[4:7], v[180:183], v[172:175], v[4:7]
	v_mfma_f32_16x16x32_bf16 v[0:3], v[206:209], v[172:175], v[0:3]
	s_setprio 0
	s_add_i32 s56, s56, 2
	s_add_u32 s54, s54, 0x100
	s_addc_u32 s55, s55, 0
	s_cmp_gt_u32 s56, 41
	s_mov_b64 s[22:23], s[24:25]
	s_barrier
